# Hyena FFT: LDS exchange between the first two radix-16 passes uses a 4-bit XOR storage permutation (stride-16 writes were 4-way bank conflicted under the baseline swizzle)
# speedup vs baseline: 1.0078x; 1.0078x over previous
; DI f32x2 cmul(f32x2 a, f32x2 b) { return mkf2(a.x * b.x - a.y * b.y, a.x * b.y + a.y * b.x); }
; DI void fft8192(f32x2* buf, const f32x2* __restrict__ tw) {
;     ...
;     __syncthreads();
; #pragma unroll
;     for (int e = 0; e < 8; ++e) {
;       const int i = tid + 256 * e;
;       const int pi = SW(i);
;       a[e] = buf[pi]; b[e] = buf[pi + 2048]; c[e] = buf[pi + 4096]; d[e] = buf[pi + 6144];
;     }
;     __syncthreads();
; #pragma unroll
;     for (int e = 0; e < 8; ++e) {
;       const int i = tid + 256 * e;
;       const int q = i & (s - 1);
;       const int ps = i - q;
;       const float rev = (float)ps * (1.f / 8192.f);
;       const f32x2 w1 = mkf2(__builtin_amdgcn_cosf(rev), -__builtin_amdgcn_sinf(rev));
;       const f32x2 w2 = cmul(w1, w1), w3 = cmul(w1, w2);
;       const f32x2 apc = mkf2(a[e].x + c[e].x, a[e].y + c[e].y), amc = mkf2(a[e].x - c[e].x, a[e].y - c[e].y);
;       const f32x2 bpd = mkf2(b[e].x + d[e].x, b[e].y + d[e].y), bmd = mkf2(b[e].x - d[e].x, b[e].y - d[e].y);
;       const int o = 4 * i - 3 * q;
;       buf[SW(o)] = mkf2(apc.x + bpd.x, apc.y + bpd.y);
;       buf[SW(o + s)] = cmul(w1, mkf2(amc.x + bmd.y, amc.y - bmd.x));
;       buf[SW(o + 2 * s)] = cmul(w2, mkf2(apc.x - bpd.x, apc.y - bpd.y));
;       buf[SW(o + 3 * s)] = cmul(w3, mkf2(amc.x - bmd.y, amc.y + bmd.x));
;     }
.LBB0_933:
	v_bfe_i32 v166, v0, 5, 1
	v_bfe_i32 v168, v0, 6, 1
	v_and_b32_e32 v166, 5, v166
	v_and_b32_e32 v168, 26, v168
	v_xor_b32_e32 v166, v166, v168
	v_xor_b32_e32 v166, v166, v0
	v_lshlrev_b32_e32 v154, 3, v166
	s_waitcnt lgkmcnt(0)
	s_barrier
	ds_read2st64_b64 v[2:5], v154 offset0:0 offset1:32
	ds_read2st64_b64 v[6:9], v154 offset0:64 offset1:96
	ds_read2st64_b64 v[10:13], v154 offset0:4 offset1:36
	ds_read2st64_b64 v[14:17], v154 offset0:68 offset1:100
	ds_read2st64_b64 v[18:21], v154 offset0:8 offset1:40
	ds_read2st64_b64 v[22:25], v154 offset0:72 offset1:104
	ds_read2st64_b64 v[26:29], v154 offset0:12 offset1:44
	ds_read2st64_b64 v[30:33], v154 offset0:76 offset1:108
	ds_read2st64_b64 v[34:37], v154 offset0:16 offset1:48
	ds_read2st64_b64 v[38:41], v154 offset0:80 offset1:112
	ds_read2st64_b64 v[42:45], v154 offset0:20 offset1:52
	ds_read2st64_b64 v[46:49], v154 offset0:84 offset1:116
	ds_read2st64_b64 v[50:53], v154 offset0:24 offset1:56
	ds_read2st64_b64 v[54:57], v154 offset0:88 offset1:120
	ds_read2st64_b64 v[58:61], v154 offset0:28 offset1:60
	ds_read2st64_b64 v[62:65], v154 offset0:92 offset1:124
	v_cvt_f32_u32_e32 v201, v0
	v_and_b32_e32 v166, 15, v0
	v_lshlrev_b32_e32 v166, 3, v166
	v_lshl_add_u32 v164, v0, 7, v166
	v_mul_f32_e32 v201, 0x39000000, v201
	v_cos_f32_e32 v210, v201
	v_sin_f32_e64 v211, -v201
	s_waitcnt lgkmcnt(14)
	v_pk_add_f32 v[202:203], v[2:3], v[6:7]
	v_pk_add_f32 v[2:3], v[2:3], v[6:7] neg_lo:[0,1] neg_hi:[0,1]
	v_pk_add_f32 v[204:205], v[4:5], v[8:9]
	v_pk_add_f32 v[4:5], v[4:5], v[8:9] neg_lo:[0,1] neg_hi:[0,1]
	v_pk_add_f32 v[6:7], v[202:203], v[204:205]
	v_pk_add_f32 v[8:9], v[202:203], v[204:205] neg_lo:[0,1] neg_hi:[0,1]
	v_pk_add_f32 v[202:203], v[2:3], v[4:5] op_sel:[0,1] op_sel_hi:[1,0] neg_hi:[0,1]
	v_pk_add_f32 v[204:205], v[2:3], v[4:5] op_sel:[0,1] op_sel_hi:[1,0] neg_lo:[0,1]
	v_pk_mul_f32 v[206:207], v[210:211], v[210:211] op_sel:[1,1] op_sel_hi:[1,0]
	v_pk_fma_f32 v[212:213], v[210:211], v[210:211], v[206:207] op_sel_hi:[0,1,1] neg_lo:[0,0,1]
	v_pk_mul_f32 v[206:207], v[210:211], v[212:213] op_sel:[1,1] op_sel_hi:[1,0]
	v_pk_fma_f32 v[220:221], v[210:211], v[212:213], v[206:207] op_sel_hi:[0,1,1] neg_lo:[0,0,1]
	v_pk_mul_f32 v[2:3], v[210:211], v[202:203] op_sel:[1,1] op_sel_hi:[1,0]
	v_pk_fma_f32 v[2:3], v[210:211], v[202:203], v[2:3] op_sel_hi:[0,1,1] neg_lo:[0,0,1]
	v_pk_mul_f32 v[4:5], v[212:213], v[8:9] op_sel:[1,1] op_sel_hi:[1,0]
	v_pk_fma_f32 v[4:5], v[212:213], v[8:9], v[4:5] op_sel_hi:[0,1,1] neg_lo:[0,0,1]
	v_pk_mul_f32 v[8:9], v[220:221], v[204:205] op_sel:[1,1] op_sel_hi:[1,0]
	v_pk_fma_f32 v[8:9], v[220:221], v[204:205], v[8:9] op_sel_hi:[0,1,1] neg_lo:[0,0,1]
	v_add_f32_e32 v214, 0x3d000000, v201
	v_cos_f32_e32 v210, v214
	v_sin_f32_e64 v211, -v214
	s_waitcnt lgkmcnt(12)
	v_pk_add_f32 v[202:203], v[10:11], v[14:15]
	v_pk_add_f32 v[10:11], v[10:11], v[14:15] neg_lo:[0,1] neg_hi:[0,1]
	v_pk_add_f32 v[204:205], v[12:13], v[16:17]
	v_pk_add_f32 v[12:13], v[12:13], v[16:17] neg_lo:[0,1] neg_hi:[0,1]
	v_pk_add_f32 v[14:15], v[202:203], v[204:205]
	v_pk_add_f32 v[16:17], v[202:203], v[204:205] neg_lo:[0,1] neg_hi:[0,1]
	v_pk_add_f32 v[202:203], v[10:11], v[12:13] op_sel:[0,1] op_sel_hi:[1,0] neg_hi:[0,1]
	v_pk_add_f32 v[204:205], v[10:11], v[12:13] op_sel:[0,1] op_sel_hi:[1,0] neg_lo:[0,1]
	v_pk_mul_f32 v[206:207], v[210:211], v[210:211] op_sel:[1,1] op_sel_hi:[1,0]
	v_pk_fma_f32 v[212:213], v[210:211], v[210:211], v[206:207] op_sel_hi:[0,1,1] neg_lo:[0,0,1]
	v_pk_mul_f32 v[206:207], v[210:211], v[212:213] op_sel:[1,1] op_sel_hi:[1,0]
	v_pk_fma_f32 v[220:221], v[210:211], v[212:213], v[206:207] op_sel_hi:[0,1,1] neg_lo:[0,0,1]
	v_pk_mul_f32 v[10:11], v[210:211], v[202:203] op_sel:[1,1] op_sel_hi:[1,0]
	v_pk_fma_f32 v[10:11], v[210:211], v[202:203], v[10:11] op_sel_hi:[0,1,1] neg_lo:[0,0,1]
	v_pk_mul_f32 v[12:13], v[212:213], v[16:17] op_sel:[1,1] op_sel_hi:[1,0]
	v_pk_fma_f32 v[12:13], v[212:213], v[16:17], v[12:13] op_sel_hi:[0,1,1] neg_lo:[0,0,1]
	v_pk_mul_f32 v[16:17], v[220:221], v[204:205] op_sel:[1,1] op_sel_hi:[1,0]
	v_pk_fma_f32 v[16:17], v[220:221], v[204:205], v[16:17] op_sel_hi:[0,1,1] neg_lo:[0,0,1]
	v_add_f32_e32 v214, 0x3d800000, v201
	v_cos_f32_e32 v210, v214
	v_sin_f32_e64 v211, -v214
	s_waitcnt lgkmcnt(10)
	v_pk_add_f32 v[202:203], v[18:19], v[22:23]
	v_pk_add_f32 v[18:19], v[18:19], v[22:23] neg_lo:[0,1] neg_hi:[0,1]
	v_pk_add_f32 v[204:205], v[20:21], v[24:25]
	v_pk_add_f32 v[20:21], v[20:21], v[24:25] neg_lo:[0,1] neg_hi:[0,1]
	v_pk_add_f32 v[22:23], v[202:203], v[204:205]
	v_pk_add_f32 v[24:25], v[202:203], v[204:205] neg_lo:[0,1] neg_hi:[0,1]
	v_pk_add_f32 v[202:203], v[18:19], v[20:21] op_sel:[0,1] op_sel_hi:[1,0] neg_hi:[0,1]
	v_pk_add_f32 v[204:205], v[18:19], v[20:21] op_sel:[0,1] op_sel_hi:[1,0] neg_lo:[0,1]
	v_pk_mul_f32 v[206:207], v[210:211], v[210:211] op_sel:[1,1] op_sel_hi:[1,0]
	v_pk_fma_f32 v[212:213], v[210:211], v[210:211], v[206:207] op_sel_hi:[0,1,1] neg_lo:[0,0,1]
	v_pk_mul_f32 v[206:207], v[210:211], v[212:213] op_sel:[1,1] op_sel_hi:[1,0]
	v_pk_fma_f32 v[220:221], v[210:211], v[212:213], v[206:207] op_sel_hi:[0,1,1] neg_lo:[0,0,1]
	v_pk_mul_f32 v[18:19], v[210:211], v[202:203] op_sel:[1,1] op_sel_hi:[1,0]
	v_pk_fma_f32 v[18:19], v[210:211], v[202:203], v[18:19] op_sel_hi:[0,1,1] neg_lo:[0,0,1]
	v_pk_mul_f32 v[20:21], v[212:213], v[24:25] op_sel:[1,1] op_sel_hi:[1,0]
	v_pk_fma_f32 v[20:21], v[212:213], v[24:25], v[20:21] op_sel_hi:[0,1,1] neg_lo:[0,0,1]
	v_pk_mul_f32 v[24:25], v[220:221], v[204:205] op_sel:[1,1] op_sel_hi:[1,0]
	v_pk_fma_f32 v[24:25], v[220:221], v[204:205], v[24:25] op_sel_hi:[0,1,1] neg_lo:[0,0,1]
	v_add_f32_e32 v214, 0x3dc00000, v201
	v_cos_f32_e32 v210, v214
	v_sin_f32_e64 v211, -v214
	s_waitcnt lgkmcnt(8)
; DI f32x2 cmul(f32x2 a, f32x2 b) { return mkf2(a.x * b.x - a.y * b.y, a.x * b.y + a.y * b.x); }
; DI void fft8192(f32x2* buf, const f32x2* __restrict__ tw) {
;     ...
; #pragma unroll
;     for (int e = 0; e < 8; ++e) {
;       const int i = tid + 256 * e;
;       const int q = i & (s - 1);
;       const int ps = i - q;
;       const float rev = (float)ps * (1.f / 8192.f);
;       const f32x2 w1 = mkf2(__builtin_amdgcn_cosf(rev), -__builtin_amdgcn_sinf(rev));
;       const f32x2 w2 = cmul(w1, w1), w3 = cmul(w1, w2);
;       const f32x2 apc = mkf2(a[e].x + c[e].x, a[e].y + c[e].y), amc = mkf2(a[e].x - c[e].x, a[e].y - c[e].y);
;       const f32x2 bpd = mkf2(b[e].x + d[e].x, b[e].y + d[e].y), bmd = mkf2(b[e].x - d[e].x, b[e].y - d[e].y);
;       const int o = 4 * i - 3 * q;
;       buf[SW(o)] = mkf2(apc.x + bpd.x, apc.y + bpd.y);
;       buf[SW(o + s)] = cmul(w1, mkf2(amc.x + bmd.y, amc.y - bmd.x));
;       buf[SW(o + 2 * s)] = cmul(w2, mkf2(apc.x - bpd.x, apc.y - bpd.y));
;       buf[SW(o + 3 * s)] = cmul(w3, mkf2(amc.x - bmd.y, amc.y + bmd.x));
;     }
	v_pk_add_f32 v[202:203], v[26:27], v[30:31]
	v_pk_add_f32 v[26:27], v[26:27], v[30:31] neg_lo:[0,1] neg_hi:[0,1]
	v_pk_add_f32 v[204:205], v[28:29], v[32:33]
	v_pk_add_f32 v[28:29], v[28:29], v[32:33] neg_lo:[0,1] neg_hi:[0,1]
	v_pk_add_f32 v[30:31], v[202:203], v[204:205]
	v_pk_add_f32 v[32:33], v[202:203], v[204:205] neg_lo:[0,1] neg_hi:[0,1]
	v_pk_add_f32 v[202:203], v[26:27], v[28:29] op_sel:[0,1] op_sel_hi:[1,0] neg_hi:[0,1]
	v_pk_add_f32 v[204:205], v[26:27], v[28:29] op_sel:[0,1] op_sel_hi:[1,0] neg_lo:[0,1]
	v_pk_mul_f32 v[206:207], v[210:211], v[210:211] op_sel:[1,1] op_sel_hi:[1,0]
	v_pk_fma_f32 v[212:213], v[210:211], v[210:211], v[206:207] op_sel_hi:[0,1,1] neg_lo:[0,0,1]
	v_pk_mul_f32 v[206:207], v[210:211], v[212:213] op_sel:[1,1] op_sel_hi:[1,0]
	v_pk_fma_f32 v[220:221], v[210:211], v[212:213], v[206:207] op_sel_hi:[0,1,1] neg_lo:[0,0,1]
	v_pk_mul_f32 v[26:27], v[210:211], v[202:203] op_sel:[1,1] op_sel_hi:[1,0]
	v_pk_fma_f32 v[26:27], v[210:211], v[202:203], v[26:27] op_sel_hi:[0,1,1] neg_lo:[0,0,1]
	v_pk_mul_f32 v[28:29], v[212:213], v[32:33] op_sel:[1,1] op_sel_hi:[1,0]
	v_pk_fma_f32 v[28:29], v[212:213], v[32:33], v[28:29] op_sel_hi:[0,1,1] neg_lo:[0,0,1]
	v_pk_mul_f32 v[32:33], v[220:221], v[204:205] op_sel:[1,1] op_sel_hi:[1,0]
	v_pk_fma_f32 v[32:33], v[220:221], v[204:205], v[32:33] op_sel_hi:[0,1,1] neg_lo:[0,0,1]
	v_add_f32_e32 v214, 0x3e000000, v201
	v_cos_f32_e32 v210, v214
	v_sin_f32_e64 v211, -v214
	s_waitcnt lgkmcnt(6)
	v_pk_add_f32 v[202:203], v[34:35], v[38:39]
	v_pk_add_f32 v[34:35], v[34:35], v[38:39] neg_lo:[0,1] neg_hi:[0,1]
	v_pk_add_f32 v[204:205], v[36:37], v[40:41]
	v_pk_add_f32 v[36:37], v[36:37], v[40:41] neg_lo:[0,1] neg_hi:[0,1]
	v_pk_add_f32 v[38:39], v[202:203], v[204:205]
	v_pk_add_f32 v[40:41], v[202:203], v[204:205] neg_lo:[0,1] neg_hi:[0,1]
	v_pk_add_f32 v[202:203], v[34:35], v[36:37] op_sel:[0,1] op_sel_hi:[1,0] neg_hi:[0,1]
	v_pk_add_f32 v[204:205], v[34:35], v[36:37] op_sel:[0,1] op_sel_hi:[1,0] neg_lo:[0,1]
	v_pk_mul_f32 v[206:207], v[210:211], v[210:211] op_sel:[1,1] op_sel_hi:[1,0]
	v_pk_fma_f32 v[212:213], v[210:211], v[210:211], v[206:207] op_sel_hi:[0,1,1] neg_lo:[0,0,1]
	v_pk_mul_f32 v[206:207], v[210:211], v[212:213] op_sel:[1,1] op_sel_hi:[1,0]
	v_pk_fma_f32 v[220:221], v[210:211], v[212:213], v[206:207] op_sel_hi:[0,1,1] neg_lo:[0,0,1]
	v_pk_mul_f32 v[34:35], v[210:211], v[202:203] op_sel:[1,1] op_sel_hi:[1,0]
	v_pk_fma_f32 v[34:35], v[210:211], v[202:203], v[34:35] op_sel_hi:[0,1,1] neg_lo:[0,0,1]
	v_pk_mul_f32 v[36:37], v[212:213], v[40:41] op_sel:[1,1] op_sel_hi:[1,0]
	v_pk_fma_f32 v[36:37], v[212:213], v[40:41], v[36:37] op_sel_hi:[0,1,1] neg_lo:[0,0,1]
	v_pk_mul_f32 v[40:41], v[220:221], v[204:205] op_sel:[1,1] op_sel_hi:[1,0]
	v_pk_fma_f32 v[40:41], v[220:221], v[204:205], v[40:41] op_sel_hi:[0,1,1] neg_lo:[0,0,1]
	v_add_f32_e32 v214, 0x3e200000, v201
	v_cos_f32_e32 v210, v214
	v_sin_f32_e64 v211, -v214
	s_waitcnt lgkmcnt(4)
	v_pk_add_f32 v[202:203], v[42:43], v[46:47]
	v_pk_add_f32 v[42:43], v[42:43], v[46:47] neg_lo:[0,1] neg_hi:[0,1]
	v_pk_add_f32 v[204:205], v[44:45], v[48:49]
	v_pk_add_f32 v[44:45], v[44:45], v[48:49] neg_lo:[0,1] neg_hi:[0,1]
	v_pk_add_f32 v[46:47], v[202:203], v[204:205]
	v_pk_add_f32 v[48:49], v[202:203], v[204:205] neg_lo:[0,1] neg_hi:[0,1]
	v_pk_add_f32 v[202:203], v[42:43], v[44:45] op_sel:[0,1] op_sel_hi:[1,0] neg_hi:[0,1]
	v_pk_add_f32 v[204:205], v[42:43], v[44:45] op_sel:[0,1] op_sel_hi:[1,0] neg_lo:[0,1]
	v_pk_mul_f32 v[206:207], v[210:211], v[210:211] op_sel:[1,1] op_sel_hi:[1,0]
	v_pk_fma_f32 v[212:213], v[210:211], v[210:211], v[206:207] op_sel_hi:[0,1,1] neg_lo:[0,0,1]
	v_pk_mul_f32 v[206:207], v[210:211], v[212:213] op_sel:[1,1] op_sel_hi:[1,0]
	v_pk_fma_f32 v[220:221], v[210:211], v[212:213], v[206:207] op_sel_hi:[0,1,1] neg_lo:[0,0,1]
	v_pk_mul_f32 v[42:43], v[210:211], v[202:203] op_sel:[1,1] op_sel_hi:[1,0]
	v_pk_fma_f32 v[42:43], v[210:211], v[202:203], v[42:43] op_sel_hi:[0,1,1] neg_lo:[0,0,1]
	v_pk_mul_f32 v[44:45], v[212:213], v[48:49] op_sel:[1,1] op_sel_hi:[1,0]
	v_pk_fma_f32 v[44:45], v[212:213], v[48:49], v[44:45] op_sel_hi:[0,1,1] neg_lo:[0,0,1]
	v_pk_mul_f32 v[48:49], v[220:221], v[204:205] op_sel:[1,1] op_sel_hi:[1,0]
	v_pk_fma_f32 v[48:49], v[220:221], v[204:205], v[48:49] op_sel_hi:[0,1,1] neg_lo:[0,0,1]
	v_add_f32_e32 v214, 0x3e400000, v201
	v_cos_f32_e32 v210, v214
	v_sin_f32_e64 v211, -v214
	s_waitcnt lgkmcnt(2)
	v_pk_add_f32 v[202:203], v[50:51], v[54:55]
	v_pk_add_f32 v[50:51], v[50:51], v[54:55] neg_lo:[0,1] neg_hi:[0,1]
	v_pk_add_f32 v[204:205], v[52:53], v[56:57]
	v_pk_add_f32 v[52:53], v[52:53], v[56:57] neg_lo:[0,1] neg_hi:[0,1]
	v_pk_add_f32 v[54:55], v[202:203], v[204:205]
	v_pk_add_f32 v[56:57], v[202:203], v[204:205] neg_lo:[0,1] neg_hi:[0,1]
	v_pk_add_f32 v[202:203], v[50:51], v[52:53] op_sel:[0,1] op_sel_hi:[1,0] neg_hi:[0,1]
	v_pk_add_f32 v[204:205], v[50:51], v[52:53] op_sel:[0,1] op_sel_hi:[1,0] neg_lo:[0,1]
	v_pk_mul_f32 v[206:207], v[210:211], v[210:211] op_sel:[1,1] op_sel_hi:[1,0]
	v_pk_fma_f32 v[212:213], v[210:211], v[210:211], v[206:207] op_sel_hi:[0,1,1] neg_lo:[0,0,1]
	v_pk_mul_f32 v[206:207], v[210:211], v[212:213] op_sel:[1,1] op_sel_hi:[1,0]
	v_pk_fma_f32 v[220:221], v[210:211], v[212:213], v[206:207] op_sel_hi:[0,1,1] neg_lo:[0,0,1]
	v_pk_mul_f32 v[50:51], v[210:211], v[202:203] op_sel:[1,1] op_sel_hi:[1,0]
	v_pk_fma_f32 v[50:51], v[210:211], v[202:203], v[50:51] op_sel_hi:[0,1,1] neg_lo:[0,0,1]
	v_pk_mul_f32 v[52:53], v[212:213], v[56:57] op_sel:[1,1] op_sel_hi:[1,0]
	v_pk_fma_f32 v[52:53], v[212:213], v[56:57], v[52:53] op_sel_hi:[0,1,1] neg_lo:[0,0,1]
	v_pk_mul_f32 v[56:57], v[220:221], v[204:205] op_sel:[1,1] op_sel_hi:[1,0]
	v_pk_fma_f32 v[56:57], v[220:221], v[204:205], v[56:57] op_sel_hi:[0,1,1] neg_lo:[0,0,1]
	v_add_f32_e32 v214, 0x3e600000, v201
	v_cos_f32_e32 v210, v214
	v_sin_f32_e64 v211, -v214
	s_waitcnt lgkmcnt(0)
; DI f32x2 cmul(f32x2 a, f32x2 b) { return mkf2(a.x * b.x - a.y * b.y, a.x * b.y + a.y * b.x); }
; DI void fft8192(f32x2* buf, const f32x2* __restrict__ tw) {
;     ...
; #pragma unroll
;     for (int e = 0; e < 8; ++e) {
;       const int i = tid + 256 * e;
;       const int q = i & (s - 1);
;       const int ps = i - q;
;       const float rev = (float)ps * (1.f / 8192.f);
;       const f32x2 w1 = mkf2(__builtin_amdgcn_cosf(rev), -__builtin_amdgcn_sinf(rev));
;       const f32x2 w2 = cmul(w1, w1), w3 = cmul(w1, w2);
;       const f32x2 apc = mkf2(a[e].x + c[e].x, a[e].y + c[e].y), amc = mkf2(a[e].x - c[e].x, a[e].y - c[e].y);
;       const f32x2 bpd = mkf2(b[e].x + d[e].x, b[e].y + d[e].y), bmd = mkf2(b[e].x - d[e].x, b[e].y - d[e].y);
;       const int o = 4 * i - 3 * q;
;       buf[SW(o)] = mkf2(apc.x + bpd.x, apc.y + bpd.y);
;       buf[SW(o + s)] = cmul(w1, mkf2(amc.x + bmd.y, amc.y - bmd.x));
;       buf[SW(o + 2 * s)] = cmul(w2, mkf2(apc.x - bpd.x, apc.y - bpd.y));
;       buf[SW(o + 3 * s)] = cmul(w3, mkf2(amc.x - bmd.y, amc.y + bmd.x));
;     }
	v_pk_add_f32 v[202:203], v[58:59], v[62:63]
	v_pk_add_f32 v[58:59], v[58:59], v[62:63] neg_lo:[0,1] neg_hi:[0,1]
	v_pk_add_f32 v[204:205], v[60:61], v[64:65]
	v_pk_add_f32 v[60:61], v[60:61], v[64:65] neg_lo:[0,1] neg_hi:[0,1]
	v_pk_add_f32 v[62:63], v[202:203], v[204:205]
	v_pk_add_f32 v[64:65], v[202:203], v[204:205] neg_lo:[0,1] neg_hi:[0,1]
	v_pk_add_f32 v[202:203], v[58:59], v[60:61] op_sel:[0,1] op_sel_hi:[1,0] neg_hi:[0,1]
	v_pk_add_f32 v[204:205], v[58:59], v[60:61] op_sel:[0,1] op_sel_hi:[1,0] neg_lo:[0,1]
	v_pk_mul_f32 v[206:207], v[210:211], v[210:211] op_sel:[1,1] op_sel_hi:[1,0]
	v_pk_fma_f32 v[212:213], v[210:211], v[210:211], v[206:207] op_sel_hi:[0,1,1] neg_lo:[0,0,1]
	v_pk_mul_f32 v[206:207], v[210:211], v[212:213] op_sel:[1,1] op_sel_hi:[1,0]
	v_pk_fma_f32 v[220:221], v[210:211], v[212:213], v[206:207] op_sel_hi:[0,1,1] neg_lo:[0,0,1]
	v_pk_mul_f32 v[58:59], v[210:211], v[202:203] op_sel:[1,1] op_sel_hi:[1,0]
	v_pk_fma_f32 v[58:59], v[210:211], v[202:203], v[58:59] op_sel_hi:[0,1,1] neg_lo:[0,0,1]
	v_pk_mul_f32 v[60:61], v[212:213], v[64:65] op_sel:[1,1] op_sel_hi:[1,0]
	v_pk_fma_f32 v[60:61], v[212:213], v[64:65], v[60:61] op_sel_hi:[0,1,1] neg_lo:[0,0,1]
	v_pk_mul_f32 v[64:65], v[220:221], v[204:205] op_sel:[1,1] op_sel_hi:[1,0]
	v_pk_fma_f32 v[64:65], v[220:221], v[204:205], v[64:65] op_sel_hi:[0,1,1] neg_lo:[0,0,1]
	s_barrier
	v_mul_f32_e32 v214, 4.0, v201
	v_cos_f32_e32 v224, v214
	v_sin_f32_e64 v225, -v214
	s_nop 0
	v_pk_mul_f32 v[206:207], v[224:225], v[224:225] op_sel:[1,1] op_sel_hi:[1,0]
	v_pk_fma_f32 v[226:227], v[224:225], v[224:225], v[206:207] op_sel_hi:[0,1,1] neg_lo:[0,0,1]
	v_pk_mul_f32 v[206:207], v[224:225], v[226:227] op_sel:[1,1] op_sel_hi:[1,0]
	v_pk_fma_f32 v[230:231], v[224:225], v[226:227], v[206:207] op_sel_hi:[0,1,1] neg_lo:[0,0,1]
	v_pk_add_f32 v[202:203], v[6:7], v[38:39]
	v_pk_add_f32 v[6:7], v[6:7], v[38:39] neg_lo:[0,1] neg_hi:[0,1]
	v_pk_add_f32 v[204:205], v[22:23], v[54:55]
	v_pk_add_f32 v[22:23], v[22:23], v[54:55] neg_lo:[0,1] neg_hi:[0,1]
	v_pk_add_f32 v[38:39], v[202:203], v[204:205]
	v_pk_add_f32 v[54:55], v[202:203], v[204:205] neg_lo:[0,1] neg_hi:[0,1]
	v_pk_add_f32 v[202:203], v[6:7], v[22:23] op_sel:[0,1] op_sel_hi:[1,0] neg_hi:[0,1]
	v_pk_add_f32 v[204:205], v[6:7], v[22:23] op_sel:[0,1] op_sel_hi:[1,0] neg_lo:[0,1]
	v_pk_mul_f32 v[6:7], v[224:225], v[202:203] op_sel:[1,1] op_sel_hi:[1,0]
	v_pk_fma_f32 v[6:7], v[224:225], v[202:203], v[6:7] op_sel_hi:[0,1,1] neg_lo:[0,0,1]
	v_pk_mul_f32 v[22:23], v[226:227], v[54:55] op_sel:[1,1] op_sel_hi:[1,0]
	v_pk_fma_f32 v[22:23], v[226:227], v[54:55], v[22:23] op_sel_hi:[0,1,1] neg_lo:[0,0,1]
	v_pk_mul_f32 v[54:55], v[230:231], v[204:205] op_sel:[1,1] op_sel_hi:[1,0]
	v_pk_fma_f32 v[54:55], v[230:231], v[204:205], v[54:55] op_sel_hi:[0,1,1] neg_lo:[0,0,1]
	v_pk_add_f32 v[202:203], v[2:3], v[34:35]
	v_pk_add_f32 v[2:3], v[2:3], v[34:35] neg_lo:[0,1] neg_hi:[0,1]
	v_pk_add_f32 v[204:205], v[18:19], v[50:51]
	v_pk_add_f32 v[18:19], v[18:19], v[50:51] neg_lo:[0,1] neg_hi:[0,1]
	v_pk_add_f32 v[34:35], v[202:203], v[204:205]
	v_pk_add_f32 v[50:51], v[202:203], v[204:205] neg_lo:[0,1] neg_hi:[0,1]
	v_pk_add_f32 v[202:203], v[2:3], v[18:19] op_sel:[0,1] op_sel_hi:[1,0] neg_hi:[0,1]
	v_pk_add_f32 v[204:205], v[2:3], v[18:19] op_sel:[0,1] op_sel_hi:[1,0] neg_lo:[0,1]
	v_pk_mul_f32 v[2:3], v[224:225], v[202:203] op_sel:[1,1] op_sel_hi:[1,0]
	v_pk_fma_f32 v[2:3], v[224:225], v[202:203], v[2:3] op_sel_hi:[0,1,1] neg_lo:[0,0,1]
	v_pk_mul_f32 v[18:19], v[226:227], v[50:51] op_sel:[1,1] op_sel_hi:[1,0]
	v_pk_fma_f32 v[18:19], v[226:227], v[50:51], v[18:19] op_sel_hi:[0,1,1] neg_lo:[0,0,1]
	v_pk_mul_f32 v[50:51], v[230:231], v[204:205] op_sel:[1,1] op_sel_hi:[1,0]
	v_pk_fma_f32 v[50:51], v[230:231], v[204:205], v[50:51] op_sel_hi:[0,1,1] neg_lo:[0,0,1]
	v_pk_add_f32 v[202:203], v[4:5], v[36:37]
	v_pk_add_f32 v[4:5], v[4:5], v[36:37] neg_lo:[0,1] neg_hi:[0,1]
	v_pk_add_f32 v[204:205], v[20:21], v[52:53]
	v_pk_add_f32 v[20:21], v[20:21], v[52:53] neg_lo:[0,1] neg_hi:[0,1]
	v_pk_add_f32 v[36:37], v[202:203], v[204:205]
	v_pk_add_f32 v[52:53], v[202:203], v[204:205] neg_lo:[0,1] neg_hi:[0,1]
	v_pk_add_f32 v[202:203], v[4:5], v[20:21] op_sel:[0,1] op_sel_hi:[1,0] neg_hi:[0,1]
	v_pk_add_f32 v[204:205], v[4:5], v[20:21] op_sel:[0,1] op_sel_hi:[1,0] neg_lo:[0,1]
	v_pk_mul_f32 v[4:5], v[224:225], v[202:203] op_sel:[1,1] op_sel_hi:[1,0]
	v_pk_fma_f32 v[4:5], v[224:225], v[202:203], v[4:5] op_sel_hi:[0,1,1] neg_lo:[0,0,1]
	v_pk_mul_f32 v[20:21], v[226:227], v[52:53] op_sel:[1,1] op_sel_hi:[1,0]
	v_pk_fma_f32 v[20:21], v[226:227], v[52:53], v[20:21] op_sel_hi:[0,1,1] neg_lo:[0,0,1]
	v_pk_mul_f32 v[52:53], v[230:231], v[204:205] op_sel:[1,1] op_sel_hi:[1,0]
	v_pk_fma_f32 v[52:53], v[230:231], v[204:205], v[52:53] op_sel_hi:[0,1,1] neg_lo:[0,0,1]
	v_pk_add_f32 v[202:203], v[8:9], v[40:41]
	v_pk_add_f32 v[8:9], v[8:9], v[40:41] neg_lo:[0,1] neg_hi:[0,1]
	v_pk_add_f32 v[204:205], v[24:25], v[56:57]
	v_pk_add_f32 v[24:25], v[24:25], v[56:57] neg_lo:[0,1] neg_hi:[0,1]
	v_pk_add_f32 v[40:41], v[202:203], v[204:205]
	v_pk_add_f32 v[56:57], v[202:203], v[204:205] neg_lo:[0,1] neg_hi:[0,1]
	v_pk_add_f32 v[202:203], v[8:9], v[24:25] op_sel:[0,1] op_sel_hi:[1,0] neg_hi:[0,1]
	v_pk_add_f32 v[204:205], v[8:9], v[24:25] op_sel:[0,1] op_sel_hi:[1,0] neg_lo:[0,1]
	v_pk_mul_f32 v[8:9], v[224:225], v[202:203] op_sel:[1,1] op_sel_hi:[1,0]
	v_pk_fma_f32 v[8:9], v[224:225], v[202:203], v[8:9] op_sel_hi:[0,1,1] neg_lo:[0,0,1]
	v_pk_mul_f32 v[24:25], v[226:227], v[56:57] op_sel:[1,1] op_sel_hi:[1,0]
	v_pk_fma_f32 v[24:25], v[226:227], v[56:57], v[24:25] op_sel_hi:[0,1,1] neg_lo:[0,0,1]
; DI f32x2 cmul(f32x2 a, f32x2 b) { return mkf2(a.x * b.x - a.y * b.y, a.x * b.y + a.y * b.x); }
; DI void fft8192(f32x2* buf, const f32x2* __restrict__ tw) {
;     ...
; #pragma unroll
;     for (int e = 0; e < 8; ++e) {
;       const int i = tid + 256 * e;
;       const int q = i & (s - 1);
;       const int ps = i - q;
;       const float rev = (float)ps * (1.f / 8192.f);
;       const f32x2 w1 = mkf2(__builtin_amdgcn_cosf(rev), -__builtin_amdgcn_sinf(rev));
;       const f32x2 w2 = cmul(w1, w1), w3 = cmul(w1, w2);
;       const f32x2 apc = mkf2(a[e].x + c[e].x, a[e].y + c[e].y), amc = mkf2(a[e].x - c[e].x, a[e].y - c[e].y);
;       const f32x2 bpd = mkf2(b[e].x + d[e].x, b[e].y + d[e].y), bmd = mkf2(b[e].x - d[e].x, b[e].y - d[e].y);
;       const int o = 4 * i - 3 * q;
;       buf[SW(o)] = mkf2(apc.x + bpd.x, apc.y + bpd.y);
;       buf[SW(o + s)] = cmul(w1, mkf2(amc.x + bmd.y, amc.y - bmd.x));
;       buf[SW(o + 2 * s)] = cmul(w2, mkf2(apc.x - bpd.x, apc.y - bpd.y));
;       buf[SW(o + 3 * s)] = cmul(w3, mkf2(amc.x - bmd.y, amc.y + bmd.x));
;     }
	v_pk_mul_f32 v[56:57], v[230:231], v[204:205] op_sel:[1,1] op_sel_hi:[1,0]
	v_pk_fma_f32 v[56:57], v[230:231], v[204:205], v[56:57] op_sel_hi:[0,1,1] neg_lo:[0,0,1]
	v_mul_f32_e32 v214, 4.0, v201
	v_add_f32_e32 v214, 0x3e000000, v214
	v_cos_f32_e32 v224, v214
	v_sin_f32_e64 v225, -v214
	s_nop 0
	v_pk_mul_f32 v[206:207], v[224:225], v[224:225] op_sel:[1,1] op_sel_hi:[1,0]
	v_pk_fma_f32 v[226:227], v[224:225], v[224:225], v[206:207] op_sel_hi:[0,1,1] neg_lo:[0,0,1]
	v_pk_mul_f32 v[206:207], v[224:225], v[226:227] op_sel:[1,1] op_sel_hi:[1,0]
	v_pk_fma_f32 v[230:231], v[224:225], v[226:227], v[206:207] op_sel_hi:[0,1,1] neg_lo:[0,0,1]
	v_pk_add_f32 v[202:203], v[14:15], v[46:47]
	v_pk_add_f32 v[14:15], v[14:15], v[46:47] neg_lo:[0,1] neg_hi:[0,1]
	v_pk_add_f32 v[204:205], v[30:31], v[62:63]
	v_pk_add_f32 v[30:31], v[30:31], v[62:63] neg_lo:[0,1] neg_hi:[0,1]
	v_pk_add_f32 v[46:47], v[202:203], v[204:205]
	v_pk_add_f32 v[62:63], v[202:203], v[204:205] neg_lo:[0,1] neg_hi:[0,1]
	v_pk_add_f32 v[202:203], v[14:15], v[30:31] op_sel:[0,1] op_sel_hi:[1,0] neg_hi:[0,1]
	v_pk_add_f32 v[204:205], v[14:15], v[30:31] op_sel:[0,1] op_sel_hi:[1,0] neg_lo:[0,1]
	v_pk_mul_f32 v[14:15], v[224:225], v[202:203] op_sel:[1,1] op_sel_hi:[1,0]
	v_pk_fma_f32 v[14:15], v[224:225], v[202:203], v[14:15] op_sel_hi:[0,1,1] neg_lo:[0,0,1]
	v_pk_mul_f32 v[30:31], v[226:227], v[62:63] op_sel:[1,1] op_sel_hi:[1,0]
	v_pk_fma_f32 v[30:31], v[226:227], v[62:63], v[30:31] op_sel_hi:[0,1,1] neg_lo:[0,0,1]
	v_pk_mul_f32 v[62:63], v[230:231], v[204:205] op_sel:[1,1] op_sel_hi:[1,0]
	v_pk_fma_f32 v[62:63], v[230:231], v[204:205], v[62:63] op_sel_hi:[0,1,1] neg_lo:[0,0,1]
	v_pk_add_f32 v[202:203], v[10:11], v[42:43]
	v_pk_add_f32 v[10:11], v[10:11], v[42:43] neg_lo:[0,1] neg_hi:[0,1]
	v_pk_add_f32 v[204:205], v[26:27], v[58:59]
	v_pk_add_f32 v[26:27], v[26:27], v[58:59] neg_lo:[0,1] neg_hi:[0,1]
	v_pk_add_f32 v[42:43], v[202:203], v[204:205]
	v_pk_add_f32 v[58:59], v[202:203], v[204:205] neg_lo:[0,1] neg_hi:[0,1]
	v_pk_add_f32 v[202:203], v[10:11], v[26:27] op_sel:[0,1] op_sel_hi:[1,0] neg_hi:[0,1]
	v_pk_add_f32 v[204:205], v[10:11], v[26:27] op_sel:[0,1] op_sel_hi:[1,0] neg_lo:[0,1]
	v_pk_mul_f32 v[10:11], v[224:225], v[202:203] op_sel:[1,1] op_sel_hi:[1,0]
	v_pk_fma_f32 v[10:11], v[224:225], v[202:203], v[10:11] op_sel_hi:[0,1,1] neg_lo:[0,0,1]
	v_pk_mul_f32 v[26:27], v[226:227], v[58:59] op_sel:[1,1] op_sel_hi:[1,0]
	v_pk_fma_f32 v[26:27], v[226:227], v[58:59], v[26:27] op_sel_hi:[0,1,1] neg_lo:[0,0,1]
	v_pk_mul_f32 v[58:59], v[230:231], v[204:205] op_sel:[1,1] op_sel_hi:[1,0]
	v_pk_fma_f32 v[58:59], v[230:231], v[204:205], v[58:59] op_sel_hi:[0,1,1] neg_lo:[0,0,1]
	v_pk_add_f32 v[202:203], v[12:13], v[44:45]
	v_pk_add_f32 v[12:13], v[12:13], v[44:45] neg_lo:[0,1] neg_hi:[0,1]
	v_pk_add_f32 v[204:205], v[28:29], v[60:61]
	v_pk_add_f32 v[28:29], v[28:29], v[60:61] neg_lo:[0,1] neg_hi:[0,1]
	v_pk_add_f32 v[44:45], v[202:203], v[204:205]
	v_pk_add_f32 v[60:61], v[202:203], v[204:205] neg_lo:[0,1] neg_hi:[0,1]
	v_pk_add_f32 v[202:203], v[12:13], v[28:29] op_sel:[0,1] op_sel_hi:[1,0] neg_hi:[0,1]
	v_pk_add_f32 v[204:205], v[12:13], v[28:29] op_sel:[0,1] op_sel_hi:[1,0] neg_lo:[0,1]
	v_pk_mul_f32 v[12:13], v[224:225], v[202:203] op_sel:[1,1] op_sel_hi:[1,0]
	v_pk_fma_f32 v[12:13], v[224:225], v[202:203], v[12:13] op_sel_hi:[0,1,1] neg_lo:[0,0,1]
	v_pk_mul_f32 v[28:29], v[226:227], v[60:61] op_sel:[1,1] op_sel_hi:[1,0]
	v_pk_fma_f32 v[28:29], v[226:227], v[60:61], v[28:29] op_sel_hi:[0,1,1] neg_lo:[0,0,1]
	v_pk_mul_f32 v[60:61], v[230:231], v[204:205] op_sel:[1,1] op_sel_hi:[1,0]
	v_pk_fma_f32 v[60:61], v[230:231], v[204:205], v[60:61] op_sel_hi:[0,1,1] neg_lo:[0,0,1]
	v_pk_add_f32 v[202:203], v[16:17], v[48:49]
	v_pk_add_f32 v[16:17], v[16:17], v[48:49] neg_lo:[0,1] neg_hi:[0,1]
	v_pk_add_f32 v[204:205], v[32:33], v[64:65]
	v_pk_add_f32 v[32:33], v[32:33], v[64:65] neg_lo:[0,1] neg_hi:[0,1]
	v_pk_add_f32 v[48:49], v[202:203], v[204:205]
	v_pk_add_f32 v[64:65], v[202:203], v[204:205] neg_lo:[0,1] neg_hi:[0,1]
	v_pk_add_f32 v[202:203], v[16:17], v[32:33] op_sel:[0,1] op_sel_hi:[1,0] neg_hi:[0,1]
	v_pk_add_f32 v[204:205], v[16:17], v[32:33] op_sel:[0,1] op_sel_hi:[1,0] neg_lo:[0,1]
	v_pk_mul_f32 v[16:17], v[224:225], v[202:203] op_sel:[1,1] op_sel_hi:[1,0]
	v_pk_fma_f32 v[16:17], v[224:225], v[202:203], v[16:17] op_sel_hi:[0,1,1] neg_lo:[0,0,1]
	v_pk_mul_f32 v[32:33], v[226:227], v[64:65] op_sel:[1,1] op_sel_hi:[1,0]
	v_pk_fma_f32 v[32:33], v[226:227], v[64:65], v[32:33] op_sel_hi:[0,1,1] neg_lo:[0,0,1]
	v_pk_mul_f32 v[64:65], v[230:231], v[204:205] op_sel:[1,1] op_sel_hi:[1,0]
	v_pk_fma_f32 v[64:65], v[230:231], v[204:205], v[64:65] op_sel_hi:[0,1,1] neg_lo:[0,0,1]
	ds_write_b64 v164, v[38:39] offset:0
	v_xor_b32_e32 v156, 8, v164
	ds_write_b64 v156, v[34:35] offset:0
	v_xor_b32_e32 v158, 16, v164
	ds_write_b64 v158, v[36:37] offset:0
	v_xor_b32_e32 v160, 24, v164
	ds_write_b64 v160, v[40:41] offset:0
	v_xor_b32_e32 v162, 32, v164
	ds_write_b64 v162, v[6:7] offset:0
	v_xor_b32_e32 v156, 40, v164
	ds_write_b64 v156, v[2:3] offset:0
	v_xor_b32_e32 v158, 48, v164
	ds_write_b64 v158, v[4:5] offset:0
	v_xor_b32_e32 v160, 56, v164
	ds_write_b64 v160, v[8:9] offset:0
	v_xor_b32_e32 v162, 64, v164
	ds_write_b64 v162, v[22:23] offset:0
	v_xor_b32_e32 v156, 0x48, v164
	ds_write_b64 v156, v[18:19] offset:0
	v_xor_b32_e32 v158, 0x50, v164
	ds_write_b64 v158, v[20:21] offset:0
	v_xor_b32_e32 v160, 0x58, v164
	ds_write_b64 v160, v[24:25] offset:0
	v_xor_b32_e32 v162, 0x60, v164
	ds_write_b64 v162, v[54:55] offset:0
	v_xor_b32_e32 v156, 0x68, v164
	ds_write_b64 v156, v[50:51] offset:0
	v_xor_b32_e32 v158, 0x70, v164
	ds_write_b64 v158, v[52:53] offset:0
	v_xor_b32_e32 v160, 0x78, v164
	ds_write_b64 v160, v[56:57] offset:0
	ds_write_b64 v164, v[46:47] offset:32768
	v_xor_b32_e32 v162, 8, v164
	ds_write_b64 v162, v[42:43] offset:32768
	v_xor_b32_e32 v156, 16, v164
	ds_write_b64 v156, v[44:45] offset:32768
	v_xor_b32_e32 v158, 24, v164
	ds_write_b64 v158, v[48:49] offset:32768
	v_xor_b32_e32 v160, 32, v164
	ds_write_b64 v160, v[14:15] offset:32768
	v_xor_b32_e32 v162, 40, v164
	ds_write_b64 v162, v[10:11] offset:32768
	v_xor_b32_e32 v156, 48, v164
	ds_write_b64 v156, v[12:13] offset:32768
	v_xor_b32_e32 v158, 56, v164
	ds_write_b64 v158, v[16:17] offset:32768
	v_xor_b32_e32 v160, 64, v164
	ds_write_b64 v160, v[30:31] offset:32768
	v_xor_b32_e32 v162, 0x48, v164
	ds_write_b64 v162, v[26:27] offset:32768
	v_xor_b32_e32 v156, 0x50, v164
	ds_write_b64 v156, v[28:29] offset:32768
	v_xor_b32_e32 v158, 0x58, v164
	ds_write_b64 v158, v[32:33] offset:32768
	v_xor_b32_e32 v160, 0x60, v164
	ds_write_b64 v160, v[62:63] offset:32768
	v_xor_b32_e32 v162, 0x68, v164
	ds_write_b64 v162, v[58:59] offset:32768
	v_xor_b32_e32 v156, 0x70, v164
	ds_write_b64 v156, v[60:61] offset:32768
	v_xor_b32_e32 v158, 0x78, v164
	ds_write_b64 v158, v[64:65] offset:32768
	s_waitcnt lgkmcnt(0)
	s_barrier
; DI f32x2 cmul(f32x2 a, f32x2 b) { return mkf2(a.x * b.x - a.y * b.y, a.x * b.y + a.y * b.x); }
; DI void fft8192(f32x2* buf, const f32x2* __restrict__ tw) {
;     ...
;     __syncthreads();
; #pragma unroll
;     for (int e = 0; e < 8; ++e) {
;       const int i = tid + 256 * e;
;       const int pi = SW(i);
;       a[e] = buf[pi]; b[e] = buf[pi + 2048]; c[e] = buf[pi + 4096]; d[e] = buf[pi + 6144];
;     }
;     __syncthreads();
; #pragma unroll
;     for (int e = 0; e < 8; ++e) {
;       const int i = tid + 256 * e;
;       const int q = i & (s - 1);
;       const int ps = i - q;
;       const float rev = (float)ps * (1.f / 8192.f);
;       const f32x2 w1 = mkf2(__builtin_amdgcn_cosf(rev), -__builtin_amdgcn_sinf(rev));
;       const f32x2 w2 = cmul(w1, w1), w3 = cmul(w1, w2);
;       const f32x2 apc = mkf2(a[e].x + c[e].x, a[e].y + c[e].y), amc = mkf2(a[e].x - c[e].x, a[e].y - c[e].y);
;       const f32x2 bpd = mkf2(b[e].x + d[e].x, b[e].y + d[e].y), bmd = mkf2(b[e].x - d[e].x, b[e].y - d[e].y);
;       const int o = 4 * i - 3 * q;
;       buf[SW(o)] = mkf2(apc.x + bpd.x, apc.y + bpd.y);
;       buf[SW(o + s)] = cmul(w1, mkf2(amc.x + bmd.y, amc.y - bmd.x));
;       buf[SW(o + 2 * s)] = cmul(w2, mkf2(apc.x - bpd.x, apc.y - bpd.y));
;       buf[SW(o + 3 * s)] = cmul(w3, mkf2(amc.x - bmd.y, amc.y + bmd.x));
;     }
	v_bfe_i32 v166, v0, 4, 4
	v_and_b32_e32 v166, 15, v166
	v_xor_b32_e32 v166, v166, v0
	v_lshlrev_b32_e32 v164, 3, v166
	ds_read2st64_b64 v[2:5], v164 offset0:0 offset1:32
	ds_read2st64_b64 v[6:9], v164 offset0:64 offset1:96
	ds_read2st64_b64 v[10:13], v164 offset0:4 offset1:36
	ds_read2st64_b64 v[14:17], v164 offset0:68 offset1:100
	ds_read2st64_b64 v[18:21], v164 offset0:8 offset1:40
	ds_read2st64_b64 v[22:25], v164 offset0:72 offset1:104
	ds_read2st64_b64 v[26:29], v164 offset0:12 offset1:44
	ds_read2st64_b64 v[30:33], v164 offset0:76 offset1:108
	ds_read2st64_b64 v[34:37], v164 offset0:16 offset1:48
	ds_read2st64_b64 v[38:41], v164 offset0:80 offset1:112
	ds_read2st64_b64 v[42:45], v164 offset0:20 offset1:52
	ds_read2st64_b64 v[46:49], v164 offset0:84 offset1:116
	ds_read2st64_b64 v[50:53], v164 offset0:24 offset1:56
	ds_read2st64_b64 v[54:57], v164 offset0:88 offset1:120
	ds_read2st64_b64 v[58:61], v164 offset0:28 offset1:60
	ds_read2st64_b64 v[62:65], v164 offset0:92 offset1:124
	v_and_b32_e32 v166, 15, v0
	v_sub_u32_e32 v168, v0, v166
	v_cvt_f32_u32_e32 v201, v168
	v_lshl_add_u32 v164, v168, 4, v166
	v_lshlrev_b32_e32 v164, 3, v164
	v_mul_f32_e32 v201, 0x39000000, v201
	v_cos_f32_e32 v210, v201
	v_sin_f32_e64 v211, -v201
	s_waitcnt lgkmcnt(14)
	v_pk_add_f32 v[202:203], v[2:3], v[6:7]
	v_pk_add_f32 v[2:3], v[2:3], v[6:7] neg_lo:[0,1] neg_hi:[0,1]
	v_pk_add_f32 v[204:205], v[4:5], v[8:9]
	v_pk_add_f32 v[4:5], v[4:5], v[8:9] neg_lo:[0,1] neg_hi:[0,1]
	v_pk_add_f32 v[6:7], v[202:203], v[204:205]
	v_pk_add_f32 v[8:9], v[202:203], v[204:205] neg_lo:[0,1] neg_hi:[0,1]
	v_pk_add_f32 v[202:203], v[2:3], v[4:5] op_sel:[0,1] op_sel_hi:[1,0] neg_hi:[0,1]
	v_pk_add_f32 v[204:205], v[2:3], v[4:5] op_sel:[0,1] op_sel_hi:[1,0] neg_lo:[0,1]
	v_pk_mul_f32 v[206:207], v[210:211], v[210:211] op_sel:[1,1] op_sel_hi:[1,0]
	v_pk_fma_f32 v[212:213], v[210:211], v[210:211], v[206:207] op_sel_hi:[0,1,1] neg_lo:[0,0,1]
	v_pk_mul_f32 v[206:207], v[210:211], v[212:213] op_sel:[1,1] op_sel_hi:[1,0]
	v_pk_fma_f32 v[220:221], v[210:211], v[212:213], v[206:207] op_sel_hi:[0,1,1] neg_lo:[0,0,1]
	v_pk_mul_f32 v[2:3], v[210:211], v[202:203] op_sel:[1,1] op_sel_hi:[1,0]
	v_pk_fma_f32 v[2:3], v[210:211], v[202:203], v[2:3] op_sel_hi:[0,1,1] neg_lo:[0,0,1]
	v_pk_mul_f32 v[4:5], v[212:213], v[8:9] op_sel:[1,1] op_sel_hi:[1,0]
	v_pk_fma_f32 v[4:5], v[212:213], v[8:9], v[4:5] op_sel_hi:[0,1,1] neg_lo:[0,0,1]
	v_pk_mul_f32 v[8:9], v[220:221], v[204:205] op_sel:[1,1] op_sel_hi:[1,0]
	v_pk_fma_f32 v[8:9], v[220:221], v[204:205], v[8:9] op_sel_hi:[0,1,1] neg_lo:[0,0,1]
	v_add_f32_e32 v214, 0x3d000000, v201
	v_cos_f32_e32 v210, v214
	v_sin_f32_e64 v211, -v214
	s_waitcnt lgkmcnt(12)
	v_pk_add_f32 v[202:203], v[10:11], v[14:15]
	v_pk_add_f32 v[10:11], v[10:11], v[14:15] neg_lo:[0,1] neg_hi:[0,1]
	v_pk_add_f32 v[204:205], v[12:13], v[16:17]
	v_pk_add_f32 v[12:13], v[12:13], v[16:17] neg_lo:[0,1] neg_hi:[0,1]
	v_pk_add_f32 v[14:15], v[202:203], v[204:205]
	v_pk_add_f32 v[16:17], v[202:203], v[204:205] neg_lo:[0,1] neg_hi:[0,1]
	v_pk_add_f32 v[202:203], v[10:11], v[12:13] op_sel:[0,1] op_sel_hi:[1,0] neg_hi:[0,1]
	v_pk_add_f32 v[204:205], v[10:11], v[12:13] op_sel:[0,1] op_sel_hi:[1,0] neg_lo:[0,1]
	v_pk_mul_f32 v[206:207], v[210:211], v[210:211] op_sel:[1,1] op_sel_hi:[1,0]
	v_pk_fma_f32 v[212:213], v[210:211], v[210:211], v[206:207] op_sel_hi:[0,1,1] neg_lo:[0,0,1]
	v_pk_mul_f32 v[206:207], v[210:211], v[212:213] op_sel:[1,1] op_sel_hi:[1,0]
	v_pk_fma_f32 v[220:221], v[210:211], v[212:213], v[206:207] op_sel_hi:[0,1,1] neg_lo:[0,0,1]
	v_pk_mul_f32 v[10:11], v[210:211], v[202:203] op_sel:[1,1] op_sel_hi:[1,0]
	v_pk_fma_f32 v[10:11], v[210:211], v[202:203], v[10:11] op_sel_hi:[0,1,1] neg_lo:[0,0,1]
	v_pk_mul_f32 v[12:13], v[212:213], v[16:17] op_sel:[1,1] op_sel_hi:[1,0]
	v_pk_fma_f32 v[12:13], v[212:213], v[16:17], v[12:13] op_sel_hi:[0,1,1] neg_lo:[0,0,1]
	v_pk_mul_f32 v[16:17], v[220:221], v[204:205] op_sel:[1,1] op_sel_hi:[1,0]
	v_pk_fma_f32 v[16:17], v[220:221], v[204:205], v[16:17] op_sel_hi:[0,1,1] neg_lo:[0,0,1]
	v_add_f32_e32 v214, 0x3d800000, v201
	v_cos_f32_e32 v210, v214
	v_sin_f32_e64 v211, -v214
	s_waitcnt lgkmcnt(10)
	v_pk_add_f32 v[202:203], v[18:19], v[22:23]
	v_pk_add_f32 v[18:19], v[18:19], v[22:23] neg_lo:[0,1] neg_hi:[0,1]
	v_pk_add_f32 v[204:205], v[20:21], v[24:25]
	v_pk_add_f32 v[20:21], v[20:21], v[24:25] neg_lo:[0,1] neg_hi:[0,1]
	v_pk_add_f32 v[22:23], v[202:203], v[204:205]
	v_pk_add_f32 v[24:25], v[202:203], v[204:205] neg_lo:[0,1] neg_hi:[0,1]
	v_pk_add_f32 v[202:203], v[18:19], v[20:21] op_sel:[0,1] op_sel_hi:[1,0] neg_hi:[0,1]
	v_pk_add_f32 v[204:205], v[18:19], v[20:21] op_sel:[0,1] op_sel_hi:[1,0] neg_lo:[0,1]
	v_pk_mul_f32 v[206:207], v[210:211], v[210:211] op_sel:[1,1] op_sel_hi:[1,0]
	v_pk_fma_f32 v[212:213], v[210:211], v[210:211], v[206:207] op_sel_hi:[0,1,1] neg_lo:[0,0,1]
	v_pk_mul_f32 v[206:207], v[210:211], v[212:213] op_sel:[1,1] op_sel_hi:[1,0]
	v_pk_fma_f32 v[220:221], v[210:211], v[212:213], v[206:207] op_sel_hi:[0,1,1] neg_lo:[0,0,1]
	v_pk_mul_f32 v[18:19], v[210:211], v[202:203] op_sel:[1,1] op_sel_hi:[1,0]
	v_pk_fma_f32 v[18:19], v[210:211], v[202:203], v[18:19] op_sel_hi:[0,1,1] neg_lo:[0,0,1]
	v_pk_mul_f32 v[20:21], v[212:213], v[24:25] op_sel:[1,1] op_sel_hi:[1,0]
	v_pk_fma_f32 v[20:21], v[212:213], v[24:25], v[20:21] op_sel_hi:[0,1,1] neg_lo:[0,0,1]
	v_pk_mul_f32 v[24:25], v[220:221], v[204:205] op_sel:[1,1] op_sel_hi:[1,0]
	v_pk_fma_f32 v[24:25], v[220:221], v[204:205], v[24:25] op_sel_hi:[0,1,1] neg_lo:[0,0,1]
	v_add_f32_e32 v214, 0x3dc00000, v201
	v_cos_f32_e32 v210, v214
	v_sin_f32_e64 v211, -v214
	s_waitcnt lgkmcnt(8)
; DI f32x2 cmul(f32x2 a, f32x2 b) { return mkf2(a.x * b.x - a.y * b.y, a.x * b.y + a.y * b.x); }
; DI void fft8192(f32x2* buf, const f32x2* __restrict__ tw) {
;     ...
; #pragma unroll
;     for (int e = 0; e < 8; ++e) {
;       const int i = tid + 256 * e;
;       const int q = i & (s - 1);
;       const int ps = i - q;
;       const float rev = (float)ps * (1.f / 8192.f);
;       const f32x2 w1 = mkf2(__builtin_amdgcn_cosf(rev), -__builtin_amdgcn_sinf(rev));
;       const f32x2 w2 = cmul(w1, w1), w3 = cmul(w1, w2);
;       const f32x2 apc = mkf2(a[e].x + c[e].x, a[e].y + c[e].y), amc = mkf2(a[e].x - c[e].x, a[e].y - c[e].y);
;       const f32x2 bpd = mkf2(b[e].x + d[e].x, b[e].y + d[e].y), bmd = mkf2(b[e].x - d[e].x, b[e].y - d[e].y);
;       const int o = 4 * i - 3 * q;
;       buf[SW(o)] = mkf2(apc.x + bpd.x, apc.y + bpd.y);
;       buf[SW(o + s)] = cmul(w1, mkf2(amc.x + bmd.y, amc.y - bmd.x));
;       buf[SW(o + 2 * s)] = cmul(w2, mkf2(apc.x - bpd.x, apc.y - bpd.y));
;       buf[SW(o + 3 * s)] = cmul(w3, mkf2(amc.x - bmd.y, amc.y + bmd.x));
;     }
	v_pk_add_f32 v[202:203], v[26:27], v[30:31]
	v_pk_add_f32 v[26:27], v[26:27], v[30:31] neg_lo:[0,1] neg_hi:[0,1]
	v_pk_add_f32 v[204:205], v[28:29], v[32:33]
	v_pk_add_f32 v[28:29], v[28:29], v[32:33] neg_lo:[0,1] neg_hi:[0,1]
	v_pk_add_f32 v[30:31], v[202:203], v[204:205]
	v_pk_add_f32 v[32:33], v[202:203], v[204:205] neg_lo:[0,1] neg_hi:[0,1]
	v_pk_add_f32 v[202:203], v[26:27], v[28:29] op_sel:[0,1] op_sel_hi:[1,0] neg_hi:[0,1]
	v_pk_add_f32 v[204:205], v[26:27], v[28:29] op_sel:[0,1] op_sel_hi:[1,0] neg_lo:[0,1]
	v_pk_mul_f32 v[206:207], v[210:211], v[210:211] op_sel:[1,1] op_sel_hi:[1,0]
	v_pk_fma_f32 v[212:213], v[210:211], v[210:211], v[206:207] op_sel_hi:[0,1,1] neg_lo:[0,0,1]
	v_pk_mul_f32 v[206:207], v[210:211], v[212:213] op_sel:[1,1] op_sel_hi:[1,0]
	v_pk_fma_f32 v[220:221], v[210:211], v[212:213], v[206:207] op_sel_hi:[0,1,1] neg_lo:[0,0,1]
	v_pk_mul_f32 v[26:27], v[210:211], v[202:203] op_sel:[1,1] op_sel_hi:[1,0]
	v_pk_fma_f32 v[26:27], v[210:211], v[202:203], v[26:27] op_sel_hi:[0,1,1] neg_lo:[0,0,1]
	v_pk_mul_f32 v[28:29], v[212:213], v[32:33] op_sel:[1,1] op_sel_hi:[1,0]
	v_pk_fma_f32 v[28:29], v[212:213], v[32:33], v[28:29] op_sel_hi:[0,1,1] neg_lo:[0,0,1]
	v_pk_mul_f32 v[32:33], v[220:221], v[204:205] op_sel:[1,1] op_sel_hi:[1,0]
	v_pk_fma_f32 v[32:33], v[220:221], v[204:205], v[32:33] op_sel_hi:[0,1,1] neg_lo:[0,0,1]
	v_add_f32_e32 v214, 0x3e000000, v201
	v_cos_f32_e32 v210, v214
	v_sin_f32_e64 v211, -v214
	s_waitcnt lgkmcnt(6)
	v_pk_add_f32 v[202:203], v[34:35], v[38:39]
	v_pk_add_f32 v[34:35], v[34:35], v[38:39] neg_lo:[0,1] neg_hi:[0,1]
	v_pk_add_f32 v[204:205], v[36:37], v[40:41]
	v_pk_add_f32 v[36:37], v[36:37], v[40:41] neg_lo:[0,1] neg_hi:[0,1]
	v_pk_add_f32 v[38:39], v[202:203], v[204:205]
	v_pk_add_f32 v[40:41], v[202:203], v[204:205] neg_lo:[0,1] neg_hi:[0,1]
	v_pk_add_f32 v[202:203], v[34:35], v[36:37] op_sel:[0,1] op_sel_hi:[1,0] neg_hi:[0,1]
	v_pk_add_f32 v[204:205], v[34:35], v[36:37] op_sel:[0,1] op_sel_hi:[1,0] neg_lo:[0,1]
	v_pk_mul_f32 v[206:207], v[210:211], v[210:211] op_sel:[1,1] op_sel_hi:[1,0]
	v_pk_fma_f32 v[212:213], v[210:211], v[210:211], v[206:207] op_sel_hi:[0,1,1] neg_lo:[0,0,1]
	v_pk_mul_f32 v[206:207], v[210:211], v[212:213] op_sel:[1,1] op_sel_hi:[1,0]
	v_pk_fma_f32 v[220:221], v[210:211], v[212:213], v[206:207] op_sel_hi:[0,1,1] neg_lo:[0,0,1]
	v_pk_mul_f32 v[34:35], v[210:211], v[202:203] op_sel:[1,1] op_sel_hi:[1,0]
	v_pk_fma_f32 v[34:35], v[210:211], v[202:203], v[34:35] op_sel_hi:[0,1,1] neg_lo:[0,0,1]
	v_pk_mul_f32 v[36:37], v[212:213], v[40:41] op_sel:[1,1] op_sel_hi:[1,0]
	v_pk_fma_f32 v[36:37], v[212:213], v[40:41], v[36:37] op_sel_hi:[0,1,1] neg_lo:[0,0,1]
	v_pk_mul_f32 v[40:41], v[220:221], v[204:205] op_sel:[1,1] op_sel_hi:[1,0]
	v_pk_fma_f32 v[40:41], v[220:221], v[204:205], v[40:41] op_sel_hi:[0,1,1] neg_lo:[0,0,1]
	v_add_f32_e32 v214, 0x3e200000, v201
	v_cos_f32_e32 v210, v214
	v_sin_f32_e64 v211, -v214
	s_waitcnt lgkmcnt(4)
	v_pk_add_f32 v[202:203], v[42:43], v[46:47]
	v_pk_add_f32 v[42:43], v[42:43], v[46:47] neg_lo:[0,1] neg_hi:[0,1]
	v_pk_add_f32 v[204:205], v[44:45], v[48:49]
	v_pk_add_f32 v[44:45], v[44:45], v[48:49] neg_lo:[0,1] neg_hi:[0,1]
	v_pk_add_f32 v[46:47], v[202:203], v[204:205]
	v_pk_add_f32 v[48:49], v[202:203], v[204:205] neg_lo:[0,1] neg_hi:[0,1]
	v_pk_add_f32 v[202:203], v[42:43], v[44:45] op_sel:[0,1] op_sel_hi:[1,0] neg_hi:[0,1]
	v_pk_add_f32 v[204:205], v[42:43], v[44:45] op_sel:[0,1] op_sel_hi:[1,0] neg_lo:[0,1]
	v_pk_mul_f32 v[206:207], v[210:211], v[210:211] op_sel:[1,1] op_sel_hi:[1,0]
	v_pk_fma_f32 v[212:213], v[210:211], v[210:211], v[206:207] op_sel_hi:[0,1,1] neg_lo:[0,0,1]
	v_pk_mul_f32 v[206:207], v[210:211], v[212:213] op_sel:[1,1] op_sel_hi:[1,0]
	v_pk_fma_f32 v[220:221], v[210:211], v[212:213], v[206:207] op_sel_hi:[0,1,1] neg_lo:[0,0,1]
	v_pk_mul_f32 v[42:43], v[210:211], v[202:203] op_sel:[1,1] op_sel_hi:[1,0]
	v_pk_fma_f32 v[42:43], v[210:211], v[202:203], v[42:43] op_sel_hi:[0,1,1] neg_lo:[0,0,1]
	v_pk_mul_f32 v[44:45], v[212:213], v[48:49] op_sel:[1,1] op_sel_hi:[1,0]
	v_pk_fma_f32 v[44:45], v[212:213], v[48:49], v[44:45] op_sel_hi:[0,1,1] neg_lo:[0,0,1]
	v_pk_mul_f32 v[48:49], v[220:221], v[204:205] op_sel:[1,1] op_sel_hi:[1,0]
	v_pk_fma_f32 v[48:49], v[220:221], v[204:205], v[48:49] op_sel_hi:[0,1,1] neg_lo:[0,0,1]
	v_add_f32_e32 v214, 0x3e400000, v201
	v_cos_f32_e32 v210, v214
	v_sin_f32_e64 v211, -v214
	s_waitcnt lgkmcnt(2)
	v_pk_add_f32 v[202:203], v[50:51], v[54:55]
	v_pk_add_f32 v[50:51], v[50:51], v[54:55] neg_lo:[0,1] neg_hi:[0,1]
	v_pk_add_f32 v[204:205], v[52:53], v[56:57]
	v_pk_add_f32 v[52:53], v[52:53], v[56:57] neg_lo:[0,1] neg_hi:[0,1]
	v_pk_add_f32 v[54:55], v[202:203], v[204:205]
	v_pk_add_f32 v[56:57], v[202:203], v[204:205] neg_lo:[0,1] neg_hi:[0,1]
	v_pk_add_f32 v[202:203], v[50:51], v[52:53] op_sel:[0,1] op_sel_hi:[1,0] neg_hi:[0,1]
	v_pk_add_f32 v[204:205], v[50:51], v[52:53] op_sel:[0,1] op_sel_hi:[1,0] neg_lo:[0,1]
	v_pk_mul_f32 v[206:207], v[210:211], v[210:211] op_sel:[1,1] op_sel_hi:[1,0]
	v_pk_fma_f32 v[212:213], v[210:211], v[210:211], v[206:207] op_sel_hi:[0,1,1] neg_lo:[0,0,1]
	v_pk_mul_f32 v[206:207], v[210:211], v[212:213] op_sel:[1,1] op_sel_hi:[1,0]
	v_pk_fma_f32 v[220:221], v[210:211], v[212:213], v[206:207] op_sel_hi:[0,1,1] neg_lo:[0,0,1]
	v_pk_mul_f32 v[50:51], v[210:211], v[202:203] op_sel:[1,1] op_sel_hi:[1,0]
	v_pk_fma_f32 v[50:51], v[210:211], v[202:203], v[50:51] op_sel_hi:[0,1,1] neg_lo:[0,0,1]
	v_pk_mul_f32 v[52:53], v[212:213], v[56:57] op_sel:[1,1] op_sel_hi:[1,0]
	v_pk_fma_f32 v[52:53], v[212:213], v[56:57], v[52:53] op_sel_hi:[0,1,1] neg_lo:[0,0,1]
	v_pk_mul_f32 v[56:57], v[220:221], v[204:205] op_sel:[1,1] op_sel_hi:[1,0]
	v_pk_fma_f32 v[56:57], v[220:221], v[204:205], v[56:57] op_sel_hi:[0,1,1] neg_lo:[0,0,1]
	v_add_f32_e32 v214, 0x3e600000, v201
	v_cos_f32_e32 v210, v214
	v_sin_f32_e64 v211, -v214
	s_waitcnt lgkmcnt(0)
; DI f32x2 cmul(f32x2 a, f32x2 b) { return mkf2(a.x * b.x - a.y * b.y, a.x * b.y + a.y * b.x); }
; DI void fft8192(f32x2* buf, const f32x2* __restrict__ tw) {
;     ...
; #pragma unroll
;     for (int e = 0; e < 8; ++e) {
;       const int i = tid + 256 * e;
;       const int q = i & (s - 1);
;       const int ps = i - q;
;       const float rev = (float)ps * (1.f / 8192.f);
;       const f32x2 w1 = mkf2(__builtin_amdgcn_cosf(rev), -__builtin_amdgcn_sinf(rev));
;       const f32x2 w2 = cmul(w1, w1), w3 = cmul(w1, w2);
;       const f32x2 apc = mkf2(a[e].x + c[e].x, a[e].y + c[e].y), amc = mkf2(a[e].x - c[e].x, a[e].y - c[e].y);
;       const f32x2 bpd = mkf2(b[e].x + d[e].x, b[e].y + d[e].y), bmd = mkf2(b[e].x - d[e].x, b[e].y - d[e].y);
;       const int o = 4 * i - 3 * q;
;       buf[SW(o)] = mkf2(apc.x + bpd.x, apc.y + bpd.y);
;       buf[SW(o + s)] = cmul(w1, mkf2(amc.x + bmd.y, amc.y - bmd.x));
;       buf[SW(o + 2 * s)] = cmul(w2, mkf2(apc.x - bpd.x, apc.y - bpd.y));
;       buf[SW(o + 3 * s)] = cmul(w3, mkf2(amc.x - bmd.y, amc.y + bmd.x));
;     }
	v_pk_add_f32 v[202:203], v[58:59], v[62:63]
	v_pk_add_f32 v[58:59], v[58:59], v[62:63] neg_lo:[0,1] neg_hi:[0,1]
	v_pk_add_f32 v[204:205], v[60:61], v[64:65]
	v_pk_add_f32 v[60:61], v[60:61], v[64:65] neg_lo:[0,1] neg_hi:[0,1]
	v_pk_add_f32 v[62:63], v[202:203], v[204:205]
	v_pk_add_f32 v[64:65], v[202:203], v[204:205] neg_lo:[0,1] neg_hi:[0,1]
	v_pk_add_f32 v[202:203], v[58:59], v[60:61] op_sel:[0,1] op_sel_hi:[1,0] neg_hi:[0,1]
	v_pk_add_f32 v[204:205], v[58:59], v[60:61] op_sel:[0,1] op_sel_hi:[1,0] neg_lo:[0,1]
	v_pk_mul_f32 v[206:207], v[210:211], v[210:211] op_sel:[1,1] op_sel_hi:[1,0]
	v_pk_fma_f32 v[212:213], v[210:211], v[210:211], v[206:207] op_sel_hi:[0,1,1] neg_lo:[0,0,1]
	v_pk_mul_f32 v[206:207], v[210:211], v[212:213] op_sel:[1,1] op_sel_hi:[1,0]
	v_pk_fma_f32 v[220:221], v[210:211], v[212:213], v[206:207] op_sel_hi:[0,1,1] neg_lo:[0,0,1]
	v_pk_mul_f32 v[58:59], v[210:211], v[202:203] op_sel:[1,1] op_sel_hi:[1,0]
	v_pk_fma_f32 v[58:59], v[210:211], v[202:203], v[58:59] op_sel_hi:[0,1,1] neg_lo:[0,0,1]
	v_pk_mul_f32 v[60:61], v[212:213], v[64:65] op_sel:[1,1] op_sel_hi:[1,0]
	v_pk_fma_f32 v[60:61], v[212:213], v[64:65], v[60:61] op_sel_hi:[0,1,1] neg_lo:[0,0,1]
	v_pk_mul_f32 v[64:65], v[220:221], v[204:205] op_sel:[1,1] op_sel_hi:[1,0]
	v_pk_fma_f32 v[64:65], v[220:221], v[204:205], v[64:65] op_sel_hi:[0,1,1] neg_lo:[0,0,1]
	s_barrier
	v_mul_f32_e32 v214, 4.0, v201
	v_cos_f32_e32 v224, v214
	v_sin_f32_e64 v225, -v214
	s_nop 0
	v_pk_mul_f32 v[206:207], v[224:225], v[224:225] op_sel:[1,1] op_sel_hi:[1,0]
	v_pk_fma_f32 v[226:227], v[224:225], v[224:225], v[206:207] op_sel_hi:[0,1,1] neg_lo:[0,0,1]
	v_pk_mul_f32 v[206:207], v[224:225], v[226:227] op_sel:[1,1] op_sel_hi:[1,0]
	v_pk_fma_f32 v[230:231], v[224:225], v[226:227], v[206:207] op_sel_hi:[0,1,1] neg_lo:[0,0,1]
	v_pk_add_f32 v[202:203], v[6:7], v[38:39]
	v_pk_add_f32 v[6:7], v[6:7], v[38:39] neg_lo:[0,1] neg_hi:[0,1]
	v_pk_add_f32 v[204:205], v[22:23], v[54:55]
	v_pk_add_f32 v[22:23], v[22:23], v[54:55] neg_lo:[0,1] neg_hi:[0,1]
	v_pk_add_f32 v[38:39], v[202:203], v[204:205]
	v_pk_add_f32 v[54:55], v[202:203], v[204:205] neg_lo:[0,1] neg_hi:[0,1]
	v_pk_add_f32 v[202:203], v[6:7], v[22:23] op_sel:[0,1] op_sel_hi:[1,0] neg_hi:[0,1]
	v_pk_add_f32 v[204:205], v[6:7], v[22:23] op_sel:[0,1] op_sel_hi:[1,0] neg_lo:[0,1]
	v_pk_mul_f32 v[6:7], v[224:225], v[202:203] op_sel:[1,1] op_sel_hi:[1,0]
	v_pk_fma_f32 v[6:7], v[224:225], v[202:203], v[6:7] op_sel_hi:[0,1,1] neg_lo:[0,0,1]
	v_pk_mul_f32 v[22:23], v[226:227], v[54:55] op_sel:[1,1] op_sel_hi:[1,0]
	v_pk_fma_f32 v[22:23], v[226:227], v[54:55], v[22:23] op_sel_hi:[0,1,1] neg_lo:[0,0,1]
	v_pk_mul_f32 v[54:55], v[230:231], v[204:205] op_sel:[1,1] op_sel_hi:[1,0]
	v_pk_fma_f32 v[54:55], v[230:231], v[204:205], v[54:55] op_sel_hi:[0,1,1] neg_lo:[0,0,1]
	v_pk_add_f32 v[202:203], v[2:3], v[34:35]
	v_pk_add_f32 v[2:3], v[2:3], v[34:35] neg_lo:[0,1] neg_hi:[0,1]
	v_pk_add_f32 v[204:205], v[18:19], v[50:51]
	v_pk_add_f32 v[18:19], v[18:19], v[50:51] neg_lo:[0,1] neg_hi:[0,1]
	v_pk_add_f32 v[34:35], v[202:203], v[204:205]
	v_pk_add_f32 v[50:51], v[202:203], v[204:205] neg_lo:[0,1] neg_hi:[0,1]
	v_pk_add_f32 v[202:203], v[2:3], v[18:19] op_sel:[0,1] op_sel_hi:[1,0] neg_hi:[0,1]
	v_pk_add_f32 v[204:205], v[2:3], v[18:19] op_sel:[0,1] op_sel_hi:[1,0] neg_lo:[0,1]
	v_pk_mul_f32 v[2:3], v[224:225], v[202:203] op_sel:[1,1] op_sel_hi:[1,0]
	v_pk_fma_f32 v[2:3], v[224:225], v[202:203], v[2:3] op_sel_hi:[0,1,1] neg_lo:[0,0,1]
	v_pk_mul_f32 v[18:19], v[226:227], v[50:51] op_sel:[1,1] op_sel_hi:[1,0]
	v_pk_fma_f32 v[18:19], v[226:227], v[50:51], v[18:19] op_sel_hi:[0,1,1] neg_lo:[0,0,1]
	v_pk_mul_f32 v[50:51], v[230:231], v[204:205] op_sel:[1,1] op_sel_hi:[1,0]
	v_pk_fma_f32 v[50:51], v[230:231], v[204:205], v[50:51] op_sel_hi:[0,1,1] neg_lo:[0,0,1]
	v_pk_add_f32 v[202:203], v[4:5], v[36:37]
	v_pk_add_f32 v[4:5], v[4:5], v[36:37] neg_lo:[0,1] neg_hi:[0,1]
	v_pk_add_f32 v[204:205], v[20:21], v[52:53]
	v_pk_add_f32 v[20:21], v[20:21], v[52:53] neg_lo:[0,1] neg_hi:[0,1]
	v_pk_add_f32 v[36:37], v[202:203], v[204:205]
	v_pk_add_f32 v[52:53], v[202:203], v[204:205] neg_lo:[0,1] neg_hi:[0,1]
	v_pk_add_f32 v[202:203], v[4:5], v[20:21] op_sel:[0,1] op_sel_hi:[1,0] neg_hi:[0,1]
	v_pk_add_f32 v[204:205], v[4:5], v[20:21] op_sel:[0,1] op_sel_hi:[1,0] neg_lo:[0,1]
	v_pk_mul_f32 v[4:5], v[224:225], v[202:203] op_sel:[1,1] op_sel_hi:[1,0]
	v_pk_fma_f32 v[4:5], v[224:225], v[202:203], v[4:5] op_sel_hi:[0,1,1] neg_lo:[0,0,1]
	v_pk_mul_f32 v[20:21], v[226:227], v[52:53] op_sel:[1,1] op_sel_hi:[1,0]
	v_pk_fma_f32 v[20:21], v[226:227], v[52:53], v[20:21] op_sel_hi:[0,1,1] neg_lo:[0,0,1]
	v_pk_mul_f32 v[52:53], v[230:231], v[204:205] op_sel:[1,1] op_sel_hi:[1,0]
	v_pk_fma_f32 v[52:53], v[230:231], v[204:205], v[52:53] op_sel_hi:[0,1,1] neg_lo:[0,0,1]
	v_pk_add_f32 v[202:203], v[8:9], v[40:41]
	v_pk_add_f32 v[8:9], v[8:9], v[40:41] neg_lo:[0,1] neg_hi:[0,1]
	v_pk_add_f32 v[204:205], v[24:25], v[56:57]
	v_pk_add_f32 v[24:25], v[24:25], v[56:57] neg_lo:[0,1] neg_hi:[0,1]
	v_pk_add_f32 v[40:41], v[202:203], v[204:205]
	v_pk_add_f32 v[56:57], v[202:203], v[204:205] neg_lo:[0,1] neg_hi:[0,1]
	v_pk_add_f32 v[202:203], v[8:9], v[24:25] op_sel:[0,1] op_sel_hi:[1,0] neg_hi:[0,1]
	v_pk_add_f32 v[204:205], v[8:9], v[24:25] op_sel:[0,1] op_sel_hi:[1,0] neg_lo:[0,1]
	v_pk_mul_f32 v[8:9], v[224:225], v[202:203] op_sel:[1,1] op_sel_hi:[1,0]
	v_pk_fma_f32 v[8:9], v[224:225], v[202:203], v[8:9] op_sel_hi:[0,1,1] neg_lo:[0,0,1]
	v_pk_mul_f32 v[24:25], v[226:227], v[56:57] op_sel:[1,1] op_sel_hi:[1,0]
	v_pk_fma_f32 v[24:25], v[226:227], v[56:57], v[24:25] op_sel_hi:[0,1,1] neg_lo:[0,0,1]
; DI f32x2 cmul(f32x2 a, f32x2 b) { return mkf2(a.x * b.x - a.y * b.y, a.x * b.y + a.y * b.x); }
; DI void fft8192(f32x2* buf, const f32x2* __restrict__ tw) {
;     ...
; #pragma unroll
;     for (int e = 0; e < 8; ++e) {
;       const int i = tid + 256 * e;
;       const int q = i & (s - 1);
;       const int ps = i - q;
;       const float rev = (float)ps * (1.f / 8192.f);
;       const f32x2 w1 = mkf2(__builtin_amdgcn_cosf(rev), -__builtin_amdgcn_sinf(rev));
;       const f32x2 w2 = cmul(w1, w1), w3 = cmul(w1, w2);
;       const f32x2 apc = mkf2(a[e].x + c[e].x, a[e].y + c[e].y), amc = mkf2(a[e].x - c[e].x, a[e].y - c[e].y);
;       const f32x2 bpd = mkf2(b[e].x + d[e].x, b[e].y + d[e].y), bmd = mkf2(b[e].x - d[e].x, b[e].y - d[e].y);
;       const int o = 4 * i - 3 * q;
;       buf[SW(o)] = mkf2(apc.x + bpd.x, apc.y + bpd.y);
;       buf[SW(o + s)] = cmul(w1, mkf2(amc.x + bmd.y, amc.y - bmd.x));
;       buf[SW(o + 2 * s)] = cmul(w2, mkf2(apc.x - bpd.x, apc.y - bpd.y));
;       buf[SW(o + 3 * s)] = cmul(w3, mkf2(amc.x - bmd.y, amc.y + bmd.x));
;     }
	v_pk_mul_f32 v[56:57], v[230:231], v[204:205] op_sel:[1,1] op_sel_hi:[1,0]
	v_pk_fma_f32 v[56:57], v[230:231], v[204:205], v[56:57] op_sel_hi:[0,1,1] neg_lo:[0,0,1]
	v_mul_f32_e32 v214, 4.0, v201
	v_add_f32_e32 v214, 0x3e000000, v214
	v_cos_f32_e32 v224, v214
	v_sin_f32_e64 v225, -v214
	s_nop 0
	v_pk_mul_f32 v[206:207], v[224:225], v[224:225] op_sel:[1,1] op_sel_hi:[1,0]
	v_pk_fma_f32 v[226:227], v[224:225], v[224:225], v[206:207] op_sel_hi:[0,1,1] neg_lo:[0,0,1]
	v_pk_mul_f32 v[206:207], v[224:225], v[226:227] op_sel:[1,1] op_sel_hi:[1,0]
	v_pk_fma_f32 v[230:231], v[224:225], v[226:227], v[206:207] op_sel_hi:[0,1,1] neg_lo:[0,0,1]
	v_pk_add_f32 v[202:203], v[14:15], v[46:47]
	v_pk_add_f32 v[14:15], v[14:15], v[46:47] neg_lo:[0,1] neg_hi:[0,1]
	v_pk_add_f32 v[204:205], v[30:31], v[62:63]
	v_pk_add_f32 v[30:31], v[30:31], v[62:63] neg_lo:[0,1] neg_hi:[0,1]
	v_pk_add_f32 v[46:47], v[202:203], v[204:205]
	v_pk_add_f32 v[62:63], v[202:203], v[204:205] neg_lo:[0,1] neg_hi:[0,1]
	v_pk_add_f32 v[202:203], v[14:15], v[30:31] op_sel:[0,1] op_sel_hi:[1,0] neg_hi:[0,1]
	v_pk_add_f32 v[204:205], v[14:15], v[30:31] op_sel:[0,1] op_sel_hi:[1,0] neg_lo:[0,1]
	v_pk_mul_f32 v[14:15], v[224:225], v[202:203] op_sel:[1,1] op_sel_hi:[1,0]
	v_pk_fma_f32 v[14:15], v[224:225], v[202:203], v[14:15] op_sel_hi:[0,1,1] neg_lo:[0,0,1]
	v_pk_mul_f32 v[30:31], v[226:227], v[62:63] op_sel:[1,1] op_sel_hi:[1,0]
	v_pk_fma_f32 v[30:31], v[226:227], v[62:63], v[30:31] op_sel_hi:[0,1,1] neg_lo:[0,0,1]
	v_pk_mul_f32 v[62:63], v[230:231], v[204:205] op_sel:[1,1] op_sel_hi:[1,0]
	v_pk_fma_f32 v[62:63], v[230:231], v[204:205], v[62:63] op_sel_hi:[0,1,1] neg_lo:[0,0,1]
	v_pk_add_f32 v[202:203], v[10:11], v[42:43]
	v_pk_add_f32 v[10:11], v[10:11], v[42:43] neg_lo:[0,1] neg_hi:[0,1]
	v_pk_add_f32 v[204:205], v[26:27], v[58:59]
	v_pk_add_f32 v[26:27], v[26:27], v[58:59] neg_lo:[0,1] neg_hi:[0,1]
	v_pk_add_f32 v[42:43], v[202:203], v[204:205]
	v_pk_add_f32 v[58:59], v[202:203], v[204:205] neg_lo:[0,1] neg_hi:[0,1]
	v_pk_add_f32 v[202:203], v[10:11], v[26:27] op_sel:[0,1] op_sel_hi:[1,0] neg_hi:[0,1]
	v_pk_add_f32 v[204:205], v[10:11], v[26:27] op_sel:[0,1] op_sel_hi:[1,0] neg_lo:[0,1]
	v_pk_mul_f32 v[10:11], v[224:225], v[202:203] op_sel:[1,1] op_sel_hi:[1,0]
	v_pk_fma_f32 v[10:11], v[224:225], v[202:203], v[10:11] op_sel_hi:[0,1,1] neg_lo:[0,0,1]
	v_pk_mul_f32 v[26:27], v[226:227], v[58:59] op_sel:[1,1] op_sel_hi:[1,0]
	v_pk_fma_f32 v[26:27], v[226:227], v[58:59], v[26:27] op_sel_hi:[0,1,1] neg_lo:[0,0,1]
	v_pk_mul_f32 v[58:59], v[230:231], v[204:205] op_sel:[1,1] op_sel_hi:[1,0]
	v_pk_fma_f32 v[58:59], v[230:231], v[204:205], v[58:59] op_sel_hi:[0,1,1] neg_lo:[0,0,1]
	v_pk_add_f32 v[202:203], v[12:13], v[44:45]
	v_pk_add_f32 v[12:13], v[12:13], v[44:45] neg_lo:[0,1] neg_hi:[0,1]
	v_pk_add_f32 v[204:205], v[28:29], v[60:61]
	v_pk_add_f32 v[28:29], v[28:29], v[60:61] neg_lo:[0,1] neg_hi:[0,1]
	v_pk_add_f32 v[44:45], v[202:203], v[204:205]
	v_pk_add_f32 v[60:61], v[202:203], v[204:205] neg_lo:[0,1] neg_hi:[0,1]
	v_pk_add_f32 v[202:203], v[12:13], v[28:29] op_sel:[0,1] op_sel_hi:[1,0] neg_hi:[0,1]
	v_pk_add_f32 v[204:205], v[12:13], v[28:29] op_sel:[0,1] op_sel_hi:[1,0] neg_lo:[0,1]
	v_pk_mul_f32 v[12:13], v[224:225], v[202:203] op_sel:[1,1] op_sel_hi:[1,0]
	v_pk_fma_f32 v[12:13], v[224:225], v[202:203], v[12:13] op_sel_hi:[0,1,1] neg_lo:[0,0,1]
	v_pk_mul_f32 v[28:29], v[226:227], v[60:61] op_sel:[1,1] op_sel_hi:[1,0]
	v_pk_fma_f32 v[28:29], v[226:227], v[60:61], v[28:29] op_sel_hi:[0,1,1] neg_lo:[0,0,1]
	v_pk_mul_f32 v[60:61], v[230:231], v[204:205] op_sel:[1,1] op_sel_hi:[1,0]
	v_pk_fma_f32 v[60:61], v[230:231], v[204:205], v[60:61] op_sel_hi:[0,1,1] neg_lo:[0,0,1]
	v_pk_add_f32 v[202:203], v[16:17], v[48:49]
	v_pk_add_f32 v[16:17], v[16:17], v[48:49] neg_lo:[0,1] neg_hi:[0,1]
	v_pk_add_f32 v[204:205], v[32:33], v[64:65]
	v_pk_add_f32 v[32:33], v[32:33], v[64:65] neg_lo:[0,1] neg_hi:[0,1]
	v_pk_add_f32 v[48:49], v[202:203], v[204:205]
	v_pk_add_f32 v[64:65], v[202:203], v[204:205] neg_lo:[0,1] neg_hi:[0,1]
	v_pk_add_f32 v[202:203], v[16:17], v[32:33] op_sel:[0,1] op_sel_hi:[1,0] neg_hi:[0,1]
	v_pk_add_f32 v[204:205], v[16:17], v[32:33] op_sel:[0,1] op_sel_hi:[1,0] neg_lo:[0,1]
	v_pk_mul_f32 v[16:17], v[224:225], v[202:203] op_sel:[1,1] op_sel_hi:[1,0]
	v_pk_fma_f32 v[16:17], v[224:225], v[202:203], v[16:17] op_sel_hi:[0,1,1] neg_lo:[0,0,1]
	v_pk_mul_f32 v[32:33], v[226:227], v[64:65] op_sel:[1,1] op_sel_hi:[1,0]
	v_pk_fma_f32 v[32:33], v[226:227], v[64:65], v[32:33] op_sel_hi:[0,1,1] neg_lo:[0,0,1]
	v_pk_mul_f32 v[64:65], v[230:231], v[204:205] op_sel:[1,1] op_sel_hi:[1,0]
	v_pk_fma_f32 v[64:65], v[230:231], v[204:205], v[64:65] op_sel_hi:[0,1,1] neg_lo:[0,0,1]
	ds_write_b64 v164, v[38:39] offset:0
	v_xor_b32_e32 v156, 0x80, v164
	ds_write_b64 v156, v[34:35] offset:0
	v_xor_b32_e32 v158, 0x128, v164
	ds_write_b64 v158, v[36:37] offset:0
	v_xor_b32_e32 v160, 0x1a8, v164
	ds_write_b64 v160, v[40:41] offset:0
	v_xor_b32_e32 v162, 0x2d0, v164
	ds_write_b64 v162, v[6:7] offset:0
	v_xor_b32_e32 v156, 0x250, v164
	ds_write_b64 v156, v[2:3] offset:0
	v_xor_b32_e32 v158, 0x3f8, v164
	ds_write_b64 v158, v[4:5] offset:0
	v_xor_b32_e32 v160, 0x378, v164
	ds_write_b64 v160, v[8:9] offset:0
	v_xor_b32_e32 v162, 0x400, v164
	ds_write_b64 v162, v[22:23] offset:0
	v_xor_b32_e32 v156, 0x480, v164
	ds_write_b64 v156, v[18:19] offset:0
	v_xor_b32_e32 v158, 0x528, v164
	ds_write_b64 v158, v[20:21] offset:0
	v_xor_b32_e32 v160, 0x5a8, v164
	ds_write_b64 v160, v[24:25] offset:0
	v_xor_b32_e32 v162, 0x6d0, v164
	ds_write_b64 v162, v[54:55] offset:0
	v_xor_b32_e32 v156, 0x650, v164
	ds_write_b64 v156, v[50:51] offset:0
	v_xor_b32_e32 v158, 0x7f8, v164
	ds_write_b64 v158, v[52:53] offset:0
	v_xor_b32_e32 v160, 0x778, v164
	ds_write_b64 v160, v[56:57] offset:0
	ds_write_b64 v164, v[46:47] offset:32768
	v_xor_b32_e32 v162, 0x80, v164
	ds_write_b64 v162, v[42:43] offset:32768
	v_xor_b32_e32 v156, 0x128, v164
	ds_write_b64 v156, v[44:45] offset:32768
	v_xor_b32_e32 v158, 0x1a8, v164
	ds_write_b64 v158, v[48:49] offset:32768
	v_xor_b32_e32 v160, 0x2d0, v164
	ds_write_b64 v160, v[14:15] offset:32768
	v_xor_b32_e32 v162, 0x250, v164
	ds_write_b64 v162, v[10:11] offset:32768
	v_xor_b32_e32 v156, 0x3f8, v164
	ds_write_b64 v156, v[12:13] offset:32768
	v_xor_b32_e32 v158, 0x378, v164
	ds_write_b64 v158, v[16:17] offset:32768
	v_xor_b32_e32 v160, 0x400, v164
	ds_write_b64 v160, v[30:31] offset:32768
	v_xor_b32_e32 v162, 0x480, v164
	ds_write_b64 v162, v[26:27] offset:32768
	v_xor_b32_e32 v156, 0x528, v164
	ds_write_b64 v156, v[28:29] offset:32768
	v_xor_b32_e32 v158, 0x5a8, v164
	ds_write_b64 v158, v[32:33] offset:32768
	v_xor_b32_e32 v160, 0x6d0, v164
	ds_write_b64 v160, v[62:63] offset:32768
	v_xor_b32_e32 v162, 0x650, v164
	ds_write_b64 v162, v[58:59] offset:32768
	v_xor_b32_e32 v156, 0x7f8, v164
	ds_write_b64 v156, v[60:61] offset:32768
	v_xor_b32_e32 v158, 0x778, v164
	ds_write_b64 v158, v[64:65] offset:32768
	s_waitcnt lgkmcnt(0)
	s_barrier
; DI f32x2 cmul(f32x2 a, f32x2 b) { return mkf2(a.x * b.x - a.y * b.y, a.x * b.y + a.y * b.x); }
; DI void fft8192(f32x2* buf, const f32x2* __restrict__ tw) {
;     ...
;     __syncthreads();
; #pragma unroll
;     for (int e = 0; e < 8; ++e) {
;       const int i = tid + 256 * e;
;       const int pi = SW(i);
;       a[e] = buf[pi]; b[e] = buf[pi + 2048]; c[e] = buf[pi + 4096]; d[e] = buf[pi + 6144];
;     }
;     __syncthreads();
; #pragma unroll
;     for (int e = 0; e < 8; ++e) {
;       const int i = tid + 256 * e;
;       const int q = i & (s - 1);
;       const int ps = i - q;
;       const float rev = (float)ps * (1.f / 8192.f);
;       const f32x2 w1 = mkf2(__builtin_amdgcn_cosf(rev), -__builtin_amdgcn_sinf(rev));
;       const f32x2 w2 = cmul(w1, w1), w3 = cmul(w1, w2);
;       const f32x2 apc = mkf2(a[e].x + c[e].x, a[e].y + c[e].y), amc = mkf2(a[e].x - c[e].x, a[e].y - c[e].y);
;       const f32x2 bpd = mkf2(b[e].x + d[e].x, b[e].y + d[e].y), bmd = mkf2(b[e].x - d[e].x, b[e].y - d[e].y);
;       const int o = 4 * i - 3 * q;
;       buf[SW(o)] = mkf2(apc.x + bpd.x, apc.y + bpd.y);
;       buf[SW(o + s)] = cmul(w1, mkf2(amc.x + bmd.y, amc.y - bmd.x));
;       buf[SW(o + 2 * s)] = cmul(w2, mkf2(apc.x - bpd.x, apc.y - bpd.y));
;       buf[SW(o + 3 * s)] = cmul(w3, mkf2(amc.x - bmd.y, amc.y + bmd.x));
;     }
	ds_read2st64_b64 v[2:5], v154 offset0:0 offset1:32
	ds_read2st64_b64 v[6:9], v154 offset0:64 offset1:96
	ds_read2st64_b64 v[10:13], v154 offset0:4 offset1:36
	ds_read2st64_b64 v[14:17], v154 offset0:68 offset1:100
	ds_read2st64_b64 v[18:21], v154 offset0:8 offset1:40
	ds_read2st64_b64 v[22:25], v154 offset0:72 offset1:104
	ds_read2st64_b64 v[26:29], v154 offset0:12 offset1:44
	ds_read2st64_b64 v[30:33], v154 offset0:76 offset1:108
	ds_read2st64_b64 v[34:37], v154 offset0:16 offset1:48
	ds_read2st64_b64 v[38:41], v154 offset0:80 offset1:112
	ds_read2st64_b64 v[42:45], v154 offset0:20 offset1:52
	ds_read2st64_b64 v[46:49], v154 offset0:84 offset1:116
	ds_read2st64_b64 v[50:53], v154 offset0:24 offset1:56
	ds_read2st64_b64 v[54:57], v154 offset0:88 offset1:120
	ds_read2st64_b64 v[58:61], v154 offset0:28 offset1:60
	ds_read2st64_b64 v[62:65], v154 offset0:92 offset1:124
	s_waitcnt lgkmcnt(14)
	v_pk_add_f32 v[202:203], v[2:3], v[6:7]
	v_pk_add_f32 v[2:3], v[2:3], v[6:7] neg_lo:[0,1] neg_hi:[0,1]
	v_pk_add_f32 v[204:205], v[4:5], v[8:9]
	v_pk_add_f32 v[4:5], v[4:5], v[8:9] neg_lo:[0,1] neg_hi:[0,1]
	v_pk_add_f32 v[6:7], v[202:203], v[204:205]
	v_pk_add_f32 v[8:9], v[202:203], v[204:205] neg_lo:[0,1] neg_hi:[0,1]
	v_pk_add_f32 v[202:203], v[2:3], v[4:5] op_sel:[0,1] op_sel_hi:[1,0] neg_hi:[0,1]
	v_pk_add_f32 v[4:5], v[2:3], v[4:5] op_sel:[0,1] op_sel_hi:[1,0] neg_lo:[0,1]
	v_pk_mov_b32 v[2:3], v[202:203], v[202:203] op_sel:[0,1]
	v_cos_f32_e32 v210, 0x3d000000
	v_sin_f32_e32 v211, 0xbd000000
	s_waitcnt lgkmcnt(12)
	v_pk_add_f32 v[202:203], v[10:11], v[14:15]
	v_pk_add_f32 v[10:11], v[10:11], v[14:15] neg_lo:[0,1] neg_hi:[0,1]
	v_pk_add_f32 v[204:205], v[12:13], v[16:17]
	v_pk_add_f32 v[12:13], v[12:13], v[16:17] neg_lo:[0,1] neg_hi:[0,1]
	v_pk_add_f32 v[14:15], v[202:203], v[204:205]
	v_pk_add_f32 v[16:17], v[202:203], v[204:205] neg_lo:[0,1] neg_hi:[0,1]
	v_pk_add_f32 v[202:203], v[10:11], v[12:13] op_sel:[0,1] op_sel_hi:[1,0] neg_hi:[0,1]
	v_pk_add_f32 v[204:205], v[10:11], v[12:13] op_sel:[0,1] op_sel_hi:[1,0] neg_lo:[0,1]
	v_pk_mul_f32 v[206:207], v[210:211], v[210:211] op_sel:[1,1] op_sel_hi:[1,0]
	v_pk_fma_f32 v[212:213], v[210:211], v[210:211], v[206:207] op_sel_hi:[0,1,1] neg_lo:[0,0,1]
	v_pk_mul_f32 v[206:207], v[210:211], v[212:213] op_sel:[1,1] op_sel_hi:[1,0]
	v_pk_fma_f32 v[220:221], v[210:211], v[212:213], v[206:207] op_sel_hi:[0,1,1] neg_lo:[0,0,1]
	v_pk_mul_f32 v[10:11], v[210:211], v[202:203] op_sel:[1,1] op_sel_hi:[1,0]
	v_pk_fma_f32 v[10:11], v[210:211], v[202:203], v[10:11] op_sel_hi:[0,1,1] neg_lo:[0,0,1]
	v_pk_mul_f32 v[12:13], v[212:213], v[16:17] op_sel:[1,1] op_sel_hi:[1,0]
	v_pk_fma_f32 v[12:13], v[212:213], v[16:17], v[12:13] op_sel_hi:[0,1,1] neg_lo:[0,0,1]
	v_pk_mul_f32 v[16:17], v[220:221], v[204:205] op_sel:[1,1] op_sel_hi:[1,0]
	v_pk_fma_f32 v[16:17], v[220:221], v[204:205], v[16:17] op_sel_hi:[0,1,1] neg_lo:[0,0,1]
	v_cos_f32_e32 v210, 0x3d800000
	v_sin_f32_e32 v211, 0xbd800000
	s_waitcnt lgkmcnt(10)
	v_pk_add_f32 v[202:203], v[18:19], v[22:23]
	v_pk_add_f32 v[18:19], v[18:19], v[22:23] neg_lo:[0,1] neg_hi:[0,1]
	v_pk_add_f32 v[204:205], v[20:21], v[24:25]
	v_pk_add_f32 v[20:21], v[20:21], v[24:25] neg_lo:[0,1] neg_hi:[0,1]
	v_pk_add_f32 v[22:23], v[202:203], v[204:205]
	v_pk_add_f32 v[24:25], v[202:203], v[204:205] neg_lo:[0,1] neg_hi:[0,1]
	v_pk_add_f32 v[202:203], v[18:19], v[20:21] op_sel:[0,1] op_sel_hi:[1,0] neg_hi:[0,1]
	v_pk_add_f32 v[204:205], v[18:19], v[20:21] op_sel:[0,1] op_sel_hi:[1,0] neg_lo:[0,1]
	v_pk_mul_f32 v[206:207], v[210:211], v[210:211] op_sel:[1,1] op_sel_hi:[1,0]
	v_pk_fma_f32 v[212:213], v[210:211], v[210:211], v[206:207] op_sel_hi:[0,1,1] neg_lo:[0,0,1]
	v_pk_mul_f32 v[206:207], v[210:211], v[212:213] op_sel:[1,1] op_sel_hi:[1,0]
	v_pk_fma_f32 v[220:221], v[210:211], v[212:213], v[206:207] op_sel_hi:[0,1,1] neg_lo:[0,0,1]
	v_pk_mul_f32 v[18:19], v[210:211], v[202:203] op_sel:[1,1] op_sel_hi:[1,0]
	v_pk_fma_f32 v[18:19], v[210:211], v[202:203], v[18:19] op_sel_hi:[0,1,1] neg_lo:[0,0,1]
	v_pk_mul_f32 v[20:21], v[212:213], v[24:25] op_sel:[1,1] op_sel_hi:[1,0]
	v_pk_fma_f32 v[20:21], v[212:213], v[24:25], v[20:21] op_sel_hi:[0,1,1] neg_lo:[0,0,1]
	v_pk_mul_f32 v[24:25], v[220:221], v[204:205] op_sel:[1,1] op_sel_hi:[1,0]
	v_pk_fma_f32 v[24:25], v[220:221], v[204:205], v[24:25] op_sel_hi:[0,1,1] neg_lo:[0,0,1]
	v_cos_f32_e32 v210, 0x3dc00000
	v_sin_f32_e32 v211, 0xbdc00000
	s_waitcnt lgkmcnt(8)
	v_pk_add_f32 v[202:203], v[26:27], v[30:31]
	v_pk_add_f32 v[26:27], v[26:27], v[30:31] neg_lo:[0,1] neg_hi:[0,1]
	v_pk_add_f32 v[204:205], v[28:29], v[32:33]
	v_pk_add_f32 v[28:29], v[28:29], v[32:33] neg_lo:[0,1] neg_hi:[0,1]
	v_pk_add_f32 v[30:31], v[202:203], v[204:205]
	v_pk_add_f32 v[32:33], v[202:203], v[204:205] neg_lo:[0,1] neg_hi:[0,1]
	v_pk_add_f32 v[202:203], v[26:27], v[28:29] op_sel:[0,1] op_sel_hi:[1,0] neg_hi:[0,1]
	v_pk_add_f32 v[204:205], v[26:27], v[28:29] op_sel:[0,1] op_sel_hi:[1,0] neg_lo:[0,1]
	v_pk_mul_f32 v[206:207], v[210:211], v[210:211] op_sel:[1,1] op_sel_hi:[1,0]
	v_pk_fma_f32 v[212:213], v[210:211], v[210:211], v[206:207] op_sel_hi:[0,1,1] neg_lo:[0,0,1]
	v_pk_mul_f32 v[206:207], v[210:211], v[212:213] op_sel:[1,1] op_sel_hi:[1,0]
	v_pk_fma_f32 v[220:221], v[210:211], v[212:213], v[206:207] op_sel_hi:[0,1,1] neg_lo:[0,0,1]
	v_pk_mul_f32 v[26:27], v[210:211], v[202:203] op_sel:[1,1] op_sel_hi:[1,0]
	v_pk_fma_f32 v[26:27], v[210:211], v[202:203], v[26:27] op_sel_hi:[0,1,1] neg_lo:[0,0,1]
	v_pk_mul_f32 v[28:29], v[212:213], v[32:33] op_sel:[1,1] op_sel_hi:[1,0]
	v_pk_fma_f32 v[28:29], v[212:213], v[32:33], v[28:29] op_sel_hi:[0,1,1] neg_lo:[0,0,1]
	v_pk_mul_f32 v[32:33], v[220:221], v[204:205] op_sel:[1,1] op_sel_hi:[1,0]
	v_pk_fma_f32 v[32:33], v[220:221], v[204:205], v[32:33] op_sel_hi:[0,1,1] neg_lo:[0,0,1]
	v_cos_f32_e32 v210, 0x3e000000
	v_sin_f32_e32 v211, 0xbe000000
	s_waitcnt lgkmcnt(6)
; DI f32x2 cmul(f32x2 a, f32x2 b) { return mkf2(a.x * b.x - a.y * b.y, a.x * b.y + a.y * b.x); }
; DI void fft8192(f32x2* buf, const f32x2* __restrict__ tw) {
;     ...
; #pragma unroll
;     for (int e = 0; e < 8; ++e) {
;       const int i = tid + 256 * e;
;       const int q = i & (s - 1);
;       const int ps = i - q;
;       const float rev = (float)ps * (1.f / 8192.f);
;       const f32x2 w1 = mkf2(__builtin_amdgcn_cosf(rev), -__builtin_amdgcn_sinf(rev));
;       const f32x2 w2 = cmul(w1, w1), w3 = cmul(w1, w2);
;       const f32x2 apc = mkf2(a[e].x + c[e].x, a[e].y + c[e].y), amc = mkf2(a[e].x - c[e].x, a[e].y - c[e].y);
;       const f32x2 bpd = mkf2(b[e].x + d[e].x, b[e].y + d[e].y), bmd = mkf2(b[e].x - d[e].x, b[e].y - d[e].y);
;       const int o = 4 * i - 3 * q;
;       buf[SW(o)] = mkf2(apc.x + bpd.x, apc.y + bpd.y);
;       buf[SW(o + s)] = cmul(w1, mkf2(amc.x + bmd.y, amc.y - bmd.x));
;       buf[SW(o + 2 * s)] = cmul(w2, mkf2(apc.x - bpd.x, apc.y - bpd.y));
;       buf[SW(o + 3 * s)] = cmul(w3, mkf2(amc.x - bmd.y, amc.y + bmd.x));
;     }
	v_pk_add_f32 v[202:203], v[34:35], v[38:39]
	v_pk_add_f32 v[34:35], v[34:35], v[38:39] neg_lo:[0,1] neg_hi:[0,1]
	v_pk_add_f32 v[204:205], v[36:37], v[40:41]
	v_pk_add_f32 v[36:37], v[36:37], v[40:41] neg_lo:[0,1] neg_hi:[0,1]
	v_pk_add_f32 v[38:39], v[202:203], v[204:205]
	v_pk_add_f32 v[40:41], v[202:203], v[204:205] neg_lo:[0,1] neg_hi:[0,1]
	v_pk_add_f32 v[202:203], v[34:35], v[36:37] op_sel:[0,1] op_sel_hi:[1,0] neg_hi:[0,1]
	v_pk_add_f32 v[204:205], v[34:35], v[36:37] op_sel:[0,1] op_sel_hi:[1,0] neg_lo:[0,1]
	v_pk_mul_f32 v[206:207], v[210:211], v[210:211] op_sel:[1,1] op_sel_hi:[1,0]
	v_pk_fma_f32 v[212:213], v[210:211], v[210:211], v[206:207] op_sel_hi:[0,1,1] neg_lo:[0,0,1]
	v_pk_mul_f32 v[206:207], v[210:211], v[212:213] op_sel:[1,1] op_sel_hi:[1,0]
	v_pk_fma_f32 v[220:221], v[210:211], v[212:213], v[206:207] op_sel_hi:[0,1,1] neg_lo:[0,0,1]
	v_pk_mul_f32 v[34:35], v[210:211], v[202:203] op_sel:[1,1] op_sel_hi:[1,0]
	v_pk_fma_f32 v[34:35], v[210:211], v[202:203], v[34:35] op_sel_hi:[0,1,1] neg_lo:[0,0,1]
	v_pk_mul_f32 v[36:37], v[212:213], v[40:41] op_sel:[1,1] op_sel_hi:[1,0]
	v_pk_fma_f32 v[36:37], v[212:213], v[40:41], v[36:37] op_sel_hi:[0,1,1] neg_lo:[0,0,1]
	v_pk_mul_f32 v[40:41], v[220:221], v[204:205] op_sel:[1,1] op_sel_hi:[1,0]
	v_pk_fma_f32 v[40:41], v[220:221], v[204:205], v[40:41] op_sel_hi:[0,1,1] neg_lo:[0,0,1]
	v_cos_f32_e32 v210, 0x3e200000
	v_sin_f32_e32 v211, 0xbe200000
	s_waitcnt lgkmcnt(4)
	v_pk_add_f32 v[202:203], v[42:43], v[46:47]
	v_pk_add_f32 v[42:43], v[42:43], v[46:47] neg_lo:[0,1] neg_hi:[0,1]
	v_pk_add_f32 v[204:205], v[44:45], v[48:49]
	v_pk_add_f32 v[44:45], v[44:45], v[48:49] neg_lo:[0,1] neg_hi:[0,1]
	v_pk_add_f32 v[46:47], v[202:203], v[204:205]
	v_pk_add_f32 v[48:49], v[202:203], v[204:205] neg_lo:[0,1] neg_hi:[0,1]
	v_pk_add_f32 v[202:203], v[42:43], v[44:45] op_sel:[0,1] op_sel_hi:[1,0] neg_hi:[0,1]
	v_pk_add_f32 v[204:205], v[42:43], v[44:45] op_sel:[0,1] op_sel_hi:[1,0] neg_lo:[0,1]
	v_pk_mul_f32 v[206:207], v[210:211], v[210:211] op_sel:[1,1] op_sel_hi:[1,0]
	v_pk_fma_f32 v[212:213], v[210:211], v[210:211], v[206:207] op_sel_hi:[0,1,1] neg_lo:[0,0,1]
	v_pk_mul_f32 v[206:207], v[210:211], v[212:213] op_sel:[1,1] op_sel_hi:[1,0]
	v_pk_fma_f32 v[220:221], v[210:211], v[212:213], v[206:207] op_sel_hi:[0,1,1] neg_lo:[0,0,1]
	v_pk_mul_f32 v[42:43], v[210:211], v[202:203] op_sel:[1,1] op_sel_hi:[1,0]
	v_pk_fma_f32 v[42:43], v[210:211], v[202:203], v[42:43] op_sel_hi:[0,1,1] neg_lo:[0,0,1]
	v_pk_mul_f32 v[44:45], v[212:213], v[48:49] op_sel:[1,1] op_sel_hi:[1,0]
	v_pk_fma_f32 v[44:45], v[212:213], v[48:49], v[44:45] op_sel_hi:[0,1,1] neg_lo:[0,0,1]
	v_pk_mul_f32 v[48:49], v[220:221], v[204:205] op_sel:[1,1] op_sel_hi:[1,0]
	v_pk_fma_f32 v[48:49], v[220:221], v[204:205], v[48:49] op_sel_hi:[0,1,1] neg_lo:[0,0,1]
	v_cos_f32_e32 v210, 0x3e400000
	v_sin_f32_e32 v211, 0xbe400000
	s_waitcnt lgkmcnt(2)
	v_pk_add_f32 v[202:203], v[50:51], v[54:55]
	v_pk_add_f32 v[50:51], v[50:51], v[54:55] neg_lo:[0,1] neg_hi:[0,1]
	v_pk_add_f32 v[204:205], v[52:53], v[56:57]
	v_pk_add_f32 v[52:53], v[52:53], v[56:57] neg_lo:[0,1] neg_hi:[0,1]
	v_pk_add_f32 v[54:55], v[202:203], v[204:205]
	v_pk_add_f32 v[56:57], v[202:203], v[204:205] neg_lo:[0,1] neg_hi:[0,1]
	v_pk_add_f32 v[202:203], v[50:51], v[52:53] op_sel:[0,1] op_sel_hi:[1,0] neg_hi:[0,1]
	v_pk_add_f32 v[204:205], v[50:51], v[52:53] op_sel:[0,1] op_sel_hi:[1,0] neg_lo:[0,1]
	v_pk_mul_f32 v[206:207], v[210:211], v[210:211] op_sel:[1,1] op_sel_hi:[1,0]
	v_pk_fma_f32 v[212:213], v[210:211], v[210:211], v[206:207] op_sel_hi:[0,1,1] neg_lo:[0,0,1]
	v_pk_mul_f32 v[206:207], v[210:211], v[212:213] op_sel:[1,1] op_sel_hi:[1,0]
	v_pk_fma_f32 v[220:221], v[210:211], v[212:213], v[206:207] op_sel_hi:[0,1,1] neg_lo:[0,0,1]
	v_pk_mul_f32 v[50:51], v[210:211], v[202:203] op_sel:[1,1] op_sel_hi:[1,0]
	v_pk_fma_f32 v[50:51], v[210:211], v[202:203], v[50:51] op_sel_hi:[0,1,1] neg_lo:[0,0,1]
	v_pk_mul_f32 v[52:53], v[212:213], v[56:57] op_sel:[1,1] op_sel_hi:[1,0]
	v_pk_fma_f32 v[52:53], v[212:213], v[56:57], v[52:53] op_sel_hi:[0,1,1] neg_lo:[0,0,1]
	v_pk_mul_f32 v[56:57], v[220:221], v[204:205] op_sel:[1,1] op_sel_hi:[1,0]
	v_pk_fma_f32 v[56:57], v[220:221], v[204:205], v[56:57] op_sel_hi:[0,1,1] neg_lo:[0,0,1]
	v_cos_f32_e32 v210, 0x3e600000
	v_sin_f32_e32 v211, 0xbe600000
	s_waitcnt lgkmcnt(0)
	v_pk_add_f32 v[202:203], v[58:59], v[62:63]
	v_pk_add_f32 v[58:59], v[58:59], v[62:63] neg_lo:[0,1] neg_hi:[0,1]
	v_pk_add_f32 v[204:205], v[60:61], v[64:65]
	v_pk_add_f32 v[60:61], v[60:61], v[64:65] neg_lo:[0,1] neg_hi:[0,1]
	v_pk_add_f32 v[62:63], v[202:203], v[204:205]
	v_pk_add_f32 v[64:65], v[202:203], v[204:205] neg_lo:[0,1] neg_hi:[0,1]
	v_pk_add_f32 v[202:203], v[58:59], v[60:61] op_sel:[0,1] op_sel_hi:[1,0] neg_hi:[0,1]
	v_pk_add_f32 v[204:205], v[58:59], v[60:61] op_sel:[0,1] op_sel_hi:[1,0] neg_lo:[0,1]
	v_pk_mul_f32 v[206:207], v[210:211], v[210:211] op_sel:[1,1] op_sel_hi:[1,0]
	v_pk_fma_f32 v[212:213], v[210:211], v[210:211], v[206:207] op_sel_hi:[0,1,1] neg_lo:[0,0,1]
	v_pk_mul_f32 v[206:207], v[210:211], v[212:213] op_sel:[1,1] op_sel_hi:[1,0]
	v_pk_fma_f32 v[220:221], v[210:211], v[212:213], v[206:207] op_sel_hi:[0,1,1] neg_lo:[0,0,1]
	v_pk_mul_f32 v[58:59], v[210:211], v[202:203] op_sel:[1,1] op_sel_hi:[1,0]
	v_pk_fma_f32 v[58:59], v[210:211], v[202:203], v[58:59] op_sel_hi:[0,1,1] neg_lo:[0,0,1]
	v_pk_mul_f32 v[60:61], v[212:213], v[64:65] op_sel:[1,1] op_sel_hi:[1,0]
	v_pk_fma_f32 v[60:61], v[212:213], v[64:65], v[60:61] op_sel_hi:[0,1,1] neg_lo:[0,0,1]
	v_pk_mul_f32 v[64:65], v[220:221], v[204:205] op_sel:[1,1] op_sel_hi:[1,0]
	v_pk_fma_f32 v[64:65], v[220:221], v[204:205], v[64:65] op_sel_hi:[0,1,1] neg_lo:[0,0,1]
	s_barrier
; DI f32x2 cmul(f32x2 a, f32x2 b) { return mkf2(a.x * b.x - a.y * b.y, a.x * b.y + a.y * b.x); }
; DI void fft8192(f32x2* buf, const f32x2* __restrict__ tw) {
;     ...
; #pragma unroll
;     for (int e = 0; e < 8; ++e) {
;       const int i = tid + 256 * e;
;       const int q = i & (s - 1);
;       const int ps = i - q;
;       const float rev = (float)ps * (1.f / 8192.f);
;       const f32x2 w1 = mkf2(__builtin_amdgcn_cosf(rev), -__builtin_amdgcn_sinf(rev));
;       const f32x2 w2 = cmul(w1, w1), w3 = cmul(w1, w2);
;       const f32x2 apc = mkf2(a[e].x + c[e].x, a[e].y + c[e].y), amc = mkf2(a[e].x - c[e].x, a[e].y - c[e].y);
;       const f32x2 bpd = mkf2(b[e].x + d[e].x, b[e].y + d[e].y), bmd = mkf2(b[e].x - d[e].x, b[e].y - d[e].y);
;       const int o = 4 * i - 3 * q;
;       buf[SW(o)] = mkf2(apc.x + bpd.x, apc.y + bpd.y);
;       buf[SW(o + s)] = cmul(w1, mkf2(amc.x + bmd.y, amc.y - bmd.x));
;       buf[SW(o + 2 * s)] = cmul(w2, mkf2(apc.x - bpd.x, apc.y - bpd.y));
;       buf[SW(o + 3 * s)] = cmul(w3, mkf2(amc.x - bmd.y, amc.y + bmd.x));
;     }
	v_pk_add_f32 v[202:203], v[6:7], v[38:39]
	v_pk_add_f32 v[6:7], v[6:7], v[38:39] neg_lo:[0,1] neg_hi:[0,1]
	v_pk_add_f32 v[204:205], v[22:23], v[54:55]
	v_pk_add_f32 v[22:23], v[22:23], v[54:55] neg_lo:[0,1] neg_hi:[0,1]
	v_pk_add_f32 v[38:39], v[202:203], v[204:205]
	v_pk_add_f32 v[54:55], v[202:203], v[204:205] neg_lo:[0,1] neg_hi:[0,1]
	v_pk_add_f32 v[202:203], v[6:7], v[22:23] op_sel:[0,1] op_sel_hi:[1,0] neg_hi:[0,1]
	v_pk_add_f32 v[22:23], v[6:7], v[22:23] op_sel:[0,1] op_sel_hi:[1,0] neg_lo:[0,1]
	v_pk_mov_b32 v[6:7], v[202:203], v[202:203] op_sel:[0,1]
	v_pk_add_f32 v[202:203], v[2:3], v[34:35]
	v_pk_add_f32 v[2:3], v[2:3], v[34:35] neg_lo:[0,1] neg_hi:[0,1]
	v_pk_add_f32 v[204:205], v[18:19], v[50:51]
	v_pk_add_f32 v[18:19], v[18:19], v[50:51] neg_lo:[0,1] neg_hi:[0,1]
	v_pk_add_f32 v[34:35], v[202:203], v[204:205]
	v_pk_add_f32 v[50:51], v[202:203], v[204:205] neg_lo:[0,1] neg_hi:[0,1]
	v_pk_add_f32 v[202:203], v[2:3], v[18:19] op_sel:[0,1] op_sel_hi:[1,0] neg_hi:[0,1]
	v_pk_add_f32 v[18:19], v[2:3], v[18:19] op_sel:[0,1] op_sel_hi:[1,0] neg_lo:[0,1]
	v_pk_mov_b32 v[2:3], v[202:203], v[202:203] op_sel:[0,1]
	v_pk_add_f32 v[202:203], v[8:9], v[36:37]
	v_pk_add_f32 v[8:9], v[8:9], v[36:37] neg_lo:[0,1] neg_hi:[0,1]
	v_pk_add_f32 v[204:205], v[20:21], v[52:53]
	v_pk_add_f32 v[20:21], v[20:21], v[52:53] neg_lo:[0,1] neg_hi:[0,1]
	v_pk_add_f32 v[36:37], v[202:203], v[204:205]
	v_pk_add_f32 v[52:53], v[202:203], v[204:205] neg_lo:[0,1] neg_hi:[0,1]
	v_pk_add_f32 v[202:203], v[8:9], v[20:21] op_sel:[0,1] op_sel_hi:[1,0] neg_hi:[0,1]
	v_pk_add_f32 v[20:21], v[8:9], v[20:21] op_sel:[0,1] op_sel_hi:[1,0] neg_lo:[0,1]
	v_pk_mov_b32 v[8:9], v[202:203], v[202:203] op_sel:[0,1]
	v_pk_add_f32 v[202:203], v[4:5], v[40:41]
	v_pk_add_f32 v[4:5], v[4:5], v[40:41] neg_lo:[0,1] neg_hi:[0,1]
	v_pk_add_f32 v[204:205], v[24:25], v[56:57]
	v_pk_add_f32 v[24:25], v[24:25], v[56:57] neg_lo:[0,1] neg_hi:[0,1]
	v_pk_add_f32 v[40:41], v[202:203], v[204:205]
	v_pk_add_f32 v[56:57], v[202:203], v[204:205] neg_lo:[0,1] neg_hi:[0,1]
	v_pk_add_f32 v[202:203], v[4:5], v[24:25] op_sel:[0,1] op_sel_hi:[1,0] neg_hi:[0,1]
	v_pk_add_f32 v[24:25], v[4:5], v[24:25] op_sel:[0,1] op_sel_hi:[1,0] neg_lo:[0,1]
	v_pk_mov_b32 v[4:5], v[202:203], v[202:203] op_sel:[0,1]
	v_cos_f32_e32 v224, 0x3e000000
	v_sin_f32_e32 v225, 0xbe000000
	s_nop 0
	v_pk_mul_f32 v[206:207], v[224:225], v[224:225] op_sel:[1,1] op_sel_hi:[1,0]
	v_pk_fma_f32 v[226:227], v[224:225], v[224:225], v[206:207] op_sel_hi:[0,1,1] neg_lo:[0,0,1]
	v_pk_mul_f32 v[206:207], v[224:225], v[226:227] op_sel:[1,1] op_sel_hi:[1,0]
	v_pk_fma_f32 v[230:231], v[224:225], v[226:227], v[206:207] op_sel_hi:[0,1,1] neg_lo:[0,0,1]
	v_pk_add_f32 v[202:203], v[14:15], v[46:47]
	v_pk_add_f32 v[14:15], v[14:15], v[46:47] neg_lo:[0,1] neg_hi:[0,1]
	v_pk_add_f32 v[204:205], v[30:31], v[62:63]
	v_pk_add_f32 v[30:31], v[30:31], v[62:63] neg_lo:[0,1] neg_hi:[0,1]
	v_pk_add_f32 v[46:47], v[202:203], v[204:205]
	v_pk_add_f32 v[62:63], v[202:203], v[204:205] neg_lo:[0,1] neg_hi:[0,1]
	v_pk_add_f32 v[202:203], v[14:15], v[30:31] op_sel:[0,1] op_sel_hi:[1,0] neg_hi:[0,1]
	v_pk_add_f32 v[204:205], v[14:15], v[30:31] op_sel:[0,1] op_sel_hi:[1,0] neg_lo:[0,1]
	v_pk_mul_f32 v[14:15], v[224:225], v[202:203] op_sel:[1,1] op_sel_hi:[1,0]
	v_pk_fma_f32 v[14:15], v[224:225], v[202:203], v[14:15] op_sel_hi:[0,1,1] neg_lo:[0,0,1]
	v_pk_mul_f32 v[30:31], v[226:227], v[62:63] op_sel:[1,1] op_sel_hi:[1,0]
	v_pk_fma_f32 v[30:31], v[226:227], v[62:63], v[30:31] op_sel_hi:[0,1,1] neg_lo:[0,0,1]
	v_pk_mul_f32 v[62:63], v[230:231], v[204:205] op_sel:[1,1] op_sel_hi:[1,0]
	v_pk_fma_f32 v[62:63], v[230:231], v[204:205], v[62:63] op_sel_hi:[0,1,1] neg_lo:[0,0,1]
	v_pk_add_f32 v[202:203], v[10:11], v[42:43]
	v_pk_add_f32 v[10:11], v[10:11], v[42:43] neg_lo:[0,1] neg_hi:[0,1]
	v_pk_add_f32 v[204:205], v[26:27], v[58:59]
	v_pk_add_f32 v[26:27], v[26:27], v[58:59] neg_lo:[0,1] neg_hi:[0,1]
	v_pk_add_f32 v[42:43], v[202:203], v[204:205]
	v_pk_add_f32 v[58:59], v[202:203], v[204:205] neg_lo:[0,1] neg_hi:[0,1]
	v_pk_add_f32 v[202:203], v[10:11], v[26:27] op_sel:[0,1] op_sel_hi:[1,0] neg_hi:[0,1]
	v_pk_add_f32 v[204:205], v[10:11], v[26:27] op_sel:[0,1] op_sel_hi:[1,0] neg_lo:[0,1]
	v_pk_mul_f32 v[10:11], v[224:225], v[202:203] op_sel:[1,1] op_sel_hi:[1,0]
	v_pk_fma_f32 v[10:11], v[224:225], v[202:203], v[10:11] op_sel_hi:[0,1,1] neg_lo:[0,0,1]
	v_pk_mul_f32 v[26:27], v[226:227], v[58:59] op_sel:[1,1] op_sel_hi:[1,0]
	v_pk_fma_f32 v[26:27], v[226:227], v[58:59], v[26:27] op_sel_hi:[0,1,1] neg_lo:[0,0,1]
	v_pk_mul_f32 v[58:59], v[230:231], v[204:205] op_sel:[1,1] op_sel_hi:[1,0]
	v_pk_fma_f32 v[58:59], v[230:231], v[204:205], v[58:59] op_sel_hi:[0,1,1] neg_lo:[0,0,1]
	v_pk_add_f32 v[202:203], v[12:13], v[44:45]
	v_pk_add_f32 v[12:13], v[12:13], v[44:45] neg_lo:[0,1] neg_hi:[0,1]
	v_pk_add_f32 v[204:205], v[28:29], v[60:61]
	v_pk_add_f32 v[28:29], v[28:29], v[60:61] neg_lo:[0,1] neg_hi:[0,1]
	v_pk_add_f32 v[44:45], v[202:203], v[204:205]
	v_pk_add_f32 v[60:61], v[202:203], v[204:205] neg_lo:[0,1] neg_hi:[0,1]
	v_pk_add_f32 v[202:203], v[12:13], v[28:29] op_sel:[0,1] op_sel_hi:[1,0] neg_hi:[0,1]
	v_pk_add_f32 v[204:205], v[12:13], v[28:29] op_sel:[0,1] op_sel_hi:[1,0] neg_lo:[0,1]
	v_pk_mul_f32 v[12:13], v[224:225], v[202:203] op_sel:[1,1] op_sel_hi:[1,0]
	v_pk_fma_f32 v[12:13], v[224:225], v[202:203], v[12:13] op_sel_hi:[0,1,1] neg_lo:[0,0,1]
	v_pk_mul_f32 v[28:29], v[226:227], v[60:61] op_sel:[1,1] op_sel_hi:[1,0]
	v_pk_fma_f32 v[28:29], v[226:227], v[60:61], v[28:29] op_sel_hi:[0,1,1] neg_lo:[0,0,1]
	v_pk_mul_f32 v[60:61], v[230:231], v[204:205] op_sel:[1,1] op_sel_hi:[1,0]
; DI void fft8192(f32x2* buf, const f32x2* __restrict__ tw) {
;     ...
;   {
;     f32x2 a[16], b[16];
;     __syncthreads();
; #pragma unroll
;     for (int e = 0; e < 16; ++e) { const int pi = SW(tid + 256 * e); a[e] = buf[pi]; b[e] = buf[pi + 4096]; }
;     __syncthreads();
; #pragma unroll
;     for (int e = 0; e < 16; ++e) {
;       const int pi = SW(tid + 256 * e);
;       buf[pi] = mkf2(a[e].x + b[e].x, a[e].y + b[e].y);
;       buf[pi + 4096] = mkf2(a[e].x - b[e].x, a[e].y - b[e].y);
;     }
;     __syncthreads();
;   }
; DI void hyena_unit(KP p, int l, int c, char* smem) {
;     ...
; #pragma unroll
;     for (int j = 0; j < 32; ++j) KF[j] = buf[SW(tid + 256 * j)];
;     const int gcol = (o == 0 ? 512 : 1024) + c;
;     const float gw0 = cw[gcol], gw1 = cw[1536 + gcol], gw2 = cw[3072 + gcol], gb = cb[gcol];
;     const float vw0 = cw[c], vw1 = cw[1536 + c], vw2 = cw[3072 + c], vb = cb[c];
	v_pk_fma_f32 v[60:61], v[230:231], v[204:205], v[60:61] op_sel_hi:[0,1,1] neg_lo:[0,0,1]
	v_pk_add_f32 v[202:203], v[16:17], v[48:49]
	v_pk_add_f32 v[16:17], v[16:17], v[48:49] neg_lo:[0,1] neg_hi:[0,1]
	v_pk_add_f32 v[204:205], v[32:33], v[64:65]
	v_pk_add_f32 v[32:33], v[32:33], v[64:65] neg_lo:[0,1] neg_hi:[0,1]
	v_pk_add_f32 v[48:49], v[202:203], v[204:205]
	v_pk_add_f32 v[64:65], v[202:203], v[204:205] neg_lo:[0,1] neg_hi:[0,1]
	v_pk_add_f32 v[202:203], v[16:17], v[32:33] op_sel:[0,1] op_sel_hi:[1,0] neg_hi:[0,1]
	v_pk_add_f32 v[204:205], v[16:17], v[32:33] op_sel:[0,1] op_sel_hi:[1,0] neg_lo:[0,1]
	v_pk_mul_f32 v[16:17], v[224:225], v[202:203] op_sel:[1,1] op_sel_hi:[1,0]
	v_pk_fma_f32 v[16:17], v[224:225], v[202:203], v[16:17] op_sel_hi:[0,1,1] neg_lo:[0,0,1]
	v_pk_mul_f32 v[32:33], v[226:227], v[64:65] op_sel:[1,1] op_sel_hi:[1,0]
	v_pk_fma_f32 v[32:33], v[226:227], v[64:65], v[32:33] op_sel_hi:[0,1,1] neg_lo:[0,0,1]
	v_pk_mul_f32 v[64:65], v[230:231], v[204:205] op_sel:[1,1] op_sel_hi:[1,0]
	v_pk_fma_f32 v[64:65], v[230:231], v[204:205], v[64:65] op_sel_hi:[0,1,1] neg_lo:[0,0,1]
	v_pk_add_f32 v[202:203], v[38:39], v[46:47]
	v_pk_add_f32 v[46:47], v[38:39], v[46:47] neg_lo:[0,1] neg_hi:[0,1]
	v_pk_add_f32 v[204:205], v[34:35], v[42:43]
	v_pk_add_f32 v[42:43], v[34:35], v[42:43] neg_lo:[0,1] neg_hi:[0,1]
	v_pk_add_f32 v[206:207], v[36:37], v[44:45]
	v_pk_add_f32 v[44:45], v[36:37], v[44:45] neg_lo:[0,1] neg_hi:[0,1]
	v_pk_add_f32 v[208:209], v[40:41], v[48:49]
	v_pk_add_f32 v[48:49], v[40:41], v[48:49] neg_lo:[0,1] neg_hi:[0,1]
	v_pk_add_f32 v[210:211], v[6:7], v[14:15]
	v_pk_add_f32 v[14:15], v[6:7], v[14:15] neg_lo:[0,1] neg_hi:[0,1]
	v_pk_add_f32 v[212:213], v[2:3], v[10:11]
	v_pk_add_f32 v[10:11], v[2:3], v[10:11] neg_lo:[0,1] neg_hi:[0,1]
	v_pk_add_f32 v[220:221], v[8:9], v[12:13]
	v_pk_add_f32 v[12:13], v[8:9], v[12:13] neg_lo:[0,1] neg_hi:[0,1]
	v_pk_add_f32 v[224:225], v[4:5], v[16:17]
	v_pk_add_f32 v[16:17], v[4:5], v[16:17] neg_lo:[0,1] neg_hi:[0,1]
	v_pk_add_f32 v[226:227], v[54:55], v[30:31]
	v_pk_add_f32 v[30:31], v[54:55], v[30:31] neg_lo:[0,1] neg_hi:[0,1]
	v_pk_add_f32 v[230:231], v[50:51], v[26:27]
	v_pk_add_f32 v[26:27], v[50:51], v[26:27] neg_lo:[0,1] neg_hi:[0,1]
	v_pk_add_f32 v[232:233], v[52:53], v[28:29]
	v_pk_add_f32 v[28:29], v[52:53], v[28:29] neg_lo:[0,1] neg_hi:[0,1]
	v_pk_add_f32 v[236:237], v[56:57], v[32:33]
	v_pk_add_f32 v[32:33], v[56:57], v[32:33] neg_lo:[0,1] neg_hi:[0,1]
	v_pk_add_f32 v[238:239], v[22:23], v[62:63]
	v_pk_add_f32 v[62:63], v[22:23], v[62:63] neg_lo:[0,1] neg_hi:[0,1]
	v_pk_add_f32 v[240:241], v[18:19], v[58:59]
	v_pk_add_f32 v[58:59], v[18:19], v[58:59] neg_lo:[0,1] neg_hi:[0,1]
	v_pk_add_f32 v[244:245], v[20:21], v[60:61]
	v_pk_add_f32 v[60:61], v[20:21], v[60:61] neg_lo:[0,1] neg_hi:[0,1]
	v_pk_add_f32 v[246:247], v[24:25], v[64:65]
	v_pk_add_f32 v[64:65], v[24:25], v[64:65] neg_lo:[0,1] neg_hi:[0,1]
	ds_write2st64_b64 v154, v[202:203], v[46:47] offset0:0 offset1:64
	ds_write2st64_b64 v154, v[204:205], v[42:43] offset0:4 offset1:68
	ds_write2st64_b64 v154, v[206:207], v[44:45] offset0:8 offset1:72
	ds_write2st64_b64 v154, v[208:209], v[48:49] offset0:12 offset1:76
	ds_write2st64_b64 v154, v[210:211], v[14:15] offset0:16 offset1:80
	ds_write2st64_b64 v154, v[212:213], v[10:11] offset0:20 offset1:84
	ds_write2st64_b64 v154, v[220:221], v[12:13] offset0:24 offset1:88
	ds_write2st64_b64 v154, v[224:225], v[16:17] offset0:28 offset1:92
	ds_write2st64_b64 v154, v[226:227], v[30:31] offset0:32 offset1:96
	ds_write2st64_b64 v154, v[230:231], v[26:27] offset0:36 offset1:100
	ds_write2st64_b64 v154, v[232:233], v[28:29] offset0:40 offset1:104
	ds_write2st64_b64 v154, v[236:237], v[32:33] offset0:44 offset1:108
	ds_write2st64_b64 v154, v[238:239], v[62:63] offset0:48 offset1:112
	ds_write2st64_b64 v154, v[240:241], v[58:59] offset0:52 offset1:116
	ds_write2st64_b64 v154, v[244:245], v[60:61] offset0:56 offset1:120
	ds_write2st64_b64 v154, v[246:247], v[64:65] offset0:60 offset1:124
	s_and_b64 s[2:3], s[96:97], exec
	s_cselect_b32 s4, 0x200, s62
	s_add_i32 s21, s4, s86
	s_lshl_b32 s5, s4, 2
	s_add_u32 s2, s88, s5
	v_mov_b32_e32 v2, s5
	s_waitcnt lgkmcnt(0)
	s_barrier
	s_addc_u32 s3, s89, 0
	global_load_dword v74, v2, s[88:89]
	global_load_dword v195, v2, s[94:95]
	global_load_dword v196, v235, s[2:3] offset:2048
	global_load_dword v75, v229, s[2:3]
	global_load_dword v76, v199, s[88:89]
	global_load_dword v197, v199, s[90:91]
	global_load_dword v77, v199, s[92:93]
	global_load_dword v200, v199, s[94:95]
	ds_read_b64 v[78:79], v157
	ds_read_b64 v[80:81], v159
	ds_read_b64 v[82:83], v161
	ds_read_b64 v[84:85], v163
	ds_read_b64 v[86:87], v165
	ds_read_b64 v[88:89], v167
	ds_read_b64 v[90:91], v169
	ds_read_b64 v[92:93], v170
	ds_read_b64 v[94:95], v171
	ds_read_b64 v[96:97], v172
	ds_read_b64 v[98:99], v173
	ds_read_b64 v[100:101], v174
	ds_read_b64 v[102:103], v175
	ds_read_b64 v[104:105], v176
	ds_read_b64 v[106:107], v177
	ds_read_b64 v[108:109], v178
	ds_read_b64 v[110:111], v179
	ds_read_b64 v[112:113], v180
	ds_read_b64 v[114:115], v181
	ds_read_b64 v[116:117], v182
	ds_read_b64 v[118:119], v183
	ds_read_b64 v[120:121], v184
	ds_read_b64 v[122:123], v185
	ds_read_b64 v[124:125], v186
	ds_read_b64 v[126:127], v187
	ds_read_b64 v[128:129], v188
	ds_read_b64 v[130:131], v189
	ds_read_b64 v[132:133], v190
	ds_read_b64 v[134:135], v191
	ds_read_b64 v[136:137], v192
	ds_read_b64 v[138:139], v193
	ds_read_b64 v[140:141], v194
	s_waitcnt lgkmcnt(5)
	v_pk_mov_b32 v[142:143], v[130:131], v[130:131] op_sel:[1,0]
	s_waitcnt lgkmcnt(4)
	v_pk_mov_b32 v[144:145], v[132:133], v[132:133] op_sel:[1,0]
	s_waitcnt lgkmcnt(3)
	v_pk_mov_b32 v[146:147], v[134:135], v[134:135] op_sel:[1,0]
	s_waitcnt lgkmcnt(2)
	v_pk_mov_b32 v[148:149], v[136:137], v[136:137] op_sel:[1,0]
	s_waitcnt lgkmcnt(1)
	v_pk_mov_b32 v[150:151], v[138:139], v[138:139] op_sel:[1,0]
	s_waitcnt lgkmcnt(0)
	v_pk_mov_b32 v[152:153], v[140:141], v[140:141] op_sel:[1,0]
	s_add_i32 s77, s40, s4
	s_mov_b32 s83, 0
	s_mov_b64 s[6:7], -1
	s_branch .LBB0_937

; DI f32x2 cmul(f32x2 a, f32x2 b) { return mkf2(a.x * b.x - a.y * b.y, a.x * b.y + a.y * b.x); }
; DI void fft8192(f32x2* buf, const f32x2* __restrict__ tw) {
;     ...
;     __syncthreads();
; #pragma unroll
;     for (int e = 0; e < 8; ++e) {
;       const int i = tid + 256 * e;
;       const int pi = SW(i);
;       a[e] = buf[pi]; b[e] = buf[pi + 2048]; c[e] = buf[pi + 4096]; d[e] = buf[pi + 6144];
;     }
;     __syncthreads();
; #pragma unroll
;     for (int e = 0; e < 8; ++e) {
;       const int i = tid + 256 * e;
;       const int q = i & (s - 1);
;       const int ps = i - q;
;       const float rev = (float)ps * (1.f / 8192.f);
;       const f32x2 w1 = mkf2(__builtin_amdgcn_cosf(rev), -__builtin_amdgcn_sinf(rev));
;       const f32x2 w2 = cmul(w1, w1), w3 = cmul(w1, w2);
;       const f32x2 apc = mkf2(a[e].x + c[e].x, a[e].y + c[e].y), amc = mkf2(a[e].x - c[e].x, a[e].y - c[e].y);
;       const f32x2 bpd = mkf2(b[e].x + d[e].x, b[e].y + d[e].y), bmd = mkf2(b[e].x - d[e].x, b[e].y - d[e].y);
;       const int o = 4 * i - 3 * q;
;       buf[SW(o)] = mkf2(apc.x + bpd.x, apc.y + bpd.y);
;       buf[SW(o + s)] = cmul(w1, mkf2(amc.x + bmd.y, amc.y - bmd.x));
;       buf[SW(o + 2 * s)] = cmul(w2, mkf2(apc.x - bpd.x, apc.y - bpd.y));
;       buf[SW(o + 3 * s)] = cmul(w3, mkf2(amc.x - bmd.y, amc.y + bmd.x));
;     }
.Lhy_inA_done:
.LBB0_987:
	v_bfe_i32 v166, v0, 5, 1
	v_bfe_i32 v168, v0, 6, 1
	v_and_b32_e32 v166, 5, v166
	v_and_b32_e32 v168, 26, v168
	v_xor_b32_e32 v166, v166, v168
	v_xor_b32_e32 v166, v166, v0
	v_lshlrev_b32_e32 v154, 3, v166
	s_waitcnt lgkmcnt(0)
	s_barrier
	ds_read2st64_b64 v[2:5], v154 offset0:0 offset1:32
	ds_read2st64_b64 v[10:13], v154 offset0:4 offset1:36
	ds_read2st64_b64 v[18:21], v154 offset0:8 offset1:40
	ds_read2st64_b64 v[26:29], v154 offset0:12 offset1:44
	ds_read2st64_b64 v[34:37], v154 offset0:16 offset1:48
	ds_read2st64_b64 v[42:45], v154 offset0:20 offset1:52
	ds_read2st64_b64 v[50:53], v154 offset0:24 offset1:56
	ds_read2st64_b64 v[58:61], v154 offset0:28 offset1:60
	v_cvt_f32_u32_e32 v201, v0
	v_and_b32_e32 v166, 15, v0
	v_lshlrev_b32_e32 v166, 3, v166
	v_lshl_add_u32 v164, v0, 7, v166
	v_mul_f32_e32 v201, 0x39000000, v201
	v_cos_f32_e32 v210, v201
	v_sin_f32_e64 v211, -v201
	s_waitcnt lgkmcnt(7)
	v_pk_add_f32 v[6:7], v[2:3], v[4:5]
	v_pk_add_f32 v[8:9], v[2:3], v[4:5] neg_lo:[0,1] neg_hi:[0,1]
	v_pk_add_f32 v[202:203], v[2:3], v[4:5] op_sel:[0,1] op_sel_hi:[1,0] neg_hi:[0,1]
	v_pk_add_f32 v[204:205], v[2:3], v[4:5] op_sel:[0,1] op_sel_hi:[1,0] neg_lo:[0,1]
	v_pk_mul_f32 v[206:207], v[210:211], v[210:211] op_sel:[1,1] op_sel_hi:[1,0]
	v_pk_fma_f32 v[212:213], v[210:211], v[210:211], v[206:207] op_sel_hi:[0,1,1] neg_lo:[0,0,1]
	v_pk_mul_f32 v[206:207], v[210:211], v[212:213] op_sel:[1,1] op_sel_hi:[1,0]
	v_pk_fma_f32 v[220:221], v[210:211], v[212:213], v[206:207] op_sel_hi:[0,1,1] neg_lo:[0,0,1]
	v_pk_mul_f32 v[2:3], v[210:211], v[202:203] op_sel:[1,1] op_sel_hi:[1,0]
	v_pk_fma_f32 v[2:3], v[210:211], v[202:203], v[2:3] op_sel_hi:[0,1,1] neg_lo:[0,0,1]
	v_pk_mul_f32 v[4:5], v[212:213], v[8:9] op_sel:[1,1] op_sel_hi:[1,0]
	v_pk_fma_f32 v[4:5], v[212:213], v[8:9], v[4:5] op_sel_hi:[0,1,1] neg_lo:[0,0,1]
	v_pk_mul_f32 v[8:9], v[220:221], v[204:205] op_sel:[1,1] op_sel_hi:[1,0]
	v_pk_fma_f32 v[8:9], v[220:221], v[204:205], v[8:9] op_sel_hi:[0,1,1] neg_lo:[0,0,1]
	v_add_f32_e32 v214, 0x3d000000, v201
	v_cos_f32_e32 v210, v214
	v_sin_f32_e64 v211, -v214
	s_waitcnt lgkmcnt(6)
	v_pk_add_f32 v[14:15], v[10:11], v[12:13]
	v_pk_add_f32 v[16:17], v[10:11], v[12:13] neg_lo:[0,1] neg_hi:[0,1]
	v_pk_add_f32 v[202:203], v[10:11], v[12:13] op_sel:[0,1] op_sel_hi:[1,0] neg_hi:[0,1]
	v_pk_add_f32 v[204:205], v[10:11], v[12:13] op_sel:[0,1] op_sel_hi:[1,0] neg_lo:[0,1]
	v_pk_mul_f32 v[206:207], v[210:211], v[210:211] op_sel:[1,1] op_sel_hi:[1,0]
	v_pk_fma_f32 v[212:213], v[210:211], v[210:211], v[206:207] op_sel_hi:[0,1,1] neg_lo:[0,0,1]
	v_pk_mul_f32 v[206:207], v[210:211], v[212:213] op_sel:[1,1] op_sel_hi:[1,0]
	v_pk_fma_f32 v[220:221], v[210:211], v[212:213], v[206:207] op_sel_hi:[0,1,1] neg_lo:[0,0,1]
	v_pk_mul_f32 v[10:11], v[210:211], v[202:203] op_sel:[1,1] op_sel_hi:[1,0]
	v_pk_fma_f32 v[10:11], v[210:211], v[202:203], v[10:11] op_sel_hi:[0,1,1] neg_lo:[0,0,1]
	v_pk_mul_f32 v[12:13], v[212:213], v[16:17] op_sel:[1,1] op_sel_hi:[1,0]
	v_pk_fma_f32 v[12:13], v[212:213], v[16:17], v[12:13] op_sel_hi:[0,1,1] neg_lo:[0,0,1]
	v_pk_mul_f32 v[16:17], v[220:221], v[204:205] op_sel:[1,1] op_sel_hi:[1,0]
	v_pk_fma_f32 v[16:17], v[220:221], v[204:205], v[16:17] op_sel_hi:[0,1,1] neg_lo:[0,0,1]
	v_add_f32_e32 v214, 0x3d800000, v201
	v_cos_f32_e32 v210, v214
	v_sin_f32_e64 v211, -v214
	s_waitcnt lgkmcnt(5)
	v_pk_add_f32 v[22:23], v[18:19], v[20:21]
	v_pk_add_f32 v[24:25], v[18:19], v[20:21] neg_lo:[0,1] neg_hi:[0,1]
	v_pk_add_f32 v[202:203], v[18:19], v[20:21] op_sel:[0,1] op_sel_hi:[1,0] neg_hi:[0,1]
	v_pk_add_f32 v[204:205], v[18:19], v[20:21] op_sel:[0,1] op_sel_hi:[1,0] neg_lo:[0,1]
	v_pk_mul_f32 v[206:207], v[210:211], v[210:211] op_sel:[1,1] op_sel_hi:[1,0]
	v_pk_fma_f32 v[212:213], v[210:211], v[210:211], v[206:207] op_sel_hi:[0,1,1] neg_lo:[0,0,1]
	v_pk_mul_f32 v[206:207], v[210:211], v[212:213] op_sel:[1,1] op_sel_hi:[1,0]
	v_pk_fma_f32 v[220:221], v[210:211], v[212:213], v[206:207] op_sel_hi:[0,1,1] neg_lo:[0,0,1]
	v_pk_mul_f32 v[18:19], v[210:211], v[202:203] op_sel:[1,1] op_sel_hi:[1,0]
	v_pk_fma_f32 v[18:19], v[210:211], v[202:203], v[18:19] op_sel_hi:[0,1,1] neg_lo:[0,0,1]
	v_pk_mul_f32 v[20:21], v[212:213], v[24:25] op_sel:[1,1] op_sel_hi:[1,0]
	v_pk_fma_f32 v[20:21], v[212:213], v[24:25], v[20:21] op_sel_hi:[0,1,1] neg_lo:[0,0,1]
	v_pk_mul_f32 v[24:25], v[220:221], v[204:205] op_sel:[1,1] op_sel_hi:[1,0]
	v_pk_fma_f32 v[24:25], v[220:221], v[204:205], v[24:25] op_sel_hi:[0,1,1] neg_lo:[0,0,1]
	v_add_f32_e32 v214, 0x3dc00000, v201
	v_cos_f32_e32 v210, v214
	v_sin_f32_e64 v211, -v214
	s_waitcnt lgkmcnt(4)
	v_pk_add_f32 v[30:31], v[26:27], v[28:29]
	v_pk_add_f32 v[32:33], v[26:27], v[28:29] neg_lo:[0,1] neg_hi:[0,1]
	v_pk_add_f32 v[202:203], v[26:27], v[28:29] op_sel:[0,1] op_sel_hi:[1,0] neg_hi:[0,1]
	v_pk_add_f32 v[204:205], v[26:27], v[28:29] op_sel:[0,1] op_sel_hi:[1,0] neg_lo:[0,1]
	v_pk_mul_f32 v[206:207], v[210:211], v[210:211] op_sel:[1,1] op_sel_hi:[1,0]
	v_pk_fma_f32 v[212:213], v[210:211], v[210:211], v[206:207] op_sel_hi:[0,1,1] neg_lo:[0,0,1]
	v_pk_mul_f32 v[206:207], v[210:211], v[212:213] op_sel:[1,1] op_sel_hi:[1,0]
	v_pk_fma_f32 v[220:221], v[210:211], v[212:213], v[206:207] op_sel_hi:[0,1,1] neg_lo:[0,0,1]
	v_pk_mul_f32 v[26:27], v[210:211], v[202:203] op_sel:[1,1] op_sel_hi:[1,0]
	v_pk_fma_f32 v[26:27], v[210:211], v[202:203], v[26:27] op_sel_hi:[0,1,1] neg_lo:[0,0,1]
	v_pk_mul_f32 v[28:29], v[212:213], v[32:33] op_sel:[1,1] op_sel_hi:[1,0]
	v_pk_fma_f32 v[28:29], v[212:213], v[32:33], v[28:29] op_sel_hi:[0,1,1] neg_lo:[0,0,1]
	v_pk_mul_f32 v[32:33], v[220:221], v[204:205] op_sel:[1,1] op_sel_hi:[1,0]
	v_pk_fma_f32 v[32:33], v[220:221], v[204:205], v[32:33] op_sel_hi:[0,1,1] neg_lo:[0,0,1]
	v_add_f32_e32 v214, 0x3e000000, v201
	v_cos_f32_e32 v210, v214
	v_sin_f32_e64 v211, -v214
	s_waitcnt lgkmcnt(3)
; DI f32x2 cmul(f32x2 a, f32x2 b) { return mkf2(a.x * b.x - a.y * b.y, a.x * b.y + a.y * b.x); }
; DI void fft8192(f32x2* buf, const f32x2* __restrict__ tw) {
;     ...
; #pragma unroll
;     for (int e = 0; e < 8; ++e) {
;       const int i = tid + 256 * e;
;       const int q = i & (s - 1);
;       const int ps = i - q;
;       const float rev = (float)ps * (1.f / 8192.f);
;       const f32x2 w1 = mkf2(__builtin_amdgcn_cosf(rev), -__builtin_amdgcn_sinf(rev));
;       const f32x2 w2 = cmul(w1, w1), w3 = cmul(w1, w2);
;       const f32x2 apc = mkf2(a[e].x + c[e].x, a[e].y + c[e].y), amc = mkf2(a[e].x - c[e].x, a[e].y - c[e].y);
;       const f32x2 bpd = mkf2(b[e].x + d[e].x, b[e].y + d[e].y), bmd = mkf2(b[e].x - d[e].x, b[e].y - d[e].y);
;       const int o = 4 * i - 3 * q;
;       buf[SW(o)] = mkf2(apc.x + bpd.x, apc.y + bpd.y);
;       buf[SW(o + s)] = cmul(w1, mkf2(amc.x + bmd.y, amc.y - bmd.x));
;       buf[SW(o + 2 * s)] = cmul(w2, mkf2(apc.x - bpd.x, apc.y - bpd.y));
;       buf[SW(o + 3 * s)] = cmul(w3, mkf2(amc.x - bmd.y, amc.y + bmd.x));
;     }
	v_pk_add_f32 v[38:39], v[34:35], v[36:37]
	v_pk_add_f32 v[40:41], v[34:35], v[36:37] neg_lo:[0,1] neg_hi:[0,1]
	v_pk_add_f32 v[202:203], v[34:35], v[36:37] op_sel:[0,1] op_sel_hi:[1,0] neg_hi:[0,1]
	v_pk_add_f32 v[204:205], v[34:35], v[36:37] op_sel:[0,1] op_sel_hi:[1,0] neg_lo:[0,1]
	v_pk_mul_f32 v[206:207], v[210:211], v[210:211] op_sel:[1,1] op_sel_hi:[1,0]
	v_pk_fma_f32 v[212:213], v[210:211], v[210:211], v[206:207] op_sel_hi:[0,1,1] neg_lo:[0,0,1]
	v_pk_mul_f32 v[206:207], v[210:211], v[212:213] op_sel:[1,1] op_sel_hi:[1,0]
	v_pk_fma_f32 v[220:221], v[210:211], v[212:213], v[206:207] op_sel_hi:[0,1,1] neg_lo:[0,0,1]
	v_pk_mul_f32 v[34:35], v[210:211], v[202:203] op_sel:[1,1] op_sel_hi:[1,0]
	v_pk_fma_f32 v[34:35], v[210:211], v[202:203], v[34:35] op_sel_hi:[0,1,1] neg_lo:[0,0,1]
	v_pk_mul_f32 v[36:37], v[212:213], v[40:41] op_sel:[1,1] op_sel_hi:[1,0]
	v_pk_fma_f32 v[36:37], v[212:213], v[40:41], v[36:37] op_sel_hi:[0,1,1] neg_lo:[0,0,1]
	v_pk_mul_f32 v[40:41], v[220:221], v[204:205] op_sel:[1,1] op_sel_hi:[1,0]
	v_pk_fma_f32 v[40:41], v[220:221], v[204:205], v[40:41] op_sel_hi:[0,1,1] neg_lo:[0,0,1]
	v_add_f32_e32 v214, 0x3e200000, v201
	v_cos_f32_e32 v210, v214
	v_sin_f32_e64 v211, -v214
	s_waitcnt lgkmcnt(2)
	v_pk_add_f32 v[46:47], v[42:43], v[44:45]
	v_pk_add_f32 v[48:49], v[42:43], v[44:45] neg_lo:[0,1] neg_hi:[0,1]
	v_pk_add_f32 v[202:203], v[42:43], v[44:45] op_sel:[0,1] op_sel_hi:[1,0] neg_hi:[0,1]
	v_pk_add_f32 v[204:205], v[42:43], v[44:45] op_sel:[0,1] op_sel_hi:[1,0] neg_lo:[0,1]
	v_pk_mul_f32 v[206:207], v[210:211], v[210:211] op_sel:[1,1] op_sel_hi:[1,0]
	v_pk_fma_f32 v[212:213], v[210:211], v[210:211], v[206:207] op_sel_hi:[0,1,1] neg_lo:[0,0,1]
	v_pk_mul_f32 v[206:207], v[210:211], v[212:213] op_sel:[1,1] op_sel_hi:[1,0]
	v_pk_fma_f32 v[220:221], v[210:211], v[212:213], v[206:207] op_sel_hi:[0,1,1] neg_lo:[0,0,1]
	v_pk_mul_f32 v[42:43], v[210:211], v[202:203] op_sel:[1,1] op_sel_hi:[1,0]
	v_pk_fma_f32 v[42:43], v[210:211], v[202:203], v[42:43] op_sel_hi:[0,1,1] neg_lo:[0,0,1]
	v_pk_mul_f32 v[44:45], v[212:213], v[48:49] op_sel:[1,1] op_sel_hi:[1,0]
	v_pk_fma_f32 v[44:45], v[212:213], v[48:49], v[44:45] op_sel_hi:[0,1,1] neg_lo:[0,0,1]
	v_pk_mul_f32 v[48:49], v[220:221], v[204:205] op_sel:[1,1] op_sel_hi:[1,0]
	v_pk_fma_f32 v[48:49], v[220:221], v[204:205], v[48:49] op_sel_hi:[0,1,1] neg_lo:[0,0,1]
	v_add_f32_e32 v214, 0x3e400000, v201
	v_cos_f32_e32 v210, v214
	v_sin_f32_e64 v211, -v214
	s_waitcnt lgkmcnt(1)
	v_pk_add_f32 v[54:55], v[50:51], v[52:53]
	v_pk_add_f32 v[56:57], v[50:51], v[52:53] neg_lo:[0,1] neg_hi:[0,1]
	v_pk_add_f32 v[202:203], v[50:51], v[52:53] op_sel:[0,1] op_sel_hi:[1,0] neg_hi:[0,1]
	v_pk_add_f32 v[204:205], v[50:51], v[52:53] op_sel:[0,1] op_sel_hi:[1,0] neg_lo:[0,1]
	v_pk_mul_f32 v[206:207], v[210:211], v[210:211] op_sel:[1,1] op_sel_hi:[1,0]
	v_pk_fma_f32 v[212:213], v[210:211], v[210:211], v[206:207] op_sel_hi:[0,1,1] neg_lo:[0,0,1]
	v_pk_mul_f32 v[206:207], v[210:211], v[212:213] op_sel:[1,1] op_sel_hi:[1,0]
	v_pk_fma_f32 v[220:221], v[210:211], v[212:213], v[206:207] op_sel_hi:[0,1,1] neg_lo:[0,0,1]
	v_pk_mul_f32 v[50:51], v[210:211], v[202:203] op_sel:[1,1] op_sel_hi:[1,0]
	v_pk_fma_f32 v[50:51], v[210:211], v[202:203], v[50:51] op_sel_hi:[0,1,1] neg_lo:[0,0,1]
	v_pk_mul_f32 v[52:53], v[212:213], v[56:57] op_sel:[1,1] op_sel_hi:[1,0]
	v_pk_fma_f32 v[52:53], v[212:213], v[56:57], v[52:53] op_sel_hi:[0,1,1] neg_lo:[0,0,1]
	v_pk_mul_f32 v[56:57], v[220:221], v[204:205] op_sel:[1,1] op_sel_hi:[1,0]
	v_pk_fma_f32 v[56:57], v[220:221], v[204:205], v[56:57] op_sel_hi:[0,1,1] neg_lo:[0,0,1]
	v_add_f32_e32 v214, 0x3e600000, v201
	v_cos_f32_e32 v210, v214
	v_sin_f32_e64 v211, -v214
	s_waitcnt lgkmcnt(0)
	v_pk_add_f32 v[62:63], v[58:59], v[60:61]
	v_pk_add_f32 v[64:65], v[58:59], v[60:61] neg_lo:[0,1] neg_hi:[0,1]
	v_pk_add_f32 v[202:203], v[58:59], v[60:61] op_sel:[0,1] op_sel_hi:[1,0] neg_hi:[0,1]
	v_pk_add_f32 v[204:205], v[58:59], v[60:61] op_sel:[0,1] op_sel_hi:[1,0] neg_lo:[0,1]
	v_pk_mul_f32 v[206:207], v[210:211], v[210:211] op_sel:[1,1] op_sel_hi:[1,0]
	v_pk_fma_f32 v[212:213], v[210:211], v[210:211], v[206:207] op_sel_hi:[0,1,1] neg_lo:[0,0,1]
	v_pk_mul_f32 v[206:207], v[210:211], v[212:213] op_sel:[1,1] op_sel_hi:[1,0]
	v_pk_fma_f32 v[220:221], v[210:211], v[212:213], v[206:207] op_sel_hi:[0,1,1] neg_lo:[0,0,1]
	v_pk_mul_f32 v[58:59], v[210:211], v[202:203] op_sel:[1,1] op_sel_hi:[1,0]
	v_pk_fma_f32 v[58:59], v[210:211], v[202:203], v[58:59] op_sel_hi:[0,1,1] neg_lo:[0,0,1]
	v_pk_mul_f32 v[60:61], v[212:213], v[64:65] op_sel:[1,1] op_sel_hi:[1,0]
	v_pk_fma_f32 v[60:61], v[212:213], v[64:65], v[60:61] op_sel_hi:[0,1,1] neg_lo:[0,0,1]
	v_pk_mul_f32 v[64:65], v[220:221], v[204:205] op_sel:[1,1] op_sel_hi:[1,0]
	v_pk_fma_f32 v[64:65], v[220:221], v[204:205], v[64:65] op_sel_hi:[0,1,1] neg_lo:[0,0,1]
	s_barrier
; DI f32x2 cmul(f32x2 a, f32x2 b) { return mkf2(a.x * b.x - a.y * b.y, a.x * b.y + a.y * b.x); }
; DI void fft8192(f32x2* buf, const f32x2* __restrict__ tw) {
;     ...
; #pragma unroll
;     for (int e = 0; e < 8; ++e) {
;       const int i = tid + 256 * e;
;       const int q = i & (s - 1);
;       const int ps = i - q;
;       const float rev = (float)ps * (1.f / 8192.f);
;       const f32x2 w1 = mkf2(__builtin_amdgcn_cosf(rev), -__builtin_amdgcn_sinf(rev));
;       const f32x2 w2 = cmul(w1, w1), w3 = cmul(w1, w2);
;       const f32x2 apc = mkf2(a[e].x + c[e].x, a[e].y + c[e].y), amc = mkf2(a[e].x - c[e].x, a[e].y - c[e].y);
;       const f32x2 bpd = mkf2(b[e].x + d[e].x, b[e].y + d[e].y), bmd = mkf2(b[e].x - d[e].x, b[e].y - d[e].y);
;       const int o = 4 * i - 3 * q;
;       buf[SW(o)] = mkf2(apc.x + bpd.x, apc.y + bpd.y);
;       buf[SW(o + s)] = cmul(w1, mkf2(amc.x + bmd.y, amc.y - bmd.x));
;       buf[SW(o + 2 * s)] = cmul(w2, mkf2(apc.x - bpd.x, apc.y - bpd.y));
;       buf[SW(o + 3 * s)] = cmul(w3, mkf2(amc.x - bmd.y, amc.y + bmd.x));
;     }
	v_mul_f32_e32 v214, 4.0, v201
	v_cos_f32_e32 v224, v214
	v_sin_f32_e64 v225, -v214
	s_nop 0
	v_pk_mul_f32 v[206:207], v[224:225], v[224:225] op_sel:[1,1] op_sel_hi:[1,0]
	v_pk_fma_f32 v[226:227], v[224:225], v[224:225], v[206:207] op_sel_hi:[0,1,1] neg_lo:[0,0,1]
	v_pk_mul_f32 v[206:207], v[224:225], v[226:227] op_sel:[1,1] op_sel_hi:[1,0]
	v_pk_fma_f32 v[230:231], v[224:225], v[226:227], v[206:207] op_sel_hi:[0,1,1] neg_lo:[0,0,1]
	v_pk_add_f32 v[202:203], v[6:7], v[38:39]
	v_pk_add_f32 v[6:7], v[6:7], v[38:39] neg_lo:[0,1] neg_hi:[0,1]
	v_pk_add_f32 v[204:205], v[22:23], v[54:55]
	v_pk_add_f32 v[22:23], v[22:23], v[54:55] neg_lo:[0,1] neg_hi:[0,1]
	v_pk_add_f32 v[38:39], v[202:203], v[204:205]
	v_pk_add_f32 v[54:55], v[202:203], v[204:205] neg_lo:[0,1] neg_hi:[0,1]
	v_pk_add_f32 v[202:203], v[6:7], v[22:23] op_sel:[0,1] op_sel_hi:[1,0] neg_hi:[0,1]
	v_pk_add_f32 v[204:205], v[6:7], v[22:23] op_sel:[0,1] op_sel_hi:[1,0] neg_lo:[0,1]
	v_pk_mul_f32 v[6:7], v[224:225], v[202:203] op_sel:[1,1] op_sel_hi:[1,0]
	v_pk_fma_f32 v[6:7], v[224:225], v[202:203], v[6:7] op_sel_hi:[0,1,1] neg_lo:[0,0,1]
	v_pk_mul_f32 v[22:23], v[226:227], v[54:55] op_sel:[1,1] op_sel_hi:[1,0]
	v_pk_fma_f32 v[22:23], v[226:227], v[54:55], v[22:23] op_sel_hi:[0,1,1] neg_lo:[0,0,1]
	v_pk_mul_f32 v[54:55], v[230:231], v[204:205] op_sel:[1,1] op_sel_hi:[1,0]
	v_pk_fma_f32 v[54:55], v[230:231], v[204:205], v[54:55] op_sel_hi:[0,1,1] neg_lo:[0,0,1]
	v_pk_add_f32 v[202:203], v[2:3], v[34:35]
	v_pk_add_f32 v[2:3], v[2:3], v[34:35] neg_lo:[0,1] neg_hi:[0,1]
	v_pk_add_f32 v[204:205], v[18:19], v[50:51]
	v_pk_add_f32 v[18:19], v[18:19], v[50:51] neg_lo:[0,1] neg_hi:[0,1]
	v_pk_add_f32 v[34:35], v[202:203], v[204:205]
	v_pk_add_f32 v[50:51], v[202:203], v[204:205] neg_lo:[0,1] neg_hi:[0,1]
	v_pk_add_f32 v[202:203], v[2:3], v[18:19] op_sel:[0,1] op_sel_hi:[1,0] neg_hi:[0,1]
	v_pk_add_f32 v[204:205], v[2:3], v[18:19] op_sel:[0,1] op_sel_hi:[1,0] neg_lo:[0,1]
	v_pk_mul_f32 v[2:3], v[224:225], v[202:203] op_sel:[1,1] op_sel_hi:[1,0]
	v_pk_fma_f32 v[2:3], v[224:225], v[202:203], v[2:3] op_sel_hi:[0,1,1] neg_lo:[0,0,1]
	v_pk_mul_f32 v[18:19], v[226:227], v[50:51] op_sel:[1,1] op_sel_hi:[1,0]
	v_pk_fma_f32 v[18:19], v[226:227], v[50:51], v[18:19] op_sel_hi:[0,1,1] neg_lo:[0,0,1]
	v_pk_mul_f32 v[50:51], v[230:231], v[204:205] op_sel:[1,1] op_sel_hi:[1,0]
	v_pk_fma_f32 v[50:51], v[230:231], v[204:205], v[50:51] op_sel_hi:[0,1,1] neg_lo:[0,0,1]
	v_pk_add_f32 v[202:203], v[4:5], v[36:37]
	v_pk_add_f32 v[4:5], v[4:5], v[36:37] neg_lo:[0,1] neg_hi:[0,1]
	v_pk_add_f32 v[204:205], v[20:21], v[52:53]
	v_pk_add_f32 v[20:21], v[20:21], v[52:53] neg_lo:[0,1] neg_hi:[0,1]
	v_pk_add_f32 v[36:37], v[202:203], v[204:205]
	v_pk_add_f32 v[52:53], v[202:203], v[204:205] neg_lo:[0,1] neg_hi:[0,1]
	v_pk_add_f32 v[202:203], v[4:5], v[20:21] op_sel:[0,1] op_sel_hi:[1,0] neg_hi:[0,1]
	v_pk_add_f32 v[204:205], v[4:5], v[20:21] op_sel:[0,1] op_sel_hi:[1,0] neg_lo:[0,1]
	v_pk_mul_f32 v[4:5], v[224:225], v[202:203] op_sel:[1,1] op_sel_hi:[1,0]
	v_pk_fma_f32 v[4:5], v[224:225], v[202:203], v[4:5] op_sel_hi:[0,1,1] neg_lo:[0,0,1]
	v_pk_mul_f32 v[20:21], v[226:227], v[52:53] op_sel:[1,1] op_sel_hi:[1,0]
	v_pk_fma_f32 v[20:21], v[226:227], v[52:53], v[20:21] op_sel_hi:[0,1,1] neg_lo:[0,0,1]
	v_pk_mul_f32 v[52:53], v[230:231], v[204:205] op_sel:[1,1] op_sel_hi:[1,0]
	v_pk_fma_f32 v[52:53], v[230:231], v[204:205], v[52:53] op_sel_hi:[0,1,1] neg_lo:[0,0,1]
	v_pk_add_f32 v[202:203], v[8:9], v[40:41]
	v_pk_add_f32 v[8:9], v[8:9], v[40:41] neg_lo:[0,1] neg_hi:[0,1]
	v_pk_add_f32 v[204:205], v[24:25], v[56:57]
	v_pk_add_f32 v[24:25], v[24:25], v[56:57] neg_lo:[0,1] neg_hi:[0,1]
	v_pk_add_f32 v[40:41], v[202:203], v[204:205]
	v_pk_add_f32 v[56:57], v[202:203], v[204:205] neg_lo:[0,1] neg_hi:[0,1]
	v_pk_add_f32 v[202:203], v[8:9], v[24:25] op_sel:[0,1] op_sel_hi:[1,0] neg_hi:[0,1]
	v_pk_add_f32 v[204:205], v[8:9], v[24:25] op_sel:[0,1] op_sel_hi:[1,0] neg_lo:[0,1]
	v_pk_mul_f32 v[8:9], v[224:225], v[202:203] op_sel:[1,1] op_sel_hi:[1,0]
	v_pk_fma_f32 v[8:9], v[224:225], v[202:203], v[8:9] op_sel_hi:[0,1,1] neg_lo:[0,0,1]
	v_pk_mul_f32 v[24:25], v[226:227], v[56:57] op_sel:[1,1] op_sel_hi:[1,0]
	v_pk_fma_f32 v[24:25], v[226:227], v[56:57], v[24:25] op_sel_hi:[0,1,1] neg_lo:[0,0,1]
	v_pk_mul_f32 v[56:57], v[230:231], v[204:205] op_sel:[1,1] op_sel_hi:[1,0]
	v_pk_fma_f32 v[56:57], v[230:231], v[204:205], v[56:57] op_sel_hi:[0,1,1] neg_lo:[0,0,1]
	v_mul_f32_e32 v214, 4.0, v201
	v_add_f32_e32 v214, 0x3e000000, v214
	v_cos_f32_e32 v224, v214
	v_sin_f32_e64 v225, -v214
	s_nop 0
	v_pk_mul_f32 v[206:207], v[224:225], v[224:225] op_sel:[1,1] op_sel_hi:[1,0]
	v_pk_fma_f32 v[226:227], v[224:225], v[224:225], v[206:207] op_sel_hi:[0,1,1] neg_lo:[0,0,1]
	v_pk_mul_f32 v[206:207], v[224:225], v[226:227] op_sel:[1,1] op_sel_hi:[1,0]
	v_pk_fma_f32 v[230:231], v[224:225], v[226:227], v[206:207] op_sel_hi:[0,1,1] neg_lo:[0,0,1]
	v_pk_add_f32 v[202:203], v[14:15], v[46:47]
	v_pk_add_f32 v[14:15], v[14:15], v[46:47] neg_lo:[0,1] neg_hi:[0,1]
	v_pk_add_f32 v[204:205], v[30:31], v[62:63]
	v_pk_add_f32 v[30:31], v[30:31], v[62:63] neg_lo:[0,1] neg_hi:[0,1]
	v_pk_add_f32 v[46:47], v[202:203], v[204:205]
	v_pk_add_f32 v[62:63], v[202:203], v[204:205] neg_lo:[0,1] neg_hi:[0,1]
	v_pk_add_f32 v[202:203], v[14:15], v[30:31] op_sel:[0,1] op_sel_hi:[1,0] neg_hi:[0,1]
	v_pk_add_f32 v[204:205], v[14:15], v[30:31] op_sel:[0,1] op_sel_hi:[1,0] neg_lo:[0,1]
	v_pk_mul_f32 v[14:15], v[224:225], v[202:203] op_sel:[1,1] op_sel_hi:[1,0]
	v_pk_fma_f32 v[14:15], v[224:225], v[202:203], v[14:15] op_sel_hi:[0,1,1] neg_lo:[0,0,1]
	v_pk_mul_f32 v[30:31], v[226:227], v[62:63] op_sel:[1,1] op_sel_hi:[1,0]
; DI f32x2 cmul(f32x2 a, f32x2 b) { return mkf2(a.x * b.x - a.y * b.y, a.x * b.y + a.y * b.x); }
; DI void fft8192(f32x2* buf, const f32x2* __restrict__ tw) {
;     ...
; #pragma unroll
;     for (int e = 0; e < 8; ++e) {
;       const int i = tid + 256 * e;
;       const int q = i & (s - 1);
;       const int ps = i - q;
;       const float rev = (float)ps * (1.f / 8192.f);
;       const f32x2 w1 = mkf2(__builtin_amdgcn_cosf(rev), -__builtin_amdgcn_sinf(rev));
;       const f32x2 w2 = cmul(w1, w1), w3 = cmul(w1, w2);
;       const f32x2 apc = mkf2(a[e].x + c[e].x, a[e].y + c[e].y), amc = mkf2(a[e].x - c[e].x, a[e].y - c[e].y);
;       const f32x2 bpd = mkf2(b[e].x + d[e].x, b[e].y + d[e].y), bmd = mkf2(b[e].x - d[e].x, b[e].y - d[e].y);
;       const int o = 4 * i - 3 * q;
;       buf[SW(o)] = mkf2(apc.x + bpd.x, apc.y + bpd.y);
;       buf[SW(o + s)] = cmul(w1, mkf2(amc.x + bmd.y, amc.y - bmd.x));
;       buf[SW(o + 2 * s)] = cmul(w2, mkf2(apc.x - bpd.x, apc.y - bpd.y));
;       buf[SW(o + 3 * s)] = cmul(w3, mkf2(amc.x - bmd.y, amc.y + bmd.x));
;     }
	v_pk_fma_f32 v[30:31], v[226:227], v[62:63], v[30:31] op_sel_hi:[0,1,1] neg_lo:[0,0,1]
	v_pk_mul_f32 v[62:63], v[230:231], v[204:205] op_sel:[1,1] op_sel_hi:[1,0]
	v_pk_fma_f32 v[62:63], v[230:231], v[204:205], v[62:63] op_sel_hi:[0,1,1] neg_lo:[0,0,1]
	v_pk_add_f32 v[202:203], v[10:11], v[42:43]
	v_pk_add_f32 v[10:11], v[10:11], v[42:43] neg_lo:[0,1] neg_hi:[0,1]
	v_pk_add_f32 v[204:205], v[26:27], v[58:59]
	v_pk_add_f32 v[26:27], v[26:27], v[58:59] neg_lo:[0,1] neg_hi:[0,1]
	v_pk_add_f32 v[42:43], v[202:203], v[204:205]
	v_pk_add_f32 v[58:59], v[202:203], v[204:205] neg_lo:[0,1] neg_hi:[0,1]
	v_pk_add_f32 v[202:203], v[10:11], v[26:27] op_sel:[0,1] op_sel_hi:[1,0] neg_hi:[0,1]
	v_pk_add_f32 v[204:205], v[10:11], v[26:27] op_sel:[0,1] op_sel_hi:[1,0] neg_lo:[0,1]
	v_pk_mul_f32 v[10:11], v[224:225], v[202:203] op_sel:[1,1] op_sel_hi:[1,0]
	v_pk_fma_f32 v[10:11], v[224:225], v[202:203], v[10:11] op_sel_hi:[0,1,1] neg_lo:[0,0,1]
	v_pk_mul_f32 v[26:27], v[226:227], v[58:59] op_sel:[1,1] op_sel_hi:[1,0]
	v_pk_fma_f32 v[26:27], v[226:227], v[58:59], v[26:27] op_sel_hi:[0,1,1] neg_lo:[0,0,1]
	v_pk_mul_f32 v[58:59], v[230:231], v[204:205] op_sel:[1,1] op_sel_hi:[1,0]
	v_pk_fma_f32 v[58:59], v[230:231], v[204:205], v[58:59] op_sel_hi:[0,1,1] neg_lo:[0,0,1]
	v_pk_add_f32 v[202:203], v[12:13], v[44:45]
	v_pk_add_f32 v[12:13], v[12:13], v[44:45] neg_lo:[0,1] neg_hi:[0,1]
	v_pk_add_f32 v[204:205], v[28:29], v[60:61]
	v_pk_add_f32 v[28:29], v[28:29], v[60:61] neg_lo:[0,1] neg_hi:[0,1]
	v_pk_add_f32 v[44:45], v[202:203], v[204:205]
	v_pk_add_f32 v[60:61], v[202:203], v[204:205] neg_lo:[0,1] neg_hi:[0,1]
	v_pk_add_f32 v[202:203], v[12:13], v[28:29] op_sel:[0,1] op_sel_hi:[1,0] neg_hi:[0,1]
	v_pk_add_f32 v[204:205], v[12:13], v[28:29] op_sel:[0,1] op_sel_hi:[1,0] neg_lo:[0,1]
	v_pk_mul_f32 v[12:13], v[224:225], v[202:203] op_sel:[1,1] op_sel_hi:[1,0]
	v_pk_fma_f32 v[12:13], v[224:225], v[202:203], v[12:13] op_sel_hi:[0,1,1] neg_lo:[0,0,1]
	v_pk_mul_f32 v[28:29], v[226:227], v[60:61] op_sel:[1,1] op_sel_hi:[1,0]
	v_pk_fma_f32 v[28:29], v[226:227], v[60:61], v[28:29] op_sel_hi:[0,1,1] neg_lo:[0,0,1]
	v_pk_mul_f32 v[60:61], v[230:231], v[204:205] op_sel:[1,1] op_sel_hi:[1,0]
	v_pk_fma_f32 v[60:61], v[230:231], v[204:205], v[60:61] op_sel_hi:[0,1,1] neg_lo:[0,0,1]
	v_pk_add_f32 v[202:203], v[16:17], v[48:49]
	v_pk_add_f32 v[16:17], v[16:17], v[48:49] neg_lo:[0,1] neg_hi:[0,1]
	v_pk_add_f32 v[204:205], v[32:33], v[64:65]
	v_pk_add_f32 v[32:33], v[32:33], v[64:65] neg_lo:[0,1] neg_hi:[0,1]
	v_pk_add_f32 v[48:49], v[202:203], v[204:205]
	v_pk_add_f32 v[64:65], v[202:203], v[204:205] neg_lo:[0,1] neg_hi:[0,1]
	v_pk_add_f32 v[202:203], v[16:17], v[32:33] op_sel:[0,1] op_sel_hi:[1,0] neg_hi:[0,1]
	v_pk_add_f32 v[204:205], v[16:17], v[32:33] op_sel:[0,1] op_sel_hi:[1,0] neg_lo:[0,1]
	v_pk_mul_f32 v[16:17], v[224:225], v[202:203] op_sel:[1,1] op_sel_hi:[1,0]
	v_pk_fma_f32 v[16:17], v[224:225], v[202:203], v[16:17] op_sel_hi:[0,1,1] neg_lo:[0,0,1]
	v_pk_mul_f32 v[32:33], v[226:227], v[64:65] op_sel:[1,1] op_sel_hi:[1,0]
	v_pk_fma_f32 v[32:33], v[226:227], v[64:65], v[32:33] op_sel_hi:[0,1,1] neg_lo:[0,0,1]
	v_pk_mul_f32 v[64:65], v[230:231], v[204:205] op_sel:[1,1] op_sel_hi:[1,0]
	v_pk_fma_f32 v[64:65], v[230:231], v[204:205], v[64:65] op_sel_hi:[0,1,1] neg_lo:[0,0,1]
	ds_write_b64 v164, v[38:39] offset:0
	v_xor_b32_e32 v156, 8, v164
	ds_write_b64 v156, v[34:35] offset:0
	v_xor_b32_e32 v158, 16, v164
	ds_write_b64 v158, v[36:37] offset:0
	v_xor_b32_e32 v160, 24, v164
	ds_write_b64 v160, v[40:41] offset:0
	v_xor_b32_e32 v162, 32, v164
	ds_write_b64 v162, v[6:7] offset:0
	v_xor_b32_e32 v156, 40, v164
	ds_write_b64 v156, v[2:3] offset:0
	v_xor_b32_e32 v158, 48, v164
	ds_write_b64 v158, v[4:5] offset:0
	v_xor_b32_e32 v160, 56, v164
	ds_write_b64 v160, v[8:9] offset:0
	v_xor_b32_e32 v162, 64, v164
	ds_write_b64 v162, v[22:23] offset:0
	v_xor_b32_e32 v156, 0x48, v164
	ds_write_b64 v156, v[18:19] offset:0
	v_xor_b32_e32 v158, 0x50, v164
	ds_write_b64 v158, v[20:21] offset:0
	v_xor_b32_e32 v160, 0x58, v164
	ds_write_b64 v160, v[24:25] offset:0
	v_xor_b32_e32 v162, 0x60, v164
	ds_write_b64 v162, v[54:55] offset:0
	v_xor_b32_e32 v156, 0x68, v164
	ds_write_b64 v156, v[50:51] offset:0
	v_xor_b32_e32 v158, 0x70, v164
	ds_write_b64 v158, v[52:53] offset:0
	v_xor_b32_e32 v160, 0x78, v164
	ds_write_b64 v160, v[56:57] offset:0
	ds_write_b64 v164, v[46:47] offset:32768
	v_xor_b32_e32 v162, 8, v164
	ds_write_b64 v162, v[42:43] offset:32768
	v_xor_b32_e32 v156, 16, v164
	ds_write_b64 v156, v[44:45] offset:32768
	v_xor_b32_e32 v158, 24, v164
	ds_write_b64 v158, v[48:49] offset:32768
	v_xor_b32_e32 v160, 32, v164
	ds_write_b64 v160, v[14:15] offset:32768
	v_xor_b32_e32 v162, 40, v164
	ds_write_b64 v162, v[10:11] offset:32768
	v_xor_b32_e32 v156, 48, v164
	ds_write_b64 v156, v[12:13] offset:32768
	v_xor_b32_e32 v158, 56, v164
	ds_write_b64 v158, v[16:17] offset:32768
	v_xor_b32_e32 v160, 64, v164
	ds_write_b64 v160, v[30:31] offset:32768
	v_xor_b32_e32 v162, 0x48, v164
	ds_write_b64 v162, v[26:27] offset:32768
	v_xor_b32_e32 v156, 0x50, v164
	ds_write_b64 v156, v[28:29] offset:32768
	v_xor_b32_e32 v158, 0x58, v164
	ds_write_b64 v158, v[32:33] offset:32768
	v_xor_b32_e32 v160, 0x60, v164
	ds_write_b64 v160, v[62:63] offset:32768
	v_xor_b32_e32 v162, 0x68, v164
	ds_write_b64 v162, v[58:59] offset:32768
	v_xor_b32_e32 v156, 0x70, v164
	ds_write_b64 v156, v[60:61] offset:32768
	v_xor_b32_e32 v158, 0x78, v164
	ds_write_b64 v158, v[64:65] offset:32768
	s_waitcnt lgkmcnt(0)
	s_barrier
; DI f32x2 cmul(f32x2 a, f32x2 b) { return mkf2(a.x * b.x - a.y * b.y, a.x * b.y + a.y * b.x); }
; DI void fft8192(f32x2* buf, const f32x2* __restrict__ tw) {
;     ...
;     __syncthreads();
; #pragma unroll
;     for (int e = 0; e < 8; ++e) {
;       const int i = tid + 256 * e;
;       const int pi = SW(i);
;       a[e] = buf[pi]; b[e] = buf[pi + 2048]; c[e] = buf[pi + 4096]; d[e] = buf[pi + 6144];
;     }
;     __syncthreads();
; #pragma unroll
;     for (int e = 0; e < 8; ++e) {
;       const int i = tid + 256 * e;
;       const int q = i & (s - 1);
;       const int ps = i - q;
;       const float rev = (float)ps * (1.f / 8192.f);
;       const f32x2 w1 = mkf2(__builtin_amdgcn_cosf(rev), -__builtin_amdgcn_sinf(rev));
;       const f32x2 w2 = cmul(w1, w1), w3 = cmul(w1, w2);
;       const f32x2 apc = mkf2(a[e].x + c[e].x, a[e].y + c[e].y), amc = mkf2(a[e].x - c[e].x, a[e].y - c[e].y);
;       const f32x2 bpd = mkf2(b[e].x + d[e].x, b[e].y + d[e].y), bmd = mkf2(b[e].x - d[e].x, b[e].y - d[e].y);
;       const int o = 4 * i - 3 * q;
;       buf[SW(o)] = mkf2(apc.x + bpd.x, apc.y + bpd.y);
;       buf[SW(o + s)] = cmul(w1, mkf2(amc.x + bmd.y, amc.y - bmd.x));
;       buf[SW(o + 2 * s)] = cmul(w2, mkf2(apc.x - bpd.x, apc.y - bpd.y));
;       buf[SW(o + 3 * s)] = cmul(w3, mkf2(amc.x - bmd.y, amc.y + bmd.x));
;     }
	v_bfe_i32 v166, v0, 4, 4
	v_and_b32_e32 v166, 15, v166
	v_xor_b32_e32 v166, v166, v0
	v_lshlrev_b32_e32 v164, 3, v166
	ds_read2st64_b64 v[2:5], v164 offset0:0 offset1:32
	ds_read2st64_b64 v[6:9], v164 offset0:64 offset1:96
	ds_read2st64_b64 v[10:13], v164 offset0:4 offset1:36
	ds_read2st64_b64 v[14:17], v164 offset0:68 offset1:100
	ds_read2st64_b64 v[18:21], v164 offset0:8 offset1:40
	ds_read2st64_b64 v[22:25], v164 offset0:72 offset1:104
	ds_read2st64_b64 v[26:29], v164 offset0:12 offset1:44
	ds_read2st64_b64 v[30:33], v164 offset0:76 offset1:108
	ds_read2st64_b64 v[34:37], v164 offset0:16 offset1:48
	ds_read2st64_b64 v[38:41], v164 offset0:80 offset1:112
	ds_read2st64_b64 v[42:45], v164 offset0:20 offset1:52
	ds_read2st64_b64 v[46:49], v164 offset0:84 offset1:116
	ds_read2st64_b64 v[50:53], v164 offset0:24 offset1:56
	ds_read2st64_b64 v[54:57], v164 offset0:88 offset1:120
	ds_read2st64_b64 v[58:61], v164 offset0:28 offset1:60
	ds_read2st64_b64 v[62:65], v164 offset0:92 offset1:124
	v_and_b32_e32 v166, 15, v0
	v_sub_u32_e32 v168, v0, v166
	v_cvt_f32_u32_e32 v201, v168
	v_lshl_add_u32 v164, v168, 4, v166
	v_lshlrev_b32_e32 v164, 3, v164
	v_mul_f32_e32 v201, 0x39000000, v201
	v_cos_f32_e32 v210, v201
	v_sin_f32_e64 v211, -v201
	s_waitcnt lgkmcnt(14)
	v_pk_add_f32 v[202:203], v[2:3], v[6:7]
	v_pk_add_f32 v[2:3], v[2:3], v[6:7] neg_lo:[0,1] neg_hi:[0,1]
	v_pk_add_f32 v[204:205], v[4:5], v[8:9]
	v_pk_add_f32 v[4:5], v[4:5], v[8:9] neg_lo:[0,1] neg_hi:[0,1]
	v_pk_add_f32 v[6:7], v[202:203], v[204:205]
	v_pk_add_f32 v[8:9], v[202:203], v[204:205] neg_lo:[0,1] neg_hi:[0,1]
	v_pk_add_f32 v[202:203], v[2:3], v[4:5] op_sel:[0,1] op_sel_hi:[1,0] neg_hi:[0,1]
	v_pk_add_f32 v[204:205], v[2:3], v[4:5] op_sel:[0,1] op_sel_hi:[1,0] neg_lo:[0,1]
	v_pk_mul_f32 v[206:207], v[210:211], v[210:211] op_sel:[1,1] op_sel_hi:[1,0]
	v_pk_fma_f32 v[212:213], v[210:211], v[210:211], v[206:207] op_sel_hi:[0,1,1] neg_lo:[0,0,1]
	v_pk_mul_f32 v[206:207], v[210:211], v[212:213] op_sel:[1,1] op_sel_hi:[1,0]
	v_pk_fma_f32 v[220:221], v[210:211], v[212:213], v[206:207] op_sel_hi:[0,1,1] neg_lo:[0,0,1]
	v_pk_mul_f32 v[2:3], v[210:211], v[202:203] op_sel:[1,1] op_sel_hi:[1,0]
	v_pk_fma_f32 v[2:3], v[210:211], v[202:203], v[2:3] op_sel_hi:[0,1,1] neg_lo:[0,0,1]
	v_pk_mul_f32 v[4:5], v[212:213], v[8:9] op_sel:[1,1] op_sel_hi:[1,0]
	v_pk_fma_f32 v[4:5], v[212:213], v[8:9], v[4:5] op_sel_hi:[0,1,1] neg_lo:[0,0,1]
	v_pk_mul_f32 v[8:9], v[220:221], v[204:205] op_sel:[1,1] op_sel_hi:[1,0]
	v_pk_fma_f32 v[8:9], v[220:221], v[204:205], v[8:9] op_sel_hi:[0,1,1] neg_lo:[0,0,1]
	v_add_f32_e32 v214, 0x3d000000, v201
	v_cos_f32_e32 v210, v214
	v_sin_f32_e64 v211, -v214
	s_waitcnt lgkmcnt(12)
	v_pk_add_f32 v[202:203], v[10:11], v[14:15]
	v_pk_add_f32 v[10:11], v[10:11], v[14:15] neg_lo:[0,1] neg_hi:[0,1]
	v_pk_add_f32 v[204:205], v[12:13], v[16:17]
	v_pk_add_f32 v[12:13], v[12:13], v[16:17] neg_lo:[0,1] neg_hi:[0,1]
	v_pk_add_f32 v[14:15], v[202:203], v[204:205]
	v_pk_add_f32 v[16:17], v[202:203], v[204:205] neg_lo:[0,1] neg_hi:[0,1]
	v_pk_add_f32 v[202:203], v[10:11], v[12:13] op_sel:[0,1] op_sel_hi:[1,0] neg_hi:[0,1]
	v_pk_add_f32 v[204:205], v[10:11], v[12:13] op_sel:[0,1] op_sel_hi:[1,0] neg_lo:[0,1]
	v_pk_mul_f32 v[206:207], v[210:211], v[210:211] op_sel:[1,1] op_sel_hi:[1,0]
	v_pk_fma_f32 v[212:213], v[210:211], v[210:211], v[206:207] op_sel_hi:[0,1,1] neg_lo:[0,0,1]
	v_pk_mul_f32 v[206:207], v[210:211], v[212:213] op_sel:[1,1] op_sel_hi:[1,0]
	v_pk_fma_f32 v[220:221], v[210:211], v[212:213], v[206:207] op_sel_hi:[0,1,1] neg_lo:[0,0,1]
	v_pk_mul_f32 v[10:11], v[210:211], v[202:203] op_sel:[1,1] op_sel_hi:[1,0]
	v_pk_fma_f32 v[10:11], v[210:211], v[202:203], v[10:11] op_sel_hi:[0,1,1] neg_lo:[0,0,1]
	v_pk_mul_f32 v[12:13], v[212:213], v[16:17] op_sel:[1,1] op_sel_hi:[1,0]
	v_pk_fma_f32 v[12:13], v[212:213], v[16:17], v[12:13] op_sel_hi:[0,1,1] neg_lo:[0,0,1]
	v_pk_mul_f32 v[16:17], v[220:221], v[204:205] op_sel:[1,1] op_sel_hi:[1,0]
	v_pk_fma_f32 v[16:17], v[220:221], v[204:205], v[16:17] op_sel_hi:[0,1,1] neg_lo:[0,0,1]
	v_add_f32_e32 v214, 0x3d800000, v201
	v_cos_f32_e32 v210, v214
	v_sin_f32_e64 v211, -v214
	s_waitcnt lgkmcnt(10)
	v_pk_add_f32 v[202:203], v[18:19], v[22:23]
	v_pk_add_f32 v[18:19], v[18:19], v[22:23] neg_lo:[0,1] neg_hi:[0,1]
	v_pk_add_f32 v[204:205], v[20:21], v[24:25]
	v_pk_add_f32 v[20:21], v[20:21], v[24:25] neg_lo:[0,1] neg_hi:[0,1]
	v_pk_add_f32 v[22:23], v[202:203], v[204:205]
	v_pk_add_f32 v[24:25], v[202:203], v[204:205] neg_lo:[0,1] neg_hi:[0,1]
	v_pk_add_f32 v[202:203], v[18:19], v[20:21] op_sel:[0,1] op_sel_hi:[1,0] neg_hi:[0,1]
	v_pk_add_f32 v[204:205], v[18:19], v[20:21] op_sel:[0,1] op_sel_hi:[1,0] neg_lo:[0,1]
	v_pk_mul_f32 v[206:207], v[210:211], v[210:211] op_sel:[1,1] op_sel_hi:[1,0]
	v_pk_fma_f32 v[212:213], v[210:211], v[210:211], v[206:207] op_sel_hi:[0,1,1] neg_lo:[0,0,1]
	v_pk_mul_f32 v[206:207], v[210:211], v[212:213] op_sel:[1,1] op_sel_hi:[1,0]
	v_pk_fma_f32 v[220:221], v[210:211], v[212:213], v[206:207] op_sel_hi:[0,1,1] neg_lo:[0,0,1]
	v_pk_mul_f32 v[18:19], v[210:211], v[202:203] op_sel:[1,1] op_sel_hi:[1,0]
	v_pk_fma_f32 v[18:19], v[210:211], v[202:203], v[18:19] op_sel_hi:[0,1,1] neg_lo:[0,0,1]
	v_pk_mul_f32 v[20:21], v[212:213], v[24:25] op_sel:[1,1] op_sel_hi:[1,0]
	v_pk_fma_f32 v[20:21], v[212:213], v[24:25], v[20:21] op_sel_hi:[0,1,1] neg_lo:[0,0,1]
	v_pk_mul_f32 v[24:25], v[220:221], v[204:205] op_sel:[1,1] op_sel_hi:[1,0]
	v_pk_fma_f32 v[24:25], v[220:221], v[204:205], v[24:25] op_sel_hi:[0,1,1] neg_lo:[0,0,1]
	v_add_f32_e32 v214, 0x3dc00000, v201
	v_cos_f32_e32 v210, v214
	v_sin_f32_e64 v211, -v214
	s_waitcnt lgkmcnt(8)
; DI f32x2 cmul(f32x2 a, f32x2 b) { return mkf2(a.x * b.x - a.y * b.y, a.x * b.y + a.y * b.x); }
; DI void fft8192(f32x2* buf, const f32x2* __restrict__ tw) {
;     ...
; #pragma unroll
;     for (int e = 0; e < 8; ++e) {
;       const int i = tid + 256 * e;
;       const int q = i & (s - 1);
;       const int ps = i - q;
;       const float rev = (float)ps * (1.f / 8192.f);
;       const f32x2 w1 = mkf2(__builtin_amdgcn_cosf(rev), -__builtin_amdgcn_sinf(rev));
;       const f32x2 w2 = cmul(w1, w1), w3 = cmul(w1, w2);
;       const f32x2 apc = mkf2(a[e].x + c[e].x, a[e].y + c[e].y), amc = mkf2(a[e].x - c[e].x, a[e].y - c[e].y);
;       const f32x2 bpd = mkf2(b[e].x + d[e].x, b[e].y + d[e].y), bmd = mkf2(b[e].x - d[e].x, b[e].y - d[e].y);
;       const int o = 4 * i - 3 * q;
;       buf[SW(o)] = mkf2(apc.x + bpd.x, apc.y + bpd.y);
;       buf[SW(o + s)] = cmul(w1, mkf2(amc.x + bmd.y, amc.y - bmd.x));
;       buf[SW(o + 2 * s)] = cmul(w2, mkf2(apc.x - bpd.x, apc.y - bpd.y));
;       buf[SW(o + 3 * s)] = cmul(w3, mkf2(amc.x - bmd.y, amc.y + bmd.x));
;     }
	v_pk_add_f32 v[202:203], v[26:27], v[30:31]
	v_pk_add_f32 v[26:27], v[26:27], v[30:31] neg_lo:[0,1] neg_hi:[0,1]
	v_pk_add_f32 v[204:205], v[28:29], v[32:33]
	v_pk_add_f32 v[28:29], v[28:29], v[32:33] neg_lo:[0,1] neg_hi:[0,1]
	v_pk_add_f32 v[30:31], v[202:203], v[204:205]
	v_pk_add_f32 v[32:33], v[202:203], v[204:205] neg_lo:[0,1] neg_hi:[0,1]
	v_pk_add_f32 v[202:203], v[26:27], v[28:29] op_sel:[0,1] op_sel_hi:[1,0] neg_hi:[0,1]
	v_pk_add_f32 v[204:205], v[26:27], v[28:29] op_sel:[0,1] op_sel_hi:[1,0] neg_lo:[0,1]
	v_pk_mul_f32 v[206:207], v[210:211], v[210:211] op_sel:[1,1] op_sel_hi:[1,0]
	v_pk_fma_f32 v[212:213], v[210:211], v[210:211], v[206:207] op_sel_hi:[0,1,1] neg_lo:[0,0,1]
	v_pk_mul_f32 v[206:207], v[210:211], v[212:213] op_sel:[1,1] op_sel_hi:[1,0]
	v_pk_fma_f32 v[220:221], v[210:211], v[212:213], v[206:207] op_sel_hi:[0,1,1] neg_lo:[0,0,1]
	v_pk_mul_f32 v[26:27], v[210:211], v[202:203] op_sel:[1,1] op_sel_hi:[1,0]
	v_pk_fma_f32 v[26:27], v[210:211], v[202:203], v[26:27] op_sel_hi:[0,1,1] neg_lo:[0,0,1]
	v_pk_mul_f32 v[28:29], v[212:213], v[32:33] op_sel:[1,1] op_sel_hi:[1,0]
	v_pk_fma_f32 v[28:29], v[212:213], v[32:33], v[28:29] op_sel_hi:[0,1,1] neg_lo:[0,0,1]
	v_pk_mul_f32 v[32:33], v[220:221], v[204:205] op_sel:[1,1] op_sel_hi:[1,0]
	v_pk_fma_f32 v[32:33], v[220:221], v[204:205], v[32:33] op_sel_hi:[0,1,1] neg_lo:[0,0,1]
	v_add_f32_e32 v214, 0x3e000000, v201
	v_cos_f32_e32 v210, v214
	v_sin_f32_e64 v211, -v214
	s_waitcnt lgkmcnt(6)
	v_pk_add_f32 v[202:203], v[34:35], v[38:39]
	v_pk_add_f32 v[34:35], v[34:35], v[38:39] neg_lo:[0,1] neg_hi:[0,1]
	v_pk_add_f32 v[204:205], v[36:37], v[40:41]
	v_pk_add_f32 v[36:37], v[36:37], v[40:41] neg_lo:[0,1] neg_hi:[0,1]
	v_pk_add_f32 v[38:39], v[202:203], v[204:205]
	v_pk_add_f32 v[40:41], v[202:203], v[204:205] neg_lo:[0,1] neg_hi:[0,1]
	v_pk_add_f32 v[202:203], v[34:35], v[36:37] op_sel:[0,1] op_sel_hi:[1,0] neg_hi:[0,1]
	v_pk_add_f32 v[204:205], v[34:35], v[36:37] op_sel:[0,1] op_sel_hi:[1,0] neg_lo:[0,1]
	v_pk_mul_f32 v[206:207], v[210:211], v[210:211] op_sel:[1,1] op_sel_hi:[1,0]
	v_pk_fma_f32 v[212:213], v[210:211], v[210:211], v[206:207] op_sel_hi:[0,1,1] neg_lo:[0,0,1]
	v_pk_mul_f32 v[206:207], v[210:211], v[212:213] op_sel:[1,1] op_sel_hi:[1,0]
	v_pk_fma_f32 v[220:221], v[210:211], v[212:213], v[206:207] op_sel_hi:[0,1,1] neg_lo:[0,0,1]
	v_pk_mul_f32 v[34:35], v[210:211], v[202:203] op_sel:[1,1] op_sel_hi:[1,0]
	v_pk_fma_f32 v[34:35], v[210:211], v[202:203], v[34:35] op_sel_hi:[0,1,1] neg_lo:[0,0,1]
	v_pk_mul_f32 v[36:37], v[212:213], v[40:41] op_sel:[1,1] op_sel_hi:[1,0]
	v_pk_fma_f32 v[36:37], v[212:213], v[40:41], v[36:37] op_sel_hi:[0,1,1] neg_lo:[0,0,1]
	v_pk_mul_f32 v[40:41], v[220:221], v[204:205] op_sel:[1,1] op_sel_hi:[1,0]
	v_pk_fma_f32 v[40:41], v[220:221], v[204:205], v[40:41] op_sel_hi:[0,1,1] neg_lo:[0,0,1]
	v_add_f32_e32 v214, 0x3e200000, v201
	v_cos_f32_e32 v210, v214
	v_sin_f32_e64 v211, -v214
	s_waitcnt lgkmcnt(4)
	v_pk_add_f32 v[202:203], v[42:43], v[46:47]
	v_pk_add_f32 v[42:43], v[42:43], v[46:47] neg_lo:[0,1] neg_hi:[0,1]
	v_pk_add_f32 v[204:205], v[44:45], v[48:49]
	v_pk_add_f32 v[44:45], v[44:45], v[48:49] neg_lo:[0,1] neg_hi:[0,1]
	v_pk_add_f32 v[46:47], v[202:203], v[204:205]
	v_pk_add_f32 v[48:49], v[202:203], v[204:205] neg_lo:[0,1] neg_hi:[0,1]
	v_pk_add_f32 v[202:203], v[42:43], v[44:45] op_sel:[0,1] op_sel_hi:[1,0] neg_hi:[0,1]
	v_pk_add_f32 v[204:205], v[42:43], v[44:45] op_sel:[0,1] op_sel_hi:[1,0] neg_lo:[0,1]
	v_pk_mul_f32 v[206:207], v[210:211], v[210:211] op_sel:[1,1] op_sel_hi:[1,0]
	v_pk_fma_f32 v[212:213], v[210:211], v[210:211], v[206:207] op_sel_hi:[0,1,1] neg_lo:[0,0,1]
	v_pk_mul_f32 v[206:207], v[210:211], v[212:213] op_sel:[1,1] op_sel_hi:[1,0]
	v_pk_fma_f32 v[220:221], v[210:211], v[212:213], v[206:207] op_sel_hi:[0,1,1] neg_lo:[0,0,1]
	v_pk_mul_f32 v[42:43], v[210:211], v[202:203] op_sel:[1,1] op_sel_hi:[1,0]
	v_pk_fma_f32 v[42:43], v[210:211], v[202:203], v[42:43] op_sel_hi:[0,1,1] neg_lo:[0,0,1]
	v_pk_mul_f32 v[44:45], v[212:213], v[48:49] op_sel:[1,1] op_sel_hi:[1,0]
	v_pk_fma_f32 v[44:45], v[212:213], v[48:49], v[44:45] op_sel_hi:[0,1,1] neg_lo:[0,0,1]
	v_pk_mul_f32 v[48:49], v[220:221], v[204:205] op_sel:[1,1] op_sel_hi:[1,0]
	v_pk_fma_f32 v[48:49], v[220:221], v[204:205], v[48:49] op_sel_hi:[0,1,1] neg_lo:[0,0,1]
	v_add_f32_e32 v214, 0x3e400000, v201
	v_cos_f32_e32 v210, v214
	v_sin_f32_e64 v211, -v214
	s_waitcnt lgkmcnt(2)
	v_pk_add_f32 v[202:203], v[50:51], v[54:55]
	v_pk_add_f32 v[50:51], v[50:51], v[54:55] neg_lo:[0,1] neg_hi:[0,1]
	v_pk_add_f32 v[204:205], v[52:53], v[56:57]
	v_pk_add_f32 v[52:53], v[52:53], v[56:57] neg_lo:[0,1] neg_hi:[0,1]
	v_pk_add_f32 v[54:55], v[202:203], v[204:205]
	v_pk_add_f32 v[56:57], v[202:203], v[204:205] neg_lo:[0,1] neg_hi:[0,1]
	v_pk_add_f32 v[202:203], v[50:51], v[52:53] op_sel:[0,1] op_sel_hi:[1,0] neg_hi:[0,1]
	v_pk_add_f32 v[204:205], v[50:51], v[52:53] op_sel:[0,1] op_sel_hi:[1,0] neg_lo:[0,1]
	v_pk_mul_f32 v[206:207], v[210:211], v[210:211] op_sel:[1,1] op_sel_hi:[1,0]
	v_pk_fma_f32 v[212:213], v[210:211], v[210:211], v[206:207] op_sel_hi:[0,1,1] neg_lo:[0,0,1]
	v_pk_mul_f32 v[206:207], v[210:211], v[212:213] op_sel:[1,1] op_sel_hi:[1,0]
	v_pk_fma_f32 v[220:221], v[210:211], v[212:213], v[206:207] op_sel_hi:[0,1,1] neg_lo:[0,0,1]
	v_pk_mul_f32 v[50:51], v[210:211], v[202:203] op_sel:[1,1] op_sel_hi:[1,0]
	v_pk_fma_f32 v[50:51], v[210:211], v[202:203], v[50:51] op_sel_hi:[0,1,1] neg_lo:[0,0,1]
	v_pk_mul_f32 v[52:53], v[212:213], v[56:57] op_sel:[1,1] op_sel_hi:[1,0]
	v_pk_fma_f32 v[52:53], v[212:213], v[56:57], v[52:53] op_sel_hi:[0,1,1] neg_lo:[0,0,1]
	v_pk_mul_f32 v[56:57], v[220:221], v[204:205] op_sel:[1,1] op_sel_hi:[1,0]
	v_pk_fma_f32 v[56:57], v[220:221], v[204:205], v[56:57] op_sel_hi:[0,1,1] neg_lo:[0,0,1]
	v_add_f32_e32 v214, 0x3e600000, v201
	v_cos_f32_e32 v210, v214
	v_sin_f32_e64 v211, -v214
	s_waitcnt lgkmcnt(0)
; DI f32x2 cmul(f32x2 a, f32x2 b) { return mkf2(a.x * b.x - a.y * b.y, a.x * b.y + a.y * b.x); }
; DI void fft8192(f32x2* buf, const f32x2* __restrict__ tw) {
;     ...
; #pragma unroll
;     for (int e = 0; e < 8; ++e) {
;       const int i = tid + 256 * e;
;       const int q = i & (s - 1);
;       const int ps = i - q;
;       const float rev = (float)ps * (1.f / 8192.f);
;       const f32x2 w1 = mkf2(__builtin_amdgcn_cosf(rev), -__builtin_amdgcn_sinf(rev));
;       const f32x2 w2 = cmul(w1, w1), w3 = cmul(w1, w2);
;       const f32x2 apc = mkf2(a[e].x + c[e].x, a[e].y + c[e].y), amc = mkf2(a[e].x - c[e].x, a[e].y - c[e].y);
;       const f32x2 bpd = mkf2(b[e].x + d[e].x, b[e].y + d[e].y), bmd = mkf2(b[e].x - d[e].x, b[e].y - d[e].y);
;       const int o = 4 * i - 3 * q;
;       buf[SW(o)] = mkf2(apc.x + bpd.x, apc.y + bpd.y);
;       buf[SW(o + s)] = cmul(w1, mkf2(amc.x + bmd.y, amc.y - bmd.x));
;       buf[SW(o + 2 * s)] = cmul(w2, mkf2(apc.x - bpd.x, apc.y - bpd.y));
;       buf[SW(o + 3 * s)] = cmul(w3, mkf2(amc.x - bmd.y, amc.y + bmd.x));
;     }
	v_pk_add_f32 v[202:203], v[58:59], v[62:63]
	v_pk_add_f32 v[58:59], v[58:59], v[62:63] neg_lo:[0,1] neg_hi:[0,1]
	v_pk_add_f32 v[204:205], v[60:61], v[64:65]
	v_pk_add_f32 v[60:61], v[60:61], v[64:65] neg_lo:[0,1] neg_hi:[0,1]
	v_pk_add_f32 v[62:63], v[202:203], v[204:205]
	v_pk_add_f32 v[64:65], v[202:203], v[204:205] neg_lo:[0,1] neg_hi:[0,1]
	v_pk_add_f32 v[202:203], v[58:59], v[60:61] op_sel:[0,1] op_sel_hi:[1,0] neg_hi:[0,1]
	v_pk_add_f32 v[204:205], v[58:59], v[60:61] op_sel:[0,1] op_sel_hi:[1,0] neg_lo:[0,1]
	v_pk_mul_f32 v[206:207], v[210:211], v[210:211] op_sel:[1,1] op_sel_hi:[1,0]
	v_pk_fma_f32 v[212:213], v[210:211], v[210:211], v[206:207] op_sel_hi:[0,1,1] neg_lo:[0,0,1]
	v_pk_mul_f32 v[206:207], v[210:211], v[212:213] op_sel:[1,1] op_sel_hi:[1,0]
	v_pk_fma_f32 v[220:221], v[210:211], v[212:213], v[206:207] op_sel_hi:[0,1,1] neg_lo:[0,0,1]
	v_pk_mul_f32 v[58:59], v[210:211], v[202:203] op_sel:[1,1] op_sel_hi:[1,0]
	v_pk_fma_f32 v[58:59], v[210:211], v[202:203], v[58:59] op_sel_hi:[0,1,1] neg_lo:[0,0,1]
	v_pk_mul_f32 v[60:61], v[212:213], v[64:65] op_sel:[1,1] op_sel_hi:[1,0]
	v_pk_fma_f32 v[60:61], v[212:213], v[64:65], v[60:61] op_sel_hi:[0,1,1] neg_lo:[0,0,1]
	v_pk_mul_f32 v[64:65], v[220:221], v[204:205] op_sel:[1,1] op_sel_hi:[1,0]
	v_pk_fma_f32 v[64:65], v[220:221], v[204:205], v[64:65] op_sel_hi:[0,1,1] neg_lo:[0,0,1]
	s_barrier
	v_mul_f32_e32 v214, 4.0, v201
	v_cos_f32_e32 v224, v214
	v_sin_f32_e64 v225, -v214
	s_nop 0
	v_pk_mul_f32 v[206:207], v[224:225], v[224:225] op_sel:[1,1] op_sel_hi:[1,0]
	v_pk_fma_f32 v[226:227], v[224:225], v[224:225], v[206:207] op_sel_hi:[0,1,1] neg_lo:[0,0,1]
	v_pk_mul_f32 v[206:207], v[224:225], v[226:227] op_sel:[1,1] op_sel_hi:[1,0]
	v_pk_fma_f32 v[230:231], v[224:225], v[226:227], v[206:207] op_sel_hi:[0,1,1] neg_lo:[0,0,1]
	v_pk_add_f32 v[202:203], v[6:7], v[38:39]
	v_pk_add_f32 v[6:7], v[6:7], v[38:39] neg_lo:[0,1] neg_hi:[0,1]
	v_pk_add_f32 v[204:205], v[22:23], v[54:55]
	v_pk_add_f32 v[22:23], v[22:23], v[54:55] neg_lo:[0,1] neg_hi:[0,1]
	v_pk_add_f32 v[38:39], v[202:203], v[204:205]
	v_pk_add_f32 v[54:55], v[202:203], v[204:205] neg_lo:[0,1] neg_hi:[0,1]
	v_pk_add_f32 v[202:203], v[6:7], v[22:23] op_sel:[0,1] op_sel_hi:[1,0] neg_hi:[0,1]
	v_pk_add_f32 v[204:205], v[6:7], v[22:23] op_sel:[0,1] op_sel_hi:[1,0] neg_lo:[0,1]
	v_pk_mul_f32 v[6:7], v[224:225], v[202:203] op_sel:[1,1] op_sel_hi:[1,0]
	v_pk_fma_f32 v[6:7], v[224:225], v[202:203], v[6:7] op_sel_hi:[0,1,1] neg_lo:[0,0,1]
	v_pk_mul_f32 v[22:23], v[226:227], v[54:55] op_sel:[1,1] op_sel_hi:[1,0]
	v_pk_fma_f32 v[22:23], v[226:227], v[54:55], v[22:23] op_sel_hi:[0,1,1] neg_lo:[0,0,1]
	v_pk_mul_f32 v[54:55], v[230:231], v[204:205] op_sel:[1,1] op_sel_hi:[1,0]
	v_pk_fma_f32 v[54:55], v[230:231], v[204:205], v[54:55] op_sel_hi:[0,1,1] neg_lo:[0,0,1]
	v_pk_add_f32 v[202:203], v[2:3], v[34:35]
	v_pk_add_f32 v[2:3], v[2:3], v[34:35] neg_lo:[0,1] neg_hi:[0,1]
	v_pk_add_f32 v[204:205], v[18:19], v[50:51]
	v_pk_add_f32 v[18:19], v[18:19], v[50:51] neg_lo:[0,1] neg_hi:[0,1]
	v_pk_add_f32 v[34:35], v[202:203], v[204:205]
	v_pk_add_f32 v[50:51], v[202:203], v[204:205] neg_lo:[0,1] neg_hi:[0,1]
	v_pk_add_f32 v[202:203], v[2:3], v[18:19] op_sel:[0,1] op_sel_hi:[1,0] neg_hi:[0,1]
	v_pk_add_f32 v[204:205], v[2:3], v[18:19] op_sel:[0,1] op_sel_hi:[1,0] neg_lo:[0,1]
	v_pk_mul_f32 v[2:3], v[224:225], v[202:203] op_sel:[1,1] op_sel_hi:[1,0]
	v_pk_fma_f32 v[2:3], v[224:225], v[202:203], v[2:3] op_sel_hi:[0,1,1] neg_lo:[0,0,1]
	v_pk_mul_f32 v[18:19], v[226:227], v[50:51] op_sel:[1,1] op_sel_hi:[1,0]
	v_pk_fma_f32 v[18:19], v[226:227], v[50:51], v[18:19] op_sel_hi:[0,1,1] neg_lo:[0,0,1]
	v_pk_mul_f32 v[50:51], v[230:231], v[204:205] op_sel:[1,1] op_sel_hi:[1,0]
	v_pk_fma_f32 v[50:51], v[230:231], v[204:205], v[50:51] op_sel_hi:[0,1,1] neg_lo:[0,0,1]
	v_pk_add_f32 v[202:203], v[4:5], v[36:37]
	v_pk_add_f32 v[4:5], v[4:5], v[36:37] neg_lo:[0,1] neg_hi:[0,1]
	v_pk_add_f32 v[204:205], v[20:21], v[52:53]
	v_pk_add_f32 v[20:21], v[20:21], v[52:53] neg_lo:[0,1] neg_hi:[0,1]
	v_pk_add_f32 v[36:37], v[202:203], v[204:205]
	v_pk_add_f32 v[52:53], v[202:203], v[204:205] neg_lo:[0,1] neg_hi:[0,1]
	v_pk_add_f32 v[202:203], v[4:5], v[20:21] op_sel:[0,1] op_sel_hi:[1,0] neg_hi:[0,1]
	v_pk_add_f32 v[204:205], v[4:5], v[20:21] op_sel:[0,1] op_sel_hi:[1,0] neg_lo:[0,1]
	v_pk_mul_f32 v[4:5], v[224:225], v[202:203] op_sel:[1,1] op_sel_hi:[1,0]
	v_pk_fma_f32 v[4:5], v[224:225], v[202:203], v[4:5] op_sel_hi:[0,1,1] neg_lo:[0,0,1]
	v_pk_mul_f32 v[20:21], v[226:227], v[52:53] op_sel:[1,1] op_sel_hi:[1,0]
	v_pk_fma_f32 v[20:21], v[226:227], v[52:53], v[20:21] op_sel_hi:[0,1,1] neg_lo:[0,0,1]
	v_pk_mul_f32 v[52:53], v[230:231], v[204:205] op_sel:[1,1] op_sel_hi:[1,0]
	v_pk_fma_f32 v[52:53], v[230:231], v[204:205], v[52:53] op_sel_hi:[0,1,1] neg_lo:[0,0,1]
	v_pk_add_f32 v[202:203], v[8:9], v[40:41]
	v_pk_add_f32 v[8:9], v[8:9], v[40:41] neg_lo:[0,1] neg_hi:[0,1]
	v_pk_add_f32 v[204:205], v[24:25], v[56:57]
	v_pk_add_f32 v[24:25], v[24:25], v[56:57] neg_lo:[0,1] neg_hi:[0,1]
	v_pk_add_f32 v[40:41], v[202:203], v[204:205]
	v_pk_add_f32 v[56:57], v[202:203], v[204:205] neg_lo:[0,1] neg_hi:[0,1]
	v_pk_add_f32 v[202:203], v[8:9], v[24:25] op_sel:[0,1] op_sel_hi:[1,0] neg_hi:[0,1]
	v_pk_add_f32 v[204:205], v[8:9], v[24:25] op_sel:[0,1] op_sel_hi:[1,0] neg_lo:[0,1]
	v_pk_mul_f32 v[8:9], v[224:225], v[202:203] op_sel:[1,1] op_sel_hi:[1,0]
	v_pk_fma_f32 v[8:9], v[224:225], v[202:203], v[8:9] op_sel_hi:[0,1,1] neg_lo:[0,0,1]
	v_pk_mul_f32 v[24:25], v[226:227], v[56:57] op_sel:[1,1] op_sel_hi:[1,0]
	v_pk_fma_f32 v[24:25], v[226:227], v[56:57], v[24:25] op_sel_hi:[0,1,1] neg_lo:[0,0,1]
; DI f32x2 cmul(f32x2 a, f32x2 b) { return mkf2(a.x * b.x - a.y * b.y, a.x * b.y + a.y * b.x); }
; DI void fft8192(f32x2* buf, const f32x2* __restrict__ tw) {
;     ...
; #pragma unroll
;     for (int e = 0; e < 8; ++e) {
;       const int i = tid + 256 * e;
;       const int q = i & (s - 1);
;       const int ps = i - q;
;       const float rev = (float)ps * (1.f / 8192.f);
;       const f32x2 w1 = mkf2(__builtin_amdgcn_cosf(rev), -__builtin_amdgcn_sinf(rev));
;       const f32x2 w2 = cmul(w1, w1), w3 = cmul(w1, w2);
;       const f32x2 apc = mkf2(a[e].x + c[e].x, a[e].y + c[e].y), amc = mkf2(a[e].x - c[e].x, a[e].y - c[e].y);
;       const f32x2 bpd = mkf2(b[e].x + d[e].x, b[e].y + d[e].y), bmd = mkf2(b[e].x - d[e].x, b[e].y - d[e].y);
;       const int o = 4 * i - 3 * q;
;       buf[SW(o)] = mkf2(apc.x + bpd.x, apc.y + bpd.y);
;       buf[SW(o + s)] = cmul(w1, mkf2(amc.x + bmd.y, amc.y - bmd.x));
;       buf[SW(o + 2 * s)] = cmul(w2, mkf2(apc.x - bpd.x, apc.y - bpd.y));
;       buf[SW(o + 3 * s)] = cmul(w3, mkf2(amc.x - bmd.y, amc.y + bmd.x));
;     }
	v_pk_mul_f32 v[56:57], v[230:231], v[204:205] op_sel:[1,1] op_sel_hi:[1,0]
	v_pk_fma_f32 v[56:57], v[230:231], v[204:205], v[56:57] op_sel_hi:[0,1,1] neg_lo:[0,0,1]
	v_mul_f32_e32 v214, 4.0, v201
	v_add_f32_e32 v214, 0x3e000000, v214
	v_cos_f32_e32 v224, v214
	v_sin_f32_e64 v225, -v214
	s_nop 0
	v_pk_mul_f32 v[206:207], v[224:225], v[224:225] op_sel:[1,1] op_sel_hi:[1,0]
	v_pk_fma_f32 v[226:227], v[224:225], v[224:225], v[206:207] op_sel_hi:[0,1,1] neg_lo:[0,0,1]
	v_pk_mul_f32 v[206:207], v[224:225], v[226:227] op_sel:[1,1] op_sel_hi:[1,0]
	v_pk_fma_f32 v[230:231], v[224:225], v[226:227], v[206:207] op_sel_hi:[0,1,1] neg_lo:[0,0,1]
	v_pk_add_f32 v[202:203], v[14:15], v[46:47]
	v_pk_add_f32 v[14:15], v[14:15], v[46:47] neg_lo:[0,1] neg_hi:[0,1]
	v_pk_add_f32 v[204:205], v[30:31], v[62:63]
	v_pk_add_f32 v[30:31], v[30:31], v[62:63] neg_lo:[0,1] neg_hi:[0,1]
	v_pk_add_f32 v[46:47], v[202:203], v[204:205]
	v_pk_add_f32 v[62:63], v[202:203], v[204:205] neg_lo:[0,1] neg_hi:[0,1]
	v_pk_add_f32 v[202:203], v[14:15], v[30:31] op_sel:[0,1] op_sel_hi:[1,0] neg_hi:[0,1]
	v_pk_add_f32 v[204:205], v[14:15], v[30:31] op_sel:[0,1] op_sel_hi:[1,0] neg_lo:[0,1]
	v_pk_mul_f32 v[14:15], v[224:225], v[202:203] op_sel:[1,1] op_sel_hi:[1,0]
	v_pk_fma_f32 v[14:15], v[224:225], v[202:203], v[14:15] op_sel_hi:[0,1,1] neg_lo:[0,0,1]
	v_pk_mul_f32 v[30:31], v[226:227], v[62:63] op_sel:[1,1] op_sel_hi:[1,0]
	v_pk_fma_f32 v[30:31], v[226:227], v[62:63], v[30:31] op_sel_hi:[0,1,1] neg_lo:[0,0,1]
	v_pk_mul_f32 v[62:63], v[230:231], v[204:205] op_sel:[1,1] op_sel_hi:[1,0]
	v_pk_fma_f32 v[62:63], v[230:231], v[204:205], v[62:63] op_sel_hi:[0,1,1] neg_lo:[0,0,1]
	v_pk_add_f32 v[202:203], v[10:11], v[42:43]
	v_pk_add_f32 v[10:11], v[10:11], v[42:43] neg_lo:[0,1] neg_hi:[0,1]
	v_pk_add_f32 v[204:205], v[26:27], v[58:59]
	v_pk_add_f32 v[26:27], v[26:27], v[58:59] neg_lo:[0,1] neg_hi:[0,1]
	v_pk_add_f32 v[42:43], v[202:203], v[204:205]
	v_pk_add_f32 v[58:59], v[202:203], v[204:205] neg_lo:[0,1] neg_hi:[0,1]
	v_pk_add_f32 v[202:203], v[10:11], v[26:27] op_sel:[0,1] op_sel_hi:[1,0] neg_hi:[0,1]
	v_pk_add_f32 v[204:205], v[10:11], v[26:27] op_sel:[0,1] op_sel_hi:[1,0] neg_lo:[0,1]
	v_pk_mul_f32 v[10:11], v[224:225], v[202:203] op_sel:[1,1] op_sel_hi:[1,0]
	v_pk_fma_f32 v[10:11], v[224:225], v[202:203], v[10:11] op_sel_hi:[0,1,1] neg_lo:[0,0,1]
	v_pk_mul_f32 v[26:27], v[226:227], v[58:59] op_sel:[1,1] op_sel_hi:[1,0]
	v_pk_fma_f32 v[26:27], v[226:227], v[58:59], v[26:27] op_sel_hi:[0,1,1] neg_lo:[0,0,1]
	v_pk_mul_f32 v[58:59], v[230:231], v[204:205] op_sel:[1,1] op_sel_hi:[1,0]
	v_pk_fma_f32 v[58:59], v[230:231], v[204:205], v[58:59] op_sel_hi:[0,1,1] neg_lo:[0,0,1]
	v_pk_add_f32 v[202:203], v[12:13], v[44:45]
	v_pk_add_f32 v[12:13], v[12:13], v[44:45] neg_lo:[0,1] neg_hi:[0,1]
	v_pk_add_f32 v[204:205], v[28:29], v[60:61]
	v_pk_add_f32 v[28:29], v[28:29], v[60:61] neg_lo:[0,1] neg_hi:[0,1]
	v_pk_add_f32 v[44:45], v[202:203], v[204:205]
	v_pk_add_f32 v[60:61], v[202:203], v[204:205] neg_lo:[0,1] neg_hi:[0,1]
	v_pk_add_f32 v[202:203], v[12:13], v[28:29] op_sel:[0,1] op_sel_hi:[1,0] neg_hi:[0,1]
	v_pk_add_f32 v[204:205], v[12:13], v[28:29] op_sel:[0,1] op_sel_hi:[1,0] neg_lo:[0,1]
	v_pk_mul_f32 v[12:13], v[224:225], v[202:203] op_sel:[1,1] op_sel_hi:[1,0]
	v_pk_fma_f32 v[12:13], v[224:225], v[202:203], v[12:13] op_sel_hi:[0,1,1] neg_lo:[0,0,1]
	v_pk_mul_f32 v[28:29], v[226:227], v[60:61] op_sel:[1,1] op_sel_hi:[1,0]
	v_pk_fma_f32 v[28:29], v[226:227], v[60:61], v[28:29] op_sel_hi:[0,1,1] neg_lo:[0,0,1]
	v_pk_mul_f32 v[60:61], v[230:231], v[204:205] op_sel:[1,1] op_sel_hi:[1,0]
	v_pk_fma_f32 v[60:61], v[230:231], v[204:205], v[60:61] op_sel_hi:[0,1,1] neg_lo:[0,0,1]
	v_pk_add_f32 v[202:203], v[16:17], v[48:49]
	v_pk_add_f32 v[16:17], v[16:17], v[48:49] neg_lo:[0,1] neg_hi:[0,1]
	v_pk_add_f32 v[204:205], v[32:33], v[64:65]
	v_pk_add_f32 v[32:33], v[32:33], v[64:65] neg_lo:[0,1] neg_hi:[0,1]
	v_pk_add_f32 v[48:49], v[202:203], v[204:205]
	v_pk_add_f32 v[64:65], v[202:203], v[204:205] neg_lo:[0,1] neg_hi:[0,1]
	v_pk_add_f32 v[202:203], v[16:17], v[32:33] op_sel:[0,1] op_sel_hi:[1,0] neg_hi:[0,1]
	v_pk_add_f32 v[204:205], v[16:17], v[32:33] op_sel:[0,1] op_sel_hi:[1,0] neg_lo:[0,1]
	v_pk_mul_f32 v[16:17], v[224:225], v[202:203] op_sel:[1,1] op_sel_hi:[1,0]
	v_pk_fma_f32 v[16:17], v[224:225], v[202:203], v[16:17] op_sel_hi:[0,1,1] neg_lo:[0,0,1]
	v_pk_mul_f32 v[32:33], v[226:227], v[64:65] op_sel:[1,1] op_sel_hi:[1,0]
	v_pk_fma_f32 v[32:33], v[226:227], v[64:65], v[32:33] op_sel_hi:[0,1,1] neg_lo:[0,0,1]
	v_pk_mul_f32 v[64:65], v[230:231], v[204:205] op_sel:[1,1] op_sel_hi:[1,0]
	v_pk_fma_f32 v[64:65], v[230:231], v[204:205], v[64:65] op_sel_hi:[0,1,1] neg_lo:[0,0,1]
	ds_write_b64 v164, v[38:39] offset:0
	v_xor_b32_e32 v156, 0x80, v164
	ds_write_b64 v156, v[34:35] offset:0
	v_xor_b32_e32 v158, 0x128, v164
	ds_write_b64 v158, v[36:37] offset:0
	v_xor_b32_e32 v160, 0x1a8, v164
	ds_write_b64 v160, v[40:41] offset:0
	v_xor_b32_e32 v162, 0x2d0, v164
	ds_write_b64 v162, v[6:7] offset:0
	v_xor_b32_e32 v156, 0x250, v164
	ds_write_b64 v156, v[2:3] offset:0
	v_xor_b32_e32 v158, 0x3f8, v164
	ds_write_b64 v158, v[4:5] offset:0
	v_xor_b32_e32 v160, 0x378, v164
	ds_write_b64 v160, v[8:9] offset:0
	v_xor_b32_e32 v162, 0x400, v164
	ds_write_b64 v162, v[22:23] offset:0
	v_xor_b32_e32 v156, 0x480, v164
	ds_write_b64 v156, v[18:19] offset:0
	v_xor_b32_e32 v158, 0x528, v164
	ds_write_b64 v158, v[20:21] offset:0
	v_xor_b32_e32 v160, 0x5a8, v164
	ds_write_b64 v160, v[24:25] offset:0
	v_xor_b32_e32 v162, 0x6d0, v164
	ds_write_b64 v162, v[54:55] offset:0
	v_xor_b32_e32 v156, 0x650, v164
	ds_write_b64 v156, v[50:51] offset:0
	v_xor_b32_e32 v158, 0x7f8, v164
	ds_write_b64 v158, v[52:53] offset:0
	v_xor_b32_e32 v160, 0x778, v164
	ds_write_b64 v160, v[56:57] offset:0
	ds_write_b64 v164, v[46:47] offset:32768
	v_xor_b32_e32 v162, 0x80, v164
	ds_write_b64 v162, v[42:43] offset:32768
	v_xor_b32_e32 v156, 0x128, v164
	ds_write_b64 v156, v[44:45] offset:32768
	v_xor_b32_e32 v158, 0x1a8, v164
	ds_write_b64 v158, v[48:49] offset:32768
	v_xor_b32_e32 v160, 0x2d0, v164
	ds_write_b64 v160, v[14:15] offset:32768
	v_xor_b32_e32 v162, 0x250, v164
	ds_write_b64 v162, v[10:11] offset:32768
	v_xor_b32_e32 v156, 0x3f8, v164
	ds_write_b64 v156, v[12:13] offset:32768
	v_xor_b32_e32 v158, 0x378, v164
	ds_write_b64 v158, v[16:17] offset:32768
	v_xor_b32_e32 v160, 0x400, v164
	ds_write_b64 v160, v[30:31] offset:32768
	v_xor_b32_e32 v162, 0x480, v164
	ds_write_b64 v162, v[26:27] offset:32768
	v_xor_b32_e32 v156, 0x528, v164
	ds_write_b64 v156, v[28:29] offset:32768
	v_xor_b32_e32 v158, 0x5a8, v164
	ds_write_b64 v158, v[32:33] offset:32768
	v_xor_b32_e32 v160, 0x6d0, v164
	ds_write_b64 v160, v[62:63] offset:32768
	v_xor_b32_e32 v162, 0x650, v164
	ds_write_b64 v162, v[58:59] offset:32768
	v_xor_b32_e32 v156, 0x7f8, v164
	ds_write_b64 v156, v[60:61] offset:32768
	v_xor_b32_e32 v158, 0x778, v164
	ds_write_b64 v158, v[64:65] offset:32768
	s_waitcnt lgkmcnt(0)
	s_barrier
; DI f32x2 cmul(f32x2 a, f32x2 b) { return mkf2(a.x * b.x - a.y * b.y, a.x * b.y + a.y * b.x); }
; DI void fft8192(f32x2* buf, const f32x2* __restrict__ tw) {
;     ...
;     __syncthreads();
; #pragma unroll
;     for (int e = 0; e < 8; ++e) {
;       const int i = tid + 256 * e;
;       const int pi = SW(i);
;       a[e] = buf[pi]; b[e] = buf[pi + 2048]; c[e] = buf[pi + 4096]; d[e] = buf[pi + 6144];
;     }
;     __syncthreads();
; #pragma unroll
;     for (int e = 0; e < 8; ++e) {
;       const int i = tid + 256 * e;
;       const int q = i & (s - 1);
;       const int ps = i - q;
;       const float rev = (float)ps * (1.f / 8192.f);
;       const f32x2 w1 = mkf2(__builtin_amdgcn_cosf(rev), -__builtin_amdgcn_sinf(rev));
;       const f32x2 w2 = cmul(w1, w1), w3 = cmul(w1, w2);
;       const f32x2 apc = mkf2(a[e].x + c[e].x, a[e].y + c[e].y), amc = mkf2(a[e].x - c[e].x, a[e].y - c[e].y);
;       const f32x2 bpd = mkf2(b[e].x + d[e].x, b[e].y + d[e].y), bmd = mkf2(b[e].x - d[e].x, b[e].y - d[e].y);
;       const int o = 4 * i - 3 * q;
;       buf[SW(o)] = mkf2(apc.x + bpd.x, apc.y + bpd.y);
;       buf[SW(o + s)] = cmul(w1, mkf2(amc.x + bmd.y, amc.y - bmd.x));
;       buf[SW(o + 2 * s)] = cmul(w2, mkf2(apc.x - bpd.x, apc.y - bpd.y));
;       buf[SW(o + 3 * s)] = cmul(w3, mkf2(amc.x - bmd.y, amc.y + bmd.x));
;     }
	ds_read2st64_b64 v[2:5], v154 offset0:0 offset1:32
	ds_read2st64_b64 v[6:9], v154 offset0:64 offset1:96
	ds_read2st64_b64 v[10:13], v154 offset0:4 offset1:36
	ds_read2st64_b64 v[14:17], v154 offset0:68 offset1:100
	ds_read2st64_b64 v[18:21], v154 offset0:8 offset1:40
	ds_read2st64_b64 v[22:25], v154 offset0:72 offset1:104
	ds_read2st64_b64 v[26:29], v154 offset0:12 offset1:44
	ds_read2st64_b64 v[30:33], v154 offset0:76 offset1:108
	ds_read2st64_b64 v[34:37], v154 offset0:16 offset1:48
	ds_read2st64_b64 v[38:41], v154 offset0:80 offset1:112
	ds_read2st64_b64 v[42:45], v154 offset0:20 offset1:52
	ds_read2st64_b64 v[46:49], v154 offset0:84 offset1:116
	ds_read2st64_b64 v[50:53], v154 offset0:24 offset1:56
	ds_read2st64_b64 v[54:57], v154 offset0:88 offset1:120
	ds_read2st64_b64 v[58:61], v154 offset0:28 offset1:60
	ds_read2st64_b64 v[62:65], v154 offset0:92 offset1:124
	s_waitcnt lgkmcnt(14)
	v_pk_add_f32 v[202:203], v[2:3], v[6:7]
	v_pk_add_f32 v[2:3], v[2:3], v[6:7] neg_lo:[0,1] neg_hi:[0,1]
	v_pk_add_f32 v[204:205], v[4:5], v[8:9]
	v_pk_add_f32 v[4:5], v[4:5], v[8:9] neg_lo:[0,1] neg_hi:[0,1]
	v_pk_add_f32 v[6:7], v[202:203], v[204:205]
	v_pk_add_f32 v[8:9], v[202:203], v[204:205] neg_lo:[0,1] neg_hi:[0,1]
	v_pk_add_f32 v[202:203], v[2:3], v[4:5] op_sel:[0,1] op_sel_hi:[1,0] neg_hi:[0,1]
	v_pk_add_f32 v[4:5], v[2:3], v[4:5] op_sel:[0,1] op_sel_hi:[1,0] neg_lo:[0,1]
	v_pk_mov_b32 v[2:3], v[202:203], v[202:203] op_sel:[0,1]
	v_cos_f32_e32 v210, 0x3d000000
	v_sin_f32_e32 v211, 0xbd000000
	s_waitcnt lgkmcnt(12)
	v_pk_add_f32 v[202:203], v[10:11], v[14:15]
	v_pk_add_f32 v[10:11], v[10:11], v[14:15] neg_lo:[0,1] neg_hi:[0,1]
	v_pk_add_f32 v[204:205], v[12:13], v[16:17]
	v_pk_add_f32 v[12:13], v[12:13], v[16:17] neg_lo:[0,1] neg_hi:[0,1]
	v_pk_add_f32 v[14:15], v[202:203], v[204:205]
	v_pk_add_f32 v[16:17], v[202:203], v[204:205] neg_lo:[0,1] neg_hi:[0,1]
	v_pk_add_f32 v[202:203], v[10:11], v[12:13] op_sel:[0,1] op_sel_hi:[1,0] neg_hi:[0,1]
	v_pk_add_f32 v[204:205], v[10:11], v[12:13] op_sel:[0,1] op_sel_hi:[1,0] neg_lo:[0,1]
	v_pk_mul_f32 v[206:207], v[210:211], v[210:211] op_sel:[1,1] op_sel_hi:[1,0]
	v_pk_fma_f32 v[212:213], v[210:211], v[210:211], v[206:207] op_sel_hi:[0,1,1] neg_lo:[0,0,1]
	v_pk_mul_f32 v[206:207], v[210:211], v[212:213] op_sel:[1,1] op_sel_hi:[1,0]
	v_pk_fma_f32 v[220:221], v[210:211], v[212:213], v[206:207] op_sel_hi:[0,1,1] neg_lo:[0,0,1]
	v_pk_mul_f32 v[10:11], v[210:211], v[202:203] op_sel:[1,1] op_sel_hi:[1,0]
	v_pk_fma_f32 v[10:11], v[210:211], v[202:203], v[10:11] op_sel_hi:[0,1,1] neg_lo:[0,0,1]
	v_pk_mul_f32 v[12:13], v[212:213], v[16:17] op_sel:[1,1] op_sel_hi:[1,0]
	v_pk_fma_f32 v[12:13], v[212:213], v[16:17], v[12:13] op_sel_hi:[0,1,1] neg_lo:[0,0,1]
	v_pk_mul_f32 v[16:17], v[220:221], v[204:205] op_sel:[1,1] op_sel_hi:[1,0]
	v_pk_fma_f32 v[16:17], v[220:221], v[204:205], v[16:17] op_sel_hi:[0,1,1] neg_lo:[0,0,1]
	v_cos_f32_e32 v210, 0x3d800000
	v_sin_f32_e32 v211, 0xbd800000
	s_waitcnt lgkmcnt(10)
	v_pk_add_f32 v[202:203], v[18:19], v[22:23]
	v_pk_add_f32 v[18:19], v[18:19], v[22:23] neg_lo:[0,1] neg_hi:[0,1]
	v_pk_add_f32 v[204:205], v[20:21], v[24:25]
	v_pk_add_f32 v[20:21], v[20:21], v[24:25] neg_lo:[0,1] neg_hi:[0,1]
	v_pk_add_f32 v[22:23], v[202:203], v[204:205]
	v_pk_add_f32 v[24:25], v[202:203], v[204:205] neg_lo:[0,1] neg_hi:[0,1]
	v_pk_add_f32 v[202:203], v[18:19], v[20:21] op_sel:[0,1] op_sel_hi:[1,0] neg_hi:[0,1]
	v_pk_add_f32 v[204:205], v[18:19], v[20:21] op_sel:[0,1] op_sel_hi:[1,0] neg_lo:[0,1]
	v_pk_mul_f32 v[206:207], v[210:211], v[210:211] op_sel:[1,1] op_sel_hi:[1,0]
	v_pk_fma_f32 v[212:213], v[210:211], v[210:211], v[206:207] op_sel_hi:[0,1,1] neg_lo:[0,0,1]
	v_pk_mul_f32 v[206:207], v[210:211], v[212:213] op_sel:[1,1] op_sel_hi:[1,0]
	v_pk_fma_f32 v[220:221], v[210:211], v[212:213], v[206:207] op_sel_hi:[0,1,1] neg_lo:[0,0,1]
	v_pk_mul_f32 v[18:19], v[210:211], v[202:203] op_sel:[1,1] op_sel_hi:[1,0]
	v_pk_fma_f32 v[18:19], v[210:211], v[202:203], v[18:19] op_sel_hi:[0,1,1] neg_lo:[0,0,1]
	v_pk_mul_f32 v[20:21], v[212:213], v[24:25] op_sel:[1,1] op_sel_hi:[1,0]
	v_pk_fma_f32 v[20:21], v[212:213], v[24:25], v[20:21] op_sel_hi:[0,1,1] neg_lo:[0,0,1]
	v_pk_mul_f32 v[24:25], v[220:221], v[204:205] op_sel:[1,1] op_sel_hi:[1,0]
	v_pk_fma_f32 v[24:25], v[220:221], v[204:205], v[24:25] op_sel_hi:[0,1,1] neg_lo:[0,0,1]
	v_cos_f32_e32 v210, 0x3dc00000
	v_sin_f32_e32 v211, 0xbdc00000
	s_waitcnt lgkmcnt(8)
	v_pk_add_f32 v[202:203], v[26:27], v[30:31]
	v_pk_add_f32 v[26:27], v[26:27], v[30:31] neg_lo:[0,1] neg_hi:[0,1]
	v_pk_add_f32 v[204:205], v[28:29], v[32:33]
	v_pk_add_f32 v[28:29], v[28:29], v[32:33] neg_lo:[0,1] neg_hi:[0,1]
	v_pk_add_f32 v[30:31], v[202:203], v[204:205]
	v_pk_add_f32 v[32:33], v[202:203], v[204:205] neg_lo:[0,1] neg_hi:[0,1]
	v_pk_add_f32 v[202:203], v[26:27], v[28:29] op_sel:[0,1] op_sel_hi:[1,0] neg_hi:[0,1]
	v_pk_add_f32 v[204:205], v[26:27], v[28:29] op_sel:[0,1] op_sel_hi:[1,0] neg_lo:[0,1]
	v_pk_mul_f32 v[206:207], v[210:211], v[210:211] op_sel:[1,1] op_sel_hi:[1,0]
	v_pk_fma_f32 v[212:213], v[210:211], v[210:211], v[206:207] op_sel_hi:[0,1,1] neg_lo:[0,0,1]
	v_pk_mul_f32 v[206:207], v[210:211], v[212:213] op_sel:[1,1] op_sel_hi:[1,0]
	v_pk_fma_f32 v[220:221], v[210:211], v[212:213], v[206:207] op_sel_hi:[0,1,1] neg_lo:[0,0,1]
	v_pk_mul_f32 v[26:27], v[210:211], v[202:203] op_sel:[1,1] op_sel_hi:[1,0]
	v_pk_fma_f32 v[26:27], v[210:211], v[202:203], v[26:27] op_sel_hi:[0,1,1] neg_lo:[0,0,1]
	v_pk_mul_f32 v[28:29], v[212:213], v[32:33] op_sel:[1,1] op_sel_hi:[1,0]
	v_pk_fma_f32 v[28:29], v[212:213], v[32:33], v[28:29] op_sel_hi:[0,1,1] neg_lo:[0,0,1]
	v_pk_mul_f32 v[32:33], v[220:221], v[204:205] op_sel:[1,1] op_sel_hi:[1,0]
	v_pk_fma_f32 v[32:33], v[220:221], v[204:205], v[32:33] op_sel_hi:[0,1,1] neg_lo:[0,0,1]
	v_cos_f32_e32 v210, 0x3e000000
	v_sin_f32_e32 v211, 0xbe000000
	s_waitcnt lgkmcnt(6)
; DI f32x2 cmul(f32x2 a, f32x2 b) { return mkf2(a.x * b.x - a.y * b.y, a.x * b.y + a.y * b.x); }
; DI void fft8192(f32x2* buf, const f32x2* __restrict__ tw) {
;     ...
; #pragma unroll
;     for (int e = 0; e < 8; ++e) {
;       const int i = tid + 256 * e;
;       const int q = i & (s - 1);
;       const int ps = i - q;
;       const float rev = (float)ps * (1.f / 8192.f);
;       const f32x2 w1 = mkf2(__builtin_amdgcn_cosf(rev), -__builtin_amdgcn_sinf(rev));
;       const f32x2 w2 = cmul(w1, w1), w3 = cmul(w1, w2);
;       const f32x2 apc = mkf2(a[e].x + c[e].x, a[e].y + c[e].y), amc = mkf2(a[e].x - c[e].x, a[e].y - c[e].y);
;       const f32x2 bpd = mkf2(b[e].x + d[e].x, b[e].y + d[e].y), bmd = mkf2(b[e].x - d[e].x, b[e].y - d[e].y);
;       const int o = 4 * i - 3 * q;
;       buf[SW(o)] = mkf2(apc.x + bpd.x, apc.y + bpd.y);
;       buf[SW(o + s)] = cmul(w1, mkf2(amc.x + bmd.y, amc.y - bmd.x));
;       buf[SW(o + 2 * s)] = cmul(w2, mkf2(apc.x - bpd.x, apc.y - bpd.y));
;       buf[SW(o + 3 * s)] = cmul(w3, mkf2(amc.x - bmd.y, amc.y + bmd.x));
;     }
	v_pk_add_f32 v[202:203], v[34:35], v[38:39]
	v_pk_add_f32 v[34:35], v[34:35], v[38:39] neg_lo:[0,1] neg_hi:[0,1]
	v_pk_add_f32 v[204:205], v[36:37], v[40:41]
	v_pk_add_f32 v[36:37], v[36:37], v[40:41] neg_lo:[0,1] neg_hi:[0,1]
	v_pk_add_f32 v[38:39], v[202:203], v[204:205]
	v_pk_add_f32 v[40:41], v[202:203], v[204:205] neg_lo:[0,1] neg_hi:[0,1]
	v_pk_add_f32 v[202:203], v[34:35], v[36:37] op_sel:[0,1] op_sel_hi:[1,0] neg_hi:[0,1]
	v_pk_add_f32 v[204:205], v[34:35], v[36:37] op_sel:[0,1] op_sel_hi:[1,0] neg_lo:[0,1]
	v_pk_mul_f32 v[206:207], v[210:211], v[210:211] op_sel:[1,1] op_sel_hi:[1,0]
	v_pk_fma_f32 v[212:213], v[210:211], v[210:211], v[206:207] op_sel_hi:[0,1,1] neg_lo:[0,0,1]
	v_pk_mul_f32 v[206:207], v[210:211], v[212:213] op_sel:[1,1] op_sel_hi:[1,0]
	v_pk_fma_f32 v[220:221], v[210:211], v[212:213], v[206:207] op_sel_hi:[0,1,1] neg_lo:[0,0,1]
	v_pk_mul_f32 v[34:35], v[210:211], v[202:203] op_sel:[1,1] op_sel_hi:[1,0]
	v_pk_fma_f32 v[34:35], v[210:211], v[202:203], v[34:35] op_sel_hi:[0,1,1] neg_lo:[0,0,1]
	v_pk_mul_f32 v[36:37], v[212:213], v[40:41] op_sel:[1,1] op_sel_hi:[1,0]
	v_pk_fma_f32 v[36:37], v[212:213], v[40:41], v[36:37] op_sel_hi:[0,1,1] neg_lo:[0,0,1]
	v_pk_mul_f32 v[40:41], v[220:221], v[204:205] op_sel:[1,1] op_sel_hi:[1,0]
	v_pk_fma_f32 v[40:41], v[220:221], v[204:205], v[40:41] op_sel_hi:[0,1,1] neg_lo:[0,0,1]
	v_cos_f32_e32 v210, 0x3e200000
	v_sin_f32_e32 v211, 0xbe200000
	s_waitcnt lgkmcnt(4)
	v_pk_add_f32 v[202:203], v[42:43], v[46:47]
	v_pk_add_f32 v[42:43], v[42:43], v[46:47] neg_lo:[0,1] neg_hi:[0,1]
	v_pk_add_f32 v[204:205], v[44:45], v[48:49]
	v_pk_add_f32 v[44:45], v[44:45], v[48:49] neg_lo:[0,1] neg_hi:[0,1]
	v_pk_add_f32 v[46:47], v[202:203], v[204:205]
	v_pk_add_f32 v[48:49], v[202:203], v[204:205] neg_lo:[0,1] neg_hi:[0,1]
	v_pk_add_f32 v[202:203], v[42:43], v[44:45] op_sel:[0,1] op_sel_hi:[1,0] neg_hi:[0,1]
	v_pk_add_f32 v[204:205], v[42:43], v[44:45] op_sel:[0,1] op_sel_hi:[1,0] neg_lo:[0,1]
	v_pk_mul_f32 v[206:207], v[210:211], v[210:211] op_sel:[1,1] op_sel_hi:[1,0]
	v_pk_fma_f32 v[212:213], v[210:211], v[210:211], v[206:207] op_sel_hi:[0,1,1] neg_lo:[0,0,1]
	v_pk_mul_f32 v[206:207], v[210:211], v[212:213] op_sel:[1,1] op_sel_hi:[1,0]
	v_pk_fma_f32 v[220:221], v[210:211], v[212:213], v[206:207] op_sel_hi:[0,1,1] neg_lo:[0,0,1]
	v_pk_mul_f32 v[42:43], v[210:211], v[202:203] op_sel:[1,1] op_sel_hi:[1,0]
	v_pk_fma_f32 v[42:43], v[210:211], v[202:203], v[42:43] op_sel_hi:[0,1,1] neg_lo:[0,0,1]
	v_pk_mul_f32 v[44:45], v[212:213], v[48:49] op_sel:[1,1] op_sel_hi:[1,0]
	v_pk_fma_f32 v[44:45], v[212:213], v[48:49], v[44:45] op_sel_hi:[0,1,1] neg_lo:[0,0,1]
	v_pk_mul_f32 v[48:49], v[220:221], v[204:205] op_sel:[1,1] op_sel_hi:[1,0]
	v_pk_fma_f32 v[48:49], v[220:221], v[204:205], v[48:49] op_sel_hi:[0,1,1] neg_lo:[0,0,1]
	v_cos_f32_e32 v210, 0x3e400000
	v_sin_f32_e32 v211, 0xbe400000
	s_waitcnt lgkmcnt(2)
	v_pk_add_f32 v[202:203], v[50:51], v[54:55]
	v_pk_add_f32 v[50:51], v[50:51], v[54:55] neg_lo:[0,1] neg_hi:[0,1]
	v_pk_add_f32 v[204:205], v[52:53], v[56:57]
	v_pk_add_f32 v[52:53], v[52:53], v[56:57] neg_lo:[0,1] neg_hi:[0,1]
	v_pk_add_f32 v[54:55], v[202:203], v[204:205]
	v_pk_add_f32 v[56:57], v[202:203], v[204:205] neg_lo:[0,1] neg_hi:[0,1]
	v_pk_add_f32 v[202:203], v[50:51], v[52:53] op_sel:[0,1] op_sel_hi:[1,0] neg_hi:[0,1]
	v_pk_add_f32 v[204:205], v[50:51], v[52:53] op_sel:[0,1] op_sel_hi:[1,0] neg_lo:[0,1]
	v_pk_mul_f32 v[206:207], v[210:211], v[210:211] op_sel:[1,1] op_sel_hi:[1,0]
	v_pk_fma_f32 v[212:213], v[210:211], v[210:211], v[206:207] op_sel_hi:[0,1,1] neg_lo:[0,0,1]
	v_pk_mul_f32 v[206:207], v[210:211], v[212:213] op_sel:[1,1] op_sel_hi:[1,0]
	v_pk_fma_f32 v[220:221], v[210:211], v[212:213], v[206:207] op_sel_hi:[0,1,1] neg_lo:[0,0,1]
	v_pk_mul_f32 v[50:51], v[210:211], v[202:203] op_sel:[1,1] op_sel_hi:[1,0]
	v_pk_fma_f32 v[50:51], v[210:211], v[202:203], v[50:51] op_sel_hi:[0,1,1] neg_lo:[0,0,1]
	v_pk_mul_f32 v[52:53], v[212:213], v[56:57] op_sel:[1,1] op_sel_hi:[1,0]
	v_pk_fma_f32 v[52:53], v[212:213], v[56:57], v[52:53] op_sel_hi:[0,1,1] neg_lo:[0,0,1]
	v_pk_mul_f32 v[56:57], v[220:221], v[204:205] op_sel:[1,1] op_sel_hi:[1,0]
	v_pk_fma_f32 v[56:57], v[220:221], v[204:205], v[56:57] op_sel_hi:[0,1,1] neg_lo:[0,0,1]
	v_cos_f32_e32 v210, 0x3e600000
	v_sin_f32_e32 v211, 0xbe600000
	s_waitcnt lgkmcnt(0)
	v_pk_add_f32 v[202:203], v[58:59], v[62:63]
	v_pk_add_f32 v[58:59], v[58:59], v[62:63] neg_lo:[0,1] neg_hi:[0,1]
	v_pk_add_f32 v[204:205], v[60:61], v[64:65]
	v_pk_add_f32 v[60:61], v[60:61], v[64:65] neg_lo:[0,1] neg_hi:[0,1]
	v_pk_add_f32 v[62:63], v[202:203], v[204:205]
	v_pk_add_f32 v[64:65], v[202:203], v[204:205] neg_lo:[0,1] neg_hi:[0,1]
	v_pk_add_f32 v[202:203], v[58:59], v[60:61] op_sel:[0,1] op_sel_hi:[1,0] neg_hi:[0,1]
	v_pk_add_f32 v[204:205], v[58:59], v[60:61] op_sel:[0,1] op_sel_hi:[1,0] neg_lo:[0,1]
	v_pk_mul_f32 v[206:207], v[210:211], v[210:211] op_sel:[1,1] op_sel_hi:[1,0]
	v_pk_fma_f32 v[212:213], v[210:211], v[210:211], v[206:207] op_sel_hi:[0,1,1] neg_lo:[0,0,1]
	v_pk_mul_f32 v[206:207], v[210:211], v[212:213] op_sel:[1,1] op_sel_hi:[1,0]
	v_pk_fma_f32 v[220:221], v[210:211], v[212:213], v[206:207] op_sel_hi:[0,1,1] neg_lo:[0,0,1]
	v_pk_mul_f32 v[58:59], v[210:211], v[202:203] op_sel:[1,1] op_sel_hi:[1,0]
	v_pk_fma_f32 v[58:59], v[210:211], v[202:203], v[58:59] op_sel_hi:[0,1,1] neg_lo:[0,0,1]
	v_pk_mul_f32 v[60:61], v[212:213], v[64:65] op_sel:[1,1] op_sel_hi:[1,0]
	v_pk_fma_f32 v[60:61], v[212:213], v[64:65], v[60:61] op_sel_hi:[0,1,1] neg_lo:[0,0,1]
	v_pk_mul_f32 v[64:65], v[220:221], v[204:205] op_sel:[1,1] op_sel_hi:[1,0]
	v_pk_fma_f32 v[64:65], v[220:221], v[204:205], v[64:65] op_sel_hi:[0,1,1] neg_lo:[0,0,1]
	s_barrier
; DI f32x2 cmul(f32x2 a, f32x2 b) { return mkf2(a.x * b.x - a.y * b.y, a.x * b.y + a.y * b.x); }
; DI void fft8192(f32x2* buf, const f32x2* __restrict__ tw) {
;     ...
; #pragma unroll
;     for (int e = 0; e < 8; ++e) {
;       const int i = tid + 256 * e;
;       const int q = i & (s - 1);
;       const int ps = i - q;
;       const float rev = (float)ps * (1.f / 8192.f);
;       const f32x2 w1 = mkf2(__builtin_amdgcn_cosf(rev), -__builtin_amdgcn_sinf(rev));
;       const f32x2 w2 = cmul(w1, w1), w3 = cmul(w1, w2);
;       const f32x2 apc = mkf2(a[e].x + c[e].x, a[e].y + c[e].y), amc = mkf2(a[e].x - c[e].x, a[e].y - c[e].y);
;       const f32x2 bpd = mkf2(b[e].x + d[e].x, b[e].y + d[e].y), bmd = mkf2(b[e].x - d[e].x, b[e].y - d[e].y);
;       const int o = 4 * i - 3 * q;
;       buf[SW(o)] = mkf2(apc.x + bpd.x, apc.y + bpd.y);
;       buf[SW(o + s)] = cmul(w1, mkf2(amc.x + bmd.y, amc.y - bmd.x));
;       buf[SW(o + 2 * s)] = cmul(w2, mkf2(apc.x - bpd.x, apc.y - bpd.y));
;       buf[SW(o + 3 * s)] = cmul(w3, mkf2(amc.x - bmd.y, amc.y + bmd.x));
;     }
	v_pk_add_f32 v[202:203], v[6:7], v[38:39]
	v_pk_add_f32 v[6:7], v[6:7], v[38:39] neg_lo:[0,1] neg_hi:[0,1]
	v_pk_add_f32 v[204:205], v[22:23], v[54:55]
	v_pk_add_f32 v[22:23], v[22:23], v[54:55] neg_lo:[0,1] neg_hi:[0,1]
	v_pk_add_f32 v[38:39], v[202:203], v[204:205]
	v_pk_add_f32 v[54:55], v[202:203], v[204:205] neg_lo:[0,1] neg_hi:[0,1]
	v_pk_add_f32 v[202:203], v[6:7], v[22:23] op_sel:[0,1] op_sel_hi:[1,0] neg_hi:[0,1]
	v_pk_add_f32 v[22:23], v[6:7], v[22:23] op_sel:[0,1] op_sel_hi:[1,0] neg_lo:[0,1]
	v_pk_mov_b32 v[6:7], v[202:203], v[202:203] op_sel:[0,1]
	v_pk_add_f32 v[202:203], v[2:3], v[34:35]
	v_pk_add_f32 v[2:3], v[2:3], v[34:35] neg_lo:[0,1] neg_hi:[0,1]
	v_pk_add_f32 v[204:205], v[18:19], v[50:51]
	v_pk_add_f32 v[18:19], v[18:19], v[50:51] neg_lo:[0,1] neg_hi:[0,1]
	v_pk_add_f32 v[34:35], v[202:203], v[204:205]
	v_pk_add_f32 v[50:51], v[202:203], v[204:205] neg_lo:[0,1] neg_hi:[0,1]
	v_pk_add_f32 v[202:203], v[2:3], v[18:19] op_sel:[0,1] op_sel_hi:[1,0] neg_hi:[0,1]
	v_pk_add_f32 v[18:19], v[2:3], v[18:19] op_sel:[0,1] op_sel_hi:[1,0] neg_lo:[0,1]
	v_pk_mov_b32 v[2:3], v[202:203], v[202:203] op_sel:[0,1]
	v_pk_add_f32 v[202:203], v[8:9], v[36:37]
	v_pk_add_f32 v[8:9], v[8:9], v[36:37] neg_lo:[0,1] neg_hi:[0,1]
	v_pk_add_f32 v[204:205], v[20:21], v[52:53]
	v_pk_add_f32 v[20:21], v[20:21], v[52:53] neg_lo:[0,1] neg_hi:[0,1]
	v_pk_add_f32 v[36:37], v[202:203], v[204:205]
	v_pk_add_f32 v[52:53], v[202:203], v[204:205] neg_lo:[0,1] neg_hi:[0,1]
	v_pk_add_f32 v[202:203], v[8:9], v[20:21] op_sel:[0,1] op_sel_hi:[1,0] neg_hi:[0,1]
	v_pk_add_f32 v[20:21], v[8:9], v[20:21] op_sel:[0,1] op_sel_hi:[1,0] neg_lo:[0,1]
	v_pk_mov_b32 v[8:9], v[202:203], v[202:203] op_sel:[0,1]
	v_pk_add_f32 v[202:203], v[4:5], v[40:41]
	v_pk_add_f32 v[4:5], v[4:5], v[40:41] neg_lo:[0,1] neg_hi:[0,1]
	v_pk_add_f32 v[204:205], v[24:25], v[56:57]
	v_pk_add_f32 v[24:25], v[24:25], v[56:57] neg_lo:[0,1] neg_hi:[0,1]
	v_pk_add_f32 v[40:41], v[202:203], v[204:205]
	v_pk_add_f32 v[56:57], v[202:203], v[204:205] neg_lo:[0,1] neg_hi:[0,1]
	v_pk_add_f32 v[202:203], v[4:5], v[24:25] op_sel:[0,1] op_sel_hi:[1,0] neg_hi:[0,1]
	v_pk_add_f32 v[24:25], v[4:5], v[24:25] op_sel:[0,1] op_sel_hi:[1,0] neg_lo:[0,1]
	v_pk_mov_b32 v[4:5], v[202:203], v[202:203] op_sel:[0,1]
	v_cos_f32_e32 v224, 0x3e000000
	v_sin_f32_e32 v225, 0xbe000000
	s_nop 0
	v_pk_mul_f32 v[206:207], v[224:225], v[224:225] op_sel:[1,1] op_sel_hi:[1,0]
	v_pk_fma_f32 v[226:227], v[224:225], v[224:225], v[206:207] op_sel_hi:[0,1,1] neg_lo:[0,0,1]
	v_pk_mul_f32 v[206:207], v[224:225], v[226:227] op_sel:[1,1] op_sel_hi:[1,0]
	v_pk_fma_f32 v[230:231], v[224:225], v[226:227], v[206:207] op_sel_hi:[0,1,1] neg_lo:[0,0,1]
	v_pk_add_f32 v[202:203], v[14:15], v[46:47]
	v_pk_add_f32 v[14:15], v[14:15], v[46:47] neg_lo:[0,1] neg_hi:[0,1]
	v_pk_add_f32 v[204:205], v[30:31], v[62:63]
	v_pk_add_f32 v[30:31], v[30:31], v[62:63] neg_lo:[0,1] neg_hi:[0,1]
	v_pk_add_f32 v[46:47], v[202:203], v[204:205]
	v_pk_add_f32 v[62:63], v[202:203], v[204:205] neg_lo:[0,1] neg_hi:[0,1]
	v_pk_add_f32 v[202:203], v[14:15], v[30:31] op_sel:[0,1] op_sel_hi:[1,0] neg_hi:[0,1]
	v_pk_add_f32 v[204:205], v[14:15], v[30:31] op_sel:[0,1] op_sel_hi:[1,0] neg_lo:[0,1]
	v_pk_mul_f32 v[14:15], v[224:225], v[202:203] op_sel:[1,1] op_sel_hi:[1,0]
	v_pk_fma_f32 v[14:15], v[224:225], v[202:203], v[14:15] op_sel_hi:[0,1,1] neg_lo:[0,0,1]
	v_pk_mul_f32 v[30:31], v[226:227], v[62:63] op_sel:[1,1] op_sel_hi:[1,0]
	v_pk_fma_f32 v[30:31], v[226:227], v[62:63], v[30:31] op_sel_hi:[0,1,1] neg_lo:[0,0,1]
	v_pk_mul_f32 v[62:63], v[230:231], v[204:205] op_sel:[1,1] op_sel_hi:[1,0]
	v_pk_fma_f32 v[62:63], v[230:231], v[204:205], v[62:63] op_sel_hi:[0,1,1] neg_lo:[0,0,1]
	v_pk_add_f32 v[202:203], v[10:11], v[42:43]
	v_pk_add_f32 v[10:11], v[10:11], v[42:43] neg_lo:[0,1] neg_hi:[0,1]
	v_pk_add_f32 v[204:205], v[26:27], v[58:59]
	v_pk_add_f32 v[26:27], v[26:27], v[58:59] neg_lo:[0,1] neg_hi:[0,1]
	v_pk_add_f32 v[42:43], v[202:203], v[204:205]
	v_pk_add_f32 v[58:59], v[202:203], v[204:205] neg_lo:[0,1] neg_hi:[0,1]
	v_pk_add_f32 v[202:203], v[10:11], v[26:27] op_sel:[0,1] op_sel_hi:[1,0] neg_hi:[0,1]
	v_pk_add_f32 v[204:205], v[10:11], v[26:27] op_sel:[0,1] op_sel_hi:[1,0] neg_lo:[0,1]
	v_pk_mul_f32 v[10:11], v[224:225], v[202:203] op_sel:[1,1] op_sel_hi:[1,0]
	v_pk_fma_f32 v[10:11], v[224:225], v[202:203], v[10:11] op_sel_hi:[0,1,1] neg_lo:[0,0,1]
	v_pk_mul_f32 v[26:27], v[226:227], v[58:59] op_sel:[1,1] op_sel_hi:[1,0]
	v_pk_fma_f32 v[26:27], v[226:227], v[58:59], v[26:27] op_sel_hi:[0,1,1] neg_lo:[0,0,1]
	v_pk_mul_f32 v[58:59], v[230:231], v[204:205] op_sel:[1,1] op_sel_hi:[1,0]
	v_pk_fma_f32 v[58:59], v[230:231], v[204:205], v[58:59] op_sel_hi:[0,1,1] neg_lo:[0,0,1]
	v_pk_add_f32 v[202:203], v[12:13], v[44:45]
	v_pk_add_f32 v[12:13], v[12:13], v[44:45] neg_lo:[0,1] neg_hi:[0,1]
	v_pk_add_f32 v[204:205], v[28:29], v[60:61]
	v_pk_add_f32 v[28:29], v[28:29], v[60:61] neg_lo:[0,1] neg_hi:[0,1]
	v_pk_add_f32 v[44:45], v[202:203], v[204:205]
	v_pk_add_f32 v[60:61], v[202:203], v[204:205] neg_lo:[0,1] neg_hi:[0,1]
	v_pk_add_f32 v[202:203], v[12:13], v[28:29] op_sel:[0,1] op_sel_hi:[1,0] neg_hi:[0,1]
	v_pk_add_f32 v[204:205], v[12:13], v[28:29] op_sel:[0,1] op_sel_hi:[1,0] neg_lo:[0,1]
	v_pk_mul_f32 v[12:13], v[224:225], v[202:203] op_sel:[1,1] op_sel_hi:[1,0]
	v_pk_fma_f32 v[12:13], v[224:225], v[202:203], v[12:13] op_sel_hi:[0,1,1] neg_lo:[0,0,1]
	v_pk_mul_f32 v[28:29], v[226:227], v[60:61] op_sel:[1,1] op_sel_hi:[1,0]
	v_pk_fma_f32 v[28:29], v[226:227], v[60:61], v[28:29] op_sel_hi:[0,1,1] neg_lo:[0,0,1]
	v_pk_mul_f32 v[60:61], v[230:231], v[204:205] op_sel:[1,1] op_sel_hi:[1,0]
; DI f32x2 cmul(f32x2 a, f32x2 b) { return mkf2(a.x * b.x - a.y * b.y, a.x * b.y + a.y * b.x); }
; DI void fft8192(f32x2* buf, const f32x2* __restrict__ tw) {
;     ...
;   {
;     f32x2 a[16], b[16];
;     __syncthreads();
; #pragma unroll
;     for (int e = 0; e < 16; ++e) { const int pi = SW(tid + 256 * e); a[e] = buf[pi]; b[e] = buf[pi + 4096]; }
;     __syncthreads();
; #pragma unroll
;     for (int e = 0; e < 16; ++e) {
;       const int pi = SW(tid + 256 * e);
;       buf[pi] = mkf2(a[e].x + b[e].x, a[e].y + b[e].y);
;       buf[pi + 4096] = mkf2(a[e].x - b[e].x, a[e].y - b[e].y);
;     }
;     __syncthreads();
;   }
; DI void hyena_unit(KP p, int l, int c, char* smem) {
;     ...
;       for (int j = 0; j < 32; ++j) {
;         const int f = tid + 256 * j;
;         f32x2 z = cmul(buf[SW(f)], KF[j]);
;         buf[SW(f)] = mkf2(z.x, -z.y);
;       }
	v_pk_fma_f32 v[60:61], v[230:231], v[204:205], v[60:61] op_sel_hi:[0,1,1] neg_lo:[0,0,1]
	v_pk_add_f32 v[202:203], v[16:17], v[48:49]
	v_pk_add_f32 v[16:17], v[16:17], v[48:49] neg_lo:[0,1] neg_hi:[0,1]
	v_pk_add_f32 v[204:205], v[32:33], v[64:65]
	v_pk_add_f32 v[32:33], v[32:33], v[64:65] neg_lo:[0,1] neg_hi:[0,1]
	v_pk_add_f32 v[48:49], v[202:203], v[204:205]
	v_pk_add_f32 v[64:65], v[202:203], v[204:205] neg_lo:[0,1] neg_hi:[0,1]
	v_pk_add_f32 v[202:203], v[16:17], v[32:33] op_sel:[0,1] op_sel_hi:[1,0] neg_hi:[0,1]
	v_pk_add_f32 v[204:205], v[16:17], v[32:33] op_sel:[0,1] op_sel_hi:[1,0] neg_lo:[0,1]
	v_pk_mul_f32 v[16:17], v[224:225], v[202:203] op_sel:[1,1] op_sel_hi:[1,0]
	v_pk_fma_f32 v[16:17], v[224:225], v[202:203], v[16:17] op_sel_hi:[0,1,1] neg_lo:[0,0,1]
	v_pk_mul_f32 v[32:33], v[226:227], v[64:65] op_sel:[1,1] op_sel_hi:[1,0]
	v_pk_fma_f32 v[32:33], v[226:227], v[64:65], v[32:33] op_sel_hi:[0,1,1] neg_lo:[0,0,1]
	v_pk_mul_f32 v[64:65], v[230:231], v[204:205] op_sel:[1,1] op_sel_hi:[1,0]
	v_pk_fma_f32 v[64:65], v[230:231], v[204:205], v[64:65] op_sel_hi:[0,1,1] neg_lo:[0,0,1]
	v_pk_add_f32 v[202:203], v[38:39], v[46:47]
	v_pk_add_f32 v[46:47], v[38:39], v[46:47] neg_lo:[0,1] neg_hi:[0,1]
	v_pk_mul_f32 v[38:39], v[78:79], v[202:203] op_sel:[1,1] op_sel_hi:[1,0]
	v_pk_fma_f32 v[202:203], v[78:79], v[202:203], v[38:39] op_sel_hi:[0,1,1] neg_lo:[0,0,1] neg_hi:[1,0,1]
	v_pk_mul_f32 v[38:39], v[110:111], v[46:47] op_sel:[1,1] op_sel_hi:[1,0]
	v_pk_fma_f32 v[46:47], v[110:111], v[46:47], v[38:39] op_sel_hi:[0,1,1] neg_lo:[0,0,1] neg_hi:[1,0,1]
	v_pk_add_f32 v[204:205], v[34:35], v[42:43]
	v_pk_add_f32 v[42:43], v[34:35], v[42:43] neg_lo:[0,1] neg_hi:[0,1]
	v_pk_mul_f32 v[34:35], v[80:81], v[204:205] op_sel:[1,1] op_sel_hi:[1,0]
	v_pk_fma_f32 v[204:205], v[80:81], v[204:205], v[34:35] op_sel_hi:[0,1,1] neg_lo:[0,0,1] neg_hi:[1,0,1]
	v_pk_mul_f32 v[34:35], v[112:113], v[42:43] op_sel:[1,1] op_sel_hi:[1,0]
	v_pk_fma_f32 v[42:43], v[112:113], v[42:43], v[34:35] op_sel_hi:[0,1,1] neg_lo:[0,0,1] neg_hi:[1,0,1]
	v_pk_add_f32 v[206:207], v[36:37], v[44:45]
	v_pk_add_f32 v[44:45], v[36:37], v[44:45] neg_lo:[0,1] neg_hi:[0,1]
	v_pk_mul_f32 v[36:37], v[82:83], v[206:207] op_sel:[1,1] op_sel_hi:[1,0]
	v_pk_fma_f32 v[206:207], v[82:83], v[206:207], v[36:37] op_sel_hi:[0,1,1] neg_lo:[0,0,1] neg_hi:[1,0,1]
	v_pk_mul_f32 v[36:37], v[114:115], v[44:45] op_sel:[1,1] op_sel_hi:[1,0]
	v_pk_fma_f32 v[44:45], v[114:115], v[44:45], v[36:37] op_sel_hi:[0,1,1] neg_lo:[0,0,1] neg_hi:[1,0,1]
	v_pk_add_f32 v[208:209], v[40:41], v[48:49]
	v_pk_add_f32 v[48:49], v[40:41], v[48:49] neg_lo:[0,1] neg_hi:[0,1]
	v_pk_mul_f32 v[40:41], v[84:85], v[208:209] op_sel:[1,1] op_sel_hi:[1,0]
	v_pk_fma_f32 v[208:209], v[84:85], v[208:209], v[40:41] op_sel_hi:[0,1,1] neg_lo:[0,0,1] neg_hi:[1,0,1]
	v_pk_mul_f32 v[40:41], v[116:117], v[48:49] op_sel:[1,1] op_sel_hi:[1,0]
	v_pk_fma_f32 v[48:49], v[116:117], v[48:49], v[40:41] op_sel_hi:[0,1,1] neg_lo:[0,0,1] neg_hi:[1,0,1]
	v_pk_add_f32 v[210:211], v[6:7], v[14:15]
	v_pk_add_f32 v[14:15], v[6:7], v[14:15] neg_lo:[0,1] neg_hi:[0,1]
	v_pk_mul_f32 v[6:7], v[86:87], v[210:211] op_sel:[1,1] op_sel_hi:[1,0]
	v_pk_fma_f32 v[210:211], v[86:87], v[210:211], v[6:7] op_sel_hi:[0,1,1] neg_lo:[0,0,1] neg_hi:[1,0,1]
	v_pk_mul_f32 v[6:7], v[118:119], v[14:15] op_sel:[1,1] op_sel_hi:[1,0]
	v_pk_fma_f32 v[14:15], v[118:119], v[14:15], v[6:7] op_sel_hi:[0,1,1] neg_lo:[0,0,1] neg_hi:[1,0,1]
	v_pk_add_f32 v[212:213], v[2:3], v[10:11]
	v_pk_add_f32 v[10:11], v[2:3], v[10:11] neg_lo:[0,1] neg_hi:[0,1]
	v_pk_mul_f32 v[2:3], v[88:89], v[212:213] op_sel:[1,1] op_sel_hi:[1,0]
	v_pk_fma_f32 v[212:213], v[88:89], v[212:213], v[2:3] op_sel_hi:[0,1,1] neg_lo:[0,0,1] neg_hi:[1,0,1]
	v_pk_mul_f32 v[2:3], v[120:121], v[10:11] op_sel:[1,1] op_sel_hi:[1,0]
	v_pk_fma_f32 v[10:11], v[120:121], v[10:11], v[2:3] op_sel_hi:[0,1,1] neg_lo:[0,0,1] neg_hi:[1,0,1]
	v_pk_add_f32 v[220:221], v[8:9], v[12:13]
	v_pk_add_f32 v[12:13], v[8:9], v[12:13] neg_lo:[0,1] neg_hi:[0,1]
	v_pk_mul_f32 v[8:9], v[90:91], v[220:221] op_sel:[1,1] op_sel_hi:[1,0]
	v_pk_fma_f32 v[220:221], v[90:91], v[220:221], v[8:9] op_sel_hi:[0,1,1] neg_lo:[0,0,1] neg_hi:[1,0,1]
	v_pk_mul_f32 v[8:9], v[122:123], v[12:13] op_sel:[1,1] op_sel_hi:[1,0]
	v_pk_fma_f32 v[12:13], v[122:123], v[12:13], v[8:9] op_sel_hi:[0,1,1] neg_lo:[0,0,1] neg_hi:[1,0,1]
	v_pk_add_f32 v[224:225], v[4:5], v[16:17]
	v_pk_add_f32 v[16:17], v[4:5], v[16:17] neg_lo:[0,1] neg_hi:[0,1]
	v_pk_mul_f32 v[4:5], v[92:93], v[224:225] op_sel:[1,1] op_sel_hi:[1,0]
	v_pk_fma_f32 v[224:225], v[92:93], v[224:225], v[4:5] op_sel_hi:[0,1,1] neg_lo:[0,0,1] neg_hi:[1,0,1]
	v_pk_mul_f32 v[4:5], v[124:125], v[16:17] op_sel:[1,1] op_sel_hi:[1,0]
	v_pk_fma_f32 v[16:17], v[124:125], v[16:17], v[4:5] op_sel_hi:[0,1,1] neg_lo:[0,0,1] neg_hi:[1,0,1]
	v_pk_add_f32 v[226:227], v[54:55], v[30:31]
	v_pk_add_f32 v[30:31], v[54:55], v[30:31] neg_lo:[0,1] neg_hi:[0,1]
	v_pk_mul_f32 v[54:55], v[94:95], v[226:227] op_sel:[1,1] op_sel_hi:[1,0]
	v_pk_fma_f32 v[226:227], v[94:95], v[226:227], v[54:55] op_sel_hi:[0,1,1] neg_lo:[0,0,1] neg_hi:[1,0,1]
	v_pk_mul_f32 v[54:55], v[126:127], v[30:31] op_sel:[1,1] op_sel_hi:[1,0]
	v_pk_fma_f32 v[30:31], v[126:127], v[30:31], v[54:55] op_sel_hi:[0,1,1] neg_lo:[0,0,1] neg_hi:[1,0,1]
	v_pk_add_f32 v[230:231], v[50:51], v[26:27]
	v_pk_add_f32 v[26:27], v[50:51], v[26:27] neg_lo:[0,1] neg_hi:[0,1]
	v_pk_mul_f32 v[50:51], v[96:97], v[230:231] op_sel:[1,1] op_sel_hi:[1,0]
	v_pk_fma_f32 v[230:231], v[96:97], v[230:231], v[50:51] op_sel_hi:[0,1,1] neg_lo:[0,0,1] neg_hi:[1,0,1]
	v_pk_mul_f32 v[50:51], v[128:129], v[26:27] op_sel:[1,1] op_sel_hi:[1,0]
; DI f32x2 cmul(f32x2 a, f32x2 b) { return mkf2(a.x * b.x - a.y * b.y, a.x * b.y + a.y * b.x); }
; DI void hyena_unit(KP p, int l, int c, char* smem) {
;     ...
;       for (int j = 0; j < 32; ++j) {
;         const int f = tid + 256 * j;
;         f32x2 z = cmul(buf[SW(f)], KF[j]);
;         buf[SW(f)] = mkf2(z.x, -z.y);
;       }
	v_pk_fma_f32 v[26:27], v[128:129], v[26:27], v[50:51] op_sel_hi:[0,1,1] neg_lo:[0,0,1] neg_hi:[1,0,1]
	v_pk_add_f32 v[232:233], v[52:53], v[28:29]
	v_pk_add_f32 v[28:29], v[52:53], v[28:29] neg_lo:[0,1] neg_hi:[0,1]
	v_pk_mul_f32 v[52:53], v[98:99], v[232:233] op_sel:[1,1] op_sel_hi:[1,0]
	v_pk_fma_f32 v[232:233], v[98:99], v[232:233], v[52:53] op_sel_hi:[0,1,1] neg_lo:[0,0,1] neg_hi:[1,0,1]
	v_pk_mul_f32 v[52:53], v[130:131], v[28:29] op_sel:[1,1] op_sel_hi:[1,0]
	v_pk_fma_f32 v[28:29], v[130:131], v[28:29], v[52:53] op_sel_hi:[0,1,1] neg_lo:[0,0,1] neg_hi:[1,0,1]
	v_pk_add_f32 v[236:237], v[56:57], v[32:33]
	v_pk_add_f32 v[32:33], v[56:57], v[32:33] neg_lo:[0,1] neg_hi:[0,1]
	v_pk_mul_f32 v[56:57], v[100:101], v[236:237] op_sel:[1,1] op_sel_hi:[1,0]
	v_pk_fma_f32 v[236:237], v[100:101], v[236:237], v[56:57] op_sel_hi:[0,1,1] neg_lo:[0,0,1] neg_hi:[1,0,1]
	v_pk_mul_f32 v[56:57], v[132:133], v[32:33] op_sel:[1,1] op_sel_hi:[1,0]
	v_pk_fma_f32 v[32:33], v[132:133], v[32:33], v[56:57] op_sel_hi:[0,1,1] neg_lo:[0,0,1] neg_hi:[1,0,1]
	v_pk_add_f32 v[238:239], v[22:23], v[62:63]
	v_pk_add_f32 v[62:63], v[22:23], v[62:63] neg_lo:[0,1] neg_hi:[0,1]
	v_pk_mul_f32 v[22:23], v[102:103], v[238:239] op_sel:[1,1] op_sel_hi:[1,0]
	v_pk_fma_f32 v[238:239], v[102:103], v[238:239], v[22:23] op_sel_hi:[0,1,1] neg_lo:[0,0,1] neg_hi:[1,0,1]
	v_pk_mul_f32 v[22:23], v[134:135], v[62:63] op_sel:[1,1] op_sel_hi:[1,0]
	v_pk_fma_f32 v[62:63], v[134:135], v[62:63], v[22:23] op_sel_hi:[0,1,1] neg_lo:[0,0,1] neg_hi:[1,0,1]
	v_pk_add_f32 v[240:241], v[18:19], v[58:59]
	v_pk_add_f32 v[58:59], v[18:19], v[58:59] neg_lo:[0,1] neg_hi:[0,1]
	v_pk_mul_f32 v[18:19], v[104:105], v[240:241] op_sel:[1,1] op_sel_hi:[1,0]
	v_pk_fma_f32 v[240:241], v[104:105], v[240:241], v[18:19] op_sel_hi:[0,1,1] neg_lo:[0,0,1] neg_hi:[1,0,1]
	v_pk_mul_f32 v[18:19], v[136:137], v[58:59] op_sel:[1,1] op_sel_hi:[1,0]
	v_pk_fma_f32 v[58:59], v[136:137], v[58:59], v[18:19] op_sel_hi:[0,1,1] neg_lo:[0,0,1] neg_hi:[1,0,1]
	v_pk_add_f32 v[244:245], v[20:21], v[60:61]
	v_pk_add_f32 v[60:61], v[20:21], v[60:61] neg_lo:[0,1] neg_hi:[0,1]
	v_pk_mul_f32 v[20:21], v[106:107], v[244:245] op_sel:[1,1] op_sel_hi:[1,0]
	v_pk_fma_f32 v[244:245], v[106:107], v[244:245], v[20:21] op_sel_hi:[0,1,1] neg_lo:[0,0,1] neg_hi:[1,0,1]
	v_pk_mul_f32 v[20:21], v[138:139], v[60:61] op_sel:[1,1] op_sel_hi:[1,0]
	v_pk_fma_f32 v[60:61], v[138:139], v[60:61], v[20:21] op_sel_hi:[0,1,1] neg_lo:[0,0,1] neg_hi:[1,0,1]
	v_pk_add_f32 v[246:247], v[24:25], v[64:65]
	v_pk_add_f32 v[64:65], v[24:25], v[64:65] neg_lo:[0,1] neg_hi:[0,1]
	v_pk_mul_f32 v[24:25], v[108:109], v[246:247] op_sel:[1,1] op_sel_hi:[1,0]
	v_pk_fma_f32 v[246:247], v[108:109], v[246:247], v[24:25] op_sel_hi:[0,1,1] neg_lo:[0,0,1] neg_hi:[1,0,1]
	v_pk_mul_f32 v[24:25], v[140:141], v[64:65] op_sel:[1,1] op_sel_hi:[1,0]
	v_pk_fma_f32 v[64:65], v[140:141], v[64:65], v[24:25] op_sel_hi:[0,1,1] neg_lo:[0,0,1] neg_hi:[1,0,1]
	ds_write2st64_b64 v154, v[202:203], v[46:47] offset0:0 offset1:64
	ds_write2st64_b64 v154, v[204:205], v[42:43] offset0:4 offset1:68
	ds_write2st64_b64 v154, v[206:207], v[44:45] offset0:8 offset1:72
	ds_write2st64_b64 v154, v[208:209], v[48:49] offset0:12 offset1:76
	ds_write2st64_b64 v154, v[210:211], v[14:15] offset0:16 offset1:80
	ds_write2st64_b64 v154, v[212:213], v[10:11] offset0:20 offset1:84
	ds_write2st64_b64 v154, v[220:221], v[12:13] offset0:24 offset1:88
	ds_write2st64_b64 v154, v[224:225], v[16:17] offset0:28 offset1:92
	ds_write2st64_b64 v154, v[226:227], v[30:31] offset0:32 offset1:96
	ds_write2st64_b64 v154, v[230:231], v[26:27] offset0:36 offset1:100
	ds_write2st64_b64 v154, v[232:233], v[28:29] offset0:40 offset1:104
	ds_write2st64_b64 v154, v[236:237], v[32:33] offset0:44 offset1:108
	ds_write2st64_b64 v154, v[238:239], v[62:63] offset0:48 offset1:112
	ds_write2st64_b64 v154, v[240:241], v[58:59] offset0:52 offset1:116
	ds_write2st64_b64 v154, v[244:245], v[60:61] offset0:56 offset1:120
	ds_write2st64_b64 v154, v[246:247], v[64:65] offset0:60 offset1:124
	v_bfe_i32 v166, v0, 5, 1
	v_bfe_i32 v168, v0, 6, 1
	v_and_b32_e32 v166, 5, v166
	v_and_b32_e32 v168, 26, v168
	v_xor_b32_e32 v166, v166, v168
	v_xor_b32_e32 v166, v166, v0
	v_lshlrev_b32_e32 v154, 3, v166
	s_waitcnt lgkmcnt(0)
	s_barrier
; DI f32x2 cmul(f32x2 a, f32x2 b) { return mkf2(a.x * b.x - a.y * b.y, a.x * b.y + a.y * b.x); }
; DI void fft8192(f32x2* buf, const f32x2* __restrict__ tw) {
;     ...
;     __syncthreads();
; #pragma unroll
;     for (int e = 0; e < 8; ++e) {
;       const int i = tid + 256 * e;
;       const int pi = SW(i);
;       a[e] = buf[pi]; b[e] = buf[pi + 2048]; c[e] = buf[pi + 4096]; d[e] = buf[pi + 6144];
;     }
;     __syncthreads();
; #pragma unroll
;     for (int e = 0; e < 8; ++e) {
;       const int i = tid + 256 * e;
;       const int q = i & (s - 1);
;       const int ps = i - q;
;       const float rev = (float)ps * (1.f / 8192.f);
;       const f32x2 w1 = mkf2(__builtin_amdgcn_cosf(rev), -__builtin_amdgcn_sinf(rev));
;       const f32x2 w2 = cmul(w1, w1), w3 = cmul(w1, w2);
;       const f32x2 apc = mkf2(a[e].x + c[e].x, a[e].y + c[e].y), amc = mkf2(a[e].x - c[e].x, a[e].y - c[e].y);
;       const f32x2 bpd = mkf2(b[e].x + d[e].x, b[e].y + d[e].y), bmd = mkf2(b[e].x - d[e].x, b[e].y - d[e].y);
;       const int o = 4 * i - 3 * q;
;       buf[SW(o)] = mkf2(apc.x + bpd.x, apc.y + bpd.y);
;       buf[SW(o + s)] = cmul(w1, mkf2(amc.x + bmd.y, amc.y - bmd.x));
;       buf[SW(o + 2 * s)] = cmul(w2, mkf2(apc.x - bpd.x, apc.y - bpd.y));
;       buf[SW(o + 3 * s)] = cmul(w3, mkf2(amc.x - bmd.y, amc.y + bmd.x));
;     }
	ds_read2st64_b64 v[2:5], v154 offset0:0 offset1:32
	ds_read2st64_b64 v[6:9], v154 offset0:64 offset1:96
	ds_read2st64_b64 v[10:13], v154 offset0:4 offset1:36
	ds_read2st64_b64 v[14:17], v154 offset0:68 offset1:100
	ds_read2st64_b64 v[18:21], v154 offset0:8 offset1:40
	ds_read2st64_b64 v[22:25], v154 offset0:72 offset1:104
	ds_read2st64_b64 v[26:29], v154 offset0:12 offset1:44
	ds_read2st64_b64 v[30:33], v154 offset0:76 offset1:108
	ds_read2st64_b64 v[34:37], v154 offset0:16 offset1:48
	ds_read2st64_b64 v[38:41], v154 offset0:80 offset1:112
	ds_read2st64_b64 v[42:45], v154 offset0:20 offset1:52
	ds_read2st64_b64 v[46:49], v154 offset0:84 offset1:116
	ds_read2st64_b64 v[50:53], v154 offset0:24 offset1:56
	ds_read2st64_b64 v[54:57], v154 offset0:88 offset1:120
	ds_read2st64_b64 v[58:61], v154 offset0:28 offset1:60
	ds_read2st64_b64 v[62:65], v154 offset0:92 offset1:124
	v_cvt_f32_u32_e32 v201, v0
	v_and_b32_e32 v166, 15, v0
	v_lshlrev_b32_e32 v166, 3, v166
	v_lshl_add_u32 v164, v0, 7, v166
	v_mul_f32_e32 v201, 0x39000000, v201
	v_cos_f32_e32 v210, v201
	v_sin_f32_e64 v211, -v201
	s_waitcnt lgkmcnt(14)
	v_pk_add_f32 v[202:203], v[2:3], v[6:7]
	v_pk_add_f32 v[2:3], v[2:3], v[6:7] neg_lo:[0,1] neg_hi:[0,1]
	v_pk_add_f32 v[204:205], v[4:5], v[8:9]
	v_pk_add_f32 v[4:5], v[4:5], v[8:9] neg_lo:[0,1] neg_hi:[0,1]
	v_pk_add_f32 v[6:7], v[202:203], v[204:205]
	v_pk_add_f32 v[8:9], v[202:203], v[204:205] neg_lo:[0,1] neg_hi:[0,1]
	v_pk_add_f32 v[202:203], v[2:3], v[4:5] op_sel:[0,1] op_sel_hi:[1,0] neg_hi:[0,1]
	v_pk_add_f32 v[204:205], v[2:3], v[4:5] op_sel:[0,1] op_sel_hi:[1,0] neg_lo:[0,1]
	v_pk_mul_f32 v[206:207], v[210:211], v[210:211] op_sel:[1,1] op_sel_hi:[1,0]
	v_pk_fma_f32 v[212:213], v[210:211], v[210:211], v[206:207] op_sel_hi:[0,1,1] neg_lo:[0,0,1]
	v_pk_mul_f32 v[206:207], v[210:211], v[212:213] op_sel:[1,1] op_sel_hi:[1,0]
	v_pk_fma_f32 v[220:221], v[210:211], v[212:213], v[206:207] op_sel_hi:[0,1,1] neg_lo:[0,0,1]
	v_pk_mul_f32 v[2:3], v[210:211], v[202:203] op_sel:[1,1] op_sel_hi:[1,0]
	v_pk_fma_f32 v[2:3], v[210:211], v[202:203], v[2:3] op_sel_hi:[0,1,1] neg_lo:[0,0,1]
	v_pk_mul_f32 v[4:5], v[212:213], v[8:9] op_sel:[1,1] op_sel_hi:[1,0]
	v_pk_fma_f32 v[4:5], v[212:213], v[8:9], v[4:5] op_sel_hi:[0,1,1] neg_lo:[0,0,1]
	v_pk_mul_f32 v[8:9], v[220:221], v[204:205] op_sel:[1,1] op_sel_hi:[1,0]
	v_pk_fma_f32 v[8:9], v[220:221], v[204:205], v[8:9] op_sel_hi:[0,1,1] neg_lo:[0,0,1]
	v_add_f32_e32 v214, 0x3d000000, v201
	v_cos_f32_e32 v210, v214
	v_sin_f32_e64 v211, -v214
	s_waitcnt lgkmcnt(12)
	v_pk_add_f32 v[202:203], v[10:11], v[14:15]
	v_pk_add_f32 v[10:11], v[10:11], v[14:15] neg_lo:[0,1] neg_hi:[0,1]
	v_pk_add_f32 v[204:205], v[12:13], v[16:17]
	v_pk_add_f32 v[12:13], v[12:13], v[16:17] neg_lo:[0,1] neg_hi:[0,1]
	v_pk_add_f32 v[14:15], v[202:203], v[204:205]
	v_pk_add_f32 v[16:17], v[202:203], v[204:205] neg_lo:[0,1] neg_hi:[0,1]
	v_pk_add_f32 v[202:203], v[10:11], v[12:13] op_sel:[0,1] op_sel_hi:[1,0] neg_hi:[0,1]
	v_pk_add_f32 v[204:205], v[10:11], v[12:13] op_sel:[0,1] op_sel_hi:[1,0] neg_lo:[0,1]
	v_pk_mul_f32 v[206:207], v[210:211], v[210:211] op_sel:[1,1] op_sel_hi:[1,0]
	v_pk_fma_f32 v[212:213], v[210:211], v[210:211], v[206:207] op_sel_hi:[0,1,1] neg_lo:[0,0,1]
	v_pk_mul_f32 v[206:207], v[210:211], v[212:213] op_sel:[1,1] op_sel_hi:[1,0]
	v_pk_fma_f32 v[220:221], v[210:211], v[212:213], v[206:207] op_sel_hi:[0,1,1] neg_lo:[0,0,1]
	v_pk_mul_f32 v[10:11], v[210:211], v[202:203] op_sel:[1,1] op_sel_hi:[1,0]
	v_pk_fma_f32 v[10:11], v[210:211], v[202:203], v[10:11] op_sel_hi:[0,1,1] neg_lo:[0,0,1]
	v_pk_mul_f32 v[12:13], v[212:213], v[16:17] op_sel:[1,1] op_sel_hi:[1,0]
	v_pk_fma_f32 v[12:13], v[212:213], v[16:17], v[12:13] op_sel_hi:[0,1,1] neg_lo:[0,0,1]
	v_pk_mul_f32 v[16:17], v[220:221], v[204:205] op_sel:[1,1] op_sel_hi:[1,0]
	v_pk_fma_f32 v[16:17], v[220:221], v[204:205], v[16:17] op_sel_hi:[0,1,1] neg_lo:[0,0,1]
	v_add_f32_e32 v214, 0x3d800000, v201
	v_cos_f32_e32 v210, v214
	v_sin_f32_e64 v211, -v214
	s_waitcnt lgkmcnt(10)
	v_pk_add_f32 v[202:203], v[18:19], v[22:23]
	v_pk_add_f32 v[18:19], v[18:19], v[22:23] neg_lo:[0,1] neg_hi:[0,1]
	v_pk_add_f32 v[204:205], v[20:21], v[24:25]
	v_pk_add_f32 v[20:21], v[20:21], v[24:25] neg_lo:[0,1] neg_hi:[0,1]
	v_pk_add_f32 v[22:23], v[202:203], v[204:205]
	v_pk_add_f32 v[24:25], v[202:203], v[204:205] neg_lo:[0,1] neg_hi:[0,1]
	v_pk_add_f32 v[202:203], v[18:19], v[20:21] op_sel:[0,1] op_sel_hi:[1,0] neg_hi:[0,1]
	v_pk_add_f32 v[204:205], v[18:19], v[20:21] op_sel:[0,1] op_sel_hi:[1,0] neg_lo:[0,1]
	v_pk_mul_f32 v[206:207], v[210:211], v[210:211] op_sel:[1,1] op_sel_hi:[1,0]
	v_pk_fma_f32 v[212:213], v[210:211], v[210:211], v[206:207] op_sel_hi:[0,1,1] neg_lo:[0,0,1]
	v_pk_mul_f32 v[206:207], v[210:211], v[212:213] op_sel:[1,1] op_sel_hi:[1,0]
	v_pk_fma_f32 v[220:221], v[210:211], v[212:213], v[206:207] op_sel_hi:[0,1,1] neg_lo:[0,0,1]
	v_pk_mul_f32 v[18:19], v[210:211], v[202:203] op_sel:[1,1] op_sel_hi:[1,0]
	v_pk_fma_f32 v[18:19], v[210:211], v[202:203], v[18:19] op_sel_hi:[0,1,1] neg_lo:[0,0,1]
	v_pk_mul_f32 v[20:21], v[212:213], v[24:25] op_sel:[1,1] op_sel_hi:[1,0]
	v_pk_fma_f32 v[20:21], v[212:213], v[24:25], v[20:21] op_sel_hi:[0,1,1] neg_lo:[0,0,1]
	v_pk_mul_f32 v[24:25], v[220:221], v[204:205] op_sel:[1,1] op_sel_hi:[1,0]
	v_pk_fma_f32 v[24:25], v[220:221], v[204:205], v[24:25] op_sel_hi:[0,1,1] neg_lo:[0,0,1]
	v_add_f32_e32 v214, 0x3dc00000, v201
	v_cos_f32_e32 v210, v214
	v_sin_f32_e64 v211, -v214
	s_waitcnt lgkmcnt(8)
; DI f32x2 cmul(f32x2 a, f32x2 b) { return mkf2(a.x * b.x - a.y * b.y, a.x * b.y + a.y * b.x); }
; DI void fft8192(f32x2* buf, const f32x2* __restrict__ tw) {
;     ...
; #pragma unroll
;     for (int e = 0; e < 8; ++e) {
;       const int i = tid + 256 * e;
;       const int q = i & (s - 1);
;       const int ps = i - q;
;       const float rev = (float)ps * (1.f / 8192.f);
;       const f32x2 w1 = mkf2(__builtin_amdgcn_cosf(rev), -__builtin_amdgcn_sinf(rev));
;       const f32x2 w2 = cmul(w1, w1), w3 = cmul(w1, w2);
;       const f32x2 apc = mkf2(a[e].x + c[e].x, a[e].y + c[e].y), amc = mkf2(a[e].x - c[e].x, a[e].y - c[e].y);
;       const f32x2 bpd = mkf2(b[e].x + d[e].x, b[e].y + d[e].y), bmd = mkf2(b[e].x - d[e].x, b[e].y - d[e].y);
;       const int o = 4 * i - 3 * q;
;       buf[SW(o)] = mkf2(apc.x + bpd.x, apc.y + bpd.y);
;       buf[SW(o + s)] = cmul(w1, mkf2(amc.x + bmd.y, amc.y - bmd.x));
;       buf[SW(o + 2 * s)] = cmul(w2, mkf2(apc.x - bpd.x, apc.y - bpd.y));
;       buf[SW(o + 3 * s)] = cmul(w3, mkf2(amc.x - bmd.y, amc.y + bmd.x));
;     }
	v_pk_add_f32 v[202:203], v[26:27], v[30:31]
	v_pk_add_f32 v[26:27], v[26:27], v[30:31] neg_lo:[0,1] neg_hi:[0,1]
	v_pk_add_f32 v[204:205], v[28:29], v[32:33]
	v_pk_add_f32 v[28:29], v[28:29], v[32:33] neg_lo:[0,1] neg_hi:[0,1]
	v_pk_add_f32 v[30:31], v[202:203], v[204:205]
	v_pk_add_f32 v[32:33], v[202:203], v[204:205] neg_lo:[0,1] neg_hi:[0,1]
	v_pk_add_f32 v[202:203], v[26:27], v[28:29] op_sel:[0,1] op_sel_hi:[1,0] neg_hi:[0,1]
	v_pk_add_f32 v[204:205], v[26:27], v[28:29] op_sel:[0,1] op_sel_hi:[1,0] neg_lo:[0,1]
	v_pk_mul_f32 v[206:207], v[210:211], v[210:211] op_sel:[1,1] op_sel_hi:[1,0]
	v_pk_fma_f32 v[212:213], v[210:211], v[210:211], v[206:207] op_sel_hi:[0,1,1] neg_lo:[0,0,1]
	v_pk_mul_f32 v[206:207], v[210:211], v[212:213] op_sel:[1,1] op_sel_hi:[1,0]
	v_pk_fma_f32 v[220:221], v[210:211], v[212:213], v[206:207] op_sel_hi:[0,1,1] neg_lo:[0,0,1]
	v_pk_mul_f32 v[26:27], v[210:211], v[202:203] op_sel:[1,1] op_sel_hi:[1,0]
	v_pk_fma_f32 v[26:27], v[210:211], v[202:203], v[26:27] op_sel_hi:[0,1,1] neg_lo:[0,0,1]
	v_pk_mul_f32 v[28:29], v[212:213], v[32:33] op_sel:[1,1] op_sel_hi:[1,0]
	v_pk_fma_f32 v[28:29], v[212:213], v[32:33], v[28:29] op_sel_hi:[0,1,1] neg_lo:[0,0,1]
	v_pk_mul_f32 v[32:33], v[220:221], v[204:205] op_sel:[1,1] op_sel_hi:[1,0]
	v_pk_fma_f32 v[32:33], v[220:221], v[204:205], v[32:33] op_sel_hi:[0,1,1] neg_lo:[0,0,1]
	v_add_f32_e32 v214, 0x3e000000, v201
	v_cos_f32_e32 v210, v214
	v_sin_f32_e64 v211, -v214
	s_waitcnt lgkmcnt(6)
	v_pk_add_f32 v[202:203], v[34:35], v[38:39]
	v_pk_add_f32 v[34:35], v[34:35], v[38:39] neg_lo:[0,1] neg_hi:[0,1]
	v_pk_add_f32 v[204:205], v[36:37], v[40:41]
	v_pk_add_f32 v[36:37], v[36:37], v[40:41] neg_lo:[0,1] neg_hi:[0,1]
	v_pk_add_f32 v[38:39], v[202:203], v[204:205]
	v_pk_add_f32 v[40:41], v[202:203], v[204:205] neg_lo:[0,1] neg_hi:[0,1]
	v_pk_add_f32 v[202:203], v[34:35], v[36:37] op_sel:[0,1] op_sel_hi:[1,0] neg_hi:[0,1]
	v_pk_add_f32 v[204:205], v[34:35], v[36:37] op_sel:[0,1] op_sel_hi:[1,0] neg_lo:[0,1]
	v_pk_mul_f32 v[206:207], v[210:211], v[210:211] op_sel:[1,1] op_sel_hi:[1,0]
	v_pk_fma_f32 v[212:213], v[210:211], v[210:211], v[206:207] op_sel_hi:[0,1,1] neg_lo:[0,0,1]
	v_pk_mul_f32 v[206:207], v[210:211], v[212:213] op_sel:[1,1] op_sel_hi:[1,0]
	v_pk_fma_f32 v[220:221], v[210:211], v[212:213], v[206:207] op_sel_hi:[0,1,1] neg_lo:[0,0,1]
	v_pk_mul_f32 v[34:35], v[210:211], v[202:203] op_sel:[1,1] op_sel_hi:[1,0]
	v_pk_fma_f32 v[34:35], v[210:211], v[202:203], v[34:35] op_sel_hi:[0,1,1] neg_lo:[0,0,1]
	v_pk_mul_f32 v[36:37], v[212:213], v[40:41] op_sel:[1,1] op_sel_hi:[1,0]
	v_pk_fma_f32 v[36:37], v[212:213], v[40:41], v[36:37] op_sel_hi:[0,1,1] neg_lo:[0,0,1]
	v_pk_mul_f32 v[40:41], v[220:221], v[204:205] op_sel:[1,1] op_sel_hi:[1,0]
	v_pk_fma_f32 v[40:41], v[220:221], v[204:205], v[40:41] op_sel_hi:[0,1,1] neg_lo:[0,0,1]
	v_add_f32_e32 v214, 0x3e200000, v201
	v_cos_f32_e32 v210, v214
	v_sin_f32_e64 v211, -v214
	s_waitcnt lgkmcnt(4)
	v_pk_add_f32 v[202:203], v[42:43], v[46:47]
	v_pk_add_f32 v[42:43], v[42:43], v[46:47] neg_lo:[0,1] neg_hi:[0,1]
	v_pk_add_f32 v[204:205], v[44:45], v[48:49]
	v_pk_add_f32 v[44:45], v[44:45], v[48:49] neg_lo:[0,1] neg_hi:[0,1]
	v_pk_add_f32 v[46:47], v[202:203], v[204:205]
	v_pk_add_f32 v[48:49], v[202:203], v[204:205] neg_lo:[0,1] neg_hi:[0,1]
	v_pk_add_f32 v[202:203], v[42:43], v[44:45] op_sel:[0,1] op_sel_hi:[1,0] neg_hi:[0,1]
	v_pk_add_f32 v[204:205], v[42:43], v[44:45] op_sel:[0,1] op_sel_hi:[1,0] neg_lo:[0,1]
	v_pk_mul_f32 v[206:207], v[210:211], v[210:211] op_sel:[1,1] op_sel_hi:[1,0]
	v_pk_fma_f32 v[212:213], v[210:211], v[210:211], v[206:207] op_sel_hi:[0,1,1] neg_lo:[0,0,1]
	v_pk_mul_f32 v[206:207], v[210:211], v[212:213] op_sel:[1,1] op_sel_hi:[1,0]
	v_pk_fma_f32 v[220:221], v[210:211], v[212:213], v[206:207] op_sel_hi:[0,1,1] neg_lo:[0,0,1]
	v_pk_mul_f32 v[42:43], v[210:211], v[202:203] op_sel:[1,1] op_sel_hi:[1,0]
	v_pk_fma_f32 v[42:43], v[210:211], v[202:203], v[42:43] op_sel_hi:[0,1,1] neg_lo:[0,0,1]
	v_pk_mul_f32 v[44:45], v[212:213], v[48:49] op_sel:[1,1] op_sel_hi:[1,0]
	v_pk_fma_f32 v[44:45], v[212:213], v[48:49], v[44:45] op_sel_hi:[0,1,1] neg_lo:[0,0,1]
	v_pk_mul_f32 v[48:49], v[220:221], v[204:205] op_sel:[1,1] op_sel_hi:[1,0]
	v_pk_fma_f32 v[48:49], v[220:221], v[204:205], v[48:49] op_sel_hi:[0,1,1] neg_lo:[0,0,1]
	v_add_f32_e32 v214, 0x3e400000, v201
	v_cos_f32_e32 v210, v214
	v_sin_f32_e64 v211, -v214
	s_waitcnt lgkmcnt(2)
	v_pk_add_f32 v[202:203], v[50:51], v[54:55]
	v_pk_add_f32 v[50:51], v[50:51], v[54:55] neg_lo:[0,1] neg_hi:[0,1]
	v_pk_add_f32 v[204:205], v[52:53], v[56:57]
	v_pk_add_f32 v[52:53], v[52:53], v[56:57] neg_lo:[0,1] neg_hi:[0,1]
	v_pk_add_f32 v[54:55], v[202:203], v[204:205]
	v_pk_add_f32 v[56:57], v[202:203], v[204:205] neg_lo:[0,1] neg_hi:[0,1]
	v_pk_add_f32 v[202:203], v[50:51], v[52:53] op_sel:[0,1] op_sel_hi:[1,0] neg_hi:[0,1]
	v_pk_add_f32 v[204:205], v[50:51], v[52:53] op_sel:[0,1] op_sel_hi:[1,0] neg_lo:[0,1]
	v_pk_mul_f32 v[206:207], v[210:211], v[210:211] op_sel:[1,1] op_sel_hi:[1,0]
	v_pk_fma_f32 v[212:213], v[210:211], v[210:211], v[206:207] op_sel_hi:[0,1,1] neg_lo:[0,0,1]
	v_pk_mul_f32 v[206:207], v[210:211], v[212:213] op_sel:[1,1] op_sel_hi:[1,0]
	v_pk_fma_f32 v[220:221], v[210:211], v[212:213], v[206:207] op_sel_hi:[0,1,1] neg_lo:[0,0,1]
	v_pk_mul_f32 v[50:51], v[210:211], v[202:203] op_sel:[1,1] op_sel_hi:[1,0]
	v_pk_fma_f32 v[50:51], v[210:211], v[202:203], v[50:51] op_sel_hi:[0,1,1] neg_lo:[0,0,1]
	v_pk_mul_f32 v[52:53], v[212:213], v[56:57] op_sel:[1,1] op_sel_hi:[1,0]
	v_pk_fma_f32 v[52:53], v[212:213], v[56:57], v[52:53] op_sel_hi:[0,1,1] neg_lo:[0,0,1]
	v_pk_mul_f32 v[56:57], v[220:221], v[204:205] op_sel:[1,1] op_sel_hi:[1,0]
	v_pk_fma_f32 v[56:57], v[220:221], v[204:205], v[56:57] op_sel_hi:[0,1,1] neg_lo:[0,0,1]
	v_add_f32_e32 v214, 0x3e600000, v201
	v_cos_f32_e32 v210, v214
	v_sin_f32_e64 v211, -v214
	s_waitcnt lgkmcnt(0)
; DI f32x2 cmul(f32x2 a, f32x2 b) { return mkf2(a.x * b.x - a.y * b.y, a.x * b.y + a.y * b.x); }
; DI void fft8192(f32x2* buf, const f32x2* __restrict__ tw) {
;     ...
; #pragma unroll
;     for (int e = 0; e < 8; ++e) {
;       const int i = tid + 256 * e;
;       const int q = i & (s - 1);
;       const int ps = i - q;
;       const float rev = (float)ps * (1.f / 8192.f);
;       const f32x2 w1 = mkf2(__builtin_amdgcn_cosf(rev), -__builtin_amdgcn_sinf(rev));
;       const f32x2 w2 = cmul(w1, w1), w3 = cmul(w1, w2);
;       const f32x2 apc = mkf2(a[e].x + c[e].x, a[e].y + c[e].y), amc = mkf2(a[e].x - c[e].x, a[e].y - c[e].y);
;       const f32x2 bpd = mkf2(b[e].x + d[e].x, b[e].y + d[e].y), bmd = mkf2(b[e].x - d[e].x, b[e].y - d[e].y);
;       const int o = 4 * i - 3 * q;
;       buf[SW(o)] = mkf2(apc.x + bpd.x, apc.y + bpd.y);
;       buf[SW(o + s)] = cmul(w1, mkf2(amc.x + bmd.y, amc.y - bmd.x));
;       buf[SW(o + 2 * s)] = cmul(w2, mkf2(apc.x - bpd.x, apc.y - bpd.y));
;       buf[SW(o + 3 * s)] = cmul(w3, mkf2(amc.x - bmd.y, amc.y + bmd.x));
;     }
	v_pk_add_f32 v[202:203], v[58:59], v[62:63]
	v_pk_add_f32 v[58:59], v[58:59], v[62:63] neg_lo:[0,1] neg_hi:[0,1]
	v_pk_add_f32 v[204:205], v[60:61], v[64:65]
	v_pk_add_f32 v[60:61], v[60:61], v[64:65] neg_lo:[0,1] neg_hi:[0,1]
	v_pk_add_f32 v[62:63], v[202:203], v[204:205]
	v_pk_add_f32 v[64:65], v[202:203], v[204:205] neg_lo:[0,1] neg_hi:[0,1]
	v_pk_add_f32 v[202:203], v[58:59], v[60:61] op_sel:[0,1] op_sel_hi:[1,0] neg_hi:[0,1]
	v_pk_add_f32 v[204:205], v[58:59], v[60:61] op_sel:[0,1] op_sel_hi:[1,0] neg_lo:[0,1]
	v_pk_mul_f32 v[206:207], v[210:211], v[210:211] op_sel:[1,1] op_sel_hi:[1,0]
	v_pk_fma_f32 v[212:213], v[210:211], v[210:211], v[206:207] op_sel_hi:[0,1,1] neg_lo:[0,0,1]
	v_pk_mul_f32 v[206:207], v[210:211], v[212:213] op_sel:[1,1] op_sel_hi:[1,0]
	v_pk_fma_f32 v[220:221], v[210:211], v[212:213], v[206:207] op_sel_hi:[0,1,1] neg_lo:[0,0,1]
	v_pk_mul_f32 v[58:59], v[210:211], v[202:203] op_sel:[1,1] op_sel_hi:[1,0]
	v_pk_fma_f32 v[58:59], v[210:211], v[202:203], v[58:59] op_sel_hi:[0,1,1] neg_lo:[0,0,1]
	v_pk_mul_f32 v[60:61], v[212:213], v[64:65] op_sel:[1,1] op_sel_hi:[1,0]
	v_pk_fma_f32 v[60:61], v[212:213], v[64:65], v[60:61] op_sel_hi:[0,1,1] neg_lo:[0,0,1]
	v_pk_mul_f32 v[64:65], v[220:221], v[204:205] op_sel:[1,1] op_sel_hi:[1,0]
	v_pk_fma_f32 v[64:65], v[220:221], v[204:205], v[64:65] op_sel_hi:[0,1,1] neg_lo:[0,0,1]
	s_barrier
	v_mul_f32_e32 v214, 4.0, v201
	v_cos_f32_e32 v224, v214
	v_sin_f32_e64 v225, -v214
	s_nop 0
	v_pk_mul_f32 v[206:207], v[224:225], v[224:225] op_sel:[1,1] op_sel_hi:[1,0]
	v_pk_fma_f32 v[226:227], v[224:225], v[224:225], v[206:207] op_sel_hi:[0,1,1] neg_lo:[0,0,1]
	v_pk_mul_f32 v[206:207], v[224:225], v[226:227] op_sel:[1,1] op_sel_hi:[1,0]
	v_pk_fma_f32 v[230:231], v[224:225], v[226:227], v[206:207] op_sel_hi:[0,1,1] neg_lo:[0,0,1]
	v_pk_add_f32 v[202:203], v[6:7], v[38:39]
	v_pk_add_f32 v[6:7], v[6:7], v[38:39] neg_lo:[0,1] neg_hi:[0,1]
	v_pk_add_f32 v[204:205], v[22:23], v[54:55]
	v_pk_add_f32 v[22:23], v[22:23], v[54:55] neg_lo:[0,1] neg_hi:[0,1]
	v_pk_add_f32 v[38:39], v[202:203], v[204:205]
	v_pk_add_f32 v[54:55], v[202:203], v[204:205] neg_lo:[0,1] neg_hi:[0,1]
	v_pk_add_f32 v[202:203], v[6:7], v[22:23] op_sel:[0,1] op_sel_hi:[1,0] neg_hi:[0,1]
	v_pk_add_f32 v[204:205], v[6:7], v[22:23] op_sel:[0,1] op_sel_hi:[1,0] neg_lo:[0,1]
	v_pk_mul_f32 v[6:7], v[224:225], v[202:203] op_sel:[1,1] op_sel_hi:[1,0]
	v_pk_fma_f32 v[6:7], v[224:225], v[202:203], v[6:7] op_sel_hi:[0,1,1] neg_lo:[0,0,1]
	v_pk_mul_f32 v[22:23], v[226:227], v[54:55] op_sel:[1,1] op_sel_hi:[1,0]
	v_pk_fma_f32 v[22:23], v[226:227], v[54:55], v[22:23] op_sel_hi:[0,1,1] neg_lo:[0,0,1]
	v_pk_mul_f32 v[54:55], v[230:231], v[204:205] op_sel:[1,1] op_sel_hi:[1,0]
	v_pk_fma_f32 v[54:55], v[230:231], v[204:205], v[54:55] op_sel_hi:[0,1,1] neg_lo:[0,0,1]
	v_pk_add_f32 v[202:203], v[2:3], v[34:35]
	v_pk_add_f32 v[2:3], v[2:3], v[34:35] neg_lo:[0,1] neg_hi:[0,1]
	v_pk_add_f32 v[204:205], v[18:19], v[50:51]
	v_pk_add_f32 v[18:19], v[18:19], v[50:51] neg_lo:[0,1] neg_hi:[0,1]
	v_pk_add_f32 v[34:35], v[202:203], v[204:205]
	v_pk_add_f32 v[50:51], v[202:203], v[204:205] neg_lo:[0,1] neg_hi:[0,1]
	v_pk_add_f32 v[202:203], v[2:3], v[18:19] op_sel:[0,1] op_sel_hi:[1,0] neg_hi:[0,1]
	v_pk_add_f32 v[204:205], v[2:3], v[18:19] op_sel:[0,1] op_sel_hi:[1,0] neg_lo:[0,1]
	v_pk_mul_f32 v[2:3], v[224:225], v[202:203] op_sel:[1,1] op_sel_hi:[1,0]
	v_pk_fma_f32 v[2:3], v[224:225], v[202:203], v[2:3] op_sel_hi:[0,1,1] neg_lo:[0,0,1]
	v_pk_mul_f32 v[18:19], v[226:227], v[50:51] op_sel:[1,1] op_sel_hi:[1,0]
	v_pk_fma_f32 v[18:19], v[226:227], v[50:51], v[18:19] op_sel_hi:[0,1,1] neg_lo:[0,0,1]
	v_pk_mul_f32 v[50:51], v[230:231], v[204:205] op_sel:[1,1] op_sel_hi:[1,0]
	v_pk_fma_f32 v[50:51], v[230:231], v[204:205], v[50:51] op_sel_hi:[0,1,1] neg_lo:[0,0,1]
	v_pk_add_f32 v[202:203], v[4:5], v[36:37]
	v_pk_add_f32 v[4:5], v[4:5], v[36:37] neg_lo:[0,1] neg_hi:[0,1]
	v_pk_add_f32 v[204:205], v[20:21], v[52:53]
	v_pk_add_f32 v[20:21], v[20:21], v[52:53] neg_lo:[0,1] neg_hi:[0,1]
	v_pk_add_f32 v[36:37], v[202:203], v[204:205]
	v_pk_add_f32 v[52:53], v[202:203], v[204:205] neg_lo:[0,1] neg_hi:[0,1]
	v_pk_add_f32 v[202:203], v[4:5], v[20:21] op_sel:[0,1] op_sel_hi:[1,0] neg_hi:[0,1]
	v_pk_add_f32 v[204:205], v[4:5], v[20:21] op_sel:[0,1] op_sel_hi:[1,0] neg_lo:[0,1]
	v_pk_mul_f32 v[4:5], v[224:225], v[202:203] op_sel:[1,1] op_sel_hi:[1,0]
	v_pk_fma_f32 v[4:5], v[224:225], v[202:203], v[4:5] op_sel_hi:[0,1,1] neg_lo:[0,0,1]
	v_pk_mul_f32 v[20:21], v[226:227], v[52:53] op_sel:[1,1] op_sel_hi:[1,0]
	v_pk_fma_f32 v[20:21], v[226:227], v[52:53], v[20:21] op_sel_hi:[0,1,1] neg_lo:[0,0,1]
	v_pk_mul_f32 v[52:53], v[230:231], v[204:205] op_sel:[1,1] op_sel_hi:[1,0]
	v_pk_fma_f32 v[52:53], v[230:231], v[204:205], v[52:53] op_sel_hi:[0,1,1] neg_lo:[0,0,1]
	v_pk_add_f32 v[202:203], v[8:9], v[40:41]
	v_pk_add_f32 v[8:9], v[8:9], v[40:41] neg_lo:[0,1] neg_hi:[0,1]
	v_pk_add_f32 v[204:205], v[24:25], v[56:57]
	v_pk_add_f32 v[24:25], v[24:25], v[56:57] neg_lo:[0,1] neg_hi:[0,1]
	v_pk_add_f32 v[40:41], v[202:203], v[204:205]
	v_pk_add_f32 v[56:57], v[202:203], v[204:205] neg_lo:[0,1] neg_hi:[0,1]
	v_pk_add_f32 v[202:203], v[8:9], v[24:25] op_sel:[0,1] op_sel_hi:[1,0] neg_hi:[0,1]
	v_pk_add_f32 v[204:205], v[8:9], v[24:25] op_sel:[0,1] op_sel_hi:[1,0] neg_lo:[0,1]
	v_pk_mul_f32 v[8:9], v[224:225], v[202:203] op_sel:[1,1] op_sel_hi:[1,0]
	v_pk_fma_f32 v[8:9], v[224:225], v[202:203], v[8:9] op_sel_hi:[0,1,1] neg_lo:[0,0,1]
	v_pk_mul_f32 v[24:25], v[226:227], v[56:57] op_sel:[1,1] op_sel_hi:[1,0]
	v_pk_fma_f32 v[24:25], v[226:227], v[56:57], v[24:25] op_sel_hi:[0,1,1] neg_lo:[0,0,1]
; DI f32x2 cmul(f32x2 a, f32x2 b) { return mkf2(a.x * b.x - a.y * b.y, a.x * b.y + a.y * b.x); }
; DI void fft8192(f32x2* buf, const f32x2* __restrict__ tw) {
;     ...
; #pragma unroll
;     for (int e = 0; e < 8; ++e) {
;       const int i = tid + 256 * e;
;       const int q = i & (s - 1);
;       const int ps = i - q;
;       const float rev = (float)ps * (1.f / 8192.f);
;       const f32x2 w1 = mkf2(__builtin_amdgcn_cosf(rev), -__builtin_amdgcn_sinf(rev));
;       const f32x2 w2 = cmul(w1, w1), w3 = cmul(w1, w2);
;       const f32x2 apc = mkf2(a[e].x + c[e].x, a[e].y + c[e].y), amc = mkf2(a[e].x - c[e].x, a[e].y - c[e].y);
;       const f32x2 bpd = mkf2(b[e].x + d[e].x, b[e].y + d[e].y), bmd = mkf2(b[e].x - d[e].x, b[e].y - d[e].y);
;       const int o = 4 * i - 3 * q;
;       buf[SW(o)] = mkf2(apc.x + bpd.x, apc.y + bpd.y);
;       buf[SW(o + s)] = cmul(w1, mkf2(amc.x + bmd.y, amc.y - bmd.x));
;       buf[SW(o + 2 * s)] = cmul(w2, mkf2(apc.x - bpd.x, apc.y - bpd.y));
;       buf[SW(o + 3 * s)] = cmul(w3, mkf2(amc.x - bmd.y, amc.y + bmd.x));
;     }
	v_pk_mul_f32 v[56:57], v[230:231], v[204:205] op_sel:[1,1] op_sel_hi:[1,0]
	v_pk_fma_f32 v[56:57], v[230:231], v[204:205], v[56:57] op_sel_hi:[0,1,1] neg_lo:[0,0,1]
	v_mul_f32_e32 v214, 4.0, v201
	v_add_f32_e32 v214, 0x3e000000, v214
	v_cos_f32_e32 v224, v214
	v_sin_f32_e64 v225, -v214
	s_nop 0
	v_pk_mul_f32 v[206:207], v[224:225], v[224:225] op_sel:[1,1] op_sel_hi:[1,0]
	v_pk_fma_f32 v[226:227], v[224:225], v[224:225], v[206:207] op_sel_hi:[0,1,1] neg_lo:[0,0,1]
	v_pk_mul_f32 v[206:207], v[224:225], v[226:227] op_sel:[1,1] op_sel_hi:[1,0]
	v_pk_fma_f32 v[230:231], v[224:225], v[226:227], v[206:207] op_sel_hi:[0,1,1] neg_lo:[0,0,1]
	v_pk_add_f32 v[202:203], v[14:15], v[46:47]
	v_pk_add_f32 v[14:15], v[14:15], v[46:47] neg_lo:[0,1] neg_hi:[0,1]
	v_pk_add_f32 v[204:205], v[30:31], v[62:63]
	v_pk_add_f32 v[30:31], v[30:31], v[62:63] neg_lo:[0,1] neg_hi:[0,1]
	v_pk_add_f32 v[46:47], v[202:203], v[204:205]
	v_pk_add_f32 v[62:63], v[202:203], v[204:205] neg_lo:[0,1] neg_hi:[0,1]
	v_pk_add_f32 v[202:203], v[14:15], v[30:31] op_sel:[0,1] op_sel_hi:[1,0] neg_hi:[0,1]
	v_pk_add_f32 v[204:205], v[14:15], v[30:31] op_sel:[0,1] op_sel_hi:[1,0] neg_lo:[0,1]
	v_pk_mul_f32 v[14:15], v[224:225], v[202:203] op_sel:[1,1] op_sel_hi:[1,0]
	v_pk_fma_f32 v[14:15], v[224:225], v[202:203], v[14:15] op_sel_hi:[0,1,1] neg_lo:[0,0,1]
	v_pk_mul_f32 v[30:31], v[226:227], v[62:63] op_sel:[1,1] op_sel_hi:[1,0]
	v_pk_fma_f32 v[30:31], v[226:227], v[62:63], v[30:31] op_sel_hi:[0,1,1] neg_lo:[0,0,1]
	v_pk_mul_f32 v[62:63], v[230:231], v[204:205] op_sel:[1,1] op_sel_hi:[1,0]
	v_pk_fma_f32 v[62:63], v[230:231], v[204:205], v[62:63] op_sel_hi:[0,1,1] neg_lo:[0,0,1]
	v_pk_add_f32 v[202:203], v[10:11], v[42:43]
	v_pk_add_f32 v[10:11], v[10:11], v[42:43] neg_lo:[0,1] neg_hi:[0,1]
	v_pk_add_f32 v[204:205], v[26:27], v[58:59]
	v_pk_add_f32 v[26:27], v[26:27], v[58:59] neg_lo:[0,1] neg_hi:[0,1]
	v_pk_add_f32 v[42:43], v[202:203], v[204:205]
	v_pk_add_f32 v[58:59], v[202:203], v[204:205] neg_lo:[0,1] neg_hi:[0,1]
	v_pk_add_f32 v[202:203], v[10:11], v[26:27] op_sel:[0,1] op_sel_hi:[1,0] neg_hi:[0,1]
	v_pk_add_f32 v[204:205], v[10:11], v[26:27] op_sel:[0,1] op_sel_hi:[1,0] neg_lo:[0,1]
	v_pk_mul_f32 v[10:11], v[224:225], v[202:203] op_sel:[1,1] op_sel_hi:[1,0]
	v_pk_fma_f32 v[10:11], v[224:225], v[202:203], v[10:11] op_sel_hi:[0,1,1] neg_lo:[0,0,1]
	v_pk_mul_f32 v[26:27], v[226:227], v[58:59] op_sel:[1,1] op_sel_hi:[1,0]
	v_pk_fma_f32 v[26:27], v[226:227], v[58:59], v[26:27] op_sel_hi:[0,1,1] neg_lo:[0,0,1]
	v_pk_mul_f32 v[58:59], v[230:231], v[204:205] op_sel:[1,1] op_sel_hi:[1,0]
	v_pk_fma_f32 v[58:59], v[230:231], v[204:205], v[58:59] op_sel_hi:[0,1,1] neg_lo:[0,0,1]
	v_pk_add_f32 v[202:203], v[12:13], v[44:45]
	v_pk_add_f32 v[12:13], v[12:13], v[44:45] neg_lo:[0,1] neg_hi:[0,1]
	v_pk_add_f32 v[204:205], v[28:29], v[60:61]
	v_pk_add_f32 v[28:29], v[28:29], v[60:61] neg_lo:[0,1] neg_hi:[0,1]
	v_pk_add_f32 v[44:45], v[202:203], v[204:205]
	v_pk_add_f32 v[60:61], v[202:203], v[204:205] neg_lo:[0,1] neg_hi:[0,1]
	v_pk_add_f32 v[202:203], v[12:13], v[28:29] op_sel:[0,1] op_sel_hi:[1,0] neg_hi:[0,1]
	v_pk_add_f32 v[204:205], v[12:13], v[28:29] op_sel:[0,1] op_sel_hi:[1,0] neg_lo:[0,1]
	v_pk_mul_f32 v[12:13], v[224:225], v[202:203] op_sel:[1,1] op_sel_hi:[1,0]
	v_pk_fma_f32 v[12:13], v[224:225], v[202:203], v[12:13] op_sel_hi:[0,1,1] neg_lo:[0,0,1]
	v_pk_mul_f32 v[28:29], v[226:227], v[60:61] op_sel:[1,1] op_sel_hi:[1,0]
	v_pk_fma_f32 v[28:29], v[226:227], v[60:61], v[28:29] op_sel_hi:[0,1,1] neg_lo:[0,0,1]
	v_pk_mul_f32 v[60:61], v[230:231], v[204:205] op_sel:[1,1] op_sel_hi:[1,0]
	v_pk_fma_f32 v[60:61], v[230:231], v[204:205], v[60:61] op_sel_hi:[0,1,1] neg_lo:[0,0,1]
	v_pk_add_f32 v[202:203], v[16:17], v[48:49]
	v_pk_add_f32 v[16:17], v[16:17], v[48:49] neg_lo:[0,1] neg_hi:[0,1]
	v_pk_add_f32 v[204:205], v[32:33], v[64:65]
	v_pk_add_f32 v[32:33], v[32:33], v[64:65] neg_lo:[0,1] neg_hi:[0,1]
	v_pk_add_f32 v[48:49], v[202:203], v[204:205]
	v_pk_add_f32 v[64:65], v[202:203], v[204:205] neg_lo:[0,1] neg_hi:[0,1]
	v_pk_add_f32 v[202:203], v[16:17], v[32:33] op_sel:[0,1] op_sel_hi:[1,0] neg_hi:[0,1]
	v_pk_add_f32 v[204:205], v[16:17], v[32:33] op_sel:[0,1] op_sel_hi:[1,0] neg_lo:[0,1]
	v_pk_mul_f32 v[16:17], v[224:225], v[202:203] op_sel:[1,1] op_sel_hi:[1,0]
	v_pk_fma_f32 v[16:17], v[224:225], v[202:203], v[16:17] op_sel_hi:[0,1,1] neg_lo:[0,0,1]
	v_pk_mul_f32 v[32:33], v[226:227], v[64:65] op_sel:[1,1] op_sel_hi:[1,0]
	v_pk_fma_f32 v[32:33], v[226:227], v[64:65], v[32:33] op_sel_hi:[0,1,1] neg_lo:[0,0,1]
	v_pk_mul_f32 v[64:65], v[230:231], v[204:205] op_sel:[1,1] op_sel_hi:[1,0]
	v_pk_fma_f32 v[64:65], v[230:231], v[204:205], v[64:65] op_sel_hi:[0,1,1] neg_lo:[0,0,1]
	ds_write_b64 v164, v[38:39] offset:0
	v_xor_b32_e32 v156, 8, v164
	ds_write_b64 v156, v[34:35] offset:0
	v_xor_b32_e32 v158, 16, v164
	ds_write_b64 v158, v[36:37] offset:0
	v_xor_b32_e32 v160, 24, v164
	ds_write_b64 v160, v[40:41] offset:0
	v_xor_b32_e32 v162, 32, v164
	ds_write_b64 v162, v[6:7] offset:0
	v_xor_b32_e32 v156, 40, v164
	ds_write_b64 v156, v[2:3] offset:0
	v_xor_b32_e32 v158, 48, v164
	ds_write_b64 v158, v[4:5] offset:0
	v_xor_b32_e32 v160, 56, v164
	ds_write_b64 v160, v[8:9] offset:0
	v_xor_b32_e32 v162, 64, v164
	ds_write_b64 v162, v[22:23] offset:0
	v_xor_b32_e32 v156, 0x48, v164
	ds_write_b64 v156, v[18:19] offset:0
	v_xor_b32_e32 v158, 0x50, v164
	ds_write_b64 v158, v[20:21] offset:0
	v_xor_b32_e32 v160, 0x58, v164
	ds_write_b64 v160, v[24:25] offset:0
	v_xor_b32_e32 v162, 0x60, v164
	ds_write_b64 v162, v[54:55] offset:0
	v_xor_b32_e32 v156, 0x68, v164
	ds_write_b64 v156, v[50:51] offset:0
	v_xor_b32_e32 v158, 0x70, v164
	ds_write_b64 v158, v[52:53] offset:0
	v_xor_b32_e32 v160, 0x78, v164
	ds_write_b64 v160, v[56:57] offset:0
	ds_write_b64 v164, v[46:47] offset:32768
	v_xor_b32_e32 v162, 8, v164
	ds_write_b64 v162, v[42:43] offset:32768
	v_xor_b32_e32 v156, 16, v164
	ds_write_b64 v156, v[44:45] offset:32768
	v_xor_b32_e32 v158, 24, v164
	ds_write_b64 v158, v[48:49] offset:32768
	v_xor_b32_e32 v160, 32, v164
	ds_write_b64 v160, v[14:15] offset:32768
	v_xor_b32_e32 v162, 40, v164
	ds_write_b64 v162, v[10:11] offset:32768
	v_xor_b32_e32 v156, 48, v164
	ds_write_b64 v156, v[12:13] offset:32768
	v_xor_b32_e32 v158, 56, v164
	ds_write_b64 v158, v[16:17] offset:32768
	v_xor_b32_e32 v160, 64, v164
	ds_write_b64 v160, v[30:31] offset:32768
	v_xor_b32_e32 v162, 0x48, v164
	ds_write_b64 v162, v[26:27] offset:32768
	v_xor_b32_e32 v156, 0x50, v164
	ds_write_b64 v156, v[28:29] offset:32768
	v_xor_b32_e32 v158, 0x58, v164
	ds_write_b64 v158, v[32:33] offset:32768
	v_xor_b32_e32 v160, 0x60, v164
	ds_write_b64 v160, v[62:63] offset:32768
	v_xor_b32_e32 v162, 0x68, v164
	ds_write_b64 v162, v[58:59] offset:32768
	v_xor_b32_e32 v156, 0x70, v164
	ds_write_b64 v156, v[60:61] offset:32768
	v_xor_b32_e32 v158, 0x78, v164
	ds_write_b64 v158, v[64:65] offset:32768
	s_waitcnt lgkmcnt(0)
	s_barrier
; DI f32x2 cmul(f32x2 a, f32x2 b) { return mkf2(a.x * b.x - a.y * b.y, a.x * b.y + a.y * b.x); }
; DI void fft8192(f32x2* buf, const f32x2* __restrict__ tw) {
;     ...
;     __syncthreads();
; #pragma unroll
;     for (int e = 0; e < 8; ++e) {
;       const int i = tid + 256 * e;
;       const int pi = SW(i);
;       a[e] = buf[pi]; b[e] = buf[pi + 2048]; c[e] = buf[pi + 4096]; d[e] = buf[pi + 6144];
;     }
;     __syncthreads();
; #pragma unroll
;     for (int e = 0; e < 8; ++e) {
;       const int i = tid + 256 * e;
;       const int q = i & (s - 1);
;       const int ps = i - q;
;       const float rev = (float)ps * (1.f / 8192.f);
;       const f32x2 w1 = mkf2(__builtin_amdgcn_cosf(rev), -__builtin_amdgcn_sinf(rev));
;       const f32x2 w2 = cmul(w1, w1), w3 = cmul(w1, w2);
;       const f32x2 apc = mkf2(a[e].x + c[e].x, a[e].y + c[e].y), amc = mkf2(a[e].x - c[e].x, a[e].y - c[e].y);
;       const f32x2 bpd = mkf2(b[e].x + d[e].x, b[e].y + d[e].y), bmd = mkf2(b[e].x - d[e].x, b[e].y - d[e].y);
;       const int o = 4 * i - 3 * q;
;       buf[SW(o)] = mkf2(apc.x + bpd.x, apc.y + bpd.y);
;       buf[SW(o + s)] = cmul(w1, mkf2(amc.x + bmd.y, amc.y - bmd.x));
;       buf[SW(o + 2 * s)] = cmul(w2, mkf2(apc.x - bpd.x, apc.y - bpd.y));
;       buf[SW(o + 3 * s)] = cmul(w3, mkf2(amc.x - bmd.y, amc.y + bmd.x));
;     }
	v_bfe_i32 v166, v0, 4, 4
	v_and_b32_e32 v166, 15, v166
	v_xor_b32_e32 v166, v166, v0
	v_lshlrev_b32_e32 v164, 3, v166
	ds_read2st64_b64 v[2:5], v164 offset0:0 offset1:32
	ds_read2st64_b64 v[6:9], v164 offset0:64 offset1:96
	ds_read2st64_b64 v[10:13], v164 offset0:4 offset1:36
	ds_read2st64_b64 v[14:17], v164 offset0:68 offset1:100
	ds_read2st64_b64 v[18:21], v164 offset0:8 offset1:40
	ds_read2st64_b64 v[22:25], v164 offset0:72 offset1:104
	ds_read2st64_b64 v[26:29], v164 offset0:12 offset1:44
	ds_read2st64_b64 v[30:33], v164 offset0:76 offset1:108
	ds_read2st64_b64 v[34:37], v164 offset0:16 offset1:48
	ds_read2st64_b64 v[38:41], v164 offset0:80 offset1:112
	ds_read2st64_b64 v[42:45], v164 offset0:20 offset1:52
	ds_read2st64_b64 v[46:49], v164 offset0:84 offset1:116
	ds_read2st64_b64 v[50:53], v164 offset0:24 offset1:56
	ds_read2st64_b64 v[54:57], v164 offset0:88 offset1:120
	ds_read2st64_b64 v[58:61], v164 offset0:28 offset1:60
	ds_read2st64_b64 v[62:65], v164 offset0:92 offset1:124
	v_and_b32_e32 v166, 15, v0
	v_sub_u32_e32 v168, v0, v166
	v_cvt_f32_u32_e32 v201, v168
	v_lshl_add_u32 v164, v168, 4, v166
	v_lshlrev_b32_e32 v164, 3, v164
	v_mul_f32_e32 v201, 0x39000000, v201
	v_cos_f32_e32 v210, v201
	v_sin_f32_e64 v211, -v201
	s_waitcnt lgkmcnt(14)
	v_pk_add_f32 v[202:203], v[2:3], v[6:7]
	v_pk_add_f32 v[2:3], v[2:3], v[6:7] neg_lo:[0,1] neg_hi:[0,1]
	v_pk_add_f32 v[204:205], v[4:5], v[8:9]
	v_pk_add_f32 v[4:5], v[4:5], v[8:9] neg_lo:[0,1] neg_hi:[0,1]
	v_pk_add_f32 v[6:7], v[202:203], v[204:205]
	v_pk_add_f32 v[8:9], v[202:203], v[204:205] neg_lo:[0,1] neg_hi:[0,1]
	v_pk_add_f32 v[202:203], v[2:3], v[4:5] op_sel:[0,1] op_sel_hi:[1,0] neg_hi:[0,1]
	v_pk_add_f32 v[204:205], v[2:3], v[4:5] op_sel:[0,1] op_sel_hi:[1,0] neg_lo:[0,1]
	v_pk_mul_f32 v[206:207], v[210:211], v[210:211] op_sel:[1,1] op_sel_hi:[1,0]
	v_pk_fma_f32 v[212:213], v[210:211], v[210:211], v[206:207] op_sel_hi:[0,1,1] neg_lo:[0,0,1]
	v_pk_mul_f32 v[206:207], v[210:211], v[212:213] op_sel:[1,1] op_sel_hi:[1,0]
	v_pk_fma_f32 v[220:221], v[210:211], v[212:213], v[206:207] op_sel_hi:[0,1,1] neg_lo:[0,0,1]
	v_pk_mul_f32 v[2:3], v[210:211], v[202:203] op_sel:[1,1] op_sel_hi:[1,0]
	v_pk_fma_f32 v[2:3], v[210:211], v[202:203], v[2:3] op_sel_hi:[0,1,1] neg_lo:[0,0,1]
	v_pk_mul_f32 v[4:5], v[212:213], v[8:9] op_sel:[1,1] op_sel_hi:[1,0]
	v_pk_fma_f32 v[4:5], v[212:213], v[8:9], v[4:5] op_sel_hi:[0,1,1] neg_lo:[0,0,1]
	v_pk_mul_f32 v[8:9], v[220:221], v[204:205] op_sel:[1,1] op_sel_hi:[1,0]
	v_pk_fma_f32 v[8:9], v[220:221], v[204:205], v[8:9] op_sel_hi:[0,1,1] neg_lo:[0,0,1]
	v_add_f32_e32 v214, 0x3d000000, v201
	v_cos_f32_e32 v210, v214
	v_sin_f32_e64 v211, -v214
	s_waitcnt lgkmcnt(12)
	v_pk_add_f32 v[202:203], v[10:11], v[14:15]
	v_pk_add_f32 v[10:11], v[10:11], v[14:15] neg_lo:[0,1] neg_hi:[0,1]
	v_pk_add_f32 v[204:205], v[12:13], v[16:17]
	v_pk_add_f32 v[12:13], v[12:13], v[16:17] neg_lo:[0,1] neg_hi:[0,1]
	v_pk_add_f32 v[14:15], v[202:203], v[204:205]
	v_pk_add_f32 v[16:17], v[202:203], v[204:205] neg_lo:[0,1] neg_hi:[0,1]
	v_pk_add_f32 v[202:203], v[10:11], v[12:13] op_sel:[0,1] op_sel_hi:[1,0] neg_hi:[0,1]
	v_pk_add_f32 v[204:205], v[10:11], v[12:13] op_sel:[0,1] op_sel_hi:[1,0] neg_lo:[0,1]
	v_pk_mul_f32 v[206:207], v[210:211], v[210:211] op_sel:[1,1] op_sel_hi:[1,0]
	v_pk_fma_f32 v[212:213], v[210:211], v[210:211], v[206:207] op_sel_hi:[0,1,1] neg_lo:[0,0,1]
	v_pk_mul_f32 v[206:207], v[210:211], v[212:213] op_sel:[1,1] op_sel_hi:[1,0]
	v_pk_fma_f32 v[220:221], v[210:211], v[212:213], v[206:207] op_sel_hi:[0,1,1] neg_lo:[0,0,1]
	v_pk_mul_f32 v[10:11], v[210:211], v[202:203] op_sel:[1,1] op_sel_hi:[1,0]
	v_pk_fma_f32 v[10:11], v[210:211], v[202:203], v[10:11] op_sel_hi:[0,1,1] neg_lo:[0,0,1]
	v_pk_mul_f32 v[12:13], v[212:213], v[16:17] op_sel:[1,1] op_sel_hi:[1,0]
	v_pk_fma_f32 v[12:13], v[212:213], v[16:17], v[12:13] op_sel_hi:[0,1,1] neg_lo:[0,0,1]
	v_pk_mul_f32 v[16:17], v[220:221], v[204:205] op_sel:[1,1] op_sel_hi:[1,0]
	v_pk_fma_f32 v[16:17], v[220:221], v[204:205], v[16:17] op_sel_hi:[0,1,1] neg_lo:[0,0,1]
	v_add_f32_e32 v214, 0x3d800000, v201
	v_cos_f32_e32 v210, v214
	v_sin_f32_e64 v211, -v214
	s_waitcnt lgkmcnt(10)
	v_pk_add_f32 v[202:203], v[18:19], v[22:23]
	v_pk_add_f32 v[18:19], v[18:19], v[22:23] neg_lo:[0,1] neg_hi:[0,1]
	v_pk_add_f32 v[204:205], v[20:21], v[24:25]
	v_pk_add_f32 v[20:21], v[20:21], v[24:25] neg_lo:[0,1] neg_hi:[0,1]
	v_pk_add_f32 v[22:23], v[202:203], v[204:205]
	v_pk_add_f32 v[24:25], v[202:203], v[204:205] neg_lo:[0,1] neg_hi:[0,1]
	v_pk_add_f32 v[202:203], v[18:19], v[20:21] op_sel:[0,1] op_sel_hi:[1,0] neg_hi:[0,1]
	v_pk_add_f32 v[204:205], v[18:19], v[20:21] op_sel:[0,1] op_sel_hi:[1,0] neg_lo:[0,1]
	v_pk_mul_f32 v[206:207], v[210:211], v[210:211] op_sel:[1,1] op_sel_hi:[1,0]
	v_pk_fma_f32 v[212:213], v[210:211], v[210:211], v[206:207] op_sel_hi:[0,1,1] neg_lo:[0,0,1]
	v_pk_mul_f32 v[206:207], v[210:211], v[212:213] op_sel:[1,1] op_sel_hi:[1,0]
	v_pk_fma_f32 v[220:221], v[210:211], v[212:213], v[206:207] op_sel_hi:[0,1,1] neg_lo:[0,0,1]
	v_pk_mul_f32 v[18:19], v[210:211], v[202:203] op_sel:[1,1] op_sel_hi:[1,0]
	v_pk_fma_f32 v[18:19], v[210:211], v[202:203], v[18:19] op_sel_hi:[0,1,1] neg_lo:[0,0,1]
	v_pk_mul_f32 v[20:21], v[212:213], v[24:25] op_sel:[1,1] op_sel_hi:[1,0]
	v_pk_fma_f32 v[20:21], v[212:213], v[24:25], v[20:21] op_sel_hi:[0,1,1] neg_lo:[0,0,1]
	v_pk_mul_f32 v[24:25], v[220:221], v[204:205] op_sel:[1,1] op_sel_hi:[1,0]
	v_pk_fma_f32 v[24:25], v[220:221], v[204:205], v[24:25] op_sel_hi:[0,1,1] neg_lo:[0,0,1]
	v_add_f32_e32 v214, 0x3dc00000, v201
	v_cos_f32_e32 v210, v214
	v_sin_f32_e64 v211, -v214
	s_waitcnt lgkmcnt(8)
; DI f32x2 cmul(f32x2 a, f32x2 b) { return mkf2(a.x * b.x - a.y * b.y, a.x * b.y + a.y * b.x); }
; DI void fft8192(f32x2* buf, const f32x2* __restrict__ tw) {
;     ...
; #pragma unroll
;     for (int e = 0; e < 8; ++e) {
;       const int i = tid + 256 * e;
;       const int q = i & (s - 1);
;       const int ps = i - q;
;       const float rev = (float)ps * (1.f / 8192.f);
;       const f32x2 w1 = mkf2(__builtin_amdgcn_cosf(rev), -__builtin_amdgcn_sinf(rev));
;       const f32x2 w2 = cmul(w1, w1), w3 = cmul(w1, w2);
;       const f32x2 apc = mkf2(a[e].x + c[e].x, a[e].y + c[e].y), amc = mkf2(a[e].x - c[e].x, a[e].y - c[e].y);
;       const f32x2 bpd = mkf2(b[e].x + d[e].x, b[e].y + d[e].y), bmd = mkf2(b[e].x - d[e].x, b[e].y - d[e].y);
;       const int o = 4 * i - 3 * q;
;       buf[SW(o)] = mkf2(apc.x + bpd.x, apc.y + bpd.y);
;       buf[SW(o + s)] = cmul(w1, mkf2(amc.x + bmd.y, amc.y - bmd.x));
;       buf[SW(o + 2 * s)] = cmul(w2, mkf2(apc.x - bpd.x, apc.y - bpd.y));
;       buf[SW(o + 3 * s)] = cmul(w3, mkf2(amc.x - bmd.y, amc.y + bmd.x));
;     }
	v_pk_add_f32 v[202:203], v[26:27], v[30:31]
	v_pk_add_f32 v[26:27], v[26:27], v[30:31] neg_lo:[0,1] neg_hi:[0,1]
	v_pk_add_f32 v[204:205], v[28:29], v[32:33]
	v_pk_add_f32 v[28:29], v[28:29], v[32:33] neg_lo:[0,1] neg_hi:[0,1]
	v_pk_add_f32 v[30:31], v[202:203], v[204:205]
	v_pk_add_f32 v[32:33], v[202:203], v[204:205] neg_lo:[0,1] neg_hi:[0,1]
	v_pk_add_f32 v[202:203], v[26:27], v[28:29] op_sel:[0,1] op_sel_hi:[1,0] neg_hi:[0,1]
	v_pk_add_f32 v[204:205], v[26:27], v[28:29] op_sel:[0,1] op_sel_hi:[1,0] neg_lo:[0,1]
	v_pk_mul_f32 v[206:207], v[210:211], v[210:211] op_sel:[1,1] op_sel_hi:[1,0]
	v_pk_fma_f32 v[212:213], v[210:211], v[210:211], v[206:207] op_sel_hi:[0,1,1] neg_lo:[0,0,1]
	v_pk_mul_f32 v[206:207], v[210:211], v[212:213] op_sel:[1,1] op_sel_hi:[1,0]
	v_pk_fma_f32 v[220:221], v[210:211], v[212:213], v[206:207] op_sel_hi:[0,1,1] neg_lo:[0,0,1]
	v_pk_mul_f32 v[26:27], v[210:211], v[202:203] op_sel:[1,1] op_sel_hi:[1,0]
	v_pk_fma_f32 v[26:27], v[210:211], v[202:203], v[26:27] op_sel_hi:[0,1,1] neg_lo:[0,0,1]
	v_pk_mul_f32 v[28:29], v[212:213], v[32:33] op_sel:[1,1] op_sel_hi:[1,0]
	v_pk_fma_f32 v[28:29], v[212:213], v[32:33], v[28:29] op_sel_hi:[0,1,1] neg_lo:[0,0,1]
	v_pk_mul_f32 v[32:33], v[220:221], v[204:205] op_sel:[1,1] op_sel_hi:[1,0]
	v_pk_fma_f32 v[32:33], v[220:221], v[204:205], v[32:33] op_sel_hi:[0,1,1] neg_lo:[0,0,1]
	v_add_f32_e32 v214, 0x3e000000, v201
	v_cos_f32_e32 v210, v214
	v_sin_f32_e64 v211, -v214
	s_waitcnt lgkmcnt(6)
	v_pk_add_f32 v[202:203], v[34:35], v[38:39]
	v_pk_add_f32 v[34:35], v[34:35], v[38:39] neg_lo:[0,1] neg_hi:[0,1]
	v_pk_add_f32 v[204:205], v[36:37], v[40:41]
	v_pk_add_f32 v[36:37], v[36:37], v[40:41] neg_lo:[0,1] neg_hi:[0,1]
	v_pk_add_f32 v[38:39], v[202:203], v[204:205]
	v_pk_add_f32 v[40:41], v[202:203], v[204:205] neg_lo:[0,1] neg_hi:[0,1]
	v_pk_add_f32 v[202:203], v[34:35], v[36:37] op_sel:[0,1] op_sel_hi:[1,0] neg_hi:[0,1]
	v_pk_add_f32 v[204:205], v[34:35], v[36:37] op_sel:[0,1] op_sel_hi:[1,0] neg_lo:[0,1]
	v_pk_mul_f32 v[206:207], v[210:211], v[210:211] op_sel:[1,1] op_sel_hi:[1,0]
	v_pk_fma_f32 v[212:213], v[210:211], v[210:211], v[206:207] op_sel_hi:[0,1,1] neg_lo:[0,0,1]
	v_pk_mul_f32 v[206:207], v[210:211], v[212:213] op_sel:[1,1] op_sel_hi:[1,0]
	v_pk_fma_f32 v[220:221], v[210:211], v[212:213], v[206:207] op_sel_hi:[0,1,1] neg_lo:[0,0,1]
	v_pk_mul_f32 v[34:35], v[210:211], v[202:203] op_sel:[1,1] op_sel_hi:[1,0]
	v_pk_fma_f32 v[34:35], v[210:211], v[202:203], v[34:35] op_sel_hi:[0,1,1] neg_lo:[0,0,1]
	v_pk_mul_f32 v[36:37], v[212:213], v[40:41] op_sel:[1,1] op_sel_hi:[1,0]
	v_pk_fma_f32 v[36:37], v[212:213], v[40:41], v[36:37] op_sel_hi:[0,1,1] neg_lo:[0,0,1]
	v_pk_mul_f32 v[40:41], v[220:221], v[204:205] op_sel:[1,1] op_sel_hi:[1,0]
	v_pk_fma_f32 v[40:41], v[220:221], v[204:205], v[40:41] op_sel_hi:[0,1,1] neg_lo:[0,0,1]
	v_add_f32_e32 v214, 0x3e200000, v201
	v_cos_f32_e32 v210, v214
	v_sin_f32_e64 v211, -v214
	s_waitcnt lgkmcnt(4)
	v_pk_add_f32 v[202:203], v[42:43], v[46:47]
	v_pk_add_f32 v[42:43], v[42:43], v[46:47] neg_lo:[0,1] neg_hi:[0,1]
	v_pk_add_f32 v[204:205], v[44:45], v[48:49]
	v_pk_add_f32 v[44:45], v[44:45], v[48:49] neg_lo:[0,1] neg_hi:[0,1]
	v_pk_add_f32 v[46:47], v[202:203], v[204:205]
	v_pk_add_f32 v[48:49], v[202:203], v[204:205] neg_lo:[0,1] neg_hi:[0,1]
	v_pk_add_f32 v[202:203], v[42:43], v[44:45] op_sel:[0,1] op_sel_hi:[1,0] neg_hi:[0,1]
	v_pk_add_f32 v[204:205], v[42:43], v[44:45] op_sel:[0,1] op_sel_hi:[1,0] neg_lo:[0,1]
	v_pk_mul_f32 v[206:207], v[210:211], v[210:211] op_sel:[1,1] op_sel_hi:[1,0]
	v_pk_fma_f32 v[212:213], v[210:211], v[210:211], v[206:207] op_sel_hi:[0,1,1] neg_lo:[0,0,1]
	v_pk_mul_f32 v[206:207], v[210:211], v[212:213] op_sel:[1,1] op_sel_hi:[1,0]
	v_pk_fma_f32 v[220:221], v[210:211], v[212:213], v[206:207] op_sel_hi:[0,1,1] neg_lo:[0,0,1]
	v_pk_mul_f32 v[42:43], v[210:211], v[202:203] op_sel:[1,1] op_sel_hi:[1,0]
	v_pk_fma_f32 v[42:43], v[210:211], v[202:203], v[42:43] op_sel_hi:[0,1,1] neg_lo:[0,0,1]
	v_pk_mul_f32 v[44:45], v[212:213], v[48:49] op_sel:[1,1] op_sel_hi:[1,0]
	v_pk_fma_f32 v[44:45], v[212:213], v[48:49], v[44:45] op_sel_hi:[0,1,1] neg_lo:[0,0,1]
	v_pk_mul_f32 v[48:49], v[220:221], v[204:205] op_sel:[1,1] op_sel_hi:[1,0]
	v_pk_fma_f32 v[48:49], v[220:221], v[204:205], v[48:49] op_sel_hi:[0,1,1] neg_lo:[0,0,1]
	v_add_f32_e32 v214, 0x3e400000, v201
	v_cos_f32_e32 v210, v214
	v_sin_f32_e64 v211, -v214
	s_waitcnt lgkmcnt(2)
	v_pk_add_f32 v[202:203], v[50:51], v[54:55]
	v_pk_add_f32 v[50:51], v[50:51], v[54:55] neg_lo:[0,1] neg_hi:[0,1]
	v_pk_add_f32 v[204:205], v[52:53], v[56:57]
	v_pk_add_f32 v[52:53], v[52:53], v[56:57] neg_lo:[0,1] neg_hi:[0,1]
	v_pk_add_f32 v[54:55], v[202:203], v[204:205]
	v_pk_add_f32 v[56:57], v[202:203], v[204:205] neg_lo:[0,1] neg_hi:[0,1]
	v_pk_add_f32 v[202:203], v[50:51], v[52:53] op_sel:[0,1] op_sel_hi:[1,0] neg_hi:[0,1]
	v_pk_add_f32 v[204:205], v[50:51], v[52:53] op_sel:[0,1] op_sel_hi:[1,0] neg_lo:[0,1]
	v_pk_mul_f32 v[206:207], v[210:211], v[210:211] op_sel:[1,1] op_sel_hi:[1,0]
	v_pk_fma_f32 v[212:213], v[210:211], v[210:211], v[206:207] op_sel_hi:[0,1,1] neg_lo:[0,0,1]
	v_pk_mul_f32 v[206:207], v[210:211], v[212:213] op_sel:[1,1] op_sel_hi:[1,0]
	v_pk_fma_f32 v[220:221], v[210:211], v[212:213], v[206:207] op_sel_hi:[0,1,1] neg_lo:[0,0,1]
	v_pk_mul_f32 v[50:51], v[210:211], v[202:203] op_sel:[1,1] op_sel_hi:[1,0]
	v_pk_fma_f32 v[50:51], v[210:211], v[202:203], v[50:51] op_sel_hi:[0,1,1] neg_lo:[0,0,1]
	v_pk_mul_f32 v[52:53], v[212:213], v[56:57] op_sel:[1,1] op_sel_hi:[1,0]
	v_pk_fma_f32 v[52:53], v[212:213], v[56:57], v[52:53] op_sel_hi:[0,1,1] neg_lo:[0,0,1]
	v_pk_mul_f32 v[56:57], v[220:221], v[204:205] op_sel:[1,1] op_sel_hi:[1,0]
	v_pk_fma_f32 v[56:57], v[220:221], v[204:205], v[56:57] op_sel_hi:[0,1,1] neg_lo:[0,0,1]
	v_add_f32_e32 v214, 0x3e600000, v201
	v_cos_f32_e32 v210, v214
	v_sin_f32_e64 v211, -v214
	s_waitcnt lgkmcnt(0)
; DI f32x2 cmul(f32x2 a, f32x2 b) { return mkf2(a.x * b.x - a.y * b.y, a.x * b.y + a.y * b.x); }
; DI void fft8192(f32x2* buf, const f32x2* __restrict__ tw) {
;     ...
; #pragma unroll
;     for (int e = 0; e < 8; ++e) {
;       const int i = tid + 256 * e;
;       const int q = i & (s - 1);
;       const int ps = i - q;
;       const float rev = (float)ps * (1.f / 8192.f);
;       const f32x2 w1 = mkf2(__builtin_amdgcn_cosf(rev), -__builtin_amdgcn_sinf(rev));
;       const f32x2 w2 = cmul(w1, w1), w3 = cmul(w1, w2);
;       const f32x2 apc = mkf2(a[e].x + c[e].x, a[e].y + c[e].y), amc = mkf2(a[e].x - c[e].x, a[e].y - c[e].y);
;       const f32x2 bpd = mkf2(b[e].x + d[e].x, b[e].y + d[e].y), bmd = mkf2(b[e].x - d[e].x, b[e].y - d[e].y);
;       const int o = 4 * i - 3 * q;
;       buf[SW(o)] = mkf2(apc.x + bpd.x, apc.y + bpd.y);
;       buf[SW(o + s)] = cmul(w1, mkf2(amc.x + bmd.y, amc.y - bmd.x));
;       buf[SW(o + 2 * s)] = cmul(w2, mkf2(apc.x - bpd.x, apc.y - bpd.y));
;       buf[SW(o + 3 * s)] = cmul(w3, mkf2(amc.x - bmd.y, amc.y + bmd.x));
;     }
	v_pk_add_f32 v[202:203], v[58:59], v[62:63]
	v_pk_add_f32 v[58:59], v[58:59], v[62:63] neg_lo:[0,1] neg_hi:[0,1]
	v_pk_add_f32 v[204:205], v[60:61], v[64:65]
	v_pk_add_f32 v[60:61], v[60:61], v[64:65] neg_lo:[0,1] neg_hi:[0,1]
	v_pk_add_f32 v[62:63], v[202:203], v[204:205]
	v_pk_add_f32 v[64:65], v[202:203], v[204:205] neg_lo:[0,1] neg_hi:[0,1]
	v_pk_add_f32 v[202:203], v[58:59], v[60:61] op_sel:[0,1] op_sel_hi:[1,0] neg_hi:[0,1]
	v_pk_add_f32 v[204:205], v[58:59], v[60:61] op_sel:[0,1] op_sel_hi:[1,0] neg_lo:[0,1]
	v_pk_mul_f32 v[206:207], v[210:211], v[210:211] op_sel:[1,1] op_sel_hi:[1,0]
	v_pk_fma_f32 v[212:213], v[210:211], v[210:211], v[206:207] op_sel_hi:[0,1,1] neg_lo:[0,0,1]
	v_pk_mul_f32 v[206:207], v[210:211], v[212:213] op_sel:[1,1] op_sel_hi:[1,0]
	v_pk_fma_f32 v[220:221], v[210:211], v[212:213], v[206:207] op_sel_hi:[0,1,1] neg_lo:[0,0,1]
	v_pk_mul_f32 v[58:59], v[210:211], v[202:203] op_sel:[1,1] op_sel_hi:[1,0]
	v_pk_fma_f32 v[58:59], v[210:211], v[202:203], v[58:59] op_sel_hi:[0,1,1] neg_lo:[0,0,1]
	v_pk_mul_f32 v[60:61], v[212:213], v[64:65] op_sel:[1,1] op_sel_hi:[1,0]
	v_pk_fma_f32 v[60:61], v[212:213], v[64:65], v[60:61] op_sel_hi:[0,1,1] neg_lo:[0,0,1]
	v_pk_mul_f32 v[64:65], v[220:221], v[204:205] op_sel:[1,1] op_sel_hi:[1,0]
	v_pk_fma_f32 v[64:65], v[220:221], v[204:205], v[64:65] op_sel_hi:[0,1,1] neg_lo:[0,0,1]
	s_barrier
	v_mul_f32_e32 v214, 4.0, v201
	v_cos_f32_e32 v224, v214
	v_sin_f32_e64 v225, -v214
	s_nop 0
	v_pk_mul_f32 v[206:207], v[224:225], v[224:225] op_sel:[1,1] op_sel_hi:[1,0]
	v_pk_fma_f32 v[226:227], v[224:225], v[224:225], v[206:207] op_sel_hi:[0,1,1] neg_lo:[0,0,1]
	v_pk_mul_f32 v[206:207], v[224:225], v[226:227] op_sel:[1,1] op_sel_hi:[1,0]
	v_pk_fma_f32 v[230:231], v[224:225], v[226:227], v[206:207] op_sel_hi:[0,1,1] neg_lo:[0,0,1]
	v_pk_add_f32 v[202:203], v[6:7], v[38:39]
	v_pk_add_f32 v[6:7], v[6:7], v[38:39] neg_lo:[0,1] neg_hi:[0,1]
	v_pk_add_f32 v[204:205], v[22:23], v[54:55]
	v_pk_add_f32 v[22:23], v[22:23], v[54:55] neg_lo:[0,1] neg_hi:[0,1]
	v_pk_add_f32 v[38:39], v[202:203], v[204:205]
	v_pk_add_f32 v[54:55], v[202:203], v[204:205] neg_lo:[0,1] neg_hi:[0,1]
	v_pk_add_f32 v[202:203], v[6:7], v[22:23] op_sel:[0,1] op_sel_hi:[1,0] neg_hi:[0,1]
	v_pk_add_f32 v[204:205], v[6:7], v[22:23] op_sel:[0,1] op_sel_hi:[1,0] neg_lo:[0,1]
	v_pk_mul_f32 v[6:7], v[224:225], v[202:203] op_sel:[1,1] op_sel_hi:[1,0]
	v_pk_fma_f32 v[6:7], v[224:225], v[202:203], v[6:7] op_sel_hi:[0,1,1] neg_lo:[0,0,1]
	v_pk_mul_f32 v[22:23], v[226:227], v[54:55] op_sel:[1,1] op_sel_hi:[1,0]
	v_pk_fma_f32 v[22:23], v[226:227], v[54:55], v[22:23] op_sel_hi:[0,1,1] neg_lo:[0,0,1]
	v_pk_mul_f32 v[54:55], v[230:231], v[204:205] op_sel:[1,1] op_sel_hi:[1,0]
	v_pk_fma_f32 v[54:55], v[230:231], v[204:205], v[54:55] op_sel_hi:[0,1,1] neg_lo:[0,0,1]
	v_pk_add_f32 v[202:203], v[2:3], v[34:35]
	v_pk_add_f32 v[2:3], v[2:3], v[34:35] neg_lo:[0,1] neg_hi:[0,1]
	v_pk_add_f32 v[204:205], v[18:19], v[50:51]
	v_pk_add_f32 v[18:19], v[18:19], v[50:51] neg_lo:[0,1] neg_hi:[0,1]
	v_pk_add_f32 v[34:35], v[202:203], v[204:205]
	v_pk_add_f32 v[50:51], v[202:203], v[204:205] neg_lo:[0,1] neg_hi:[0,1]
	v_pk_add_f32 v[202:203], v[2:3], v[18:19] op_sel:[0,1] op_sel_hi:[1,0] neg_hi:[0,1]
	v_pk_add_f32 v[204:205], v[2:3], v[18:19] op_sel:[0,1] op_sel_hi:[1,0] neg_lo:[0,1]
	v_pk_mul_f32 v[2:3], v[224:225], v[202:203] op_sel:[1,1] op_sel_hi:[1,0]
	v_pk_fma_f32 v[2:3], v[224:225], v[202:203], v[2:3] op_sel_hi:[0,1,1] neg_lo:[0,0,1]
	v_pk_mul_f32 v[18:19], v[226:227], v[50:51] op_sel:[1,1] op_sel_hi:[1,0]
	v_pk_fma_f32 v[18:19], v[226:227], v[50:51], v[18:19] op_sel_hi:[0,1,1] neg_lo:[0,0,1]
	v_pk_mul_f32 v[50:51], v[230:231], v[204:205] op_sel:[1,1] op_sel_hi:[1,0]
	v_pk_fma_f32 v[50:51], v[230:231], v[204:205], v[50:51] op_sel_hi:[0,1,1] neg_lo:[0,0,1]
	v_pk_add_f32 v[202:203], v[4:5], v[36:37]
	v_pk_add_f32 v[4:5], v[4:5], v[36:37] neg_lo:[0,1] neg_hi:[0,1]
	v_pk_add_f32 v[204:205], v[20:21], v[52:53]
	v_pk_add_f32 v[20:21], v[20:21], v[52:53] neg_lo:[0,1] neg_hi:[0,1]
	v_pk_add_f32 v[36:37], v[202:203], v[204:205]
	v_pk_add_f32 v[52:53], v[202:203], v[204:205] neg_lo:[0,1] neg_hi:[0,1]
	v_pk_add_f32 v[202:203], v[4:5], v[20:21] op_sel:[0,1] op_sel_hi:[1,0] neg_hi:[0,1]
	v_pk_add_f32 v[204:205], v[4:5], v[20:21] op_sel:[0,1] op_sel_hi:[1,0] neg_lo:[0,1]
	v_pk_mul_f32 v[4:5], v[224:225], v[202:203] op_sel:[1,1] op_sel_hi:[1,0]
	v_pk_fma_f32 v[4:5], v[224:225], v[202:203], v[4:5] op_sel_hi:[0,1,1] neg_lo:[0,0,1]
	v_pk_mul_f32 v[20:21], v[226:227], v[52:53] op_sel:[1,1] op_sel_hi:[1,0]
	v_pk_fma_f32 v[20:21], v[226:227], v[52:53], v[20:21] op_sel_hi:[0,1,1] neg_lo:[0,0,1]
	v_pk_mul_f32 v[52:53], v[230:231], v[204:205] op_sel:[1,1] op_sel_hi:[1,0]
	v_pk_fma_f32 v[52:53], v[230:231], v[204:205], v[52:53] op_sel_hi:[0,1,1] neg_lo:[0,0,1]
	v_pk_add_f32 v[202:203], v[8:9], v[40:41]
	v_pk_add_f32 v[8:9], v[8:9], v[40:41] neg_lo:[0,1] neg_hi:[0,1]
	v_pk_add_f32 v[204:205], v[24:25], v[56:57]
	v_pk_add_f32 v[24:25], v[24:25], v[56:57] neg_lo:[0,1] neg_hi:[0,1]
	v_pk_add_f32 v[40:41], v[202:203], v[204:205]
	v_pk_add_f32 v[56:57], v[202:203], v[204:205] neg_lo:[0,1] neg_hi:[0,1]
	v_pk_add_f32 v[202:203], v[8:9], v[24:25] op_sel:[0,1] op_sel_hi:[1,0] neg_hi:[0,1]
	v_pk_add_f32 v[204:205], v[8:9], v[24:25] op_sel:[0,1] op_sel_hi:[1,0] neg_lo:[0,1]
	v_pk_mul_f32 v[8:9], v[224:225], v[202:203] op_sel:[1,1] op_sel_hi:[1,0]
	v_pk_fma_f32 v[8:9], v[224:225], v[202:203], v[8:9] op_sel_hi:[0,1,1] neg_lo:[0,0,1]
	v_pk_mul_f32 v[24:25], v[226:227], v[56:57] op_sel:[1,1] op_sel_hi:[1,0]
	v_pk_fma_f32 v[24:25], v[226:227], v[56:57], v[24:25] op_sel_hi:[0,1,1] neg_lo:[0,0,1]
; DI f32x2 cmul(f32x2 a, f32x2 b) { return mkf2(a.x * b.x - a.y * b.y, a.x * b.y + a.y * b.x); }
; DI void fft8192(f32x2* buf, const f32x2* __restrict__ tw) {
;     ...
; #pragma unroll
;     for (int e = 0; e < 8; ++e) {
;       const int i = tid + 256 * e;
;       const int q = i & (s - 1);
;       const int ps = i - q;
;       const float rev = (float)ps * (1.f / 8192.f);
;       const f32x2 w1 = mkf2(__builtin_amdgcn_cosf(rev), -__builtin_amdgcn_sinf(rev));
;       const f32x2 w2 = cmul(w1, w1), w3 = cmul(w1, w2);
;       const f32x2 apc = mkf2(a[e].x + c[e].x, a[e].y + c[e].y), amc = mkf2(a[e].x - c[e].x, a[e].y - c[e].y);
;       const f32x2 bpd = mkf2(b[e].x + d[e].x, b[e].y + d[e].y), bmd = mkf2(b[e].x - d[e].x, b[e].y - d[e].y);
;       const int o = 4 * i - 3 * q;
;       buf[SW(o)] = mkf2(apc.x + bpd.x, apc.y + bpd.y);
;       buf[SW(o + s)] = cmul(w1, mkf2(amc.x + bmd.y, amc.y - bmd.x));
;       buf[SW(o + 2 * s)] = cmul(w2, mkf2(apc.x - bpd.x, apc.y - bpd.y));
;       buf[SW(o + 3 * s)] = cmul(w3, mkf2(amc.x - bmd.y, amc.y + bmd.x));
;     }
	v_pk_mul_f32 v[56:57], v[230:231], v[204:205] op_sel:[1,1] op_sel_hi:[1,0]
	v_pk_fma_f32 v[56:57], v[230:231], v[204:205], v[56:57] op_sel_hi:[0,1,1] neg_lo:[0,0,1]
	v_mul_f32_e32 v214, 4.0, v201
	v_add_f32_e32 v214, 0x3e000000, v214
	v_cos_f32_e32 v224, v214
	v_sin_f32_e64 v225, -v214
	s_nop 0
	v_pk_mul_f32 v[206:207], v[224:225], v[224:225] op_sel:[1,1] op_sel_hi:[1,0]
	v_pk_fma_f32 v[226:227], v[224:225], v[224:225], v[206:207] op_sel_hi:[0,1,1] neg_lo:[0,0,1]
	v_pk_mul_f32 v[206:207], v[224:225], v[226:227] op_sel:[1,1] op_sel_hi:[1,0]
	v_pk_fma_f32 v[230:231], v[224:225], v[226:227], v[206:207] op_sel_hi:[0,1,1] neg_lo:[0,0,1]
	v_pk_add_f32 v[202:203], v[14:15], v[46:47]
	v_pk_add_f32 v[14:15], v[14:15], v[46:47] neg_lo:[0,1] neg_hi:[0,1]
	v_pk_add_f32 v[204:205], v[30:31], v[62:63]
	v_pk_add_f32 v[30:31], v[30:31], v[62:63] neg_lo:[0,1] neg_hi:[0,1]
	v_pk_add_f32 v[46:47], v[202:203], v[204:205]
	v_pk_add_f32 v[62:63], v[202:203], v[204:205] neg_lo:[0,1] neg_hi:[0,1]
	v_pk_add_f32 v[202:203], v[14:15], v[30:31] op_sel:[0,1] op_sel_hi:[1,0] neg_hi:[0,1]
	v_pk_add_f32 v[204:205], v[14:15], v[30:31] op_sel:[0,1] op_sel_hi:[1,0] neg_lo:[0,1]
	v_pk_mul_f32 v[14:15], v[224:225], v[202:203] op_sel:[1,1] op_sel_hi:[1,0]
	v_pk_fma_f32 v[14:15], v[224:225], v[202:203], v[14:15] op_sel_hi:[0,1,1] neg_lo:[0,0,1]
	v_pk_mul_f32 v[30:31], v[226:227], v[62:63] op_sel:[1,1] op_sel_hi:[1,0]
	v_pk_fma_f32 v[30:31], v[226:227], v[62:63], v[30:31] op_sel_hi:[0,1,1] neg_lo:[0,0,1]
	v_pk_mul_f32 v[62:63], v[230:231], v[204:205] op_sel:[1,1] op_sel_hi:[1,0]
	v_pk_fma_f32 v[62:63], v[230:231], v[204:205], v[62:63] op_sel_hi:[0,1,1] neg_lo:[0,0,1]
	v_pk_add_f32 v[202:203], v[10:11], v[42:43]
	v_pk_add_f32 v[10:11], v[10:11], v[42:43] neg_lo:[0,1] neg_hi:[0,1]
	v_pk_add_f32 v[204:205], v[26:27], v[58:59]
	v_pk_add_f32 v[26:27], v[26:27], v[58:59] neg_lo:[0,1] neg_hi:[0,1]
	v_pk_add_f32 v[42:43], v[202:203], v[204:205]
	v_pk_add_f32 v[58:59], v[202:203], v[204:205] neg_lo:[0,1] neg_hi:[0,1]
	v_pk_add_f32 v[202:203], v[10:11], v[26:27] op_sel:[0,1] op_sel_hi:[1,0] neg_hi:[0,1]
	v_pk_add_f32 v[204:205], v[10:11], v[26:27] op_sel:[0,1] op_sel_hi:[1,0] neg_lo:[0,1]
	v_pk_mul_f32 v[10:11], v[224:225], v[202:203] op_sel:[1,1] op_sel_hi:[1,0]
	v_pk_fma_f32 v[10:11], v[224:225], v[202:203], v[10:11] op_sel_hi:[0,1,1] neg_lo:[0,0,1]
	v_pk_mul_f32 v[26:27], v[226:227], v[58:59] op_sel:[1,1] op_sel_hi:[1,0]
	v_pk_fma_f32 v[26:27], v[226:227], v[58:59], v[26:27] op_sel_hi:[0,1,1] neg_lo:[0,0,1]
	v_pk_mul_f32 v[58:59], v[230:231], v[204:205] op_sel:[1,1] op_sel_hi:[1,0]
	v_pk_fma_f32 v[58:59], v[230:231], v[204:205], v[58:59] op_sel_hi:[0,1,1] neg_lo:[0,0,1]
	v_pk_add_f32 v[202:203], v[12:13], v[44:45]
	v_pk_add_f32 v[12:13], v[12:13], v[44:45] neg_lo:[0,1] neg_hi:[0,1]
	v_pk_add_f32 v[204:205], v[28:29], v[60:61]
	v_pk_add_f32 v[28:29], v[28:29], v[60:61] neg_lo:[0,1] neg_hi:[0,1]
	v_pk_add_f32 v[44:45], v[202:203], v[204:205]
	v_pk_add_f32 v[60:61], v[202:203], v[204:205] neg_lo:[0,1] neg_hi:[0,1]
	v_pk_add_f32 v[202:203], v[12:13], v[28:29] op_sel:[0,1] op_sel_hi:[1,0] neg_hi:[0,1]
	v_pk_add_f32 v[204:205], v[12:13], v[28:29] op_sel:[0,1] op_sel_hi:[1,0] neg_lo:[0,1]
	v_pk_mul_f32 v[12:13], v[224:225], v[202:203] op_sel:[1,1] op_sel_hi:[1,0]
	v_pk_fma_f32 v[12:13], v[224:225], v[202:203], v[12:13] op_sel_hi:[0,1,1] neg_lo:[0,0,1]
	v_pk_mul_f32 v[28:29], v[226:227], v[60:61] op_sel:[1,1] op_sel_hi:[1,0]
	v_pk_fma_f32 v[28:29], v[226:227], v[60:61], v[28:29] op_sel_hi:[0,1,1] neg_lo:[0,0,1]
	v_pk_mul_f32 v[60:61], v[230:231], v[204:205] op_sel:[1,1] op_sel_hi:[1,0]
	v_pk_fma_f32 v[60:61], v[230:231], v[204:205], v[60:61] op_sel_hi:[0,1,1] neg_lo:[0,0,1]
	v_pk_add_f32 v[202:203], v[16:17], v[48:49]
	v_pk_add_f32 v[16:17], v[16:17], v[48:49] neg_lo:[0,1] neg_hi:[0,1]
	v_pk_add_f32 v[204:205], v[32:33], v[64:65]
	v_pk_add_f32 v[32:33], v[32:33], v[64:65] neg_lo:[0,1] neg_hi:[0,1]
	v_pk_add_f32 v[48:49], v[202:203], v[204:205]
	v_pk_add_f32 v[64:65], v[202:203], v[204:205] neg_lo:[0,1] neg_hi:[0,1]
	v_pk_add_f32 v[202:203], v[16:17], v[32:33] op_sel:[0,1] op_sel_hi:[1,0] neg_hi:[0,1]
	v_pk_add_f32 v[204:205], v[16:17], v[32:33] op_sel:[0,1] op_sel_hi:[1,0] neg_lo:[0,1]
	v_pk_mul_f32 v[16:17], v[224:225], v[202:203] op_sel:[1,1] op_sel_hi:[1,0]
	v_pk_fma_f32 v[16:17], v[224:225], v[202:203], v[16:17] op_sel_hi:[0,1,1] neg_lo:[0,0,1]
	v_pk_mul_f32 v[32:33], v[226:227], v[64:65] op_sel:[1,1] op_sel_hi:[1,0]
	v_pk_fma_f32 v[32:33], v[226:227], v[64:65], v[32:33] op_sel_hi:[0,1,1] neg_lo:[0,0,1]
	v_pk_mul_f32 v[64:65], v[230:231], v[204:205] op_sel:[1,1] op_sel_hi:[1,0]
	v_pk_fma_f32 v[64:65], v[230:231], v[204:205], v[64:65] op_sel_hi:[0,1,1] neg_lo:[0,0,1]
	ds_write_b64 v164, v[38:39] offset:0
	v_xor_b32_e32 v156, 0x80, v164
	ds_write_b64 v156, v[34:35] offset:0
	v_xor_b32_e32 v158, 0x128, v164
	ds_write_b64 v158, v[36:37] offset:0
	v_xor_b32_e32 v160, 0x1a8, v164
	ds_write_b64 v160, v[40:41] offset:0
	v_xor_b32_e32 v162, 0x2d0, v164
	ds_write_b64 v162, v[6:7] offset:0
	v_xor_b32_e32 v156, 0x250, v164
	ds_write_b64 v156, v[2:3] offset:0
	v_xor_b32_e32 v158, 0x3f8, v164
	ds_write_b64 v158, v[4:5] offset:0
	v_xor_b32_e32 v160, 0x378, v164
	ds_write_b64 v160, v[8:9] offset:0
	v_xor_b32_e32 v162, 0x400, v164
	ds_write_b64 v162, v[22:23] offset:0
	v_xor_b32_e32 v156, 0x480, v164
	ds_write_b64 v156, v[18:19] offset:0
	v_xor_b32_e32 v158, 0x528, v164
	ds_write_b64 v158, v[20:21] offset:0
	v_xor_b32_e32 v160, 0x5a8, v164
	ds_write_b64 v160, v[24:25] offset:0
	v_xor_b32_e32 v162, 0x6d0, v164
	ds_write_b64 v162, v[54:55] offset:0
	v_xor_b32_e32 v156, 0x650, v164
	ds_write_b64 v156, v[50:51] offset:0
	v_xor_b32_e32 v158, 0x7f8, v164
	ds_write_b64 v158, v[52:53] offset:0
	v_xor_b32_e32 v160, 0x778, v164
	ds_write_b64 v160, v[56:57] offset:0
	ds_write_b64 v164, v[46:47] offset:32768
	v_xor_b32_e32 v162, 0x80, v164
	ds_write_b64 v162, v[42:43] offset:32768
	v_xor_b32_e32 v156, 0x128, v164
	ds_write_b64 v156, v[44:45] offset:32768
	v_xor_b32_e32 v158, 0x1a8, v164
	ds_write_b64 v158, v[48:49] offset:32768
	v_xor_b32_e32 v160, 0x2d0, v164
	ds_write_b64 v160, v[14:15] offset:32768
	v_xor_b32_e32 v162, 0x250, v164
	ds_write_b64 v162, v[10:11] offset:32768
	v_xor_b32_e32 v156, 0x3f8, v164
	ds_write_b64 v156, v[12:13] offset:32768
	v_xor_b32_e32 v158, 0x378, v164
	ds_write_b64 v158, v[16:17] offset:32768
	v_xor_b32_e32 v160, 0x400, v164
	ds_write_b64 v160, v[30:31] offset:32768
	v_xor_b32_e32 v162, 0x480, v164
	ds_write_b64 v162, v[26:27] offset:32768
	v_xor_b32_e32 v156, 0x528, v164
	ds_write_b64 v156, v[28:29] offset:32768
	v_xor_b32_e32 v158, 0x5a8, v164
	ds_write_b64 v158, v[32:33] offset:32768
	v_xor_b32_e32 v160, 0x6d0, v164
	ds_write_b64 v160, v[62:63] offset:32768
	v_xor_b32_e32 v162, 0x650, v164
	ds_write_b64 v162, v[58:59] offset:32768
	v_xor_b32_e32 v156, 0x7f8, v164
	ds_write_b64 v156, v[60:61] offset:32768
	v_xor_b32_e32 v158, 0x778, v164
	ds_write_b64 v158, v[64:65] offset:32768
	s_waitcnt lgkmcnt(0)
	s_barrier
; DI f32x2 cmul(f32x2 a, f32x2 b) { return mkf2(a.x * b.x - a.y * b.y, a.x * b.y + a.y * b.x); }
; DI void fft8192(f32x2* buf, const f32x2* __restrict__ tw) {
;     ...
;     __syncthreads();
; #pragma unroll
;     for (int e = 0; e < 8; ++e) {
;       const int i = tid + 256 * e;
;       const int pi = SW(i);
;       a[e] = buf[pi]; b[e] = buf[pi + 2048]; c[e] = buf[pi + 4096]; d[e] = buf[pi + 6144];
;     }
;     __syncthreads();
; #pragma unroll
;     for (int e = 0; e < 8; ++e) {
;       const int i = tid + 256 * e;
;       const int q = i & (s - 1);
;       const int ps = i - q;
;       const float rev = (float)ps * (1.f / 8192.f);
;       const f32x2 w1 = mkf2(__builtin_amdgcn_cosf(rev), -__builtin_amdgcn_sinf(rev));
;       const f32x2 w2 = cmul(w1, w1), w3 = cmul(w1, w2);
;       const f32x2 apc = mkf2(a[e].x + c[e].x, a[e].y + c[e].y), amc = mkf2(a[e].x - c[e].x, a[e].y - c[e].y);
;       const f32x2 bpd = mkf2(b[e].x + d[e].x, b[e].y + d[e].y), bmd = mkf2(b[e].x - d[e].x, b[e].y - d[e].y);
;       const int o = 4 * i - 3 * q;
;       buf[SW(o)] = mkf2(apc.x + bpd.x, apc.y + bpd.y);
;       buf[SW(o + s)] = cmul(w1, mkf2(amc.x + bmd.y, amc.y - bmd.x));
;       buf[SW(o + 2 * s)] = cmul(w2, mkf2(apc.x - bpd.x, apc.y - bpd.y));
;       buf[SW(o + 3 * s)] = cmul(w3, mkf2(amc.x - bmd.y, amc.y + bmd.x));
;     }
	ds_read2st64_b64 v[2:5], v154 offset0:0 offset1:32
	ds_read2st64_b64 v[6:9], v154 offset0:64 offset1:96
	ds_read2st64_b64 v[10:13], v154 offset0:4 offset1:36
	ds_read2st64_b64 v[14:17], v154 offset0:68 offset1:100
	ds_read2st64_b64 v[18:21], v154 offset0:8 offset1:40
	ds_read2st64_b64 v[22:25], v154 offset0:72 offset1:104
	ds_read2st64_b64 v[26:29], v154 offset0:12 offset1:44
	ds_read2st64_b64 v[30:33], v154 offset0:76 offset1:108
	ds_read2st64_b64 v[34:37], v154 offset0:16 offset1:48
	ds_read2st64_b64 v[38:41], v154 offset0:80 offset1:112
	ds_read2st64_b64 v[42:45], v154 offset0:20 offset1:52
	ds_read2st64_b64 v[46:49], v154 offset0:84 offset1:116
	ds_read2st64_b64 v[50:53], v154 offset0:24 offset1:56
	ds_read2st64_b64 v[54:57], v154 offset0:88 offset1:120
	ds_read2st64_b64 v[58:61], v154 offset0:28 offset1:60
	ds_read2st64_b64 v[62:65], v154 offset0:92 offset1:124
	s_waitcnt lgkmcnt(14)
	v_pk_add_f32 v[202:203], v[2:3], v[6:7]
	v_pk_add_f32 v[2:3], v[2:3], v[6:7] neg_lo:[0,1] neg_hi:[0,1]
	v_pk_add_f32 v[204:205], v[4:5], v[8:9]
	v_pk_add_f32 v[4:5], v[4:5], v[8:9] neg_lo:[0,1] neg_hi:[0,1]
	v_pk_add_f32 v[6:7], v[202:203], v[204:205]
	v_pk_add_f32 v[8:9], v[202:203], v[204:205] neg_lo:[0,1] neg_hi:[0,1]
	v_pk_add_f32 v[202:203], v[2:3], v[4:5] op_sel:[0,1] op_sel_hi:[1,0] neg_hi:[0,1]
	v_pk_add_f32 v[4:5], v[2:3], v[4:5] op_sel:[0,1] op_sel_hi:[1,0] neg_lo:[0,1]
	v_pk_mov_b32 v[2:3], v[202:203], v[202:203] op_sel:[0,1]
	v_cos_f32_e32 v210, 0x3d000000
	v_sin_f32_e32 v211, 0xbd000000
	s_waitcnt lgkmcnt(12)
	v_pk_add_f32 v[202:203], v[10:11], v[14:15]
	v_pk_add_f32 v[10:11], v[10:11], v[14:15] neg_lo:[0,1] neg_hi:[0,1]
	v_pk_add_f32 v[204:205], v[12:13], v[16:17]
	v_pk_add_f32 v[12:13], v[12:13], v[16:17] neg_lo:[0,1] neg_hi:[0,1]
	v_pk_add_f32 v[14:15], v[202:203], v[204:205]
	v_pk_add_f32 v[16:17], v[202:203], v[204:205] neg_lo:[0,1] neg_hi:[0,1]
	v_pk_add_f32 v[202:203], v[10:11], v[12:13] op_sel:[0,1] op_sel_hi:[1,0] neg_hi:[0,1]
	v_pk_add_f32 v[204:205], v[10:11], v[12:13] op_sel:[0,1] op_sel_hi:[1,0] neg_lo:[0,1]
	v_pk_mul_f32 v[206:207], v[210:211], v[210:211] op_sel:[1,1] op_sel_hi:[1,0]
	v_pk_fma_f32 v[212:213], v[210:211], v[210:211], v[206:207] op_sel_hi:[0,1,1] neg_lo:[0,0,1]
	v_pk_mul_f32 v[206:207], v[210:211], v[212:213] op_sel:[1,1] op_sel_hi:[1,0]
	v_pk_fma_f32 v[220:221], v[210:211], v[212:213], v[206:207] op_sel_hi:[0,1,1] neg_lo:[0,0,1]
	v_pk_mul_f32 v[10:11], v[210:211], v[202:203] op_sel:[1,1] op_sel_hi:[1,0]
	v_pk_fma_f32 v[10:11], v[210:211], v[202:203], v[10:11] op_sel_hi:[0,1,1] neg_lo:[0,0,1]
	v_pk_mul_f32 v[12:13], v[212:213], v[16:17] op_sel:[1,1] op_sel_hi:[1,0]
	v_pk_fma_f32 v[12:13], v[212:213], v[16:17], v[12:13] op_sel_hi:[0,1,1] neg_lo:[0,0,1]
	v_pk_mul_f32 v[16:17], v[220:221], v[204:205] op_sel:[1,1] op_sel_hi:[1,0]
	v_pk_fma_f32 v[16:17], v[220:221], v[204:205], v[16:17] op_sel_hi:[0,1,1] neg_lo:[0,0,1]
	v_cos_f32_e32 v210, 0x3d800000
	v_sin_f32_e32 v211, 0xbd800000
	s_waitcnt lgkmcnt(10)
	v_pk_add_f32 v[202:203], v[18:19], v[22:23]
	v_pk_add_f32 v[18:19], v[18:19], v[22:23] neg_lo:[0,1] neg_hi:[0,1]
	v_pk_add_f32 v[204:205], v[20:21], v[24:25]
	v_pk_add_f32 v[20:21], v[20:21], v[24:25] neg_lo:[0,1] neg_hi:[0,1]
	v_pk_add_f32 v[22:23], v[202:203], v[204:205]
	v_pk_add_f32 v[24:25], v[202:203], v[204:205] neg_lo:[0,1] neg_hi:[0,1]
	v_pk_add_f32 v[202:203], v[18:19], v[20:21] op_sel:[0,1] op_sel_hi:[1,0] neg_hi:[0,1]
	v_pk_add_f32 v[204:205], v[18:19], v[20:21] op_sel:[0,1] op_sel_hi:[1,0] neg_lo:[0,1]
	v_pk_mul_f32 v[206:207], v[210:211], v[210:211] op_sel:[1,1] op_sel_hi:[1,0]
	v_pk_fma_f32 v[212:213], v[210:211], v[210:211], v[206:207] op_sel_hi:[0,1,1] neg_lo:[0,0,1]
	v_pk_mul_f32 v[206:207], v[210:211], v[212:213] op_sel:[1,1] op_sel_hi:[1,0]
	v_pk_fma_f32 v[220:221], v[210:211], v[212:213], v[206:207] op_sel_hi:[0,1,1] neg_lo:[0,0,1]
	v_pk_mul_f32 v[18:19], v[210:211], v[202:203] op_sel:[1,1] op_sel_hi:[1,0]
	v_pk_fma_f32 v[18:19], v[210:211], v[202:203], v[18:19] op_sel_hi:[0,1,1] neg_lo:[0,0,1]
	v_pk_mul_f32 v[20:21], v[212:213], v[24:25] op_sel:[1,1] op_sel_hi:[1,0]
	v_pk_fma_f32 v[20:21], v[212:213], v[24:25], v[20:21] op_sel_hi:[0,1,1] neg_lo:[0,0,1]
	v_pk_mul_f32 v[24:25], v[220:221], v[204:205] op_sel:[1,1] op_sel_hi:[1,0]
	v_pk_fma_f32 v[24:25], v[220:221], v[204:205], v[24:25] op_sel_hi:[0,1,1] neg_lo:[0,0,1]
	v_cos_f32_e32 v210, 0x3dc00000
	v_sin_f32_e32 v211, 0xbdc00000
	s_waitcnt lgkmcnt(8)
	v_pk_add_f32 v[202:203], v[26:27], v[30:31]
	v_pk_add_f32 v[26:27], v[26:27], v[30:31] neg_lo:[0,1] neg_hi:[0,1]
	v_pk_add_f32 v[204:205], v[28:29], v[32:33]
	v_pk_add_f32 v[28:29], v[28:29], v[32:33] neg_lo:[0,1] neg_hi:[0,1]
	v_pk_add_f32 v[30:31], v[202:203], v[204:205]
	v_pk_add_f32 v[32:33], v[202:203], v[204:205] neg_lo:[0,1] neg_hi:[0,1]
	v_pk_add_f32 v[202:203], v[26:27], v[28:29] op_sel:[0,1] op_sel_hi:[1,0] neg_hi:[0,1]
	v_pk_add_f32 v[204:205], v[26:27], v[28:29] op_sel:[0,1] op_sel_hi:[1,0] neg_lo:[0,1]
	v_pk_mul_f32 v[206:207], v[210:211], v[210:211] op_sel:[1,1] op_sel_hi:[1,0]
	v_pk_fma_f32 v[212:213], v[210:211], v[210:211], v[206:207] op_sel_hi:[0,1,1] neg_lo:[0,0,1]
	v_pk_mul_f32 v[206:207], v[210:211], v[212:213] op_sel:[1,1] op_sel_hi:[1,0]
	v_pk_fma_f32 v[220:221], v[210:211], v[212:213], v[206:207] op_sel_hi:[0,1,1] neg_lo:[0,0,1]
	v_pk_mul_f32 v[26:27], v[210:211], v[202:203] op_sel:[1,1] op_sel_hi:[1,0]
	v_pk_fma_f32 v[26:27], v[210:211], v[202:203], v[26:27] op_sel_hi:[0,1,1] neg_lo:[0,0,1]
	v_pk_mul_f32 v[28:29], v[212:213], v[32:33] op_sel:[1,1] op_sel_hi:[1,0]
	v_pk_fma_f32 v[28:29], v[212:213], v[32:33], v[28:29] op_sel_hi:[0,1,1] neg_lo:[0,0,1]
	v_pk_mul_f32 v[32:33], v[220:221], v[204:205] op_sel:[1,1] op_sel_hi:[1,0]
	v_pk_fma_f32 v[32:33], v[220:221], v[204:205], v[32:33] op_sel_hi:[0,1,1] neg_lo:[0,0,1]
	v_cos_f32_e32 v210, 0x3e000000
	v_sin_f32_e32 v211, 0xbe000000
	s_waitcnt lgkmcnt(6)
; DI f32x2 cmul(f32x2 a, f32x2 b) { return mkf2(a.x * b.x - a.y * b.y, a.x * b.y + a.y * b.x); }
; DI void fft8192(f32x2* buf, const f32x2* __restrict__ tw) {
;     ...
; #pragma unroll
;     for (int e = 0; e < 8; ++e) {
;       const int i = tid + 256 * e;
;       const int q = i & (s - 1);
;       const int ps = i - q;
;       const float rev = (float)ps * (1.f / 8192.f);
;       const f32x2 w1 = mkf2(__builtin_amdgcn_cosf(rev), -__builtin_amdgcn_sinf(rev));
;       const f32x2 w2 = cmul(w1, w1), w3 = cmul(w1, w2);
;       const f32x2 apc = mkf2(a[e].x + c[e].x, a[e].y + c[e].y), amc = mkf2(a[e].x - c[e].x, a[e].y - c[e].y);
;       const f32x2 bpd = mkf2(b[e].x + d[e].x, b[e].y + d[e].y), bmd = mkf2(b[e].x - d[e].x, b[e].y - d[e].y);
;       const int o = 4 * i - 3 * q;
;       buf[SW(o)] = mkf2(apc.x + bpd.x, apc.y + bpd.y);
;       buf[SW(o + s)] = cmul(w1, mkf2(amc.x + bmd.y, amc.y - bmd.x));
;       buf[SW(o + 2 * s)] = cmul(w2, mkf2(apc.x - bpd.x, apc.y - bpd.y));
;       buf[SW(o + 3 * s)] = cmul(w3, mkf2(amc.x - bmd.y, amc.y + bmd.x));
;     }
	v_pk_add_f32 v[202:203], v[34:35], v[38:39]
	v_pk_add_f32 v[34:35], v[34:35], v[38:39] neg_lo:[0,1] neg_hi:[0,1]
	v_pk_add_f32 v[204:205], v[36:37], v[40:41]
	v_pk_add_f32 v[36:37], v[36:37], v[40:41] neg_lo:[0,1] neg_hi:[0,1]
	v_pk_add_f32 v[38:39], v[202:203], v[204:205]
	v_pk_add_f32 v[40:41], v[202:203], v[204:205] neg_lo:[0,1] neg_hi:[0,1]
	v_pk_add_f32 v[202:203], v[34:35], v[36:37] op_sel:[0,1] op_sel_hi:[1,0] neg_hi:[0,1]
	v_pk_add_f32 v[204:205], v[34:35], v[36:37] op_sel:[0,1] op_sel_hi:[1,0] neg_lo:[0,1]
	v_pk_mul_f32 v[206:207], v[210:211], v[210:211] op_sel:[1,1] op_sel_hi:[1,0]
	v_pk_fma_f32 v[212:213], v[210:211], v[210:211], v[206:207] op_sel_hi:[0,1,1] neg_lo:[0,0,1]
	v_pk_mul_f32 v[206:207], v[210:211], v[212:213] op_sel:[1,1] op_sel_hi:[1,0]
	v_pk_fma_f32 v[220:221], v[210:211], v[212:213], v[206:207] op_sel_hi:[0,1,1] neg_lo:[0,0,1]
	v_pk_mul_f32 v[34:35], v[210:211], v[202:203] op_sel:[1,1] op_sel_hi:[1,0]
	v_pk_fma_f32 v[34:35], v[210:211], v[202:203], v[34:35] op_sel_hi:[0,1,1] neg_lo:[0,0,1]
	v_pk_mul_f32 v[36:37], v[212:213], v[40:41] op_sel:[1,1] op_sel_hi:[1,0]
	v_pk_fma_f32 v[36:37], v[212:213], v[40:41], v[36:37] op_sel_hi:[0,1,1] neg_lo:[0,0,1]
	v_pk_mul_f32 v[40:41], v[220:221], v[204:205] op_sel:[1,1] op_sel_hi:[1,0]
	v_pk_fma_f32 v[40:41], v[220:221], v[204:205], v[40:41] op_sel_hi:[0,1,1] neg_lo:[0,0,1]
	v_cos_f32_e32 v210, 0x3e200000
	v_sin_f32_e32 v211, 0xbe200000
	s_waitcnt lgkmcnt(4)
	v_pk_add_f32 v[202:203], v[42:43], v[46:47]
	v_pk_add_f32 v[42:43], v[42:43], v[46:47] neg_lo:[0,1] neg_hi:[0,1]
	v_pk_add_f32 v[204:205], v[44:45], v[48:49]
	v_pk_add_f32 v[44:45], v[44:45], v[48:49] neg_lo:[0,1] neg_hi:[0,1]
	v_pk_add_f32 v[46:47], v[202:203], v[204:205]
	v_pk_add_f32 v[48:49], v[202:203], v[204:205] neg_lo:[0,1] neg_hi:[0,1]
	v_pk_add_f32 v[202:203], v[42:43], v[44:45] op_sel:[0,1] op_sel_hi:[1,0] neg_hi:[0,1]
	v_pk_add_f32 v[204:205], v[42:43], v[44:45] op_sel:[0,1] op_sel_hi:[1,0] neg_lo:[0,1]
	v_pk_mul_f32 v[206:207], v[210:211], v[210:211] op_sel:[1,1] op_sel_hi:[1,0]
	v_pk_fma_f32 v[212:213], v[210:211], v[210:211], v[206:207] op_sel_hi:[0,1,1] neg_lo:[0,0,1]
	v_pk_mul_f32 v[206:207], v[210:211], v[212:213] op_sel:[1,1] op_sel_hi:[1,0]
	v_pk_fma_f32 v[220:221], v[210:211], v[212:213], v[206:207] op_sel_hi:[0,1,1] neg_lo:[0,0,1]
	v_pk_mul_f32 v[42:43], v[210:211], v[202:203] op_sel:[1,1] op_sel_hi:[1,0]
	v_pk_fma_f32 v[42:43], v[210:211], v[202:203], v[42:43] op_sel_hi:[0,1,1] neg_lo:[0,0,1]
	v_pk_mul_f32 v[44:45], v[212:213], v[48:49] op_sel:[1,1] op_sel_hi:[1,0]
	v_pk_fma_f32 v[44:45], v[212:213], v[48:49], v[44:45] op_sel_hi:[0,1,1] neg_lo:[0,0,1]
	v_pk_mul_f32 v[48:49], v[220:221], v[204:205] op_sel:[1,1] op_sel_hi:[1,0]
	v_pk_fma_f32 v[48:49], v[220:221], v[204:205], v[48:49] op_sel_hi:[0,1,1] neg_lo:[0,0,1]
	v_cos_f32_e32 v210, 0x3e400000
	v_sin_f32_e32 v211, 0xbe400000
	s_waitcnt lgkmcnt(2)
	v_pk_add_f32 v[202:203], v[50:51], v[54:55]
	v_pk_add_f32 v[50:51], v[50:51], v[54:55] neg_lo:[0,1] neg_hi:[0,1]
	v_pk_add_f32 v[204:205], v[52:53], v[56:57]
	v_pk_add_f32 v[52:53], v[52:53], v[56:57] neg_lo:[0,1] neg_hi:[0,1]
	v_pk_add_f32 v[54:55], v[202:203], v[204:205]
	v_pk_add_f32 v[56:57], v[202:203], v[204:205] neg_lo:[0,1] neg_hi:[0,1]
	v_pk_add_f32 v[202:203], v[50:51], v[52:53] op_sel:[0,1] op_sel_hi:[1,0] neg_hi:[0,1]
	v_pk_add_f32 v[204:205], v[50:51], v[52:53] op_sel:[0,1] op_sel_hi:[1,0] neg_lo:[0,1]
	v_pk_mul_f32 v[206:207], v[210:211], v[210:211] op_sel:[1,1] op_sel_hi:[1,0]
	v_pk_fma_f32 v[212:213], v[210:211], v[210:211], v[206:207] op_sel_hi:[0,1,1] neg_lo:[0,0,1]
	v_pk_mul_f32 v[206:207], v[210:211], v[212:213] op_sel:[1,1] op_sel_hi:[1,0]
	v_pk_fma_f32 v[220:221], v[210:211], v[212:213], v[206:207] op_sel_hi:[0,1,1] neg_lo:[0,0,1]
	v_pk_mul_f32 v[50:51], v[210:211], v[202:203] op_sel:[1,1] op_sel_hi:[1,0]
	v_pk_fma_f32 v[50:51], v[210:211], v[202:203], v[50:51] op_sel_hi:[0,1,1] neg_lo:[0,0,1]
	v_pk_mul_f32 v[52:53], v[212:213], v[56:57] op_sel:[1,1] op_sel_hi:[1,0]
	v_pk_fma_f32 v[52:53], v[212:213], v[56:57], v[52:53] op_sel_hi:[0,1,1] neg_lo:[0,0,1]
	v_pk_mul_f32 v[56:57], v[220:221], v[204:205] op_sel:[1,1] op_sel_hi:[1,0]
	v_pk_fma_f32 v[56:57], v[220:221], v[204:205], v[56:57] op_sel_hi:[0,1,1] neg_lo:[0,0,1]
	v_cos_f32_e32 v210, 0x3e600000
	v_sin_f32_e32 v211, 0xbe600000
	s_waitcnt lgkmcnt(0)
	v_pk_add_f32 v[202:203], v[58:59], v[62:63]
	v_pk_add_f32 v[58:59], v[58:59], v[62:63] neg_lo:[0,1] neg_hi:[0,1]
	v_pk_add_f32 v[204:205], v[60:61], v[64:65]
	v_pk_add_f32 v[60:61], v[60:61], v[64:65] neg_lo:[0,1] neg_hi:[0,1]
	v_pk_add_f32 v[62:63], v[202:203], v[204:205]
	v_pk_add_f32 v[64:65], v[202:203], v[204:205] neg_lo:[0,1] neg_hi:[0,1]
	v_pk_add_f32 v[202:203], v[58:59], v[60:61] op_sel:[0,1] op_sel_hi:[1,0] neg_hi:[0,1]
	v_pk_add_f32 v[204:205], v[58:59], v[60:61] op_sel:[0,1] op_sel_hi:[1,0] neg_lo:[0,1]
	v_pk_mul_f32 v[206:207], v[210:211], v[210:211] op_sel:[1,1] op_sel_hi:[1,0]
	v_pk_fma_f32 v[212:213], v[210:211], v[210:211], v[206:207] op_sel_hi:[0,1,1] neg_lo:[0,0,1]
	v_pk_mul_f32 v[206:207], v[210:211], v[212:213] op_sel:[1,1] op_sel_hi:[1,0]
	v_pk_fma_f32 v[220:221], v[210:211], v[212:213], v[206:207] op_sel_hi:[0,1,1] neg_lo:[0,0,1]
	v_pk_mul_f32 v[58:59], v[210:211], v[202:203] op_sel:[1,1] op_sel_hi:[1,0]
	v_pk_fma_f32 v[58:59], v[210:211], v[202:203], v[58:59] op_sel_hi:[0,1,1] neg_lo:[0,0,1]
	v_pk_mul_f32 v[60:61], v[212:213], v[64:65] op_sel:[1,1] op_sel_hi:[1,0]
	v_pk_fma_f32 v[60:61], v[212:213], v[64:65], v[60:61] op_sel_hi:[0,1,1] neg_lo:[0,0,1]
	v_pk_mul_f32 v[64:65], v[220:221], v[204:205] op_sel:[1,1] op_sel_hi:[1,0]
	v_pk_fma_f32 v[64:65], v[220:221], v[204:205], v[64:65] op_sel_hi:[0,1,1] neg_lo:[0,0,1]
	s_barrier
; DI f32x2 cmul(f32x2 a, f32x2 b) { return mkf2(a.x * b.x - a.y * b.y, a.x * b.y + a.y * b.x); }
; DI void fft8192(f32x2* buf, const f32x2* __restrict__ tw) {
;     ...
; #pragma unroll
;     for (int e = 0; e < 8; ++e) {
;       const int i = tid + 256 * e;
;       const int q = i & (s - 1);
;       const int ps = i - q;
;       const float rev = (float)ps * (1.f / 8192.f);
;       const f32x2 w1 = mkf2(__builtin_amdgcn_cosf(rev), -__builtin_amdgcn_sinf(rev));
;       const f32x2 w2 = cmul(w1, w1), w3 = cmul(w1, w2);
;       const f32x2 apc = mkf2(a[e].x + c[e].x, a[e].y + c[e].y), amc = mkf2(a[e].x - c[e].x, a[e].y - c[e].y);
;       const f32x2 bpd = mkf2(b[e].x + d[e].x, b[e].y + d[e].y), bmd = mkf2(b[e].x - d[e].x, b[e].y - d[e].y);
;       const int o = 4 * i - 3 * q;
;       buf[SW(o)] = mkf2(apc.x + bpd.x, apc.y + bpd.y);
;       buf[SW(o + s)] = cmul(w1, mkf2(amc.x + bmd.y, amc.y - bmd.x));
;       buf[SW(o + 2 * s)] = cmul(w2, mkf2(apc.x - bpd.x, apc.y - bpd.y));
;       buf[SW(o + 3 * s)] = cmul(w3, mkf2(amc.x - bmd.y, amc.y + bmd.x));
;     }
	v_pk_add_f32 v[202:203], v[6:7], v[38:39]
	v_pk_add_f32 v[6:7], v[6:7], v[38:39] neg_lo:[0,1] neg_hi:[0,1]
	v_pk_add_f32 v[204:205], v[22:23], v[54:55]
	v_pk_add_f32 v[22:23], v[22:23], v[54:55] neg_lo:[0,1] neg_hi:[0,1]
	v_pk_add_f32 v[38:39], v[202:203], v[204:205]
	v_pk_add_f32 v[54:55], v[202:203], v[204:205] neg_lo:[0,1] neg_hi:[0,1]
	v_pk_add_f32 v[202:203], v[6:7], v[22:23] op_sel:[0,1] op_sel_hi:[1,0] neg_hi:[0,1]
	v_pk_add_f32 v[22:23], v[6:7], v[22:23] op_sel:[0,1] op_sel_hi:[1,0] neg_lo:[0,1]
	v_pk_mov_b32 v[6:7], v[202:203], v[202:203] op_sel:[0,1]
	v_pk_add_f32 v[202:203], v[2:3], v[34:35]
	v_pk_add_f32 v[2:3], v[2:3], v[34:35] neg_lo:[0,1] neg_hi:[0,1]
	v_pk_add_f32 v[204:205], v[18:19], v[50:51]
	v_pk_add_f32 v[18:19], v[18:19], v[50:51] neg_lo:[0,1] neg_hi:[0,1]
	v_pk_add_f32 v[34:35], v[202:203], v[204:205]
	v_pk_add_f32 v[50:51], v[202:203], v[204:205] neg_lo:[0,1] neg_hi:[0,1]
	v_pk_add_f32 v[202:203], v[2:3], v[18:19] op_sel:[0,1] op_sel_hi:[1,0] neg_hi:[0,1]
	v_pk_add_f32 v[18:19], v[2:3], v[18:19] op_sel:[0,1] op_sel_hi:[1,0] neg_lo:[0,1]
	v_pk_mov_b32 v[2:3], v[202:203], v[202:203] op_sel:[0,1]
	v_pk_add_f32 v[202:203], v[8:9], v[36:37]
	v_pk_add_f32 v[8:9], v[8:9], v[36:37] neg_lo:[0,1] neg_hi:[0,1]
	v_pk_add_f32 v[204:205], v[20:21], v[52:53]
	v_pk_add_f32 v[20:21], v[20:21], v[52:53] neg_lo:[0,1] neg_hi:[0,1]
	v_pk_add_f32 v[36:37], v[202:203], v[204:205]
	v_pk_add_f32 v[52:53], v[202:203], v[204:205] neg_lo:[0,1] neg_hi:[0,1]
	v_pk_add_f32 v[202:203], v[8:9], v[20:21] op_sel:[0,1] op_sel_hi:[1,0] neg_hi:[0,1]
	v_pk_add_f32 v[20:21], v[8:9], v[20:21] op_sel:[0,1] op_sel_hi:[1,0] neg_lo:[0,1]
	v_pk_mov_b32 v[8:9], v[202:203], v[202:203] op_sel:[0,1]
	v_pk_add_f32 v[202:203], v[4:5], v[40:41]
	v_pk_add_f32 v[4:5], v[4:5], v[40:41] neg_lo:[0,1] neg_hi:[0,1]
	v_pk_add_f32 v[204:205], v[24:25], v[56:57]
	v_pk_add_f32 v[24:25], v[24:25], v[56:57] neg_lo:[0,1] neg_hi:[0,1]
	v_pk_add_f32 v[40:41], v[202:203], v[204:205]
	v_pk_add_f32 v[56:57], v[202:203], v[204:205] neg_lo:[0,1] neg_hi:[0,1]
	v_pk_add_f32 v[202:203], v[4:5], v[24:25] op_sel:[0,1] op_sel_hi:[1,0] neg_hi:[0,1]
	v_pk_add_f32 v[24:25], v[4:5], v[24:25] op_sel:[0,1] op_sel_hi:[1,0] neg_lo:[0,1]
	v_pk_mov_b32 v[4:5], v[202:203], v[202:203] op_sel:[0,1]
	v_cos_f32_e32 v224, 0x3e000000
	v_sin_f32_e32 v225, 0xbe000000
	s_nop 0
	v_pk_mul_f32 v[206:207], v[224:225], v[224:225] op_sel:[1,1] op_sel_hi:[1,0]
	v_pk_fma_f32 v[226:227], v[224:225], v[224:225], v[206:207] op_sel_hi:[0,1,1] neg_lo:[0,0,1]
	v_pk_mul_f32 v[206:207], v[224:225], v[226:227] op_sel:[1,1] op_sel_hi:[1,0]
	v_pk_fma_f32 v[230:231], v[224:225], v[226:227], v[206:207] op_sel_hi:[0,1,1] neg_lo:[0,0,1]
	v_pk_add_f32 v[202:203], v[14:15], v[46:47]
	v_pk_add_f32 v[14:15], v[14:15], v[46:47] neg_lo:[0,1] neg_hi:[0,1]
	v_pk_add_f32 v[204:205], v[30:31], v[62:63]
	v_pk_add_f32 v[30:31], v[30:31], v[62:63] neg_lo:[0,1] neg_hi:[0,1]
	v_pk_add_f32 v[46:47], v[202:203], v[204:205]
	v_pk_add_f32 v[62:63], v[202:203], v[204:205] neg_lo:[0,1] neg_hi:[0,1]
	v_pk_add_f32 v[202:203], v[14:15], v[30:31] op_sel:[0,1] op_sel_hi:[1,0] neg_hi:[0,1]
	v_pk_add_f32 v[204:205], v[14:15], v[30:31] op_sel:[0,1] op_sel_hi:[1,0] neg_lo:[0,1]
	v_pk_mul_f32 v[14:15], v[224:225], v[202:203] op_sel:[1,1] op_sel_hi:[1,0]
	v_pk_fma_f32 v[14:15], v[224:225], v[202:203], v[14:15] op_sel_hi:[0,1,1] neg_lo:[0,0,1]
	v_pk_mul_f32 v[30:31], v[226:227], v[62:63] op_sel:[1,1] op_sel_hi:[1,0]
	v_pk_fma_f32 v[30:31], v[226:227], v[62:63], v[30:31] op_sel_hi:[0,1,1] neg_lo:[0,0,1]
	v_pk_mul_f32 v[62:63], v[230:231], v[204:205] op_sel:[1,1] op_sel_hi:[1,0]
	v_pk_fma_f32 v[62:63], v[230:231], v[204:205], v[62:63] op_sel_hi:[0,1,1] neg_lo:[0,0,1]
	v_pk_add_f32 v[202:203], v[10:11], v[42:43]
	v_pk_add_f32 v[10:11], v[10:11], v[42:43] neg_lo:[0,1] neg_hi:[0,1]
	v_pk_add_f32 v[204:205], v[26:27], v[58:59]
	v_pk_add_f32 v[26:27], v[26:27], v[58:59] neg_lo:[0,1] neg_hi:[0,1]
	v_pk_add_f32 v[42:43], v[202:203], v[204:205]
	v_pk_add_f32 v[58:59], v[202:203], v[204:205] neg_lo:[0,1] neg_hi:[0,1]
	v_pk_add_f32 v[202:203], v[10:11], v[26:27] op_sel:[0,1] op_sel_hi:[1,0] neg_hi:[0,1]
	v_pk_add_f32 v[204:205], v[10:11], v[26:27] op_sel:[0,1] op_sel_hi:[1,0] neg_lo:[0,1]
	v_pk_mul_f32 v[10:11], v[224:225], v[202:203] op_sel:[1,1] op_sel_hi:[1,0]
	v_pk_fma_f32 v[10:11], v[224:225], v[202:203], v[10:11] op_sel_hi:[0,1,1] neg_lo:[0,0,1]
	v_pk_mul_f32 v[26:27], v[226:227], v[58:59] op_sel:[1,1] op_sel_hi:[1,0]
	v_pk_fma_f32 v[26:27], v[226:227], v[58:59], v[26:27] op_sel_hi:[0,1,1] neg_lo:[0,0,1]
	v_pk_mul_f32 v[58:59], v[230:231], v[204:205] op_sel:[1,1] op_sel_hi:[1,0]
	v_pk_fma_f32 v[58:59], v[230:231], v[204:205], v[58:59] op_sel_hi:[0,1,1] neg_lo:[0,0,1]
	v_pk_add_f32 v[202:203], v[12:13], v[44:45]
	v_pk_add_f32 v[12:13], v[12:13], v[44:45] neg_lo:[0,1] neg_hi:[0,1]
	v_pk_add_f32 v[204:205], v[28:29], v[60:61]
	v_pk_add_f32 v[28:29], v[28:29], v[60:61] neg_lo:[0,1] neg_hi:[0,1]
	v_pk_add_f32 v[44:45], v[202:203], v[204:205]
	v_pk_add_f32 v[60:61], v[202:203], v[204:205] neg_lo:[0,1] neg_hi:[0,1]
	v_pk_add_f32 v[202:203], v[12:13], v[28:29] op_sel:[0,1] op_sel_hi:[1,0] neg_hi:[0,1]
	v_pk_add_f32 v[204:205], v[12:13], v[28:29] op_sel:[0,1] op_sel_hi:[1,0] neg_lo:[0,1]
	v_pk_mul_f32 v[12:13], v[224:225], v[202:203] op_sel:[1,1] op_sel_hi:[1,0]
	v_pk_fma_f32 v[12:13], v[224:225], v[202:203], v[12:13] op_sel_hi:[0,1,1] neg_lo:[0,0,1]
	v_pk_mul_f32 v[28:29], v[226:227], v[60:61] op_sel:[1,1] op_sel_hi:[1,0]
	v_pk_fma_f32 v[28:29], v[226:227], v[60:61], v[28:29] op_sel_hi:[0,1,1] neg_lo:[0,0,1]
	v_pk_mul_f32 v[60:61], v[230:231], v[204:205] op_sel:[1,1] op_sel_hi:[1,0]
; DI void fft8192(f32x2* buf, const f32x2* __restrict__ tw) {
;     ...
;   {
;     f32x2 a[16], b[16];
;     __syncthreads();
; #pragma unroll
;     for (int e = 0; e < 16; ++e) { const int pi = SW(tid + 256 * e); a[e] = buf[pi]; b[e] = buf[pi + 4096]; }
;     __syncthreads();
; #pragma unroll
;     for (int e = 0; e < 16; ++e) {
;       const int pi = SW(tid + 256 * e);
;       buf[pi] = mkf2(a[e].x + b[e].x, a[e].y + b[e].y);
;       buf[pi + 4096] = mkf2(a[e].x - b[e].x, a[e].y - b[e].y);
;     }
;     __syncthreads();
;   }
; DI void hyena_unit(KP p, int l, int c, char* smem) {
;     ...
;       const u16* g0 = Zhy + (size_t)(b0 * 1536 + gcol) * 4096;
;       const u16* g1 = Zhy + (size_t)(b1 * 1536 + gcol) * 4096;
; #pragma unroll 4
;       for (int jj = 0; jj < 16; ++jj) {
;         const int t = tid + 256 * jj;
;         const f32x2 r = buf[SW(t)];
;         const float y0 = r.x * (1.f / 8192.f), y1 = -r.y * (1.f / 8192.f);
;         const float x0 = sconv3(g0, t, 4096, gw0, gw1, gw2, gb), x1 = sconv3(g1, t, 4096, gw0, gw1, gw2, gb);
	v_pk_fma_f32 v[60:61], v[230:231], v[204:205], v[60:61] op_sel_hi:[0,1,1] neg_lo:[0,0,1]
	v_pk_add_f32 v[202:203], v[16:17], v[48:49]
	v_pk_add_f32 v[16:17], v[16:17], v[48:49] neg_lo:[0,1] neg_hi:[0,1]
	v_pk_add_f32 v[204:205], v[32:33], v[64:65]
	v_pk_add_f32 v[32:33], v[32:33], v[64:65] neg_lo:[0,1] neg_hi:[0,1]
	v_pk_add_f32 v[48:49], v[202:203], v[204:205]
	v_pk_add_f32 v[64:65], v[202:203], v[204:205] neg_lo:[0,1] neg_hi:[0,1]
	v_pk_add_f32 v[202:203], v[16:17], v[32:33] op_sel:[0,1] op_sel_hi:[1,0] neg_hi:[0,1]
	v_pk_add_f32 v[204:205], v[16:17], v[32:33] op_sel:[0,1] op_sel_hi:[1,0] neg_lo:[0,1]
	v_pk_mul_f32 v[16:17], v[224:225], v[202:203] op_sel:[1,1] op_sel_hi:[1,0]
	v_pk_fma_f32 v[16:17], v[224:225], v[202:203], v[16:17] op_sel_hi:[0,1,1] neg_lo:[0,0,1]
	v_pk_mul_f32 v[32:33], v[226:227], v[64:65] op_sel:[1,1] op_sel_hi:[1,0]
	v_pk_fma_f32 v[32:33], v[226:227], v[64:65], v[32:33] op_sel_hi:[0,1,1] neg_lo:[0,0,1]
	v_pk_mul_f32 v[64:65], v[230:231], v[204:205] op_sel:[1,1] op_sel_hi:[1,0]
	v_pk_fma_f32 v[64:65], v[230:231], v[204:205], v[64:65] op_sel_hi:[0,1,1] neg_lo:[0,0,1]
	v_pk_add_f32 v[202:203], v[38:39], v[46:47]
	v_pk_add_f32 v[204:205], v[34:35], v[42:43]
	v_pk_add_f32 v[206:207], v[36:37], v[44:45]
	v_pk_add_f32 v[208:209], v[40:41], v[48:49]
	v_pk_add_f32 v[210:211], v[6:7], v[14:15]
	v_pk_add_f32 v[212:213], v[2:3], v[10:11]
	v_pk_add_f32 v[220:221], v[8:9], v[12:13]
	v_pk_add_f32 v[224:225], v[4:5], v[16:17]
	v_pk_add_f32 v[226:227], v[54:55], v[30:31]
	v_pk_add_f32 v[230:231], v[50:51], v[26:27]
	v_pk_add_f32 v[232:233], v[52:53], v[28:29]
	v_pk_add_f32 v[236:237], v[56:57], v[32:33]
	v_pk_add_f32 v[238:239], v[22:23], v[62:63]
	v_pk_add_f32 v[240:241], v[18:19], v[58:59]
	v_pk_add_f32 v[244:245], v[20:21], v[60:61]
	v_pk_add_f32 v[246:247], v[24:25], v[64:65]
	ds_write_b64 v154, v[202:203] offset:0
	ds_write_b64 v154, v[204:205] offset:2048
	ds_write_b64 v154, v[206:207] offset:4096
	ds_write_b64 v154, v[208:209] offset:6144
	ds_write_b64 v154, v[210:211] offset:8192
	ds_write_b64 v154, v[212:213] offset:10240
	ds_write_b64 v154, v[220:221] offset:12288
	ds_write_b64 v154, v[224:225] offset:14336
	ds_write_b64 v154, v[226:227] offset:16384
	ds_write_b64 v154, v[230:231] offset:18432
	ds_write_b64 v154, v[232:233] offset:20480
	ds_write_b64 v154, v[236:237] offset:22528
	ds_write_b64 v154, v[238:239] offset:24576
	ds_write_b64 v154, v[240:241] offset:26624
	ds_write_b64 v154, v[244:245] offset:28672
	ds_write_b64 v154, v[246:247] offset:30720
	s_lshl_b32 s2, s83, 11
	s_lshl_b32 s4, s78, 10
	s_sub_i32 s2, s28, s2
	s_sub_i32 s4, s6, s4
	s_ashr_i32 s3, s2, 31
	s_ashr_i32 s5, s4, 31
	s_lshl_b64 s[2:3], s[2:3], 13
	s_lshl_b64 s[4:5], s[4:5], 13
	s_add_u32 s8, s55, s2
	s_addc_u32 s9, s81, s3
	s_add_u32 s10, s55, s4
	s_addc_u32 s11, s81, s5
	s_add_i32 s2, s82, s21
	s_ashr_i32 s3, s2, 31
	s_lshl_b64 s[2:3], s[2:3], 13
	s_add_u32 s6, s80, s2
	s_addc_u32 s7, s76, s3
	s_add_i32 s4, s29, s21
	s_ashr_i32 s5, s4, 31
	s_lshl_b64 s[4:5], s[4:5], 13
	s_add_u32 s12, s80, s4
	s_addc_u32 s13, s76, s5
	s_and_b64 s[4:5], s[96:97], exec
	s_cselect_b32 s5, s25, s9
	s_cselect_b32 s4, s24, s8
	s_cselect_b32 s9, s27, s11
	s_cselect_b32 s8, s26, s10
	v_lshl_add_u64 v[4:5], s[4:5], 0, v[68:69]
	s_add_i32 s4, s77, s82
	s_ashr_i32 s5, s4, 31
	s_lshl_b64 s[4:5], s[4:5], 13
	v_lshl_add_u64 v[2:3], s[8:9], 0, v[68:69]
	v_lshl_add_u64 v[6:7], v[70:71], 0, s[4:5]
	v_lshl_add_u64 v[8:9], v[70:71], 0, s[2:3]
	s_mov_b64 s[22:23], 0
	v_mov_b32_e32 v198, v66
	s_waitcnt lgkmcnt(0)
	s_barrier
	v_lshlrev_b32_e32 v201, 1, v66
	v_xor_b32_e32 v203, v66, v155
	v_add_u32_e32 v202, 0x1000, v201
	v_lshlrev_b32_e32 v203, 3, v203
	s_mov_b64 s[8:9], 0x1000
	v_lshl_add_u64 v[204:205], v[4:5], 0, s[8:9]
	v_lshl_add_u64 v[206:207], v[2:3], 0, s[8:9]
	v_cmp_eq_u32_e64 s[8:9], 0, v66
	v_cmp_eq_u32_e32 vcc, 0xff, v66
	s_mov_b64 s[10:11], vcc
	ds_read_b64 v[224:225], v203
	ds_read_b64 v[226:227], v203 offset:2048
	ds_read_b64 v[230:231], v203 offset:4096
	ds_read_b64 v[232:233], v203 offset:6144
	ds_read_b64 v[236:237], v203 offset:8192
	ds_read_b64 v[238:239], v203 offset:10240
	ds_read_b64 v[240:241], v203 offset:12288
	ds_read_b64 v[244:245], v203 offset:14336
	global_load_ushort v10, v201, s[6:7] offset:-2
	global_load_ushort v11, v201, s[6:7] offset:0
	global_load_ushort v12, v201, s[6:7] offset:2
	global_load_ushort v13, v201, s[12:13] offset:-2
	global_load_ushort v14, v201, s[12:13] offset:0
	global_load_ushort v15, v201, s[12:13] offset:2
	global_load_ushort v16, v201, s[6:7] offset:510
	global_load_ushort v17, v201, s[6:7] offset:512
	global_load_ushort v18, v201, s[6:7] offset:514
	global_load_ushort v19, v201, s[12:13] offset:510
	global_load_ushort v20, v201, s[12:13] offset:512
	global_load_ushort v21, v201, s[12:13] offset:514
	global_load_ushort v22, v201, s[6:7] offset:1022
	global_load_ushort v23, v201, s[6:7] offset:1024
	global_load_ushort v24, v201, s[6:7] offset:1026
	global_load_ushort v25, v201, s[12:13] offset:1022
	global_load_ushort v26, v201, s[12:13] offset:1024
	global_load_ushort v27, v201, s[12:13] offset:1026
	global_load_ushort v28, v201, s[6:7] offset:1534
	global_load_ushort v29, v201, s[6:7] offset:1536
	global_load_ushort v30, v201, s[6:7] offset:1538
	global_load_ushort v31, v201, s[12:13] offset:1534
	global_load_ushort v32, v201, s[12:13] offset:1536
	global_load_ushort v34, v201, s[12:13] offset:1538
	global_load_ushort v35, v201, s[6:7] offset:2046
	global_load_ushort v36, v201, s[6:7] offset:2048
	global_load_ushort v37, v201, s[6:7] offset:2050
	global_load_ushort v38, v201, s[12:13] offset:2046
	global_load_ushort v39, v201, s[12:13] offset:2048
	global_load_ushort v40, v201, s[12:13] offset:2050
	global_load_ushort v41, v201, s[6:7] offset:2558
	global_load_ushort v42, v201, s[6:7] offset:2560
	global_load_ushort v43, v201, s[6:7] offset:2562
	global_load_ushort v44, v201, s[12:13] offset:2558
	global_load_ushort v45, v201, s[12:13] offset:2560
	global_load_ushort v46, v201, s[12:13] offset:2562
	global_load_ushort v47, v201, s[6:7] offset:3070
	global_load_ushort v48, v201, s[6:7] offset:3072
	global_load_ushort v49, v201, s[6:7] offset:3074
	global_load_ushort v50, v201, s[12:13] offset:3070
	global_load_ushort v51, v201, s[12:13] offset:3072
	global_load_ushort v52, v201, s[12:13] offset:3074
	global_load_ushort v53, v201, s[6:7] offset:3582
	global_load_ushort v54, v201, s[6:7] offset:3584
	global_load_ushort v55, v201, s[6:7] offset:3586
	global_load_ushort v56, v201, s[12:13] offset:3582
	global_load_ushort v57, v201, s[12:13] offset:3584
	global_load_ushort v58, v201, s[12:13] offset:3586
	s_waitcnt vmcnt(42)
; DI float bf2f(u16 v) { return __uint_as_float(((unsigned)v) << 16); }
; DI float sconv3(const u16* row, int t, int n, float w0, float w1, float w2, float bias) {
;   float xm = (t > 0) ? bf2f(row[t - 1]) : 0.f, x0 = bf2f(row[t]), xp = (t + 1 < n) ? bf2f(row[t + 1]) : 0.f;
;   return w0 * xm + w1 * x0 + w2 * xp + bias;
; }
; DI void hyena_unit(KP p, int l, int c, char* smem) {
;     ...
; #pragma unroll 4
;       for (int jj = 0; jj < 16; ++jj) {
;         const int t = tid + 256 * jj;
;         const f32x2 r = buf[SW(t)];
;         const float y0 = r.x * (1.f / 8192.f), y1 = -r.y * (1.f / 8192.f);
;         const float x0 = sconv3(g0, t, 4096, gw0, gw1, gw2, gb), x1 = sconv3(g1, t, 4096, gw0, gw1, gw2, gb);
;         if (o == 0) { r0[t] = f2bf(x0 * y0); r1[t] = f2bf(x1 * y1); }
;         else { y0p[t] = f2bf(x0 * y0); y1p[t] = f2bf(x1 * y1); }
;       }
	s_waitcnt lgkmcnt(0)
	v_cndmask_b32_e64 v10, v10, 0, s[8:9]
	v_cndmask_b32_e64 v13, v13, 0, s[8:9]
	v_lshlrev_b32_e32 v10, 16, v10
	v_lshlrev_b32_e32 v11, 16, v11
	v_lshlrev_b32_e32 v12, 16, v12
	v_lshlrev_b32_e32 v13, 16, v13
	v_lshlrev_b32_e32 v14, 16, v14
	v_lshlrev_b32_e32 v15, 16, v15
	v_mul_f32_e32 v11, v196, v11
	v_mul_f32_e32 v14, v196, v14
	v_fmac_f32_e32 v11, v74, v10
	v_fmac_f32_e32 v14, v74, v13
	v_fmac_f32_e32 v11, v75, v12
	v_fmac_f32_e32 v14, v75, v15
	v_mul_f32_e32 v10, 0x39000000, v224
	v_mul_f32_e32 v13, 0xb9000000, v225
	v_add_f32_e32 v11, v195, v11
	v_add_f32_e32 v14, v195, v14
	v_mul_f32_e32 v10, v10, v11
	v_mul_f32_e32 v13, v13, v14
	v_cvt_pk_bf16_f32 v10, v10, v10
	v_cvt_pk_bf16_f32 v13, v13, v13
	global_store_short v[4:5], v10, off
	global_store_short v[2:3], v13, off
	s_waitcnt vmcnt(38)
	v_lshlrev_b32_e32 v16, 16, v16
	v_lshlrev_b32_e32 v17, 16, v17
	v_lshlrev_b32_e32 v18, 16, v18
	v_lshlrev_b32_e32 v19, 16, v19
	v_lshlrev_b32_e32 v20, 16, v20
	v_lshlrev_b32_e32 v21, 16, v21
	v_mul_f32_e32 v17, v196, v17
	v_mul_f32_e32 v20, v196, v20
	v_fmac_f32_e32 v17, v74, v16
	v_fmac_f32_e32 v20, v74, v19
	v_fmac_f32_e32 v17, v75, v18
	v_fmac_f32_e32 v20, v75, v21
	v_mul_f32_e32 v16, 0x39000000, v226
	v_mul_f32_e32 v19, 0xb9000000, v227
	v_add_f32_e32 v17, v195, v17
	v_add_f32_e32 v20, v195, v20
	v_mul_f32_e32 v16, v16, v17
	v_mul_f32_e32 v19, v19, v20
	v_cvt_pk_bf16_f32 v16, v16, v16
	v_cvt_pk_bf16_f32 v19, v19, v19
	global_store_short v[4:5], v16, off offset:512
	global_store_short v[2:3], v19, off offset:512
	s_waitcnt vmcnt(34)
	v_lshlrev_b32_e32 v22, 16, v22
	v_lshlrev_b32_e32 v23, 16, v23
	v_lshlrev_b32_e32 v24, 16, v24
	v_lshlrev_b32_e32 v25, 16, v25
	v_lshlrev_b32_e32 v26, 16, v26
	v_lshlrev_b32_e32 v27, 16, v27
	v_mul_f32_e32 v23, v196, v23
	v_mul_f32_e32 v26, v196, v26
	v_fmac_f32_e32 v23, v74, v22
	v_fmac_f32_e32 v26, v74, v25
	v_fmac_f32_e32 v23, v75, v24
	v_fmac_f32_e32 v26, v75, v27
	v_mul_f32_e32 v22, 0x39000000, v230
	v_mul_f32_e32 v25, 0xb9000000, v231
	v_add_f32_e32 v23, v195, v23
	v_add_f32_e32 v26, v195, v26
	v_mul_f32_e32 v22, v22, v23
	v_mul_f32_e32 v25, v25, v26
	v_cvt_pk_bf16_f32 v22, v22, v22
	v_cvt_pk_bf16_f32 v25, v25, v25
	global_store_short v[4:5], v22, off offset:1024
	global_store_short v[2:3], v25, off offset:1024
	s_waitcnt vmcnt(30)
	v_lshlrev_b32_e32 v28, 16, v28
	v_lshlrev_b32_e32 v29, 16, v29
	v_lshlrev_b32_e32 v30, 16, v30
	v_lshlrev_b32_e32 v31, 16, v31
	v_lshlrev_b32_e32 v32, 16, v32
	v_lshlrev_b32_e32 v34, 16, v34
	v_mul_f32_e32 v29, v196, v29
	v_mul_f32_e32 v32, v196, v32
	v_fmac_f32_e32 v29, v74, v28
	v_fmac_f32_e32 v32, v74, v31
	v_fmac_f32_e32 v29, v75, v30
	v_fmac_f32_e32 v32, v75, v34
	v_mul_f32_e32 v28, 0x39000000, v232
	v_mul_f32_e32 v31, 0xb9000000, v233
	v_add_f32_e32 v29, v195, v29
	v_add_f32_e32 v32, v195, v32
	v_mul_f32_e32 v28, v28, v29
	v_mul_f32_e32 v31, v31, v32
	v_cvt_pk_bf16_f32 v28, v28, v28
	v_cvt_pk_bf16_f32 v31, v31, v31
	global_store_short v[4:5], v28, off offset:1536
	global_store_short v[2:3], v31, off offset:1536
	s_waitcnt vmcnt(26)
	v_lshlrev_b32_e32 v35, 16, v35
	v_lshlrev_b32_e32 v36, 16, v36
	v_lshlrev_b32_e32 v37, 16, v37
	v_lshlrev_b32_e32 v38, 16, v38
	v_lshlrev_b32_e32 v39, 16, v39
	v_lshlrev_b32_e32 v40, 16, v40
	v_mul_f32_e32 v36, v196, v36
	v_mul_f32_e32 v39, v196, v39
	v_fmac_f32_e32 v36, v74, v35
	v_fmac_f32_e32 v39, v74, v38
	v_fmac_f32_e32 v36, v75, v37
	v_fmac_f32_e32 v39, v75, v40
	v_mul_f32_e32 v35, 0x39000000, v236
	v_mul_f32_e32 v38, 0xb9000000, v237
	v_add_f32_e32 v36, v195, v36
	v_add_f32_e32 v39, v195, v39
	v_mul_f32_e32 v35, v35, v36
	v_mul_f32_e32 v38, v38, v39
	v_cvt_pk_bf16_f32 v35, v35, v35
	v_cvt_pk_bf16_f32 v38, v38, v38
	global_store_short v[4:5], v35, off offset:2048
	global_store_short v[2:3], v38, off offset:2048
	s_waitcnt vmcnt(22)
	v_lshlrev_b32_e32 v41, 16, v41
	v_lshlrev_b32_e32 v42, 16, v42
	v_lshlrev_b32_e32 v43, 16, v43
	v_lshlrev_b32_e32 v44, 16, v44
	v_lshlrev_b32_e32 v45, 16, v45
	v_lshlrev_b32_e32 v46, 16, v46
	v_mul_f32_e32 v42, v196, v42
	v_mul_f32_e32 v45, v196, v45
	v_fmac_f32_e32 v42, v74, v41
	v_fmac_f32_e32 v45, v74, v44
	v_fmac_f32_e32 v42, v75, v43
	v_fmac_f32_e32 v45, v75, v46
	v_mul_f32_e32 v41, 0x39000000, v238
	v_mul_f32_e32 v44, 0xb9000000, v239
	v_add_f32_e32 v42, v195, v42
	v_add_f32_e32 v45, v195, v45
	v_mul_f32_e32 v41, v41, v42
	v_mul_f32_e32 v44, v44, v45
	v_cvt_pk_bf16_f32 v41, v41, v41
	v_cvt_pk_bf16_f32 v44, v44, v44
	global_store_short v[4:5], v41, off offset:2560
	global_store_short v[2:3], v44, off offset:2560
	s_waitcnt vmcnt(18)
	v_lshlrev_b32_e32 v47, 16, v47
	v_lshlrev_b32_e32 v48, 16, v48
	v_lshlrev_b32_e32 v49, 16, v49
	v_lshlrev_b32_e32 v50, 16, v50
	v_lshlrev_b32_e32 v51, 16, v51
	v_lshlrev_b32_e32 v52, 16, v52
	v_mul_f32_e32 v48, v196, v48
	v_mul_f32_e32 v51, v196, v51
	v_fmac_f32_e32 v48, v74, v47
	v_fmac_f32_e32 v51, v74, v50
	v_fmac_f32_e32 v48, v75, v49
	v_fmac_f32_e32 v51, v75, v52
	v_mul_f32_e32 v47, 0x39000000, v240
	v_mul_f32_e32 v50, 0xb9000000, v241
	v_add_f32_e32 v48, v195, v48
	v_add_f32_e32 v51, v195, v51
	v_mul_f32_e32 v47, v47, v48
	v_mul_f32_e32 v50, v50, v51
	v_cvt_pk_bf16_f32 v47, v47, v47
	v_cvt_pk_bf16_f32 v50, v50, v50
	global_store_short v[4:5], v47, off offset:3072
	global_store_short v[2:3], v50, off offset:3072
	s_waitcnt vmcnt(14)
; DI float bf2f(u16 v) { return __uint_as_float(((unsigned)v) << 16); }
; DI float sconv3(const u16* row, int t, int n, float w0, float w1, float w2, float bias) {
;   float xm = (t > 0) ? bf2f(row[t - 1]) : 0.f, x0 = bf2f(row[t]), xp = (t + 1 < n) ? bf2f(row[t + 1]) : 0.f;
;   return w0 * xm + w1 * x0 + w2 * xp + bias;
; }
; DI void hyena_unit(KP p, int l, int c, char* smem) {
;     ...
; #pragma unroll 4
;       for (int jj = 0; jj < 16; ++jj) {
;         const int t = tid + 256 * jj;
;         const f32x2 r = buf[SW(t)];
;         const float y0 = r.x * (1.f / 8192.f), y1 = -r.y * (1.f / 8192.f);
;         const float x0 = sconv3(g0, t, 4096, gw0, gw1, gw2, gb), x1 = sconv3(g1, t, 4096, gw0, gw1, gw2, gb);
;         if (o == 0) { r0[t] = f2bf(x0 * y0); r1[t] = f2bf(x1 * y1); }
;         else { y0p[t] = f2bf(x0 * y0); y1p[t] = f2bf(x1 * y1); }
;       }
	v_lshlrev_b32_e32 v53, 16, v53
	v_lshlrev_b32_e32 v54, 16, v54
	v_lshlrev_b32_e32 v55, 16, v55
	v_lshlrev_b32_e32 v56, 16, v56
	v_lshlrev_b32_e32 v57, 16, v57
	v_lshlrev_b32_e32 v58, 16, v58
	v_mul_f32_e32 v54, v196, v54
	v_mul_f32_e32 v57, v196, v57
	v_fmac_f32_e32 v54, v74, v53
	v_fmac_f32_e32 v57, v74, v56
	v_fmac_f32_e32 v54, v75, v55
	v_fmac_f32_e32 v57, v75, v58
	v_mul_f32_e32 v53, 0x39000000, v244
	v_mul_f32_e32 v56, 0xb9000000, v245
	v_add_f32_e32 v54, v195, v54
	v_add_f32_e32 v57, v195, v57
	v_mul_f32_e32 v53, v53, v54
	v_mul_f32_e32 v56, v56, v57
	v_cvt_pk_bf16_f32 v53, v53, v53
	v_cvt_pk_bf16_f32 v56, v56, v56
	global_store_short v[4:5], v53, off offset:3584
	global_store_short v[2:3], v56, off offset:3584
	ds_read_b64 v[224:225], v203 offset:16384
	ds_read_b64 v[226:227], v203 offset:18432
	ds_read_b64 v[230:231], v203 offset:20480
	ds_read_b64 v[232:233], v203 offset:22528
	ds_read_b64 v[236:237], v203 offset:24576
	ds_read_b64 v[238:239], v203 offset:26624
	ds_read_b64 v[240:241], v203 offset:28672
	ds_read_b64 v[244:245], v203 offset:30720
	global_load_ushort v10, v202, s[6:7] offset:-2
	global_load_ushort v11, v202, s[6:7] offset:0
	global_load_ushort v12, v202, s[6:7] offset:2
	global_load_ushort v13, v202, s[12:13] offset:-2
	global_load_ushort v14, v202, s[12:13] offset:0
	global_load_ushort v15, v202, s[12:13] offset:2
	global_load_ushort v16, v202, s[6:7] offset:510
	global_load_ushort v17, v202, s[6:7] offset:512
	global_load_ushort v18, v202, s[6:7] offset:514
	global_load_ushort v19, v202, s[12:13] offset:510
	global_load_ushort v20, v202, s[12:13] offset:512
	global_load_ushort v21, v202, s[12:13] offset:514
	global_load_ushort v22, v202, s[6:7] offset:1022
	global_load_ushort v23, v202, s[6:7] offset:1024
	global_load_ushort v24, v202, s[6:7] offset:1026
	global_load_ushort v25, v202, s[12:13] offset:1022
	global_load_ushort v26, v202, s[12:13] offset:1024
	global_load_ushort v27, v202, s[12:13] offset:1026
	global_load_ushort v28, v202, s[6:7] offset:1534
	global_load_ushort v29, v202, s[6:7] offset:1536
	global_load_ushort v30, v202, s[6:7] offset:1538
	global_load_ushort v31, v202, s[12:13] offset:1534
	global_load_ushort v32, v202, s[12:13] offset:1536
	global_load_ushort v34, v202, s[12:13] offset:1538
	global_load_ushort v35, v202, s[6:7] offset:2046
	global_load_ushort v36, v202, s[6:7] offset:2048
	global_load_ushort v37, v202, s[6:7] offset:2050
	global_load_ushort v38, v202, s[12:13] offset:2046
	global_load_ushort v39, v202, s[12:13] offset:2048
	global_load_ushort v40, v202, s[12:13] offset:2050
	global_load_ushort v41, v202, s[6:7] offset:2558
	global_load_ushort v42, v202, s[6:7] offset:2560
	global_load_ushort v43, v202, s[6:7] offset:2562
	global_load_ushort v44, v202, s[12:13] offset:2558
	global_load_ushort v45, v202, s[12:13] offset:2560
	global_load_ushort v46, v202, s[12:13] offset:2562
	global_load_ushort v47, v202, s[6:7] offset:3070
	global_load_ushort v48, v202, s[6:7] offset:3072
	global_load_ushort v49, v202, s[6:7] offset:3074
	global_load_ushort v50, v202, s[12:13] offset:3070
	global_load_ushort v51, v202, s[12:13] offset:3072
	global_load_ushort v52, v202, s[12:13] offset:3074
	global_load_ushort v53, v202, s[6:7] offset:3582
	global_load_ushort v54, v202, s[6:7] offset:3584
	global_load_ushort v55, v202, s[6:7] offset:3586
	global_load_ushort v56, v202, s[12:13] offset:3582
	global_load_ushort v57, v202, s[12:13] offset:3584
	global_load_ushort v58, v202, s[12:13] offset:3586
	s_waitcnt vmcnt(42)
	s_waitcnt lgkmcnt(0)
	v_lshlrev_b32_e32 v10, 16, v10
	v_lshlrev_b32_e32 v11, 16, v11
	v_lshlrev_b32_e32 v12, 16, v12
	v_lshlrev_b32_e32 v13, 16, v13
	v_lshlrev_b32_e32 v14, 16, v14
	v_lshlrev_b32_e32 v15, 16, v15
	v_mul_f32_e32 v11, v196, v11
	v_mul_f32_e32 v14, v196, v14
	v_fmac_f32_e32 v11, v74, v10
	v_fmac_f32_e32 v14, v74, v13
	v_fmac_f32_e32 v11, v75, v12
	v_fmac_f32_e32 v14, v75, v15
	v_mul_f32_e32 v10, 0x39000000, v224
	v_mul_f32_e32 v13, 0xb9000000, v225
	v_add_f32_e32 v11, v195, v11
	v_add_f32_e32 v14, v195, v14
	v_mul_f32_e32 v10, v10, v11
	v_mul_f32_e32 v13, v13, v14
	v_cvt_pk_bf16_f32 v10, v10, v10
	v_cvt_pk_bf16_f32 v13, v13, v13
	global_store_short v[204:205], v10, off
	global_store_short v[206:207], v13, off
	s_waitcnt vmcnt(38)
	v_lshlrev_b32_e32 v16, 16, v16
	v_lshlrev_b32_e32 v17, 16, v17
	v_lshlrev_b32_e32 v18, 16, v18
	v_lshlrev_b32_e32 v19, 16, v19
	v_lshlrev_b32_e32 v20, 16, v20
	v_lshlrev_b32_e32 v21, 16, v21
	v_mul_f32_e32 v17, v196, v17
	v_mul_f32_e32 v20, v196, v20
	v_fmac_f32_e32 v17, v74, v16
	v_fmac_f32_e32 v20, v74, v19
	v_fmac_f32_e32 v17, v75, v18
	v_fmac_f32_e32 v20, v75, v21
	v_mul_f32_e32 v16, 0x39000000, v226
	v_mul_f32_e32 v19, 0xb9000000, v227
	v_add_f32_e32 v17, v195, v17
	v_add_f32_e32 v20, v195, v20
	v_mul_f32_e32 v16, v16, v17
	v_mul_f32_e32 v19, v19, v20
	v_cvt_pk_bf16_f32 v16, v16, v16
	v_cvt_pk_bf16_f32 v19, v19, v19
	global_store_short v[204:205], v16, off offset:512
	global_store_short v[206:207], v19, off offset:512
	s_waitcnt vmcnt(34)
; DI float bf2f(u16 v) { return __uint_as_float(((unsigned)v) << 16); }
; DI float sconv3(const u16* row, int t, int n, float w0, float w1, float w2, float bias) {
;   float xm = (t > 0) ? bf2f(row[t - 1]) : 0.f, x0 = bf2f(row[t]), xp = (t + 1 < n) ? bf2f(row[t + 1]) : 0.f;
;   return w0 * xm + w1 * x0 + w2 * xp + bias;
; }
; DI void hyena_unit(KP p, int l, int c, char* smem) {
;     ...
; #pragma unroll 4
;       for (int jj = 0; jj < 16; ++jj) {
;         const int t = tid + 256 * jj;
;         const f32x2 r = buf[SW(t)];
;         const float y0 = r.x * (1.f / 8192.f), y1 = -r.y * (1.f / 8192.f);
;         const float x0 = sconv3(g0, t, 4096, gw0, gw1, gw2, gb), x1 = sconv3(g1, t, 4096, gw0, gw1, gw2, gb);
;         if (o == 0) { r0[t] = f2bf(x0 * y0); r1[t] = f2bf(x1 * y1); }
;         else { y0p[t] = f2bf(x0 * y0); y1p[t] = f2bf(x1 * y1); }
;       }
	v_lshlrev_b32_e32 v22, 16, v22
	v_lshlrev_b32_e32 v23, 16, v23
	v_lshlrev_b32_e32 v24, 16, v24
	v_lshlrev_b32_e32 v25, 16, v25
	v_lshlrev_b32_e32 v26, 16, v26
	v_lshlrev_b32_e32 v27, 16, v27
	v_mul_f32_e32 v23, v196, v23
	v_mul_f32_e32 v26, v196, v26
	v_fmac_f32_e32 v23, v74, v22
	v_fmac_f32_e32 v26, v74, v25
	v_fmac_f32_e32 v23, v75, v24
	v_fmac_f32_e32 v26, v75, v27
	v_mul_f32_e32 v22, 0x39000000, v230
	v_mul_f32_e32 v25, 0xb9000000, v231
	v_add_f32_e32 v23, v195, v23
	v_add_f32_e32 v26, v195, v26
	v_mul_f32_e32 v22, v22, v23
	v_mul_f32_e32 v25, v25, v26
	v_cvt_pk_bf16_f32 v22, v22, v22
	v_cvt_pk_bf16_f32 v25, v25, v25
	global_store_short v[204:205], v22, off offset:1024
	global_store_short v[206:207], v25, off offset:1024
	s_waitcnt vmcnt(30)
	v_lshlrev_b32_e32 v28, 16, v28
	v_lshlrev_b32_e32 v29, 16, v29
	v_lshlrev_b32_e32 v30, 16, v30
	v_lshlrev_b32_e32 v31, 16, v31
	v_lshlrev_b32_e32 v32, 16, v32
	v_lshlrev_b32_e32 v34, 16, v34
	v_mul_f32_e32 v29, v196, v29
	v_mul_f32_e32 v32, v196, v32
	v_fmac_f32_e32 v29, v74, v28
	v_fmac_f32_e32 v32, v74, v31
	v_fmac_f32_e32 v29, v75, v30
	v_fmac_f32_e32 v32, v75, v34
	v_mul_f32_e32 v28, 0x39000000, v232
	v_mul_f32_e32 v31, 0xb9000000, v233
	v_add_f32_e32 v29, v195, v29
	v_add_f32_e32 v32, v195, v32
	v_mul_f32_e32 v28, v28, v29
	v_mul_f32_e32 v31, v31, v32
	v_cvt_pk_bf16_f32 v28, v28, v28
	v_cvt_pk_bf16_f32 v31, v31, v31
	global_store_short v[204:205], v28, off offset:1536
	global_store_short v[206:207], v31, off offset:1536
	s_waitcnt vmcnt(26)
	v_lshlrev_b32_e32 v35, 16, v35
	v_lshlrev_b32_e32 v36, 16, v36
	v_lshlrev_b32_e32 v37, 16, v37
	v_lshlrev_b32_e32 v38, 16, v38
	v_lshlrev_b32_e32 v39, 16, v39
	v_lshlrev_b32_e32 v40, 16, v40
	v_mul_f32_e32 v36, v196, v36
	v_mul_f32_e32 v39, v196, v39
	v_fmac_f32_e32 v36, v74, v35
	v_fmac_f32_e32 v39, v74, v38
	v_fmac_f32_e32 v36, v75, v37
	v_fmac_f32_e32 v39, v75, v40
	v_mul_f32_e32 v35, 0x39000000, v236
	v_mul_f32_e32 v38, 0xb9000000, v237
	v_add_f32_e32 v36, v195, v36
	v_add_f32_e32 v39, v195, v39
	v_mul_f32_e32 v35, v35, v36
	v_mul_f32_e32 v38, v38, v39
	v_cvt_pk_bf16_f32 v35, v35, v35
	v_cvt_pk_bf16_f32 v38, v38, v38
	global_store_short v[204:205], v35, off offset:2048
	global_store_short v[206:207], v38, off offset:2048
	s_waitcnt vmcnt(22)
	v_lshlrev_b32_e32 v41, 16, v41
	v_lshlrev_b32_e32 v42, 16, v42
	v_lshlrev_b32_e32 v43, 16, v43
	v_lshlrev_b32_e32 v44, 16, v44
	v_lshlrev_b32_e32 v45, 16, v45
	v_lshlrev_b32_e32 v46, 16, v46
	v_mul_f32_e32 v42, v196, v42
	v_mul_f32_e32 v45, v196, v45
	v_fmac_f32_e32 v42, v74, v41
	v_fmac_f32_e32 v45, v74, v44
	v_fmac_f32_e32 v42, v75, v43
	v_fmac_f32_e32 v45, v75, v46
	v_mul_f32_e32 v41, 0x39000000, v238
	v_mul_f32_e32 v44, 0xb9000000, v239
	v_add_f32_e32 v42, v195, v42
	v_add_f32_e32 v45, v195, v45
	v_mul_f32_e32 v41, v41, v42
	v_mul_f32_e32 v44, v44, v45
	v_cvt_pk_bf16_f32 v41, v41, v41
	v_cvt_pk_bf16_f32 v44, v44, v44
	global_store_short v[204:205], v41, off offset:2560
	global_store_short v[206:207], v44, off offset:2560
	s_waitcnt vmcnt(18)
	v_lshlrev_b32_e32 v47, 16, v47
	v_lshlrev_b32_e32 v48, 16, v48
	v_lshlrev_b32_e32 v49, 16, v49
	v_lshlrev_b32_e32 v50, 16, v50
	v_lshlrev_b32_e32 v51, 16, v51
	v_lshlrev_b32_e32 v52, 16, v52
	v_mul_f32_e32 v48, v196, v48
	v_mul_f32_e32 v51, v196, v51
	v_fmac_f32_e32 v48, v74, v47
	v_fmac_f32_e32 v51, v74, v50
	v_fmac_f32_e32 v48, v75, v49
	v_fmac_f32_e32 v51, v75, v52
	v_mul_f32_e32 v47, 0x39000000, v240
	v_mul_f32_e32 v50, 0xb9000000, v241
	v_add_f32_e32 v48, v195, v48
	v_add_f32_e32 v51, v195, v51
	v_mul_f32_e32 v47, v47, v48
	v_mul_f32_e32 v50, v50, v51
	v_cvt_pk_bf16_f32 v47, v47, v47
	v_cvt_pk_bf16_f32 v50, v50, v50
	global_store_short v[204:205], v47, off offset:3072
	global_store_short v[206:207], v50, off offset:3072
	s_waitcnt vmcnt(14)
	v_cndmask_b32_e64 v55, v55, 0, s[10:11]
	v_cndmask_b32_e64 v58, v58, 0, s[10:11]
	v_lshlrev_b32_e32 v53, 16, v53
	v_lshlrev_b32_e32 v54, 16, v54
	v_lshlrev_b32_e32 v55, 16, v55
	v_lshlrev_b32_e32 v56, 16, v56
	v_lshlrev_b32_e32 v57, 16, v57
	v_lshlrev_b32_e32 v58, 16, v58
	v_mul_f32_e32 v54, v196, v54
	v_mul_f32_e32 v57, v196, v57
	v_fmac_f32_e32 v54, v74, v53
	v_fmac_f32_e32 v57, v74, v56
	v_fmac_f32_e32 v54, v75, v55
	v_fmac_f32_e32 v57, v75, v58
	v_mul_f32_e32 v53, 0x39000000, v244
	v_mul_f32_e32 v56, 0xb9000000, v245
	v_add_f32_e32 v54, v195, v54
	v_add_f32_e32 v57, v195, v57
	v_mul_f32_e32 v53, v53, v54
	v_mul_f32_e32 v56, v56, v57
	v_cvt_pk_bf16_f32 v53, v53, v53
	v_cvt_pk_bf16_f32 v56, v56, v56
	global_store_short v[204:205], v53, off offset:3584
	global_store_short v[206:207], v56, off offset:3584
	s_branch .LBB0_936
